# removed the per-phase s_setprio flips in the GEMM K-loops; pass1 state-update LDS reads batched; attention lane reductions via permlane
# speedup vs baseline: 1.0762x; 1.0058x over previous
.LBB0_106:
	s_add_i32 s41, 0, 0x10000
	v_add_u32_e32 v128, s41, v139
	ds_read_b128 v[142:145], v128
	ds_read_b128 v[146:149], v128 offset:1024
	ds_read_b128 v[150:153], v128 offset:2048
	ds_read_b128 v[154:157], v128 offset:3072
	s_add_u32 s20, s16, s18
	v_mov_b32_e32 v188, v129
	v_mov_b32_e32 v130, v135
	s_addc_u32 s21, s17, s19
	ds_read_b128 v[158:161], v141
	ds_read_b128 v[162:165], v141 offset:1024
	ds_read_b128 v[166:169], v141 offset:2048
	ds_read_b128 v[170:173], v141 offset:3072
	ds_read_b128 v[174:177], v141 offset:4096
	ds_read_b128 v[178:181], v141 offset:5120
	ds_read_b128 v[182:185], v141 offset:6144
	ds_read_b128 v[190:193], v141 offset:7168
	s_add_i32 s11, s28, 0xc000
	v_lshl_add_u64 v[186:187], s[20:21], 0, v[188:189]
	v_mov_b32_e32 v131, v189
	v_lshl_add_u64 v[186:187], v[186:187], 0, s[48:49]
	s_mov_b32 m0, s11
	v_lshl_add_u64 v[130:131], s[20:21], 0, v[130:131]
	s_add_i32 s40, s28, 0xe000
	global_load_lds_dwordx4 v[186:187], off
	v_lshl_add_u64 v[130:131], v[130:131], 0, s[48:49]
	s_mov_b32 m0, s40
	s_nop 0
	global_load_lds_dwordx4 v[130:131], off
	s_waitcnt lgkmcnt(8)
	s_barrier
	s_waitcnt lgkmcnt(0)
	s_waitcnt lgkmcnt(0)
	v_mfma_f32_16x16x32_bf16 v[124:127], v[142:145], v[158:161], v[124:127]
	v_mfma_f32_16x16x32_bf16 v[120:123], v[150:153], v[158:161], v[120:123]
	v_mfma_f32_16x16x32_bf16 v[116:119], v[142:145], v[166:169], v[116:119]
	v_mfma_f32_16x16x32_bf16 v[112:115], v[150:153], v[166:169], v[112:115]
	v_mfma_f32_16x16x32_bf16 v[108:111], v[142:145], v[174:177], v[108:111]
	v_mfma_f32_16x16x32_bf16 v[104:107], v[150:153], v[174:177], v[104:107]
	v_mfma_f32_16x16x32_bf16 v[100:103], v[142:145], v[182:185], v[100:103]
	v_mfma_f32_16x16x32_bf16 v[96:99], v[150:153], v[182:185], v[96:99]
	v_mfma_f32_16x16x32_bf16 v[124:127], v[146:149], v[162:165], v[124:127]
	v_mfma_f32_16x16x32_bf16 v[120:123], v[154:157], v[162:165], v[120:123]
	v_mfma_f32_16x16x32_bf16 v[116:119], v[146:149], v[170:173], v[116:119]
	v_mfma_f32_16x16x32_bf16 v[112:115], v[154:157], v[170:173], v[112:115]
	v_mfma_f32_16x16x32_bf16 v[108:111], v[146:149], v[178:181], v[108:111]
	v_mfma_f32_16x16x32_bf16 v[104:107], v[154:157], v[178:181], v[104:107]
	v_mfma_f32_16x16x32_bf16 v[100:103], v[146:149], v[190:193], v[100:103]
	v_mfma_f32_16x16x32_bf16 v[96:99], v[154:157], v[190:193], v[96:99]
	s_barrier
	s_add_i32 s43, 0, 0x14000
	s_add_u32 s22, s14, s18
	v_add_u32_e32 v130, s43, v139
	v_mov_b32_e32 v188, v133
	v_mov_b32_e32 v186, v137
	s_addc_u32 s23, s15, s19
	ds_read_b128 v[194:197], v130
	ds_read_b128 v[202:205], v130 offset:1024
	ds_read_b128 v[222:225], v130 offset:2048
	ds_read_b128 v[226:229], v130 offset:3072
	s_add_i32 s41, s41, s27
	v_lshl_add_u64 v[198:199], s[22:23], 0, v[188:189]
	v_mov_b32_e32 v187, v189
	v_lshl_add_u64 v[198:199], v[198:199], 0, s[88:89]
	s_mov_b32 m0, s41
	v_lshl_add_u64 v[186:187], s[22:23], 0, v[186:187]
	s_add_i32 s42, s41, 0x2000
	global_load_lds_dwordx4 v[198:199], off
	v_lshl_add_u64 v[186:187], v[186:187], 0, s[88:89]
	s_mov_b32 m0, s42
	s_nop 0
	global_load_lds_dwordx4 v[186:187], off
	s_barrier
	s_waitcnt lgkmcnt(0)
	s_waitcnt lgkmcnt(0)
	v_mfma_f32_16x16x32_bf16 v[92:95], v[194:197], v[158:161], v[92:95]
	v_mfma_f32_16x16x32_bf16 v[88:91], v[222:225], v[158:161], v[88:91]
	v_mfma_f32_16x16x32_bf16 v[84:87], v[194:197], v[166:169], v[84:87]
	v_mfma_f32_16x16x32_bf16 v[80:83], v[222:225], v[166:169], v[80:83]
	v_mfma_f32_16x16x32_bf16 v[76:79], v[194:197], v[174:177], v[76:79]
	v_mfma_f32_16x16x32_bf16 v[72:75], v[222:225], v[174:177], v[72:75]
	v_mfma_f32_16x16x32_bf16 v[68:71], v[194:197], v[182:185], v[68:71]
	v_mfma_f32_16x16x32_bf16 v[64:67], v[222:225], v[182:185], v[64:67]
	v_mfma_f32_16x16x32_bf16 v[92:95], v[202:205], v[162:165], v[92:95]
	v_mfma_f32_16x16x32_bf16 v[88:91], v[226:229], v[162:165], v[88:91]
	v_mfma_f32_16x16x32_bf16 v[84:87], v[202:205], v[170:173], v[84:87]
	v_mfma_f32_16x16x32_bf16 v[80:83], v[226:229], v[170:173], v[80:83]
	v_mfma_f32_16x16x32_bf16 v[76:79], v[202:205], v[178:181], v[76:79]
	v_mfma_f32_16x16x32_bf16 v[72:75], v[226:229], v[178:181], v[72:75]
	v_mfma_f32_16x16x32_bf16 v[68:71], v[202:205], v[190:193], v[68:71]
	v_mfma_f32_16x16x32_bf16 v[64:67], v[226:229], v[190:193], v[64:67]
	v_mov_b32_e32 v188, v129
	v_mov_b32_e32 v186, v135
	s_barrier
	ds_read_b128 v[158:161], v141 offset:16384
	ds_read_b128 v[162:165], v141 offset:17408
	ds_read_b128 v[166:169], v141 offset:18432
	ds_read_b128 v[170:173], v141 offset:19456
	ds_read_b128 v[174:177], v141 offset:20480
	ds_read_b128 v[178:181], v141 offset:21504
	ds_read_b128 v[182:185], v141 offset:22528
	ds_read_b128 v[190:193], v141 offset:23552
	v_mov_b32_e32 v187, v189
	v_lshl_add_u64 v[198:199], s[20:21], 0, v[188:189]
	s_mov_b32 m0, s28
	v_lshl_add_u64 v[198:199], v[198:199], 0, s[88:89]
	v_lshl_add_u64 v[186:187], s[20:21], 0, v[186:187]
	global_load_lds_dwordx4 v[198:199], off
	v_lshl_add_u64 v[186:187], v[186:187], 0, s[88:89]
	s_mov_b32 m0, s29
	s_nop 0
	global_load_lds_dwordx4 v[186:187], off
	s_barrier
	s_waitcnt lgkmcnt(0)
	s_waitcnt lgkmcnt(0)
	v_mfma_f32_16x16x32_bf16 v[60:63], v[142:145], v[158:161], v[60:63]
	v_mfma_f32_16x16x32_bf16 v[56:59], v[150:153], v[158:161], v[56:59]
	v_mfma_f32_16x16x32_bf16 v[52:55], v[142:145], v[166:169], v[52:55]
	v_mfma_f32_16x16x32_bf16 v[48:51], v[150:153], v[166:169], v[48:51]
	v_mfma_f32_16x16x32_bf16 v[44:47], v[142:145], v[174:177], v[44:47]
	v_mfma_f32_16x16x32_bf16 v[40:43], v[150:153], v[174:177], v[40:43]
	v_mfma_f32_16x16x32_bf16 v[36:39], v[142:145], v[182:185], v[36:39]
	v_mfma_f32_16x16x32_bf16 v[32:35], v[150:153], v[182:185], v[32:35]
	v_mfma_f32_16x16x32_bf16 v[60:63], v[146:149], v[162:165], v[60:63]
	v_mfma_f32_16x16x32_bf16 v[56:59], v[154:157], v[162:165], v[56:59]
	v_mfma_f32_16x16x32_bf16 v[52:55], v[146:149], v[170:173], v[52:55]
	v_mfma_f32_16x16x32_bf16 v[48:51], v[154:157], v[170:173], v[48:51]
	v_mfma_f32_16x16x32_bf16 v[44:47], v[146:149], v[178:181], v[44:47]
	v_mfma_f32_16x16x32_bf16 v[40:43], v[154:157], v[178:181], v[40:43]
	v_mfma_f32_16x16x32_bf16 v[36:39], v[146:149], v[190:193], v[36:39]
	v_mfma_f32_16x16x32_bf16 v[32:35], v[154:157], v[190:193], v[32:35]
	s_barrier
	v_mov_b32_e32 v188, v133
	v_mov_b32_e32 v142, v137
	s_add_i32 s43, s43, s27
	v_lshl_add_u64 v[144:145], s[22:23], 0, v[188:189]
	v_mov_b32_e32 v143, v189
	v_lshl_add_u64 v[144:145], v[144:145], 0, s[50:51]
	s_mov_b32 m0, s43
	v_lshl_add_u64 v[142:143], s[22:23], 0, v[142:143]
	s_add_i32 s44, s43, 0x2000
	global_load_lds_dwordx4 v[144:145], off
	v_lshl_add_u64 v[142:143], v[142:143], 0, s[50:51]
	s_mov_b32 m0, s44
	s_nop 0
	global_load_lds_dwordx4 v[142:143], off
	s_waitcnt vmcnt(6)
	s_barrier
	v_mfma_f32_16x16x32_bf16 v[28:31], v[194:197], v[158:161], v[28:31]
	v_mfma_f32_16x16x32_bf16 v[24:27], v[222:225], v[158:161], v[24:27]
	v_mfma_f32_16x16x32_bf16 v[20:23], v[194:197], v[166:169], v[20:23]
	v_mfma_f32_16x16x32_bf16 v[16:19], v[222:225], v[166:169], v[16:19]
	v_mfma_f32_16x16x32_bf16 v[12:15], v[194:197], v[174:177], v[12:15]
	v_mfma_f32_16x16x32_bf16 v[8:11], v[222:225], v[174:177], v[8:11]
	v_mfma_f32_16x16x32_bf16 v[4:7], v[194:197], v[182:185], v[4:7]
	v_mfma_f32_16x16x32_bf16 v[0:3], v[222:225], v[182:185], v[0:3]
	v_mfma_f32_16x16x32_bf16 v[28:31], v[202:205], v[162:165], v[28:31]
	v_mfma_f32_16x16x32_bf16 v[24:27], v[226:229], v[162:165], v[24:27]
	v_mfma_f32_16x16x32_bf16 v[20:23], v[202:205], v[170:173], v[20:23]
	v_mfma_f32_16x16x32_bf16 v[16:19], v[226:229], v[170:173], v[16:19]
	v_mfma_f32_16x16x32_bf16 v[12:15], v[202:205], v[178:181], v[12:15]
	v_mfma_f32_16x16x32_bf16 v[8:11], v[226:229], v[178:181], v[8:11]
	v_mfma_f32_16x16x32_bf16 v[4:7], v[202:205], v[190:193], v[4:7]
	v_mfma_f32_16x16x32_bf16 v[0:3], v[226:229], v[190:193], v[0:3]
	s_add_i32 s46, 0, 0x18000
	v_add_u32_e32 v131, s46, v139
	s_barrier
	ds_read_b128 v[142:145], v131
	ds_read_b128 v[146:149], v131 offset:1024
	ds_read_b128 v[150:153], v131 offset:2048
	ds_read_b128 v[154:157], v131 offset:3072
	v_mov_b32_e32 v188, v129
	v_mov_b32_e32 v186, v135
	ds_read_b128 v[158:161], v141 offset:32768
	ds_read_b128 v[162:165], v141 offset:33792
	ds_read_b128 v[166:169], v141 offset:34816
	ds_read_b128 v[170:173], v141 offset:35840
	ds_read_b128 v[174:177], v141 offset:36864
	ds_read_b128 v[178:181], v141 offset:37888
	ds_read_b128 v[182:185], v141 offset:38912
	ds_read_b128 v[190:193], v141 offset:39936
	v_mov_b32_e32 v187, v189
	v_lshl_add_u64 v[194:195], s[20:21], 0, v[188:189]
	s_mov_b32 m0, s30
	v_lshl_add_u64 v[194:195], v[194:195], 0, s[50:51]
	v_lshl_add_u64 v[186:187], s[20:21], 0, v[186:187]
	global_load_lds_dwordx4 v[194:195], off
	v_lshl_add_u64 v[186:187], v[186:187], 0, s[50:51]
	s_mov_b32 m0, s31
	s_nop 0
	global_load_lds_dwordx4 v[186:187], off
	s_waitcnt lgkmcnt(8)
	s_barrier
	s_waitcnt lgkmcnt(0)
	s_waitcnt lgkmcnt(0)
	v_mfma_f32_16x16x32_bf16 v[124:127], v[142:145], v[158:161], v[124:127]
	v_mfma_f32_16x16x32_bf16 v[120:123], v[150:153], v[158:161], v[120:123]
	v_mfma_f32_16x16x32_bf16 v[116:119], v[142:145], v[166:169], v[116:119]
	v_mfma_f32_16x16x32_bf16 v[112:115], v[150:153], v[166:169], v[112:115]
	v_mfma_f32_16x16x32_bf16 v[108:111], v[142:145], v[174:177], v[108:111]
	v_mfma_f32_16x16x32_bf16 v[104:107], v[150:153], v[174:177], v[104:107]
	v_mfma_f32_16x16x32_bf16 v[100:103], v[142:145], v[182:185], v[100:103]
	v_mfma_f32_16x16x32_bf16 v[96:99], v[150:153], v[182:185], v[96:99]
	v_mfma_f32_16x16x32_bf16 v[124:127], v[146:149], v[162:165], v[124:127]
	v_mfma_f32_16x16x32_bf16 v[120:123], v[154:157], v[162:165], v[120:123]
	v_mfma_f32_16x16x32_bf16 v[116:119], v[146:149], v[170:173], v[116:119]
	v_mfma_f32_16x16x32_bf16 v[112:115], v[154:157], v[170:173], v[112:115]
	v_mfma_f32_16x16x32_bf16 v[108:111], v[146:149], v[178:181], v[108:111]
	v_mfma_f32_16x16x32_bf16 v[104:107], v[154:157], v[178:181], v[104:107]
	v_mfma_f32_16x16x32_bf16 v[100:103], v[146:149], v[190:193], v[100:103]
	v_mfma_f32_16x16x32_bf16 v[96:99], v[154:157], v[190:193], v[96:99]
	s_barrier
	s_add_i32 s47, 0, 0x1c000
	v_add_u32_e32 v132, s47, v139
	v_mov_b32_e32 v188, v133
	v_mov_b32_e32 v186, v137
	ds_read_b128 v[194:197], v132
	ds_read_b128 v[202:205], v132 offset:1024
	ds_read_b128 v[222:225], v132 offset:2048
	ds_read_b128 v[226:229], v132 offset:3072
	s_add_i32 s46, s46, s27
	v_lshl_add_u64 v[198:199], s[22:23], 0, v[188:189]
	v_mov_b32_e32 v187, v189
	v_lshl_add_u64 v[198:199], v[198:199], 0, s[2:3]
	s_mov_b32 m0, s46
	v_lshl_add_u64 v[186:187], s[22:23], 0, v[186:187]
	s_add_i32 s45, s46, 0x2000
	global_load_lds_dwordx4 v[198:199], off
	v_lshl_add_u64 v[186:187], v[186:187], 0, s[2:3]
	s_mov_b32 m0, s45
	s_nop 0
	global_load_lds_dwordx4 v[186:187], off
	s_barrier
	s_waitcnt lgkmcnt(0)
	s_waitcnt lgkmcnt(0)
	v_mfma_f32_16x16x32_bf16 v[92:95], v[194:197], v[158:161], v[92:95]
	v_mfma_f32_16x16x32_bf16 v[88:91], v[222:225], v[158:161], v[88:91]
	v_mfma_f32_16x16x32_bf16 v[84:87], v[194:197], v[166:169], v[84:87]
	v_mfma_f32_16x16x32_bf16 v[80:83], v[222:225], v[166:169], v[80:83]
	v_mfma_f32_16x16x32_bf16 v[76:79], v[194:197], v[174:177], v[76:79]
	v_mfma_f32_16x16x32_bf16 v[72:75], v[222:225], v[174:177], v[72:75]
	v_mfma_f32_16x16x32_bf16 v[68:71], v[194:197], v[182:185], v[68:71]
	v_mfma_f32_16x16x32_bf16 v[64:67], v[222:225], v[182:185], v[64:67]
	v_mfma_f32_16x16x32_bf16 v[92:95], v[202:205], v[162:165], v[92:95]
	v_mfma_f32_16x16x32_bf16 v[88:91], v[226:229], v[162:165], v[88:91]
	v_mfma_f32_16x16x32_bf16 v[84:87], v[202:205], v[170:173], v[84:87]
	v_mfma_f32_16x16x32_bf16 v[80:83], v[226:229], v[170:173], v[80:83]
	v_mfma_f32_16x16x32_bf16 v[76:79], v[202:205], v[178:181], v[76:79]
	v_mfma_f32_16x16x32_bf16 v[72:75], v[226:229], v[178:181], v[72:75]
	v_mfma_f32_16x16x32_bf16 v[68:71], v[202:205], v[190:193], v[68:71]
	v_mfma_f32_16x16x32_bf16 v[64:67], v[226:229], v[190:193], v[64:67]
	v_mov_b32_e32 v188, v129
	v_mov_b32_e32 v186, v135
	s_barrier
	ds_read_b128 v[158:161], v141 offset:49152
	ds_read_b128 v[162:165], v141 offset:50176
	ds_read_b128 v[166:169], v141 offset:51200
	ds_read_b128 v[170:173], v141 offset:52224
	ds_read_b128 v[174:177], v141 offset:53248
	ds_read_b128 v[178:181], v141 offset:54272
	ds_read_b128 v[182:185], v141 offset:55296
	ds_read_b128 v[190:193], v141 offset:56320
	v_mov_b32_e32 v187, v189
	v_lshl_add_u64 v[198:199], s[20:21], 0, v[188:189]
	s_mov_b32 m0, s33
	v_lshl_add_u64 v[198:199], v[198:199], 0, s[2:3]
	v_lshl_add_u64 v[186:187], s[20:21], 0, v[186:187]
	global_load_lds_dwordx4 v[198:199], off
	v_lshl_add_u64 v[186:187], v[186:187], 0, s[2:3]
	s_mov_b32 m0, s34
	s_nop 0
	global_load_lds_dwordx4 v[186:187], off
	s_barrier
	s_waitcnt lgkmcnt(0)
	s_waitcnt lgkmcnt(0)
	v_mfma_f32_16x16x32_bf16 v[60:63], v[142:145], v[158:161], v[60:63]
	v_mfma_f32_16x16x32_bf16 v[56:59], v[150:153], v[158:161], v[56:59]
	v_mfma_f32_16x16x32_bf16 v[52:55], v[142:145], v[166:169], v[52:55]
	v_mfma_f32_16x16x32_bf16 v[48:51], v[150:153], v[166:169], v[48:51]
	v_mfma_f32_16x16x32_bf16 v[44:47], v[142:145], v[174:177], v[44:47]
	v_mfma_f32_16x16x32_bf16 v[40:43], v[150:153], v[174:177], v[40:43]
	v_mfma_f32_16x16x32_bf16 v[36:39], v[142:145], v[182:185], v[36:39]
	v_mfma_f32_16x16x32_bf16 v[32:35], v[150:153], v[182:185], v[32:35]
	v_mfma_f32_16x16x32_bf16 v[60:63], v[146:149], v[162:165], v[60:63]
	v_mfma_f32_16x16x32_bf16 v[56:59], v[154:157], v[162:165], v[56:59]
	v_mfma_f32_16x16x32_bf16 v[52:55], v[146:149], v[170:173], v[52:55]
	v_mfma_f32_16x16x32_bf16 v[48:51], v[154:157], v[170:173], v[48:51]
	v_mfma_f32_16x16x32_bf16 v[44:47], v[146:149], v[178:181], v[44:47]
	v_mfma_f32_16x16x32_bf16 v[40:43], v[154:157], v[178:181], v[40:43]
	v_mfma_f32_16x16x32_bf16 v[36:39], v[146:149], v[190:193], v[36:39]
	v_mfma_f32_16x16x32_bf16 v[32:35], v[154:157], v[190:193], v[32:35]
	s_barrier
	v_mov_b32_e32 v188, v133
	v_mov_b32_e32 v142, v137
	s_add_i32 s20, s47, s27
	v_lshl_add_u64 v[144:145], s[22:23], 0, v[188:189]
	v_mov_b32_e32 v143, v189
	v_lshl_add_u64 v[144:145], v[144:145], 0, s[52:53]
	s_mov_b32 m0, s20
	v_lshl_add_u64 v[142:143], s[22:23], 0, v[142:143]
	s_add_i32 s21, s20, 0x2000
	global_load_lds_dwordx4 v[144:145], off
	v_lshl_add_u64 v[142:143], v[142:143], 0, s[52:53]
	s_mov_b32 m0, s21
	s_nop 0
	global_load_lds_dwordx4 v[142:143], off
	s_waitcnt vmcnt(6)
	s_barrier
	v_mfma_f32_16x16x32_bf16 v[28:31], v[194:197], v[158:161], v[28:31]
	v_mfma_f32_16x16x32_bf16 v[24:27], v[222:225], v[158:161], v[24:27]
	v_mfma_f32_16x16x32_bf16 v[20:23], v[194:197], v[166:169], v[20:23]
	v_mfma_f32_16x16x32_bf16 v[16:19], v[222:225], v[166:169], v[16:19]
	v_mfma_f32_16x16x32_bf16 v[12:15], v[194:197], v[174:177], v[12:15]
	v_mfma_f32_16x16x32_bf16 v[8:11], v[222:225], v[174:177], v[8:11]
	v_mfma_f32_16x16x32_bf16 v[4:7], v[194:197], v[182:185], v[4:7]
	v_mfma_f32_16x16x32_bf16 v[0:3], v[222:225], v[182:185], v[0:3]
	v_mfma_f32_16x16x32_bf16 v[28:31], v[202:205], v[162:165], v[28:31]
	v_mfma_f32_16x16x32_bf16 v[24:27], v[226:229], v[162:165], v[24:27]
	v_mfma_f32_16x16x32_bf16 v[20:23], v[202:205], v[170:173], v[20:23]
	v_mfma_f32_16x16x32_bf16 v[16:19], v[226:229], v[170:173], v[16:19]
	v_mfma_f32_16x16x32_bf16 v[12:15], v[202:205], v[178:181], v[12:15]
	v_mfma_f32_16x16x32_bf16 v[8:11], v[226:229], v[178:181], v[8:11]
	v_mfma_f32_16x16x32_bf16 v[4:7], v[202:205], v[190:193], v[4:7]
	v_mfma_f32_16x16x32_bf16 v[0:3], v[226:229], v[190:193], v[0:3]
	s_add_i32 s9, s9, 2
	s_add_u32 s18, s18, 0x100
	s_addc_u32 s19, s19, 0
	s_cmp_lt_u32 s9, 28
	s_barrier
	s_cbranch_scc1 .LBB0_106
	ds_read_b128 v[142:145], v128
	ds_read_b128 v[146:149], v128 offset:1024
	ds_read_b128 v[150:153], v128 offset:2048
	ds_read_b128 v[154:157], v128 offset:3072
	s_add_u32 s14, s16, 0x80f80
	v_mov_b32_e32 v128, v135
	v_mov_b32_e32 v134, v129
	s_addc_u32 s15, s17, 0
	s_mov_b32 m0, s11
	ds_read_b128 v[158:161], v141
	ds_read_b128 v[162:165], v141 offset:1024
	ds_read_b128 v[166:169], v141 offset:2048
	ds_read_b128 v[170:173], v141 offset:3072
	ds_read_b128 v[174:177], v141 offset:4096
	ds_read_b128 v[178:181], v141 offset:5120
	ds_read_b128 v[182:185], v141 offset:6144
	ds_read_b128 v[190:193], v141 offset:7168
	s_nop 0
	global_load_lds_dwordx4 v134, s[14:15]
	s_mov_b32 m0, s40
	s_nop 0
	global_load_lds_dwordx4 v128, s[14:15]
	s_waitcnt lgkmcnt(8)
	s_barrier
	s_waitcnt lgkmcnt(0)
	s_waitcnt lgkmcnt(0)
	v_mfma_f32_16x16x32_bf16 v[124:127], v[142:145], v[158:161], v[124:127]
	v_mfma_f32_16x16x32_bf16 v[120:123], v[150:153], v[158:161], v[120:123]
	v_mfma_f32_16x16x32_bf16 v[116:119], v[142:145], v[166:169], v[116:119]
	v_mfma_f32_16x16x32_bf16 v[112:115], v[150:153], v[166:169], v[112:115]
	v_mfma_f32_16x16x32_bf16 v[108:111], v[142:145], v[174:177], v[108:111]
	v_mfma_f32_16x16x32_bf16 v[104:107], v[150:153], v[174:177], v[104:107]
	v_mfma_f32_16x16x32_bf16 v[100:103], v[142:145], v[182:185], v[100:103]
	v_mfma_f32_16x16x32_bf16 v[96:99], v[150:153], v[182:185], v[96:99]
	v_mfma_f32_16x16x32_bf16 v[124:127], v[146:149], v[162:165], v[124:127]
	v_mfma_f32_16x16x32_bf16 v[120:123], v[154:157], v[162:165], v[120:123]
	v_mfma_f32_16x16x32_bf16 v[116:119], v[146:149], v[170:173], v[116:119]
	v_mfma_f32_16x16x32_bf16 v[112:115], v[154:157], v[170:173], v[112:115]
	v_mfma_f32_16x16x32_bf16 v[108:111], v[146:149], v[178:181], v[108:111]
	v_mfma_f32_16x16x32_bf16 v[194:197], v[154:157], v[178:181], v[104:107]
	v_mfma_f32_16x16x32_bf16 v[202:205], v[146:149], v[190:193], v[100:103]
	v_mfma_f32_16x16x32_bf16 v[96:99], v[154:157], v[190:193], v[96:99]
	s_barrier
	ds_read_b128 v[100:103], v130
	ds_read_b128 v[104:107], v130 offset:1024
	ds_read_b128 v[222:225], v130 offset:2048
	ds_read_b128 v[226:229], v130 offset:3072
	v_mov_b32_e32 v128, v137
	v_mov_b32_e32 v130, v133
	s_mov_b32 m0, s41
	s_nop 0
	global_load_lds_dwordx4 v130, s[12:13]
	s_mov_b32 m0, s42
	s_nop 0
	global_load_lds_dwordx4 v128, s[12:13]
	s_barrier
	s_waitcnt lgkmcnt(0)
	s_waitcnt lgkmcnt(0)
	v_mfma_f32_16x16x32_bf16 v[92:95], v[100:103], v[158:161], v[92:95]
	v_mfma_f32_16x16x32_bf16 v[88:91], v[222:225], v[158:161], v[88:91]
	v_mfma_f32_16x16x32_bf16 v[84:87], v[100:103], v[166:169], v[84:87]
	v_mfma_f32_16x16x32_bf16 v[80:83], v[222:225], v[166:169], v[80:83]
	v_mfma_f32_16x16x32_bf16 v[76:79], v[100:103], v[174:177], v[76:79]
	v_mfma_f32_16x16x32_bf16 v[72:75], v[222:225], v[174:177], v[72:75]
	v_mfma_f32_16x16x32_bf16 v[68:71], v[100:103], v[182:185], v[68:71]
	v_mfma_f32_16x16x32_bf16 v[64:67], v[222:225], v[182:185], v[64:67]
	v_mfma_f32_16x16x32_bf16 v[230:233], v[104:107], v[162:165], v[92:95]
	v_mfma_f32_16x16x32_bf16 v[158:161], v[226:229], v[162:165], v[88:91]
	v_mfma_f32_16x16x32_bf16 v[162:165], v[104:107], v[170:173], v[84:87]
	v_mfma_f32_16x16x32_bf16 v[166:169], v[226:229], v[170:173], v[80:83]
	v_mfma_f32_16x16x32_bf16 v[76:79], v[104:107], v[178:181], v[76:79]
	v_mfma_f32_16x16x32_bf16 v[72:75], v[226:229], v[178:181], v[72:75]
	v_mfma_f32_16x16x32_bf16 v[68:71], v[104:107], v[190:193], v[68:71]
	v_mfma_f32_16x16x32_bf16 v[64:67], v[226:229], v[190:193], v[64:67]
	v_mov_b32_e32 v128, v135
	v_mov_b32_e32 v130, v129
	s_mov_b32 m0, s28
	s_barrier
	ds_read_b128 v[80:83], v141 offset:16384
	ds_read_b128 v[84:87], v141 offset:17408
	ds_read_b128 v[88:91], v141 offset:18432
	ds_read_b128 v[92:95], v141 offset:19456
	ds_read_b128 v[170:173], v141 offset:20480
	ds_read_b128 v[174:177], v141 offset:21504
	ds_read_b128 v[178:181], v141 offset:22528
	ds_read_b128 v[182:185], v141 offset:23552
	s_nop 0
	global_load_lds_dwordx4 v130, s[6:7]
	s_mov_b32 m0, s29
	s_nop 0
	global_load_lds_dwordx4 v128, s[6:7]
	s_barrier
	s_waitcnt lgkmcnt(0)
	s_waitcnt lgkmcnt(0)
	v_mfma_f32_16x16x32_bf16 v[60:63], v[142:145], v[80:83], v[60:63]
	v_mfma_f32_16x16x32_bf16 v[56:59], v[150:153], v[80:83], v[56:59]
	v_mfma_f32_16x16x32_bf16 v[52:55], v[142:145], v[88:91], v[52:55]
	v_mfma_f32_16x16x32_bf16 v[48:51], v[150:153], v[88:91], v[48:51]
	v_mfma_f32_16x16x32_bf16 v[44:47], v[142:145], v[170:173], v[44:47]
	v_mfma_f32_16x16x32_bf16 v[40:43], v[150:153], v[170:173], v[40:43]
	v_mfma_f32_16x16x32_bf16 v[36:39], v[142:145], v[178:181], v[36:39]
	v_mfma_f32_16x16x32_bf16 v[32:35], v[150:153], v[178:181], v[32:35]
	v_mfma_f32_16x16x32_bf16 v[190:193], v[146:149], v[84:87], v[60:63]
	v_mfma_f32_16x16x32_bf16 v[234:237], v[154:157], v[84:87], v[56:59]
	v_mfma_f32_16x16x32_bf16 v[238:241], v[146:149], v[92:95], v[52:55]
	v_mfma_f32_16x16x32_bf16 v[242:245], v[154:157], v[92:95], v[48:51]
	v_mfma_f32_16x16x32_bf16 v[44:47], v[146:149], v[174:177], v[44:47]
	v_mfma_f32_16x16x32_bf16 v[40:43], v[154:157], v[174:177], v[40:43]
	v_mfma_f32_16x16x32_bf16 v[142:145], v[146:149], v[182:185], v[36:39]
	v_mfma_f32_16x16x32_bf16 v[146:149], v[154:157], v[182:185], v[32:35]
	s_barrier
	s_add_u32 s14, s12, 0x80000
	v_mov_b32_e32 v32, v137
	v_mov_b32_e32 v33, v133
	s_addc_u32 s15, s13, 0
	s_mov_b32 m0, s43
	s_nop 0
	global_load_lds_dwordx4 v33, s[14:15]
	s_mov_b32 m0, s44
	s_nop 0
	global_load_lds_dwordx4 v32, s[14:15]
	s_waitcnt vmcnt(6)
	s_barrier
	v_mfma_f32_16x16x32_bf16 v[28:31], v[100:103], v[80:83], v[28:31]
	v_mfma_f32_16x16x32_bf16 v[24:27], v[222:225], v[80:83], v[24:27]
	v_mfma_f32_16x16x32_bf16 v[20:23], v[100:103], v[88:91], v[20:23]
	v_mfma_f32_16x16x32_bf16 v[16:19], v[222:225], v[88:91], v[16:19]
	v_mfma_f32_16x16x32_bf16 v[12:15], v[100:103], v[170:173], v[12:15]
	v_mfma_f32_16x16x32_bf16 v[8:11], v[222:225], v[170:173], v[8:11]
	v_mfma_f32_16x16x32_bf16 v[4:7], v[100:103], v[178:181], v[4:7]
	v_mfma_f32_16x16x32_bf16 v[0:3], v[222:225], v[178:181], v[0:3]
	v_mfma_f32_16x16x32_bf16 v[28:31], v[104:107], v[84:87], v[28:31]
	v_mfma_f32_16x16x32_bf16 v[24:27], v[226:229], v[84:87], v[24:27]
	v_mfma_f32_16x16x32_bf16 v[150:153], v[104:107], v[92:95], v[20:23]
	v_mfma_f32_16x16x32_bf16 v[154:157], v[226:229], v[92:95], v[16:19]
	v_mfma_f32_16x16x32_bf16 v[12:15], v[104:107], v[174:177], v[12:15]
	v_mfma_f32_16x16x32_bf16 v[8:11], v[226:229], v[174:177], v[8:11]
	v_mfma_f32_16x16x32_bf16 v[170:173], v[104:107], v[182:185], v[4:7]
	v_mfma_f32_16x16x32_bf16 v[174:177], v[226:229], v[182:185], v[0:3]
	s_barrier
	s_nop 0
	ds_read_b128 v[0:3], v131
	ds_read_b128 v[4:7], v131 offset:1024
	ds_read_b128 v[178:181], v131 offset:2048
	ds_read_b128 v[182:185], v131 offset:3072
	s_add_u32 s14, s6, 0x80000
	v_mov_b32_e32 v48, v135
	v_mov_b32_e32 v49, v129
	s_addc_u32 s15, s7, 0
	s_mov_b32 m0, s30
	ds_read_b128 v[16:19], v141 offset:32768
	ds_read_b128 v[20:23], v141 offset:33792
	ds_read_b128 v[32:35], v141 offset:34816
	ds_read_b128 v[36:39], v141 offset:35840
	ds_read_b128 v[56:59], v141 offset:36864
	ds_read_b128 v[60:63], v141 offset:37888
	ds_read_b128 v[222:225], v141 offset:38912
	ds_read_b128 v[226:229], v141 offset:39936
	s_nop 0
	global_load_lds_dwordx4 v49, s[14:15]
	s_mov_b32 m0, s31
	s_nop 0
	global_load_lds_dwordx4 v48, s[14:15]
	s_waitcnt lgkmcnt(8)
	s_barrier
	s_waitcnt lgkmcnt(0)
	s_waitcnt lgkmcnt(0)
	v_mfma_f32_16x16x32_bf16 v[48:51], v[0:3], v[16:19], v[124:127]
	v_mfma_f32_16x16x32_bf16 v[100:103], v[4:7], v[20:23], v[48:51]
	v_mfma_f32_16x16x32_bf16 v[48:51], v[178:181], v[16:19], v[120:123]
	v_mfma_f32_16x16x32_bf16 v[104:107], v[182:185], v[20:23], v[48:51]
	v_mfma_f32_16x16x32_bf16 v[48:51], v[0:3], v[32:35], v[116:119]
	v_mfma_f32_16x16x32_bf16 v[88:91], v[4:7], v[36:39], v[48:51]
	v_mfma_f32_16x16x32_bf16 v[48:51], v[178:181], v[32:35], v[112:115]
	v_mfma_f32_16x16x32_bf16 v[92:95], v[182:185], v[36:39], v[48:51]
	v_mfma_f32_16x16x32_bf16 v[48:51], v[0:3], v[56:59], v[108:111]
	v_mfma_f32_16x16x32_bf16 v[84:87], v[4:7], v[60:63], v[48:51]
	v_mfma_f32_16x16x32_bf16 v[48:51], v[178:181], v[56:59], v[194:197]
	v_mfma_f32_16x16x32_bf16 v[80:83], v[182:185], v[60:63], v[48:51]
	v_mfma_f32_16x16x32_bf16 v[48:51], v[0:3], v[222:225], v[202:205]
	v_mfma_f32_16x16x32_bf16 v[52:55], v[4:7], v[226:229], v[48:51]
	v_mfma_f32_16x16x32_bf16 v[48:51], v[178:181], v[222:225], v[96:99]
	v_mfma_f32_16x16x32_bf16 v[48:51], v[182:185], v[226:229], v[48:51]
	s_barrier
	v_mov_b32_e32 v96, v137
	v_mov_b32_e32 v188, v133
	ds_read_b128 v[194:197], v132
	ds_read_b128 v[202:205], v132 offset:1024
	ds_read_b128 v[246:249], v132 offset:2048
	ds_read_b128 v[198:201], v132 offset:3072
	s_mov_b64 s[14:15], 0x80
	v_lshl_add_u64 v[98:99], s[12:13], 0, v[188:189]
	v_mov_b32_e32 v97, v189
	s_mov_b32 m0, s46
	v_lshl_add_u64 v[98:99], v[98:99], 0, s[14:15]
	v_lshl_add_u64 v[96:97], s[12:13], 0, v[96:97]
	global_load_lds_dwordx4 v[98:99], off
	v_lshl_add_u64 v[96:97], v[96:97], 0, s[14:15]
	s_mov_b32 m0, s45
	s_nop 0
	global_load_lds_dwordx4 v[96:97], off
	s_barrier
	s_waitcnt lgkmcnt(0)
	s_waitcnt lgkmcnt(0)
	v_mfma_f32_16x16x32_bf16 v[96:99], v[194:197], v[16:19], v[230:233]
	v_mfma_f32_16x16x32_bf16 v[16:19], v[246:249], v[16:19], v[158:161]
	v_mfma_f32_16x16x32_bf16 v[124:127], v[198:201], v[20:23], v[16:19]
	v_mfma_f32_16x16x32_bf16 v[16:19], v[194:197], v[32:35], v[162:165]
	v_mfma_f32_16x16x32_bf16 v[112:115], v[202:205], v[36:39], v[16:19]
	v_mfma_f32_16x16x32_bf16 v[16:19], v[246:249], v[32:35], v[166:169]
	v_mfma_f32_16x16x32_bf16 v[116:119], v[198:201], v[36:39], v[16:19]
	v_mfma_f32_16x16x32_bf16 v[16:19], v[194:197], v[56:59], v[76:79]
	v_mfma_f32_16x16x32_bf16 v[108:111], v[202:205], v[60:63], v[16:19]
	v_mfma_f32_16x16x32_bf16 v[16:19], v[246:249], v[56:59], v[72:75]
	v_mfma_f32_16x16x32_bf16 v[120:123], v[202:205], v[20:23], v[96:99]
	v_mfma_f32_16x16x32_bf16 v[96:99], v[198:201], v[60:63], v[16:19]
	v_mfma_f32_16x16x32_bf16 v[16:19], v[194:197], v[222:225], v[68:71]
	v_mfma_f32_16x16x32_bf16 v[60:63], v[202:205], v[226:229], v[16:19]
	v_mfma_f32_16x16x32_bf16 v[16:19], v[246:249], v[222:225], v[64:67]
	v_mfma_f32_16x16x32_bf16 v[56:59], v[198:201], v[226:229], v[16:19]
	s_nop 5
	v_mov_b32_e32 v16, v135
	v_mov_b32_e32 v188, v129
	s_barrier
	ds_read_b128 v[72:75], v141 offset:49152
	ds_read_b128 v[158:161], v141 offset:50176
	ds_read_b128 v[162:165], v141 offset:51200
	ds_read_b128 v[166:169], v141 offset:52224
	ds_read_b128 v[222:225], v141 offset:53248
	ds_read_b128 v[226:229], v141 offset:54272
	ds_read_b128 v[230:233], v141 offset:55296
	ds_read_b128 v[206:209], v141 offset:56320
	v_mov_b32_e32 v17, v189
	v_lshl_add_u64 v[18:19], s[6:7], 0, v[188:189]
	s_mov_b32 m0, s33
	v_lshl_add_u64 v[18:19], v[18:19], 0, s[14:15]
	v_lshl_add_u64 v[16:17], s[6:7], 0, v[16:17]
	global_load_lds_dwordx4 v[18:19], off
	v_lshl_add_u64 v[16:17], v[16:17], 0, s[14:15]
	s_mov_b32 m0, s34
	s_nop 0
	global_load_lds_dwordx4 v[16:17], off
	s_barrier
	s_waitcnt lgkmcnt(0)
	s_waitcnt lgkmcnt(0)
	v_mfma_f32_16x16x32_bf16 v[16:19], v[0:3], v[72:75], v[190:193]
	v_mfma_f32_16x16x32_bf16 v[68:71], v[4:7], v[158:161], v[16:19]
	v_mfma_f32_16x16x32_bf16 v[16:19], v[178:181], v[72:75], v[234:237]
	v_mfma_f32_16x16x32_bf16 v[64:67], v[182:185], v[158:161], v[16:19]
	v_mfma_f32_16x16x32_bf16 v[16:19], v[0:3], v[162:165], v[238:241]
	v_mfma_f32_16x16x32_bf16 v[36:39], v[4:7], v[166:169], v[16:19]
	v_mfma_f32_16x16x32_bf16 v[16:19], v[178:181], v[162:165], v[242:245]
	v_mfma_f32_16x16x32_bf16 v[32:35], v[182:185], v[166:169], v[16:19]
	v_mfma_f32_16x16x32_bf16 v[16:19], v[0:3], v[222:225], v[44:47]
	v_mfma_f32_16x16x32_bf16 v[0:3], v[0:3], v[230:233], v[142:145]
	v_mfma_f32_16x16x32_bf16 v[20:23], v[4:7], v[226:229], v[16:19]
	v_mfma_f32_16x16x32_bf16 v[16:19], v[178:181], v[222:225], v[40:43]
	v_mfma_f32_16x16x32_bf16 v[4:7], v[4:7], v[206:209], v[0:3]
	v_mfma_f32_16x16x32_bf16 v[0:3], v[178:181], v[230:233], v[146:149]
	v_mfma_f32_16x16x32_bf16 v[16:19], v[182:185], v[226:229], v[16:19]
	v_mfma_f32_16x16x32_bf16 v[0:3], v[182:185], v[206:209], v[0:3]
	s_barrier
	s_add_u32 s14, s12, 0x80080
	v_mov_b32_e32 v40, v137
	v_mov_b32_e32 v41, v133
	s_addc_u32 s15, s13, 0
	s_mov_b32 m0, s20
	s_nop 0
	global_load_lds_dwordx4 v41, s[14:15]
	s_mov_b32 m0, s21
	s_nop 0
	global_load_lds_dwordx4 v40, s[14:15]
	s_waitcnt vmcnt(6)
	s_barrier
; __device__ __forceinline__ unsigned cvt_pk_bf16(float lo, float hi) { unsigned r; asm("v_cvt_pk_bf16_f32 %0, %1, %2" : "=v"(r) : "v"(lo), "v"(hi)); return r; }
;     __device__ __forceinline__ void operator()(const f32x4 (&acc)[2][2][4][2], const Unit& u, int wr, int wc, int fr, int fq) const {
;         const int row0 = u.pm * BM + wr * 64 + fr, col0 = u.pn * BM + wc * 32 + 8 * fq;
;         float gvv[2][4];
; #pragma unroll
;         for (int ai = 0; ai < 2; ++ai)
; #pragma unroll
;             for (int m = 0; m < 4; ++m) gvv[ai][m] = gatev[row0 + ai * HALF + m * 16];
; #pragma unroll
;         for (int ai = 0; ai < 2; ++ai)
; #pragma unroll
;             for (int m = 0; m < 4; ++m) { const int row = row0 + ai * HALF + m * 16; const float gv = gvv[ai][m]; bf16_t* rowp = O + (size_t)row * DM + col0;
; #pragma unroll
;                 for (int bj = 0; bj < 2; ++bj) { const f32x4 v0 = acc[ai][bj][m][0] * gv, v1 = acc[ai][bj][m][1] * gv;
;                     u32x4 w; w.x = cvt_pk_bf16(v0[0], v0[1]); w.y = cvt_pk_bf16(v0[2], v0[3]); w.z = cvt_pk_bf16(v1[0], v1[1]); w.w = cvt_pk_bf16(v1[2], v1[3]);
;                     *(u32x4*)(rowp + bj * HALF) = w; } }
	v_mfma_f32_16x16x32_bf16 v[24:27], v[246:249], v[72:75], v[24:27]
	v_mfma_f32_16x16x32_bf16 v[28:31], v[194:197], v[72:75], v[28:31]
	v_mfma_f32_16x16x32_bf16 v[72:75], v[198:201], v[158:161], v[24:27]
	v_mfma_f32_16x16x32_bf16 v[24:27], v[194:197], v[162:165], v[150:153]
	v_mfma_f32_16x16x32_bf16 v[44:47], v[202:205], v[166:169], v[24:27]
	v_mfma_f32_16x16x32_bf16 v[24:27], v[246:249], v[162:165], v[154:157]
	v_mfma_f32_16x16x32_bf16 v[8:11], v[246:249], v[222:225], v[8:11]
	v_mfma_f32_16x16x32_bf16 v[40:43], v[198:201], v[166:169], v[24:27]
	v_mfma_f32_16x16x32_bf16 v[12:15], v[194:197], v[222:225], v[12:15]
	v_mfma_f32_16x16x32_bf16 v[24:27], v[198:201], v[226:229], v[8:11]
	v_mfma_f32_16x16x32_bf16 v[8:11], v[194:197], v[230:233], v[170:173]
	v_mfma_f32_16x16x32_bf16 v[76:79], v[202:205], v[158:161], v[28:31]
	v_mfma_f32_16x16x32_bf16 v[28:31], v[202:205], v[226:229], v[12:15]
	v_mfma_f32_16x16x32_bf16 v[12:15], v[202:205], v[206:209], v[8:11]
	v_mfma_f32_16x16x32_bf16 v[8:11], v[246:249], v[230:233], v[174:177]
	v_mfma_f32_16x16x32_bf16 v[8:11], v[198:201], v[206:209], v[8:11]
	v_lshl_add_u32 v130, s37, 8, v138
	v_readlane_b32 s14, v252, 22
	v_ashrrev_i32_e32 v131, 31, v130
	v_readlane_b32 s15, v252, 23
	v_or_b32_e32 v146, 16, v130
	v_or_b32_e32 v150, 32, v130
	v_lshl_add_u64 v[142:143], v[130:131], 2, s[14:15]
	v_ashrrev_i32_e32 v147, 31, v146
	v_ashrrev_i32_e32 v151, 31, v150
	s_barrier
	global_load_dword v144, v[142:143], off
	v_lshl_add_u64 v[148:149], v[146:147], 2, s[14:15]
	v_lshl_add_u64 v[152:153], v[150:151], 2, s[14:15]
	v_or_b32_e32 v154, 48, v130
	global_load_dword v148, v[148:149], off
	v_ashrrev_i32_e32 v155, 31, v154
	global_load_dword v152, v[152:153], off
	v_lshl_add_u64 v[156:157], v[154:155], 2, s[14:15]
	global_load_dword v134, v[156:157], off
	global_load_dword v158, v[142:143], off offset:512
	global_load_dword v136, v[142:143], off offset:576
	global_load_dword v132, v[142:143], off offset:640
	global_load_dword v128, v[142:143], off offset:704
	v_lshl_or_b32 v156, s36, 8, v140
	v_readlane_b32 s14, v252, 5
	v_ashrrev_i32_e32 v157, 31, v156
	v_lshlrev_b64 v[130:131], 11, v[130:131]
	v_readlane_b32 s15, v252, 6
	v_lshlrev_b64 v[146:147], 11, v[146:147]
	v_lshlrev_b64 v[156:157], 1, v[156:157]
	v_lshl_add_u64 v[130:131], s[14:15], 0, v[130:131]
	v_lshlrev_b64 v[150:151], 11, v[150:151]
	v_lshl_add_u64 v[142:143], s[14:15], 0, v[146:147]
	v_lshl_add_u64 v[130:131], v[130:131], 0, v[156:157]
	v_lshl_add_u64 v[146:147], s[14:15], 0, v[150:151]
	v_lshl_add_u64 v[142:143], v[142:143], 0, v[156:157]
	v_lshl_add_u64 v[146:147], v[146:147], 0, v[156:157]
	s_mov_b32 s9, 0x40000
	v_readlane_b32 s66, v255, 21
	s_mov_b32 s36, s8
	s_mov_b32 s37, s10
	s_mov_b64 s[16:17], s[6:7]
	v_readlane_b32 s67, v255, 22
	v_mov_b64_e32 v[206:207], 0xff
	v_mov_b64_e32 v[208:209], 0x100
	s_waitcnt vmcnt(0)
	v_pk_mul_f32 v[102:103], v[102:103], v[144:145] op_sel_hi:[1,0]
	v_pk_mul_f32 v[100:101], v[100:101], v[144:145] op_sel_hi:[1,0]
	v_pk_mul_f32 v[106:107], v[106:107], v[144:145] op_sel_hi:[1,0]
	v_pk_mul_f32 v[126:127], v[126:127], v[144:145] op_sel_hi:[1,0]
	v_pk_mul_f32 v[124:125], v[124:125], v[144:145] op_sel_hi:[1,0]
	v_pk_mul_f32 v[104:105], v[104:105], v[144:145] op_sel_hi:[1,0]
	v_pk_mul_f32 v[122:123], v[122:123], v[144:145] op_sel_hi:[1,0]
	v_pk_mul_f32 v[120:121], v[120:121], v[144:145] op_sel_hi:[1,0]
	v_cvt_pk_bf16_f32 v100, v100, v101
	v_cvt_pk_bf16_f32 v101, v102, v103
	v_cvt_pk_bf16_f32 v102, v104, v105
	v_cvt_pk_bf16_f32 v103, v106, v107
	v_cvt_pk_bf16_f32 v106, v124, v125
	v_cvt_pk_bf16_f32 v107, v126, v127
	v_pk_mul_f32 v[90:91], v[90:91], v[148:149] op_sel_hi:[1,0]
	v_pk_mul_f32 v[88:89], v[88:89], v[148:149] op_sel_hi:[1,0]
	v_pk_mul_f32 v[94:95], v[94:95], v[148:149] op_sel_hi:[1,0]
	v_pk_mul_f32 v[92:93], v[92:93], v[148:149] op_sel_hi:[1,0]
	v_pk_mul_f32 v[124:125], v[82:83], v[152:153] op_sel_hi:[1,0]
	v_pk_mul_f32 v[126:127], v[80:81], v[152:153] op_sel_hi:[1,0]
	v_cvt_pk_bf16_f32 v80, v88, v89
	v_cvt_pk_bf16_f32 v81, v90, v91
	v_cvt_pk_bf16_f32 v82, v92, v93
	v_cvt_pk_bf16_f32 v83, v94, v95
	v_cvt_pk_bf16_f32 v104, v120, v121
	v_cvt_pk_bf16_f32 v105, v122, v123
	v_pk_mul_f32 v[114:115], v[114:115], v[148:149] op_sel_hi:[1,0]
	v_pk_mul_f32 v[112:113], v[112:113], v[148:149] op_sel_hi:[1,0]
	v_pk_mul_f32 v[118:119], v[118:119], v[148:149] op_sel_hi:[1,0]
	v_pk_mul_f32 v[116:117], v[116:117], v[148:149] op_sel_hi:[1,0]
	v_pk_mul_f32 v[120:121], v[86:87], v[152:153] op_sel_hi:[1,0]
	v_pk_mul_f32 v[122:123], v[84:85], v[152:153] op_sel_hi:[1,0]
	v_pk_mul_f32 v[110:111], v[110:111], v[152:153] op_sel_hi:[1,0]
	v_pk_mul_f32 v[108:109], v[108:109], v[152:153] op_sel_hi:[1,0]
	v_pk_mul_f32 v[98:99], v[98:99], v[152:153] op_sel_hi:[1,0]
	v_pk_mul_f32 v[96:97], v[96:97], v[152:153] op_sel_hi:[1,0]
	global_store_dwordx4 v[130:131], v[100:103], off
	global_store_dwordx4 v[130:131], v[104:107], off offset:256
	v_cvt_pk_bf16_f32 v84, v112, v113
	v_cvt_pk_bf16_f32 v85, v114, v115
	v_cvt_pk_bf16_f32 v86, v116, v117
	v_cvt_pk_bf16_f32 v87, v118, v119
	v_cvt_pk_bf16_f32 v88, v122, v123
	v_cvt_pk_bf16_f32 v89, v120, v121
	v_cvt_pk_bf16_f32 v90, v126, v127
	v_cvt_pk_bf16_f32 v91, v124, v125
	v_cvt_pk_bf16_f32 v92, v108, v109
	v_cvt_pk_bf16_f32 v93, v110, v111
	v_cvt_pk_bf16_f32 v94, v96, v97
	v_cvt_pk_bf16_f32 v95, v98, v99
	global_store_dwordx4 v[142:143], v[80:83], off
	global_store_dwordx4 v[142:143], v[84:87], off offset:256
	global_store_dwordx4 v[146:147], v[88:91], off
; __device__ __forceinline__ unsigned cvt_pk_bf16(float lo, float hi) { unsigned r; asm("v_cvt_pk_bf16_f32 %0, %1, %2" : "=v"(r) : "v"(lo), "v"(hi)); return r; }
; #define PG8_WAIT_V(n) asm volatile("s_waitcnt vmcnt(" #n ")" ::: "memory")
;     __device__ __forceinline__ void operator()(const f32x4 (&acc)[2][2][4][2], const Unit& u, int wr, int wc, int fr, int fq) const {
;         const int row0 = u.pm * BM + wr * 64 + fr, col0 = u.pn * BM + wc * 32 + 8 * fq;
;         float gvv[2][4];
; #pragma unroll
;         for (int ai = 0; ai < 2; ++ai)
; #pragma unroll
;             for (int m = 0; m < 4; ++m) gvv[ai][m] = gatev[row0 + ai * HALF + m * 16];
; #pragma unroll
;         for (int ai = 0; ai < 2; ++ai)
; #pragma unroll
;             for (int m = 0; m < 4; ++m) { const int row = row0 + ai * HALF + m * 16; const float gv = gvv[ai][m]; bf16_t* rowp = O + (size_t)row * DM + col0;
; #pragma unroll
;                 for (int bj = 0; bj < 2; ++bj) { const f32x4 v0 = acc[ai][bj][m][0] * gv, v1 = acc[ai][bj][m][1] * gv;
;                     u32x4 w; w.x = cvt_pk_bf16(v0[0], v0[1]); w.y = cvt_pk_bf16(v0[2], v0[3]); w.z = cvt_pk_bf16(v1[0], v1[1]); w.w = cvt_pk_bf16(v1[2], v1[3]);
;                     *(u32x4*)(rowp + bj * HALF) = w; } }
; template <bool GATHER, class Epi>
; __device__ __forceinline__ void gemm_phase(LAS unsigned char* lds, const Sched& S, const Epi& E) {
;     ...
;         E(acc, cur, wr, wc, fr, fq);
;         PG8_WAIT_V(0);
;         if (!has_next) break;
;         if (!Epi::KEEP || nxt.br == 0)
; #pragma unroll
;         for (int a = 0; a < 2; ++a)
; #pragma unroll
;             for (int b = 0; b < 2; ++b)
; #pragma unroll
;                 for (int m = 0; m < 4; ++m)
; #pragma unroll
;                     for (int n = 0; n < 2; ++n) acc[a][b][m][n] = (f32x4){0.f, 0.f, 0.f, 0.f};
;         cur = nxt; cA = nA; cB = nB; ++ui;
;     }
;     PG8_WAIT_V(0);
	global_store_dwordx4 v[146:147], v[92:95], off offset:256
	v_lshlrev_b64 v[80:81], 11, v[154:155]
	v_lshl_add_u64 v[80:81], s[14:15], 0, v[80:81]
	v_pk_mul_f32 v[82:83], v[50:51], v[134:135] op_sel_hi:[1,0]
	v_pk_mul_f32 v[50:51], v[48:49], v[134:135] op_sel_hi:[1,0]
	v_lshl_add_u64 v[80:81], v[80:81], 0, v[156:157]
	v_pk_mul_f32 v[54:55], v[54:55], v[134:135] op_sel_hi:[1,0]
	v_pk_mul_f32 v[52:53], v[52:53], v[134:135] op_sel_hi:[1,0]
	v_cvt_pk_bf16_f32 v49, v54, v55
	v_cvt_pk_bf16_f32 v50, v50, v51
	v_cvt_pk_bf16_f32 v51, v82, v83
	v_pk_mul_f32 v[54:55], v[56:57], v[134:135] op_sel_hi:[1,0]
	v_cvt_pk_bf16_f32 v48, v52, v53
	global_store_dwordx4 v[80:81], v[48:51], off
	v_pk_mul_f32 v[52:53], v[58:59], v[134:135] op_sel_hi:[1,0]
	v_pk_mul_f32 v[56:57], v[64:65], v[158:159] op_sel_hi:[1,0]
	v_pk_mul_f32 v[50:51], v[62:63], v[134:135] op_sel_hi:[1,0]
	v_pk_mul_f32 v[48:49], v[60:61], v[134:135] op_sel_hi:[1,0]
	s_mov_b64 s[14:15], 0x40000
	v_cvt_pk_bf16_f32 v48, v48, v49
	v_cvt_pk_bf16_f32 v49, v50, v51
	v_cvt_pk_bf16_f32 v50, v54, v55
	v_cvt_pk_bf16_f32 v51, v52, v53
	global_store_dwordx4 v[80:81], v[48:51], off offset:256
	v_pk_mul_f32 v[54:55], v[66:67], v[158:159] op_sel_hi:[1,0]
	v_lshl_add_u64 v[52:53], v[130:131], 0, s[14:15]
	v_pk_mul_f32 v[50:51], v[70:71], v[158:159] op_sel_hi:[1,0]
	v_pk_mul_f32 v[48:49], v[68:69], v[158:159] op_sel_hi:[1,0]
	v_pk_mul_f32 v[36:37], v[36:37], v[136:137] op_sel_hi:[1,0]
	v_cvt_pk_bf16_f32 v48, v48, v49
	v_cvt_pk_bf16_f32 v49, v50, v51
	v_cvt_pk_bf16_f32 v51, v54, v55
	v_add_co_u32_e32 v54, vcc, s9, v130
	v_cvt_pk_bf16_f32 v50, v56, v57
	v_pk_mul_f32 v[56:57], v[72:73], v[158:159] op_sel_hi:[1,0]
	s_nop 0
	v_addc_co_u32_e32 v55, vcc, 0, v131, vcc
	global_store_dwordx4 v[54:55], v[48:51], off
	v_pk_mul_f32 v[54:55], v[74:75], v[158:159] op_sel_hi:[1,0]
	s_mov_b32 s9, 0x48000
	v_pk_mul_f32 v[50:51], v[78:79], v[158:159] op_sel_hi:[1,0]
	v_pk_mul_f32 v[48:49], v[76:77], v[158:159] op_sel_hi:[1,0]
	v_pk_mul_f32 v[38:39], v[38:39], v[136:137] op_sel_hi:[1,0]
	v_cvt_pk_bf16_f32 v48, v48, v49
	v_cvt_pk_bf16_f32 v49, v50, v51
	v_cvt_pk_bf16_f32 v50, v56, v57
	v_cvt_pk_bf16_f32 v51, v54, v55
	global_store_dwordx4 v[52:53], v[48:51], off offset:256
	s_mov_b64 s[14:15], 0x48000
	v_pk_mul_f32 v[20:21], v[20:21], v[132:133] op_sel_hi:[1,0]
	v_pk_mul_f32 v[50:51], v[34:35], v[136:137] op_sel_hi:[1,0]
	v_pk_mul_f32 v[34:35], v[32:33], v[136:137] op_sel_hi:[1,0]
	v_cvt_pk_bf16_f32 v32, v36, v37
	v_add_co_u32_e32 v36, vcc, s9, v130
	v_cvt_pk_bf16_f32 v33, v38, v39
	v_cvt_pk_bf16_f32 v34, v34, v35
	v_cvt_pk_bf16_f32 v35, v50, v51
	v_lshl_add_u64 v[48:49], v[130:131], 0, s[14:15]
	s_nop 0
	v_addc_co_u32_e32 v37, vcc, 0, v131, vcc
	global_store_dwordx4 v[36:37], v[32:35], off
	v_pk_mul_f32 v[36:37], v[42:43], v[136:137] op_sel_hi:[1,0]
	v_pk_mul_f32 v[38:39], v[40:41], v[136:137] op_sel_hi:[1,0]
	v_pk_mul_f32 v[34:35], v[46:47], v[136:137] op_sel_hi:[1,0]
	v_pk_mul_f32 v[32:33], v[44:45], v[136:137] op_sel_hi:[1,0]
	s_mov_b32 s9, 0x50000
	v_cvt_pk_bf16_f32 v32, v32, v33
	v_cvt_pk_bf16_f32 v33, v34, v35
	v_cvt_pk_bf16_f32 v34, v38, v39
	v_cvt_pk_bf16_f32 v35, v36, v37
	global_store_dwordx4 v[48:49], v[32:35], off offset:256
	v_pk_mul_f32 v[22:23], v[22:23], v[132:133] op_sel_hi:[1,0]
	s_mov_b64 s[14:15], 0x50000
	v_pk_mul_f32 v[34:35], v[18:19], v[132:133] op_sel_hi:[1,0]
	v_pk_mul_f32 v[18:19], v[16:17], v[132:133] op_sel_hi:[1,0]
	v_cvt_pk_bf16_f32 v16, v20, v21
	v_add_co_u32_e32 v20, vcc, s9, v130
	v_cvt_pk_bf16_f32 v17, v22, v23
	v_cvt_pk_bf16_f32 v18, v18, v19
	v_cvt_pk_bf16_f32 v19, v34, v35
	v_lshl_add_u64 v[32:33], v[130:131], 0, s[14:15]
	s_nop 0
	v_addc_co_u32_e32 v21, vcc, 0, v131, vcc
	global_store_dwordx4 v[20:21], v[16:19], off
	v_pk_mul_f32 v[20:21], v[26:27], v[132:133] op_sel_hi:[1,0]
	v_pk_mul_f32 v[22:23], v[24:25], v[132:133] op_sel_hi:[1,0]
	v_pk_mul_f32 v[18:19], v[30:31], v[132:133] op_sel_hi:[1,0]
	v_pk_mul_f32 v[16:17], v[28:29], v[132:133] op_sel_hi:[1,0]
	v_pk_mul_f32 v[4:5], v[4:5], v[128:129] op_sel_hi:[1,0]
	v_cvt_pk_bf16_f32 v16, v16, v17
	v_cvt_pk_bf16_f32 v17, v18, v19
	v_cvt_pk_bf16_f32 v18, v22, v23
	v_cvt_pk_bf16_f32 v19, v20, v21
	s_mov_b32 s9, 0x58000
	global_store_dwordx4 v[32:33], v[16:19], off offset:256
	s_mov_b64 s[14:15], 0x58000
	v_pk_mul_f32 v[6:7], v[6:7], v[128:129] op_sel_hi:[1,0]
	v_pk_mul_f32 v[18:19], v[2:3], v[128:129] op_sel_hi:[1,0]
	v_pk_mul_f32 v[2:3], v[0:1], v[128:129] op_sel_hi:[1,0]
	v_cvt_pk_bf16_f32 v0, v4, v5
	v_add_co_u32_e32 v4, vcc, s9, v130
	v_cvt_pk_bf16_f32 v1, v6, v7
	v_cvt_pk_bf16_f32 v2, v2, v3
	v_cvt_pk_bf16_f32 v3, v18, v19
	v_lshl_add_u64 v[16:17], v[130:131], 0, s[14:15]
	s_nop 0
	v_addc_co_u32_e32 v5, vcc, 0, v131, vcc
	global_store_dwordx4 v[4:5], v[0:3], off
	v_pk_mul_f32 v[4:5], v[10:11], v[128:129] op_sel_hi:[1,0]
	v_pk_mul_f32 v[6:7], v[8:9], v[128:129] op_sel_hi:[1,0]
	v_pk_mul_f32 v[2:3], v[14:15], v[128:129] op_sel_hi:[1,0]
	v_pk_mul_f32 v[0:1], v[12:13], v[128:129] op_sel_hi:[1,0]
	s_andn2_b64 vcc, exec, s[4:5]
	v_cvt_pk_bf16_f32 v0, v0, v1
	v_cvt_pk_bf16_f32 v1, v2, v3
	v_cvt_pk_bf16_f32 v2, v6, v7
	v_cvt_pk_bf16_f32 v3, v4, v5
	global_store_dwordx4 v[16:17], v[0:3], off offset:256
	s_waitcnt vmcnt(0)
	s_mov_b64 s[14:15], s[12:13]
	s_cbranch_vccnz .LBB0_97
	s_waitcnt vmcnt(0)
	s_cmpk_gt_u32 s24, 0xff
	v_readlane_b32 s34, v255, 31
	v_readlane_b32 s35, v255, 32
	v_readlane_b32 s36, v255, 33
	v_readlane_b32 s37, v255, 34
	s_cbranch_scc1 .LBB0_110
	s_barrier

.LBB0_117:
	s_ashr_i32 s10, s31, 3
	s_ashr_i32 s11, s10, 31
	s_lshl_b64 s[10:11], s[10:11], 22
	s_add_u32 s16, s19, s10
	s_addc_u32 s17, s20, s11
	s_ashr_i32 s9, s8, 31
	s_lshl_b64 s[10:11], s[8:9], 18
	s_add_u32 s10, s16, s10
	s_addc_u32 s11, s17, s11
	s_and_b64 s[6:7], s[6:7], exec
	s_cselect_b32 s7, s11, s13
	s_cselect_b32 s6, s10, s12
	v_mov_b32_e32 v188, v224
	v_mov_b32_e32 v194, v225
	s_mov_b32 m0, s23
	ds_read_b128 v[96:99], v234
	ds_read_b128 v[104:107], v234 offset:1024
	ds_read_b128 v[112:115], v234 offset:2048
	ds_read_b128 v[190:193], v234 offset:3072
	s_nop 0
	global_load_lds_dwordx4 v188, s[6:7]
	s_mov_b32 m0, s24
	s_nop 0
	global_load_lds_dwordx4 v194, s[6:7]
	s_barrier
	s_waitcnt lgkmcnt(0)
	s_waitcnt lgkmcnt(0)
	v_mfma_f32_16x16x32_bf16 v[92:95], v[96:99], v[180:183], v[92:95]
	v_mfma_f32_16x16x32_bf16 v[88:91], v[112:115], v[180:183], v[88:91]
	v_mfma_f32_16x16x32_bf16 v[84:87], v[96:99], v[172:175], v[84:87]
	v_mfma_f32_16x16x32_bf16 v[80:83], v[112:115], v[172:175], v[80:83]
	v_mfma_f32_16x16x32_bf16 v[76:79], v[96:99], v[164:167], v[76:79]
	v_mfma_f32_16x16x32_bf16 v[72:75], v[112:115], v[164:167], v[72:75]
	v_mfma_f32_16x16x32_bf16 v[68:71], v[96:99], v[156:159], v[68:71]
	v_mfma_f32_16x16x32_bf16 v[64:67], v[112:115], v[156:159], v[64:67]
	v_mfma_f32_16x16x32_bf16 v[92:95], v[104:107], v[184:187], v[92:95]
	v_mfma_f32_16x16x32_bf16 v[180:183], v[190:193], v[184:187], v[88:91]
	v_mfma_f32_16x16x32_bf16 v[84:87], v[104:107], v[176:179], v[84:87]
	v_mfma_f32_16x16x32_bf16 v[172:175], v[190:193], v[176:179], v[80:83]
	v_mfma_f32_16x16x32_bf16 v[76:79], v[104:107], v[168:171], v[76:79]
	v_mfma_f32_16x16x32_bf16 v[164:167], v[190:193], v[168:171], v[72:75]
	v_mfma_f32_16x16x32_bf16 v[68:71], v[104:107], v[160:163], v[68:71]
	v_mfma_f32_16x16x32_bf16 v[156:159], v[190:193], v[160:163], v[64:67]
	v_mov_b32_e32 v188, v226
	v_mov_b32_e32 v194, v227
	s_mov_b32 m0, s22
	s_barrier
	ds_read_b128 v[64:67], v233 offset:16384
	ds_read_b128 v[72:75], v233 offset:17408
	ds_read_b128 v[80:83], v233 offset:18432
	ds_read_b128 v[88:91], v233 offset:19456
	ds_read_b128 v[160:163], v233 offset:20480
	ds_read_b128 v[168:171], v233 offset:21504
	ds_read_b128 v[176:179], v233 offset:22528
	ds_read_b128 v[184:187], v233 offset:23552
	s_nop 0
	global_load_lds_dwordx4 v188, s[66:67]
	s_mov_b32 m0, s25
	s_nop 0
	global_load_lds_dwordx4 v194, s[66:67]
	s_barrier
	s_waitcnt lgkmcnt(0)
	s_waitcnt lgkmcnt(0)
	v_mfma_f32_16x16x32_bf16 v[60:63], v[140:143], v[64:67], v[60:63]
	v_mfma_f32_16x16x32_bf16 v[56:59], v[148:151], v[64:67], v[56:59]
	v_mfma_f32_16x16x32_bf16 v[52:55], v[140:143], v[80:83], v[52:55]
	v_mfma_f32_16x16x32_bf16 v[48:51], v[148:151], v[80:83], v[48:51]
	v_mfma_f32_16x16x32_bf16 v[44:47], v[140:143], v[160:163], v[44:47]
	v_mfma_f32_16x16x32_bf16 v[40:43], v[148:151], v[160:163], v[40:43]
	v_mfma_f32_16x16x32_bf16 v[36:39], v[140:143], v[176:179], v[36:39]
	v_mfma_f32_16x16x32_bf16 v[32:35], v[148:151], v[176:179], v[32:35]
	v_mfma_f32_16x16x32_bf16 v[60:63], v[144:147], v[72:75], v[60:63]
	v_mfma_f32_16x16x32_bf16 v[194:197], v[152:155], v[72:75], v[56:59]
	v_mfma_f32_16x16x32_bf16 v[52:55], v[144:147], v[88:91], v[52:55]
	v_mfma_f32_16x16x32_bf16 v[202:205], v[152:155], v[88:91], v[48:51]
	v_mfma_f32_16x16x32_bf16 v[44:47], v[144:147], v[168:171], v[44:47]
	v_mfma_f32_16x16x32_bf16 v[238:241], v[152:155], v[168:171], v[40:43]
	v_mfma_f32_16x16x32_bf16 v[36:39], v[144:147], v[184:187], v[36:39]
	v_mfma_f32_16x16x32_bf16 v[140:143], v[152:155], v[184:187], v[32:35]
	s_barrier
	s_add_u32 s12, s6, 0x8000000
	v_mov_b32_e32 v32, v224
	v_mov_b32_e32 v33, v225
	s_addc_u32 s13, s7, 0
	s_mov_b32 m0, s35
	s_nop 0
	global_load_lds_dwordx4 v32, s[12:13]
	s_mov_b32 m0, s36
	s_nop 0
	global_load_lds_dwordx4 v33, s[12:13]
	s_waitcnt vmcnt(6)
	s_barrier
	v_mfma_f32_16x16x32_bf16 v[28:31], v[96:99], v[64:67], v[28:31]
	v_mfma_f32_16x16x32_bf16 v[24:27], v[112:115], v[64:67], v[24:27]
	v_mfma_f32_16x16x32_bf16 v[20:23], v[96:99], v[80:83], v[20:23]
	v_mfma_f32_16x16x32_bf16 v[16:19], v[112:115], v[80:83], v[16:19]
	v_mfma_f32_16x16x32_bf16 v[12:15], v[96:99], v[160:163], v[12:15]
	v_mfma_f32_16x16x32_bf16 v[8:11], v[112:115], v[160:163], v[8:11]
	v_mfma_f32_16x16x32_bf16 v[4:7], v[96:99], v[176:179], v[4:7]
	v_mfma_f32_16x16x32_bf16 v[0:3], v[112:115], v[176:179], v[0:3]
	v_mfma_f32_16x16x32_bf16 v[28:31], v[104:107], v[72:75], v[28:31]
	v_mfma_f32_16x16x32_bf16 v[144:147], v[190:193], v[72:75], v[24:27]
	v_mfma_f32_16x16x32_bf16 v[20:23], v[104:107], v[88:91], v[20:23]
	v_mfma_f32_16x16x32_bf16 v[148:151], v[190:193], v[88:91], v[16:19]
	v_mfma_f32_16x16x32_bf16 v[12:15], v[104:107], v[168:171], v[12:15]
	v_mfma_f32_16x16x32_bf16 v[152:155], v[190:193], v[168:171], v[8:11]
	v_mfma_f32_16x16x32_bf16 v[4:7], v[104:107], v[184:187], v[4:7]
	v_mfma_f32_16x16x32_bf16 v[160:163], v[190:193], v[184:187], v[0:3]
	s_barrier
	s_nop 0
	ds_read_b128 v[0:3], v235
	ds_read_b128 v[8:11], v235 offset:1024
	ds_read_b128 v[168:171], v235 offset:2048
	ds_read_b128 v[176:179], v235 offset:3072
	v_mov_b32_e32 v64, v228
	v_mov_b32_e32 v65, v229
	s_mov_b32 m0, s26
	ds_read_b128 v[16:19], v233 offset:32768
	ds_read_b128 v[24:27], v233 offset:33792
	ds_read_b128 v[32:35], v233 offset:34816
	ds_read_b128 v[40:43], v233 offset:35840
	ds_read_b128 v[48:51], v233 offset:36864
	ds_read_b128 v[56:59], v233 offset:37888
	ds_read_b128 v[184:187], v233 offset:38912
	ds_read_b128 v[190:193], v233 offset:39936
	s_nop 0
	global_load_lds_dwordx4 v64, s[66:67]
	s_mov_b32 m0, s27
	s_nop 0
	global_load_lds_dwordx4 v65, s[66:67]
	s_waitcnt lgkmcnt(8)
	s_barrier
; __device__ __forceinline__ unsigned cvt_pk_bf16(float lo, float hi) { unsigned r; asm("v_cvt_pk_bf16_f32 %0, %1, %2" : "=v"(r) : "v"(lo), "v"(hi)); return r; }
;     __device__ __forceinline__ void operator()(const f32x4 (&acc)[2][2][4][2], const Unit& u, int wr, int wc, int fr, int fq) const {
;         const int row0 = u.pm * BM + wr * 64 + fr, col0 = u.pn * HALF + wc * 32 + 8 * fq;
; #pragma unroll
;         for (int ai = 0; ai < 2; ++ai)
; #pragma unroll
;             for (int m = 0; m < 4; ++m) { bf16_t* rowp = O + (size_t)(row0 + ai * HALF + m * 16) * FF + col0;
;                 float h[8];
; #pragma unroll
;                 for (int n = 0; n < 2; ++n)
; #pragma unroll
;                     for (int j = 0; j < 4; ++j) { const float g = acc[ai][0][m][n][j], up = acc[ai][1][m][n][j]; h[n * 4 + j] = g * __builtin_amdgcn_rcpf(1.0f + __expf(-g)) * up; }
;                 u32x4 w; w.x = cvt_pk_bf16(h[0], h[1]); w.y = cvt_pk_bf16(h[2], h[3]); w.z = cvt_pk_bf16(h[4], h[5]); w.w = cvt_pk_bf16(h[6], h[7]);
;                 *(u32x4*)rowp = w; }
	s_waitcnt lgkmcnt(0)
	s_waitcnt lgkmcnt(0)
	v_mfma_f32_16x16x32_bf16 v[64:67], v[0:3], v[16:19], v[124:127]
	v_mfma_f32_16x16x32_bf16 v[124:127], v[8:11], v[24:27], v[64:67]
	v_mfma_f32_16x16x32_bf16 v[64:67], v[168:171], v[16:19], v[120:123]
	v_mfma_f32_16x16x32_bf16 v[112:115], v[176:179], v[24:27], v[64:67]
	v_mfma_f32_16x16x32_bf16 v[64:67], v[0:3], v[32:35], v[116:119]
	v_mfma_f32_16x16x32_bf16 v[104:107], v[8:11], v[40:43], v[64:67]
	v_mfma_f32_16x16x32_bf16 v[64:67], v[168:171], v[32:35], v[128:131]
	v_mfma_f32_16x16x32_bf16 v[96:99], v[176:179], v[40:43], v[64:67]
	v_mfma_f32_16x16x32_bf16 v[64:67], v[0:3], v[48:51], v[108:111]
	v_mfma_f32_16x16x32_bf16 v[88:91], v[8:11], v[56:59], v[64:67]
	v_mfma_f32_16x16x32_bf16 v[64:67], v[168:171], v[48:51], v[132:135]
	v_mfma_f32_16x16x32_bf16 v[80:83], v[176:179], v[56:59], v[64:67]
	v_mfma_f32_16x16x32_bf16 v[64:67], v[0:3], v[184:187], v[100:103]
	v_mfma_f32_16x16x32_bf16 v[72:75], v[8:11], v[190:193], v[64:67]
	v_mfma_f32_16x16x32_bf16 v[64:67], v[168:171], v[184:187], v[136:139]
	v_mfma_f32_16x16x32_bf16 v[64:67], v[176:179], v[190:193], v[64:67]
	s_barrier
	v_mov_b32_e32 v188, v224
	v_mov_b32_e32 v100, v225
	ds_read_b128 v[120:123], v236
	ds_read_b128 v[128:131], v236 offset:1024
	ds_read_b128 v[132:135], v236 offset:2048
	ds_read_b128 v[136:139], v236 offset:3072
	s_mov_b64 s[12:13], 0x80
	v_lshl_add_u64 v[102:103], s[6:7], 0, v[188:189]
	v_mov_b32_e32 v101, v189
	s_mov_b32 m0, s40
	v_lshl_add_u64 v[102:103], v[102:103], 0, s[12:13]
	v_lshl_add_u64 v[100:101], s[6:7], 0, v[100:101]
	global_load_lds_dwordx4 v[102:103], off
	v_lshl_add_u64 v[100:101], v[100:101], 0, s[12:13]
	s_mov_b32 m0, s37
	s_nop 0
	global_load_lds_dwordx4 v[100:101], off
	s_barrier
	s_waitcnt lgkmcnt(0)
	s_waitcnt lgkmcnt(0)
	v_mfma_f32_16x16x32_bf16 v[92:95], v[120:123], v[16:19], v[92:95]
	v_mfma_f32_16x16x32_bf16 v[16:19], v[132:135], v[16:19], v[180:183]
	v_mfma_f32_16x16x32_bf16 v[116:119], v[136:139], v[24:27], v[16:19]
	v_mfma_f32_16x16x32_bf16 v[16:19], v[120:123], v[32:35], v[84:87]
	v_mfma_f32_16x16x32_bf16 v[108:111], v[128:131], v[40:43], v[16:19]
	v_mfma_f32_16x16x32_bf16 v[16:19], v[132:135], v[32:35], v[172:175]
	v_mfma_f32_16x16x32_bf16 v[100:103], v[136:139], v[40:43], v[16:19]
	v_mfma_f32_16x16x32_bf16 v[16:19], v[120:123], v[48:51], v[76:79]
	v_mfma_f32_16x16x32_bf16 v[234:237], v[128:131], v[24:27], v[92:95]
	v_mfma_f32_16x16x32_bf16 v[92:95], v[128:131], v[56:59], v[16:19]
	v_mfma_f32_16x16x32_bf16 v[16:19], v[132:135], v[48:51], v[164:167]
	v_mfma_f32_16x16x32_bf16 v[84:87], v[136:139], v[56:59], v[16:19]
	v_mfma_f32_16x16x32_bf16 v[16:19], v[120:123], v[184:187], v[68:71]
	v_mfma_f32_16x16x32_bf16 v[76:79], v[128:131], v[190:193], v[16:19]
	v_mfma_f32_16x16x32_bf16 v[16:19], v[132:135], v[184:187], v[156:159]
	v_mfma_f32_16x16x32_bf16 v[68:71], v[136:139], v[190:193], v[16:19]
	v_readlane_b32 s12, v252, 12
	s_nop 4
	v_mov_b32_e32 v16, v226
	v_mov_b32_e32 v17, v227
	s_mov_b32 m0, s28
	v_readlane_b32 s13, v252, 13
	s_barrier
	ds_read_b128 v[156:159], v233 offset:49152
	ds_read_b128 v[164:167], v233 offset:50176
	ds_read_b128 v[172:175], v233 offset:51200
	ds_read_b128 v[180:183], v233 offset:52224
	ds_read_b128 v[184:187], v233 offset:53248
	ds_read_b128 v[190:193], v233 offset:54272
	ds_read_b128 v[242:245], v233 offset:55296
	ds_read_b128 v[246:249], v233 offset:56320
	s_nop 0
	global_load_lds_dwordx4 v16, s[12:13]
	s_mov_b32 m0, s29
	s_nop 0
	global_load_lds_dwordx4 v17, s[12:13]
	s_barrier
	s_waitcnt lgkmcnt(0)
	s_waitcnt lgkmcnt(0)
	v_mfma_f32_16x16x32_bf16 v[16:19], v[0:3], v[156:159], v[60:63]
	v_mfma_f32_16x16x32_bf16 v[56:59], v[8:11], v[164:167], v[16:19]
	v_mfma_f32_16x16x32_bf16 v[16:19], v[168:171], v[156:159], v[194:197]
	v_mfma_f32_16x16x32_bf16 v[48:51], v[176:179], v[164:167], v[16:19]
	v_mfma_f32_16x16x32_bf16 v[16:19], v[0:3], v[172:175], v[52:55]
	v_mfma_f32_16x16x32_bf16 v[40:43], v[8:11], v[180:183], v[16:19]
	v_mfma_f32_16x16x32_bf16 v[16:19], v[168:171], v[172:175], v[202:205]
	v_mfma_f32_16x16x32_bf16 v[32:35], v[176:179], v[180:183], v[16:19]
	v_mfma_f32_16x16x32_bf16 v[16:19], v[0:3], v[184:187], v[44:47]
	v_mfma_f32_16x16x32_bf16 v[0:3], v[0:3], v[242:245], v[36:39]
	v_mfma_f32_16x16x32_bf16 v[24:27], v[8:11], v[190:193], v[16:19]
	v_mfma_f32_16x16x32_bf16 v[16:19], v[168:171], v[184:187], v[238:241]
	v_mfma_f32_16x16x32_bf16 v[8:11], v[8:11], v[246:249], v[0:3]
	v_mfma_f32_16x16x32_bf16 v[0:3], v[168:171], v[242:245], v[140:143]
	v_mfma_f32_16x16x32_bf16 v[16:19], v[176:179], v[190:193], v[16:19]
	v_mfma_f32_16x16x32_bf16 v[0:3], v[176:179], v[246:249], v[0:3]
	s_barrier
	s_add_u32 s6, s6, 0x8000080
	v_mov_b32_e32 v36, v224
	v_mov_b32_e32 v37, v225
	s_addc_u32 s7, s7, 0
	s_mov_b32 m0, s14
	s_nop 0
	global_load_lds_dwordx4 v36, s[6:7]
	s_mov_b32 m0, s15
	s_nop 0
	global_load_lds_dwordx4 v37, s[6:7]
	s_waitcnt vmcnt(6)
	s_barrier
	v_mfma_f32_16x16x32_bf16 v[28:31], v[120:123], v[156:159], v[28:31]
	v_mfma_f32_16x16x32_bf16 v[60:63], v[128:131], v[164:167], v[28:31]
	v_mfma_f32_16x16x32_bf16 v[28:31], v[132:135], v[156:159], v[144:147]
	v_mfma_f32_16x16x32_bf16 v[20:23], v[120:123], v[172:175], v[20:23]
	v_mfma_f32_16x16x32_bf16 v[12:15], v[120:123], v[184:187], v[12:15]
	v_mfma_f32_16x16x32_bf16 v[52:55], v[136:139], v[164:167], v[28:31]
	v_mfma_f32_16x16x32_bf16 v[44:47], v[128:131], v[180:183], v[20:23]
	v_mfma_f32_16x16x32_bf16 v[20:23], v[132:135], v[172:175], v[148:151]
	v_mfma_f32_16x16x32_bf16 v[28:31], v[128:131], v[190:193], v[12:15]
	v_mfma_f32_16x16x32_bf16 v[12:15], v[132:135], v[184:187], v[152:155]
	v_mfma_f32_16x16x32_bf16 v[4:7], v[120:123], v[242:245], v[4:7]
	v_mfma_f32_16x16x32_bf16 v[36:39], v[136:139], v[180:183], v[20:23]
	v_mfma_f32_16x16x32_bf16 v[20:23], v[136:139], v[190:193], v[12:15]
	v_mfma_f32_16x16x32_bf16 v[12:15], v[128:131], v[246:249], v[4:7]
	v_mfma_f32_16x16x32_bf16 v[4:7], v[132:135], v[242:245], v[160:163]
	v_mfma_f32_16x16x32_bf16 v[4:7], v[136:139], v[246:249], v[4:7]
	v_lshl_add_u32 v120, s34, 8, v230
	v_ashrrev_i32_e32 v121, 31, v120
	v_lshlrev_b64 v[128:129], 12, v[120:121]
	v_mul_f32_e32 v121, 0xbfb8aa3b, v124
	v_exp_f32_e32 v121, v121
	v_lshl_or_b32 v122, s33, 7, v232
	v_ashrrev_i32_e32 v123, 31, v122
	v_lshl_add_u64 v[128:129], s[94:95], 0, v[128:129]
	v_add_f32_e32 v121, 1.0, v121
	v_rcp_f32_e32 v121, v121
	s_barrier
; __device__ __forceinline__ unsigned cvt_pk_bf16(float lo, float hi) { unsigned r; asm("v_cvt_pk_bf16_f32 %0, %1, %2" : "=v"(r) : "v"(lo), "v"(hi)); return r; }
;     __device__ __forceinline__ void operator()(const f32x4 (&acc)[2][2][4][2], const Unit& u, int wr, int wc, int fr, int fq) const {
;         const int row0 = u.pm * BM + wr * 64 + fr, col0 = u.pn * HALF + wc * 32 + 8 * fq;
; #pragma unroll
;         for (int ai = 0; ai < 2; ++ai)
; #pragma unroll
;             for (int m = 0; m < 4; ++m) { bf16_t* rowp = O + (size_t)(row0 + ai * HALF + m * 16) * FF + col0;
;                 float h[8];
; #pragma unroll
;                 for (int n = 0; n < 2; ++n)
; #pragma unroll
;                     for (int j = 0; j < 4; ++j) { const float g = acc[ai][0][m][n][j], up = acc[ai][1][m][n][j]; h[n * 4 + j] = g * __builtin_amdgcn_rcpf(1.0f + __expf(-g)) * up; }
;                 u32x4 w; w.x = cvt_pk_bf16(h[0], h[1]); w.y = cvt_pk_bf16(h[2], h[3]); w.z = cvt_pk_bf16(h[4], h[5]); w.w = cvt_pk_bf16(h[6], h[7]);
;                 *(u32x4*)rowp = w; }
	s_mov_b32 s6, 0x80000
	s_mov_b32 s33, s8
	v_mul_f32_e32 v121, v124, v121
	v_mul_f32_e32 v124, 0xbfb8aa3b, v125
	v_exp_f32_e32 v124, v124
	v_mul_f32_e32 v121, v121, v234
	s_mov_b32 s34, s31
	s_mov_b64 s[12:13], s[10:11]
	v_add_f32_e32 v124, 1.0, v124
	v_rcp_f32_e32 v124, v124
	v_readlane_b32 s35, v255, 32
	v_readlane_b32 s36, v255, 33
	v_readlane_b32 s37, v255, 34
	v_mul_f32_e32 v124, v125, v124
	v_mul_f32_e32 v125, 0xbfb8aa3b, v126
	v_exp_f32_e32 v125, v125
	v_mul_f32_e32 v124, v124, v235
	v_add_f32_e32 v125, 1.0, v125
	v_rcp_f32_e32 v125, v125
	s_nop 0
	v_mul_f32_e32 v125, v126, v125
	v_mul_f32_e32 v126, 0xbfb8aa3b, v127
	v_exp_f32_e32 v126, v126
	v_mul_f32_e32 v125, v125, v236
	v_add_f32_e32 v126, 1.0, v126
	v_rcp_f32_e32 v126, v126
	s_nop 0
	v_mul_f32_e32 v126, v127, v126
	v_mul_f32_e32 v127, 0xbfb8aa3b, v112
	v_exp_f32_e32 v127, v127
	v_mul_f32_e32 v126, v126, v237
	v_add_f32_e32 v127, 1.0, v127
	v_rcp_f32_e32 v127, v127
	s_nop 0
	v_mul_f32_e32 v112, v112, v127
	v_mul_f32_e32 v127, v112, v116
	v_mul_f32_e32 v112, 0xbfb8aa3b, v113
	v_exp_f32_e32 v112, v112
	v_cvt_pk_bf16_f32 v116, v121, v124
	s_nop 0
	v_add_f32_e32 v112, 1.0, v112
	v_rcp_f32_e32 v112, v112
	s_nop 0
	v_mul_f32_e32 v112, v113, v112
	v_mul_f32_e32 v130, v112, v117
	v_mul_f32_e32 v112, 0xbfb8aa3b, v114
	v_exp_f32_e32 v112, v112
	v_cvt_pk_bf16_f32 v117, v125, v126
	s_nop 0
	v_add_f32_e32 v112, 1.0, v112
	v_rcp_f32_e32 v112, v112
	s_nop 0
	v_mul_f32_e32 v112, v114, v112
	v_mul_f32_e32 v131, v112, v118
	v_mul_f32_e32 v112, 0xbfb8aa3b, v115
	v_exp_f32_e32 v112, v112
	v_cvt_pk_bf16_f32 v118, v127, v130
	s_nop 0
	v_add_f32_e32 v112, 1.0, v112
	v_rcp_f32_e32 v112, v112
	s_nop 0
	v_mul_f32_e32 v112, v115, v112
	v_lshlrev_b64 v[114:115], 1, v[122:123]
	v_mul_f32_e32 v119, v112, v119
	v_lshl_add_u64 v[112:113], v[128:129], 0, v[114:115]
	v_cvt_pk_bf16_f32 v119, v131, v119
	global_store_dwordx4 v[112:113], v[116:119], off
	s_nop 1
	v_mul_f32_e32 v118, 0xbfb8aa3b, v104
	v_exp_f32_e32 v118, v118
	v_or_b32_e32 v116, 16, v120
	v_ashrrev_i32_e32 v117, 31, v116
	v_lshlrev_b64 v[116:117], 12, v[116:117]
	v_add_f32_e32 v118, 1.0, v118
	v_rcp_f32_e32 v118, v118
	v_lshl_add_u64 v[116:117], s[94:95], 0, v[116:117]
	v_mul_f32_e32 v104, v104, v118
	v_mul_f32_e32 v104, v104, v108
	v_mul_f32_e32 v108, 0xbfb8aa3b, v105
	v_exp_f32_e32 v108, v108
	s_nop 0
	v_add_f32_e32 v108, 1.0, v108
	v_rcp_f32_e32 v108, v108
	s_nop 0
	v_mul_f32_e32 v105, v105, v108
	v_mul_f32_e32 v108, 0xbfb8aa3b, v106
	v_exp_f32_e32 v108, v108
	v_mul_f32_e32 v105, v105, v109
	v_add_f32_e32 v108, 1.0, v108
	v_rcp_f32_e32 v108, v108
	s_nop 0
	v_mul_f32_e32 v106, v106, v108
	v_mul_f32_e32 v108, 0xbfb8aa3b, v107
	v_exp_f32_e32 v108, v108
	v_mul_f32_e32 v106, v106, v110
	v_add_f32_e32 v108, 1.0, v108
	v_rcp_f32_e32 v108, v108
	s_nop 0
	v_mul_f32_e32 v107, v107, v108
	v_mul_f32_e32 v108, 0xbfb8aa3b, v96
	v_exp_f32_e32 v108, v108
	v_mul_f32_e32 v107, v107, v111
	v_add_f32_e32 v108, 1.0, v108
	v_rcp_f32_e32 v108, v108
	s_nop 0
	v_mul_f32_e32 v96, v96, v108
	v_mul_f32_e32 v108, v96, v100
	v_mul_f32_e32 v96, 0xbfb8aa3b, v97
	v_exp_f32_e32 v96, v96
	s_nop 0
	v_add_f32_e32 v96, 1.0, v96
	v_rcp_f32_e32 v96, v96
	s_nop 0
	v_mul_f32_e32 v96, v97, v96
	v_mul_f32_e32 v109, v96, v101
	v_mul_f32_e32 v96, 0xbfb8aa3b, v98
	v_exp_f32_e32 v96, v96
	v_lshl_add_u64 v[100:101], v[116:117], 0, v[114:115]
	v_cvt_pk_bf16_f32 v97, v106, v107
	v_add_f32_e32 v96, 1.0, v96
	v_rcp_f32_e32 v96, v96
	s_nop 0
	v_mul_f32_e32 v96, v98, v96
	v_mul_f32_e32 v102, v96, v102
	v_mul_f32_e32 v96, 0xbfb8aa3b, v99
	v_exp_f32_e32 v96, v96
	v_cvt_pk_bf16_f32 v98, v108, v109
	s_nop 0
	v_add_f32_e32 v96, 1.0, v96
	v_rcp_f32_e32 v96, v96
	s_nop 0
	v_mul_f32_e32 v96, v99, v96
	v_mul_f32_e32 v99, v96, v103
	v_cvt_pk_bf16_f32 v96, v104, v105
	v_cvt_pk_bf16_f32 v99, v102, v99
	global_store_dwordx4 v[100:101], v[96:99], off
	s_nop 1
	v_mul_f32_e32 v98, 0xbfb8aa3b, v88
	v_exp_f32_e32 v98, v98
	v_or_b32_e32 v96, 32, v120
	v_ashrrev_i32_e32 v97, 31, v96
	v_lshlrev_b64 v[96:97], 12, v[96:97]
	v_add_f32_e32 v98, 1.0, v98
	v_rcp_f32_e32 v98, v98
	v_lshl_add_u64 v[96:97], s[94:95], 0, v[96:97]
	v_mul_f32_e32 v88, v88, v98
	v_mul_f32_e32 v88, v88, v92
	v_mul_f32_e32 v92, 0xbfb8aa3b, v89
	v_exp_f32_e32 v92, v92
	s_nop 0
	v_add_f32_e32 v92, 1.0, v92
	v_rcp_f32_e32 v92, v92
	s_nop 0
	v_mul_f32_e32 v89, v89, v92
	v_mul_f32_e32 v92, 0xbfb8aa3b, v90
	v_exp_f32_e32 v92, v92
	v_mul_f32_e32 v89, v89, v93
	v_add_f32_e32 v92, 1.0, v92
	v_rcp_f32_e32 v92, v92
	s_nop 0
	v_mul_f32_e32 v90, v90, v92
	v_mul_f32_e32 v92, 0xbfb8aa3b, v91
	v_exp_f32_e32 v92, v92
	v_mul_f32_e32 v90, v90, v94
	v_add_f32_e32 v92, 1.0, v92
	v_rcp_f32_e32 v92, v92
	s_nop 0
	v_mul_f32_e32 v91, v91, v92
	v_mul_f32_e32 v92, 0xbfb8aa3b, v80
	v_exp_f32_e32 v92, v92
	v_mul_f32_e32 v91, v91, v95
	v_add_f32_e32 v92, 1.0, v92
	v_rcp_f32_e32 v92, v92
	s_nop 0
	v_mul_f32_e32 v80, v80, v92
	v_mul_f32_e32 v92, v80, v84
	v_mul_f32_e32 v80, 0xbfb8aa3b, v81
	v_exp_f32_e32 v80, v80
	s_nop 0
	v_add_f32_e32 v80, 1.0, v80
	v_rcp_f32_e32 v80, v80
	s_nop 0
	v_mul_f32_e32 v80, v81, v80
	v_mul_f32_e32 v93, v80, v85
	v_mul_f32_e32 v80, 0xbfb8aa3b, v82
	v_exp_f32_e32 v80, v80
	v_lshl_add_u64 v[84:85], v[96:97], 0, v[114:115]
	v_cvt_pk_bf16_f32 v81, v90, v91
	v_add_f32_e32 v80, 1.0, v80
	v_rcp_f32_e32 v80, v80
	s_nop 0
	v_mul_f32_e32 v80, v82, v80
	v_mul_f32_e32 v86, v80, v86
	v_mul_f32_e32 v80, 0xbfb8aa3b, v83
	v_exp_f32_e32 v80, v80
	v_cvt_pk_bf16_f32 v82, v92, v93
	s_nop 0
	v_add_f32_e32 v80, 1.0, v80
	v_rcp_f32_e32 v80, v80
	s_nop 0
	v_mul_f32_e32 v80, v83, v80
	v_mul_f32_e32 v83, v80, v87
	v_cvt_pk_bf16_f32 v80, v88, v89
	v_cvt_pk_bf16_f32 v83, v86, v83
; __device__ __forceinline__ unsigned cvt_pk_bf16(float lo, float hi) { unsigned r; asm("v_cvt_pk_bf16_f32 %0, %1, %2" : "=v"(r) : "v"(lo), "v"(hi)); return r; }
;     __device__ __forceinline__ void operator()(const f32x4 (&acc)[2][2][4][2], const Unit& u, int wr, int wc, int fr, int fq) const {
;         const int row0 = u.pm * BM + wr * 64 + fr, col0 = u.pn * HALF + wc * 32 + 8 * fq;
; #pragma unroll
;         for (int ai = 0; ai < 2; ++ai)
; #pragma unroll
;             for (int m = 0; m < 4; ++m) { bf16_t* rowp = O + (size_t)(row0 + ai * HALF + m * 16) * FF + col0;
;                 float h[8];
; #pragma unroll
;                 for (int n = 0; n < 2; ++n)
; #pragma unroll
;                     for (int j = 0; j < 4; ++j) { const float g = acc[ai][0][m][n][j], up = acc[ai][1][m][n][j]; h[n * 4 + j] = g * __builtin_amdgcn_rcpf(1.0f + __expf(-g)) * up; }
;                 u32x4 w; w.x = cvt_pk_bf16(h[0], h[1]); w.y = cvt_pk_bf16(h[2], h[3]); w.z = cvt_pk_bf16(h[4], h[5]); w.w = cvt_pk_bf16(h[6], h[7]);
;                 *(u32x4*)rowp = w; }
	global_store_dwordx4 v[84:85], v[80:83], off
	s_nop 1
	v_mul_f32_e32 v82, 0xbfb8aa3b, v72
	v_exp_f32_e32 v82, v82
	v_or_b32_e32 v80, 48, v120
	v_ashrrev_i32_e32 v81, 31, v80
	v_lshlrev_b64 v[80:81], 12, v[80:81]
	v_add_f32_e32 v82, 1.0, v82
	v_rcp_f32_e32 v82, v82
	v_lshl_add_u64 v[80:81], s[94:95], 0, v[80:81]
	v_mul_f32_e32 v72, v72, v82
	v_mul_f32_e32 v72, v72, v76
	v_mul_f32_e32 v76, 0xbfb8aa3b, v73
	v_exp_f32_e32 v76, v76
	s_nop 0
	v_add_f32_e32 v76, 1.0, v76
	v_rcp_f32_e32 v76, v76
	s_nop 0
	v_mul_f32_e32 v73, v73, v76
	v_mul_f32_e32 v76, 0xbfb8aa3b, v74
	v_exp_f32_e32 v76, v76
	v_mul_f32_e32 v73, v73, v77
	v_add_f32_e32 v76, 1.0, v76
	v_rcp_f32_e32 v76, v76
	s_nop 0
	v_mul_f32_e32 v74, v74, v76
	v_mul_f32_e32 v76, 0xbfb8aa3b, v75
	v_exp_f32_e32 v76, v76
	v_mul_f32_e32 v74, v74, v78
	v_add_f32_e32 v76, 1.0, v76
	v_rcp_f32_e32 v76, v76
	s_nop 0
	v_mul_f32_e32 v75, v75, v76
	v_mul_f32_e32 v76, 0xbfb8aa3b, v64
	v_exp_f32_e32 v76, v76
	v_mul_f32_e32 v75, v75, v79
	v_add_f32_e32 v76, 1.0, v76
	v_rcp_f32_e32 v76, v76
	s_nop 0
	v_mul_f32_e32 v64, v64, v76
	v_mul_f32_e32 v76, v64, v68
	v_mul_f32_e32 v64, 0xbfb8aa3b, v65
	v_exp_f32_e32 v64, v64
	s_nop 0
	v_add_f32_e32 v64, 1.0, v64
	v_rcp_f32_e32 v64, v64
	s_nop 0
	v_mul_f32_e32 v64, v65, v64
	v_mul_f32_e32 v77, v64, v69
	v_mul_f32_e32 v64, 0xbfb8aa3b, v66
	v_exp_f32_e32 v64, v64
	v_lshl_add_u64 v[68:69], v[80:81], 0, v[114:115]
	v_cvt_pk_bf16_f32 v65, v74, v75
	v_add_f32_e32 v64, 1.0, v64
	v_rcp_f32_e32 v64, v64
	s_nop 0
	v_mul_f32_e32 v64, v66, v64
	v_mul_f32_e32 v70, v64, v70
	v_mul_f32_e32 v64, 0xbfb8aa3b, v67
	v_exp_f32_e32 v64, v64
	v_cvt_pk_bf16_f32 v66, v76, v77
	s_nop 0
	v_add_f32_e32 v64, 1.0, v64
	v_rcp_f32_e32 v64, v64
	s_nop 0
	v_mul_f32_e32 v64, v67, v64
	v_mul_f32_e32 v67, v64, v71
	v_cvt_pk_bf16_f32 v64, v72, v73
	v_cvt_pk_bf16_f32 v67, v70, v67
	global_store_dwordx4 v[68:69], v[64:67], off
	s_nop 1
	v_mul_f32_e32 v64, 0xbfb8aa3b, v56
	v_exp_f32_e32 v64, v64
	s_nop 0
	v_add_f32_e32 v64, 1.0, v64
	v_rcp_f32_e32 v64, v64
	s_nop 0
	v_mul_f32_e32 v56, v56, v64
	v_mul_f32_e32 v56, v56, v60
	v_mul_f32_e32 v60, 0xbfb8aa3b, v57
	v_exp_f32_e32 v60, v60
	s_nop 0
	v_add_f32_e32 v60, 1.0, v60
	v_rcp_f32_e32 v60, v60
	s_nop 0
	v_mul_f32_e32 v57, v57, v60
	v_mul_f32_e32 v60, 0xbfb8aa3b, v58
	v_exp_f32_e32 v60, v60
	v_mul_f32_e32 v57, v57, v61
	v_add_f32_e32 v60, 1.0, v60
	v_rcp_f32_e32 v60, v60
	s_nop 0
	v_mul_f32_e32 v58, v58, v60
	v_mul_f32_e32 v60, 0xbfb8aa3b, v59
	v_exp_f32_e32 v60, v60
	v_mul_f32_e32 v58, v58, v62
	v_add_f32_e32 v60, 1.0, v60
	v_rcp_f32_e32 v60, v60
	s_nop 0
	v_mul_f32_e32 v59, v59, v60
	v_mul_f32_e32 v60, 0xbfb8aa3b, v48
	v_exp_f32_e32 v60, v60
	v_mul_f32_e32 v59, v59, v63
	v_add_f32_e32 v60, 1.0, v60
	v_rcp_f32_e32 v60, v60
	s_nop 0
	v_mul_f32_e32 v48, v48, v60
	v_mul_f32_e32 v52, v48, v52
	v_mul_f32_e32 v48, 0xbfb8aa3b, v49
	v_exp_f32_e32 v48, v48
	s_nop 0
	v_add_f32_e32 v48, 1.0, v48
	v_rcp_f32_e32 v48, v48
	s_nop 0
	v_mul_f32_e32 v48, v49, v48
	v_mul_f32_e32 v53, v48, v53
	v_mul_f32_e32 v48, 0xbfb8aa3b, v50
	v_exp_f32_e32 v48, v48
	v_cvt_pk_bf16_f32 v49, v58, v59
	s_nop 0
	v_add_f32_e32 v48, 1.0, v48
	v_rcp_f32_e32 v48, v48
	s_nop 0
	v_mul_f32_e32 v48, v50, v48
	v_mul_f32_e32 v54, v48, v54
	v_mul_f32_e32 v48, 0xbfb8aa3b, v51
	v_exp_f32_e32 v48, v48
	v_cvt_pk_bf16_f32 v50, v52, v53
	v_add_co_u32_e32 v52, vcc, s6, v112
	v_add_f32_e32 v48, 1.0, v48
	v_rcp_f32_e32 v48, v48
	v_addc_co_u32_e32 v53, vcc, 0, v113, vcc
	s_mov_b32 s6, 0x90000
	v_mul_f32_e32 v48, v51, v48
	v_mul_f32_e32 v51, v48, v55
	v_cvt_pk_bf16_f32 v48, v56, v57
	v_cvt_pk_bf16_f32 v51, v54, v51
	global_store_dwordx4 v[52:53], v[48:51], off
	s_nop 1
	v_mul_f32_e32 v48, 0xbfb8aa3b, v40
	v_exp_f32_e32 v48, v48
	s_nop 0
	v_add_f32_e32 v48, 1.0, v48
	v_rcp_f32_e32 v48, v48
	s_nop 0
	v_mul_f32_e32 v40, v40, v48
	v_mul_f32_e32 v40, v40, v44
	v_mul_f32_e32 v44, 0xbfb8aa3b, v41
	v_exp_f32_e32 v44, v44
	s_nop 0
	v_add_f32_e32 v44, 1.0, v44
	v_rcp_f32_e32 v44, v44
	s_nop 0
	v_mul_f32_e32 v41, v41, v44
	v_mul_f32_e32 v44, 0xbfb8aa3b, v42
	v_exp_f32_e32 v44, v44
	v_mul_f32_e32 v41, v41, v45
	v_add_f32_e32 v44, 1.0, v44
	v_rcp_f32_e32 v44, v44
	s_nop 0
	v_mul_f32_e32 v42, v42, v44
	v_mul_f32_e32 v44, 0xbfb8aa3b, v43
	v_exp_f32_e32 v44, v44
	v_mul_f32_e32 v42, v42, v46
	v_add_f32_e32 v44, 1.0, v44
	v_rcp_f32_e32 v44, v44
	s_nop 0
	v_mul_f32_e32 v43, v43, v44
	v_mul_f32_e32 v44, 0xbfb8aa3b, v32
	v_exp_f32_e32 v44, v44
	v_mul_f32_e32 v43, v43, v47
; __device__ __forceinline__ unsigned cvt_pk_bf16(float lo, float hi) { unsigned r; asm("v_cvt_pk_bf16_f32 %0, %1, %2" : "=v"(r) : "v"(lo), "v"(hi)); return r; }
; #define PG8_WAIT_V(n) asm volatile("s_waitcnt vmcnt(" #n ")" ::: "memory")
;     __device__ __forceinline__ void operator()(const f32x4 (&acc)[2][2][4][2], const Unit& u, int wr, int wc, int fr, int fq) const {
;         const int row0 = u.pm * BM + wr * 64 + fr, col0 = u.pn * HALF + wc * 32 + 8 * fq;
; #pragma unroll
;         for (int ai = 0; ai < 2; ++ai)
; #pragma unroll
;             for (int m = 0; m < 4; ++m) { bf16_t* rowp = O + (size_t)(row0 + ai * HALF + m * 16) * FF + col0;
;                 float h[8];
; #pragma unroll
;                 for (int n = 0; n < 2; ++n)
; #pragma unroll
;                     for (int j = 0; j < 4; ++j) { const float g = acc[ai][0][m][n][j], up = acc[ai][1][m][n][j]; h[n * 4 + j] = g * __builtin_amdgcn_rcpf(1.0f + __expf(-g)) * up; }
;                 u32x4 w; w.x = cvt_pk_bf16(h[0], h[1]); w.y = cvt_pk_bf16(h[2], h[3]); w.z = cvt_pk_bf16(h[4], h[5]); w.w = cvt_pk_bf16(h[6], h[7]);
;                 *(u32x4*)rowp = w; }
; template <bool GATHER, class Epi>
; __device__ __forceinline__ void gemm_phase(LAS unsigned char* lds, const Sched& S, const Epi& E) {
;     ...
;         PG8_WAIT_V(0);
;         if (!has_next) break;
	v_add_f32_e32 v44, 1.0, v44
	v_rcp_f32_e32 v44, v44
	s_nop 0
	v_mul_f32_e32 v32, v32, v44
	v_mul_f32_e32 v36, v32, v36
	v_mul_f32_e32 v32, 0xbfb8aa3b, v33
	v_exp_f32_e32 v32, v32
	s_nop 0
	v_add_f32_e32 v32, 1.0, v32
	v_rcp_f32_e32 v32, v32
	s_nop 0
	v_mul_f32_e32 v32, v33, v32
	v_mul_f32_e32 v37, v32, v37
	v_mul_f32_e32 v32, 0xbfb8aa3b, v34
	v_exp_f32_e32 v32, v32
	v_cvt_pk_bf16_f32 v33, v42, v43
	s_nop 0
	v_add_f32_e32 v32, 1.0, v32
	v_rcp_f32_e32 v32, v32
	s_nop 0
	v_mul_f32_e32 v32, v34, v32
	v_mul_f32_e32 v38, v32, v38
	v_mul_f32_e32 v32, 0xbfb8aa3b, v35
	v_exp_f32_e32 v32, v32
	v_cvt_pk_bf16_f32 v34, v36, v37
	v_add_co_u32_e32 v36, vcc, s6, v112
	v_add_f32_e32 v32, 1.0, v32
	v_rcp_f32_e32 v32, v32
	v_addc_co_u32_e32 v37, vcc, 0, v113, vcc
	s_mov_b32 s6, 0xa0000
	v_mul_f32_e32 v32, v35, v32
	v_mul_f32_e32 v35, v32, v39
	v_cvt_pk_bf16_f32 v32, v40, v41
	v_cvt_pk_bf16_f32 v35, v38, v35
	global_store_dwordx4 v[36:37], v[32:35], off
	s_nop 1
	v_mul_f32_e32 v32, 0xbfb8aa3b, v24
	v_exp_f32_e32 v32, v32
	s_nop 0
	v_add_f32_e32 v32, 1.0, v32
	v_rcp_f32_e32 v32, v32
	s_nop 0
	v_mul_f32_e32 v24, v24, v32
	v_mul_f32_e32 v24, v24, v28
	v_mul_f32_e32 v28, 0xbfb8aa3b, v25
	v_exp_f32_e32 v28, v28
	s_nop 0
	v_add_f32_e32 v28, 1.0, v28
	v_rcp_f32_e32 v28, v28
	s_nop 0
	v_mul_f32_e32 v25, v25, v28
	v_mul_f32_e32 v28, 0xbfb8aa3b, v26
	v_exp_f32_e32 v28, v28
	v_mul_f32_e32 v25, v25, v29
	v_add_f32_e32 v28, 1.0, v28
	v_rcp_f32_e32 v28, v28
	s_nop 0
	v_mul_f32_e32 v26, v26, v28
	v_mul_f32_e32 v28, 0xbfb8aa3b, v27
	v_exp_f32_e32 v28, v28
	v_mul_f32_e32 v26, v26, v30
	v_add_f32_e32 v28, 1.0, v28
	v_rcp_f32_e32 v28, v28
	s_nop 0
	v_mul_f32_e32 v27, v27, v28
	v_mul_f32_e32 v28, 0xbfb8aa3b, v16
	v_exp_f32_e32 v28, v28
	v_mul_f32_e32 v27, v27, v31
	v_add_f32_e32 v28, 1.0, v28
	v_rcp_f32_e32 v28, v28
	s_nop 0
	v_mul_f32_e32 v16, v16, v28
	v_mul_f32_e32 v20, v16, v20
	v_mul_f32_e32 v16, 0xbfb8aa3b, v17
	v_exp_f32_e32 v16, v16
	s_nop 0
	v_add_f32_e32 v16, 1.0, v16
	v_rcp_f32_e32 v16, v16
	s_nop 0
	v_mul_f32_e32 v16, v17, v16
	v_mul_f32_e32 v21, v16, v21
	v_mul_f32_e32 v16, 0xbfb8aa3b, v18
	v_exp_f32_e32 v16, v16
	v_cvt_pk_bf16_f32 v17, v26, v27
	s_nop 0
	v_add_f32_e32 v16, 1.0, v16
	v_rcp_f32_e32 v16, v16
	s_nop 0
	v_mul_f32_e32 v16, v18, v16
	v_mul_f32_e32 v22, v16, v22
	v_mul_f32_e32 v16, 0xbfb8aa3b, v19
	v_exp_f32_e32 v16, v16
	v_cvt_pk_bf16_f32 v18, v20, v21
	v_add_co_u32_e32 v20, vcc, s6, v112
	v_add_f32_e32 v16, 1.0, v16
	v_rcp_f32_e32 v16, v16
	v_addc_co_u32_e32 v21, vcc, 0, v113, vcc
	v_mul_f32_e32 v16, v19, v16
	v_mul_f32_e32 v19, v16, v23
	v_cvt_pk_bf16_f32 v16, v24, v25
	v_cvt_pk_bf16_f32 v19, v22, v19
	global_store_dwordx4 v[20:21], v[16:19], off
	s_nop 1
	v_mul_f32_e32 v16, 0xbfb8aa3b, v8
	v_exp_f32_e32 v16, v16
	s_nop 0
	v_add_f32_e32 v16, 1.0, v16
	v_rcp_f32_e32 v16, v16
	s_nop 0
	v_mul_f32_e32 v8, v8, v16
	v_mul_f32_e32 v8, v8, v12
	v_mul_f32_e32 v12, 0xbfb8aa3b, v9
	v_exp_f32_e32 v12, v12
	s_nop 0
	v_add_f32_e32 v12, 1.0, v12
	v_rcp_f32_e32 v12, v12
	s_nop 0
	v_mul_f32_e32 v9, v9, v12
	v_mul_f32_e32 v12, 0xbfb8aa3b, v10
	v_exp_f32_e32 v12, v12
	v_mul_f32_e32 v9, v9, v13
	v_add_f32_e32 v12, 1.0, v12
	v_rcp_f32_e32 v12, v12
	s_nop 0
	v_mul_f32_e32 v10, v10, v12
	v_mul_f32_e32 v12, 0xbfb8aa3b, v11
	v_exp_f32_e32 v12, v12
	v_mul_f32_e32 v10, v10, v14
	v_add_f32_e32 v12, 1.0, v12
	v_rcp_f32_e32 v12, v12
	s_nop 0
	v_mul_f32_e32 v11, v11, v12
	v_mul_f32_e32 v12, 0xbfb8aa3b, v0
	v_exp_f32_e32 v12, v12
	v_mul_f32_e32 v11, v11, v15
	v_add_f32_e32 v12, 1.0, v12
	v_rcp_f32_e32 v12, v12
	s_nop 0
	v_mul_f32_e32 v0, v0, v12
	v_mul_f32_e32 v4, v0, v4
	v_mul_f32_e32 v0, 0xbfb8aa3b, v1
	v_exp_f32_e32 v0, v0
	s_nop 0
	v_add_f32_e32 v0, 1.0, v0
	v_rcp_f32_e32 v0, v0
	s_nop 0
	v_mul_f32_e32 v0, v1, v0
	v_mul_f32_e32 v5, v0, v5
	v_mul_f32_e32 v0, 0xbfb8aa3b, v2
	v_exp_f32_e32 v0, v0
	v_cvt_pk_bf16_f32 v1, v10, v11
	s_nop 0
	v_add_f32_e32 v0, 1.0, v0
	v_rcp_f32_e32 v0, v0
	s_nop 0
	v_mul_f32_e32 v0, v2, v0
	v_mul_f32_e32 v6, v0, v6
	v_mul_f32_e32 v0, 0xbfb8aa3b, v3
	v_exp_f32_e32 v0, v0
	v_cvt_pk_bf16_f32 v2, v4, v5
	v_add_co_u32_e32 v4, vcc, 0xb0000, v112
	v_add_f32_e32 v0, 1.0, v0
	v_rcp_f32_e32 v0, v0
	v_addc_co_u32_e32 v5, vcc, 0, v113, vcc
	s_andn2_b64 vcc, exec, s[4:5]
	v_mul_f32_e32 v0, v3, v0
	v_mul_f32_e32 v3, v0, v7
	v_cvt_pk_bf16_f32 v0, v8, v9
	v_cvt_pk_bf16_f32 v3, v6, v3
	global_store_dwordx4 v[4:5], v[0:3], off
	s_waitcnt vmcnt(0)
	s_cbranch_vccz .LBB0_128

; template <bool GATHER, class Epi>
; __device__ __forceinline__ void gemm_phase(LAS unsigned char* lds, const Sched& S, const Epi& E) {
;     ...
;         for (; t < nt - 2; t += 2) PG8_TRIP(false);
.LBB0_125:
	s_add_i32 s35, 0, 0x10000
	v_add_u32_e32 v140, s35, v231
	ds_read_b128 v[128:131], v140
	ds_read_b128 v[132:135], v140 offset:1024
	ds_read_b128 v[136:139], v140 offset:2048
	ds_read_b128 v[140:143], v140 offset:3072
	s_add_u32 s14, s86, s10
	v_mov_b32_e32 v188, v228
	v_mov_b32_e32 v176, v229
	s_addc_u32 s15, s87, s11
	ds_read_b128 v[144:147], v233
	ds_read_b128 v[148:151], v233 offset:1024
	ds_read_b128 v[152:155], v233 offset:2048
	ds_read_b128 v[156:159], v233 offset:3072
	ds_read_b128 v[160:163], v233 offset:4096
	ds_read_b128 v[164:167], v233 offset:5120
	ds_read_b128 v[168:171], v233 offset:6144
	ds_read_b128 v[172:175], v233 offset:7168
	s_add_i32 s41, s22, 0xc000
	v_lshl_add_u64 v[178:179], s[14:15], 0, v[188:189]
	v_mov_b32_e32 v177, v189
	v_lshl_add_u64 v[178:179], v[178:179], 0, s[44:45]
	s_mov_b32 m0, s41
	v_lshl_add_u64 v[176:177], s[14:15], 0, v[176:177]
	s_add_i32 s42, s22, 0xe000
	global_load_lds_dwordx4 v[178:179], off
	v_lshl_add_u64 v[176:177], v[176:177], 0, s[44:45]
	s_mov_b32 m0, s42
	s_nop 0
	global_load_lds_dwordx4 v[176:177], off
	s_waitcnt lgkmcnt(8)
	s_barrier
	s_waitcnt lgkmcnt(0)
	s_waitcnt lgkmcnt(0)
	v_mfma_f32_16x16x32_bf16 v[124:127], v[128:131], v[144:147], v[124:127]
	v_mfma_f32_16x16x32_bf16 v[120:123], v[136:139], v[144:147], v[120:123]
	v_mfma_f32_16x16x32_bf16 v[116:119], v[128:131], v[152:155], v[116:119]
	v_mfma_f32_16x16x32_bf16 v[112:115], v[136:139], v[152:155], v[112:115]
	v_mfma_f32_16x16x32_bf16 v[108:111], v[128:131], v[160:163], v[108:111]
	v_mfma_f32_16x16x32_bf16 v[104:107], v[136:139], v[160:163], v[104:107]
	v_mfma_f32_16x16x32_bf16 v[100:103], v[128:131], v[168:171], v[100:103]
	v_mfma_f32_16x16x32_bf16 v[96:99], v[136:139], v[168:171], v[96:99]
	v_mfma_f32_16x16x32_bf16 v[124:127], v[132:135], v[148:151], v[124:127]
	v_mfma_f32_16x16x32_bf16 v[120:123], v[140:143], v[148:151], v[120:123]
	v_mfma_f32_16x16x32_bf16 v[116:119], v[132:135], v[156:159], v[116:119]
	v_mfma_f32_16x16x32_bf16 v[112:115], v[140:143], v[156:159], v[112:115]
	v_mfma_f32_16x16x32_bf16 v[108:111], v[132:135], v[164:167], v[108:111]
	v_mfma_f32_16x16x32_bf16 v[104:107], v[140:143], v[164:167], v[104:107]
	v_mfma_f32_16x16x32_bf16 v[100:103], v[132:135], v[172:175], v[100:103]
	v_mfma_f32_16x16x32_bf16 v[96:99], v[140:143], v[172:175], v[96:99]
	s_barrier
	s_add_i32 s36, 0, 0x14000
	s_add_u32 s16, s12, s10
	v_add_u32_e32 v234, s36, v231
	v_mov_b32_e32 v188, v224
	v_mov_b32_e32 v194, v225
	s_addc_u32 s17, s13, s11
	ds_read_b128 v[176:179], v234
	ds_read_b128 v[180:183], v234 offset:1024
	ds_read_b128 v[184:187], v234 offset:2048
	ds_read_b128 v[190:193], v234 offset:3072
	s_add_i32 s35, s35, s21
	v_lshl_add_u64 v[196:197], s[16:17], 0, v[188:189]
	v_mov_b32_e32 v195, v189
	v_lshl_add_u64 v[196:197], v[196:197], 0, s[88:89]
	s_mov_b32 m0, s35
	v_lshl_add_u64 v[194:195], s[16:17], 0, v[194:195]
	global_load_lds_dwordx4 v[196:197], off
	v_lshl_add_u64 v[194:195], v[194:195], 0, s[88:89]
	s_add_i32 m0, s35, 0x2000
	s_nop 0
	global_load_lds_dwordx4 v[194:195], off
	s_barrier
	s_waitcnt lgkmcnt(0)
	s_waitcnt lgkmcnt(0)
	v_mfma_f32_16x16x32_bf16 v[92:95], v[176:179], v[144:147], v[92:95]
	v_mfma_f32_16x16x32_bf16 v[88:91], v[184:187], v[144:147], v[88:91]
	v_mfma_f32_16x16x32_bf16 v[84:87], v[176:179], v[152:155], v[84:87]
	v_mfma_f32_16x16x32_bf16 v[80:83], v[184:187], v[152:155], v[80:83]
	v_mfma_f32_16x16x32_bf16 v[76:79], v[176:179], v[160:163], v[76:79]
	v_mfma_f32_16x16x32_bf16 v[72:75], v[184:187], v[160:163], v[72:75]
	v_mfma_f32_16x16x32_bf16 v[68:71], v[176:179], v[168:171], v[68:71]
	v_mfma_f32_16x16x32_bf16 v[64:67], v[184:187], v[168:171], v[64:67]
	v_mfma_f32_16x16x32_bf16 v[92:95], v[180:183], v[148:151], v[92:95]
	v_mfma_f32_16x16x32_bf16 v[88:91], v[190:193], v[148:151], v[88:91]
	v_mfma_f32_16x16x32_bf16 v[84:87], v[180:183], v[156:159], v[84:87]
	v_mfma_f32_16x16x32_bf16 v[80:83], v[190:193], v[156:159], v[80:83]
	v_mfma_f32_16x16x32_bf16 v[76:79], v[180:183], v[164:167], v[76:79]
	v_mfma_f32_16x16x32_bf16 v[72:75], v[190:193], v[164:167], v[72:75]
	v_mfma_f32_16x16x32_bf16 v[68:71], v[180:183], v[172:175], v[68:71]
	v_mfma_f32_16x16x32_bf16 v[64:67], v[190:193], v[172:175], v[64:67]
	v_mov_b32_e32 v188, v226
	v_mov_b32_e32 v194, v227
	s_barrier
	ds_read_b128 v[144:147], v233 offset:16384
	ds_read_b128 v[148:151], v233 offset:17408
	ds_read_b128 v[152:155], v233 offset:18432
	ds_read_b128 v[156:159], v233 offset:19456
	ds_read_b128 v[160:163], v233 offset:20480
	ds_read_b128 v[164:167], v233 offset:21504
	ds_read_b128 v[168:171], v233 offset:22528
	ds_read_b128 v[172:175], v233 offset:23552
	v_mov_b32_e32 v195, v189
	v_lshl_add_u64 v[196:197], s[14:15], 0, v[188:189]
	s_mov_b32 m0, s22
	v_lshl_add_u64 v[196:197], v[196:197], 0, s[46:47]
	v_lshl_add_u64 v[194:195], s[14:15], 0, v[194:195]
	global_load_lds_dwordx4 v[196:197], off
	v_lshl_add_u64 v[194:195], v[194:195], 0, s[46:47]
	s_mov_b32 m0, s25
	s_nop 0
	global_load_lds_dwordx4 v[194:195], off
	s_barrier
	s_waitcnt lgkmcnt(0)
	s_waitcnt lgkmcnt(0)
	v_mfma_f32_16x16x32_bf16 v[60:63], v[128:131], v[144:147], v[60:63]
	v_mfma_f32_16x16x32_bf16 v[56:59], v[136:139], v[144:147], v[56:59]
	v_mfma_f32_16x16x32_bf16 v[52:55], v[128:131], v[152:155], v[52:55]
	v_mfma_f32_16x16x32_bf16 v[48:51], v[136:139], v[152:155], v[48:51]
	v_mfma_f32_16x16x32_bf16 v[44:47], v[128:131], v[160:163], v[44:47]
	v_mfma_f32_16x16x32_bf16 v[40:43], v[136:139], v[160:163], v[40:43]
	v_mfma_f32_16x16x32_bf16 v[36:39], v[128:131], v[168:171], v[36:39]
	v_mfma_f32_16x16x32_bf16 v[32:35], v[136:139], v[168:171], v[32:35]
	v_mfma_f32_16x16x32_bf16 v[60:63], v[132:135], v[148:151], v[60:63]
	v_mfma_f32_16x16x32_bf16 v[56:59], v[140:143], v[148:151], v[56:59]
	v_mfma_f32_16x16x32_bf16 v[52:55], v[132:135], v[156:159], v[52:55]
	v_mfma_f32_16x16x32_bf16 v[48:51], v[140:143], v[156:159], v[48:51]
	v_mfma_f32_16x16x32_bf16 v[44:47], v[132:135], v[164:167], v[44:47]
	v_mfma_f32_16x16x32_bf16 v[40:43], v[140:143], v[164:167], v[40:43]
	v_mfma_f32_16x16x32_bf16 v[36:39], v[132:135], v[172:175], v[36:39]
	v_mfma_f32_16x16x32_bf16 v[32:35], v[140:143], v[172:175], v[32:35]
	s_barrier
	v_mov_b32_e32 v188, v224
	v_mov_b32_e32 v128, v225
	s_add_i32 s35, s36, s21
	v_lshl_add_u64 v[130:131], s[16:17], 0, v[188:189]
	v_mov_b32_e32 v129, v189
	v_lshl_add_u64 v[130:131], v[130:131], 0, s[48:49]
	s_mov_b32 m0, s35
	v_lshl_add_u64 v[128:129], s[16:17], 0, v[128:129]
	s_add_i32 s36, s35, 0x2000
	global_load_lds_dwordx4 v[130:131], off
	v_lshl_add_u64 v[128:129], v[128:129], 0, s[48:49]
	s_mov_b32 m0, s36
	s_nop 0
	global_load_lds_dwordx4 v[128:129], off
	s_waitcnt vmcnt(6)
	s_barrier
	v_mfma_f32_16x16x32_bf16 v[28:31], v[176:179], v[144:147], v[28:31]
	v_mfma_f32_16x16x32_bf16 v[24:27], v[184:187], v[144:147], v[24:27]
	v_mfma_f32_16x16x32_bf16 v[20:23], v[176:179], v[152:155], v[20:23]
	v_mfma_f32_16x16x32_bf16 v[16:19], v[184:187], v[152:155], v[16:19]
	v_mfma_f32_16x16x32_bf16 v[12:15], v[176:179], v[160:163], v[12:15]
	v_mfma_f32_16x16x32_bf16 v[8:11], v[184:187], v[160:163], v[8:11]
	v_mfma_f32_16x16x32_bf16 v[4:7], v[176:179], v[168:171], v[4:7]
	v_mfma_f32_16x16x32_bf16 v[0:3], v[184:187], v[168:171], v[0:3]
	v_mfma_f32_16x16x32_bf16 v[28:31], v[180:183], v[148:151], v[28:31]
	v_mfma_f32_16x16x32_bf16 v[24:27], v[190:193], v[148:151], v[24:27]
	v_mfma_f32_16x16x32_bf16 v[20:23], v[180:183], v[156:159], v[20:23]
	v_mfma_f32_16x16x32_bf16 v[16:19], v[190:193], v[156:159], v[16:19]
	v_mfma_f32_16x16x32_bf16 v[12:15], v[180:183], v[164:167], v[12:15]
	v_mfma_f32_16x16x32_bf16 v[8:11], v[190:193], v[164:167], v[8:11]
	v_mfma_f32_16x16x32_bf16 v[4:7], v[180:183], v[172:175], v[4:7]
	v_mfma_f32_16x16x32_bf16 v[0:3], v[190:193], v[172:175], v[0:3]
	s_add_i32 s40, 0, 0x18000
	v_add_u32_e32 v235, s40, v231
	s_barrier
	ds_read_b128 v[128:131], v235
	ds_read_b128 v[132:135], v235 offset:1024
	ds_read_b128 v[136:139], v235 offset:2048
	ds_read_b128 v[140:143], v235 offset:3072
	v_mov_b32_e32 v188, v228
	v_mov_b32_e32 v176, v229
	ds_read_b128 v[144:147], v233 offset:32768
	ds_read_b128 v[148:151], v233 offset:33792
	ds_read_b128 v[152:155], v233 offset:34816
	ds_read_b128 v[156:159], v233 offset:35840
	ds_read_b128 v[160:163], v233 offset:36864
	ds_read_b128 v[164:167], v233 offset:37888
	ds_read_b128 v[168:171], v233 offset:38912
	ds_read_b128 v[172:175], v233 offset:39936
	v_mov_b32_e32 v177, v189
	v_lshl_add_u64 v[178:179], s[14:15], 0, v[188:189]
	s_mov_b32 m0, s26
	v_lshl_add_u64 v[178:179], v[178:179], 0, s[46:47]
	v_lshl_add_u64 v[176:177], s[14:15], 0, v[176:177]
	global_load_lds_dwordx4 v[178:179], off
	v_lshl_add_u64 v[176:177], v[176:177], 0, s[46:47]
	s_mov_b32 m0, s27
	s_nop 0
	global_load_lds_dwordx4 v[176:177], off
	s_waitcnt lgkmcnt(8)
	s_barrier
	s_waitcnt lgkmcnt(0)
	s_waitcnt lgkmcnt(0)
	v_mfma_f32_16x16x32_bf16 v[124:127], v[128:131], v[144:147], v[124:127]
	v_mfma_f32_16x16x32_bf16 v[120:123], v[136:139], v[144:147], v[120:123]
	v_mfma_f32_16x16x32_bf16 v[116:119], v[128:131], v[152:155], v[116:119]
	v_mfma_f32_16x16x32_bf16 v[112:115], v[136:139], v[152:155], v[112:115]
	v_mfma_f32_16x16x32_bf16 v[108:111], v[128:131], v[160:163], v[108:111]
	v_mfma_f32_16x16x32_bf16 v[104:107], v[136:139], v[160:163], v[104:107]
	v_mfma_f32_16x16x32_bf16 v[100:103], v[128:131], v[168:171], v[100:103]
	v_mfma_f32_16x16x32_bf16 v[96:99], v[136:139], v[168:171], v[96:99]
	v_mfma_f32_16x16x32_bf16 v[124:127], v[132:135], v[148:151], v[124:127]
	v_mfma_f32_16x16x32_bf16 v[120:123], v[140:143], v[148:151], v[120:123]
	v_mfma_f32_16x16x32_bf16 v[116:119], v[132:135], v[156:159], v[116:119]
	v_mfma_f32_16x16x32_bf16 v[112:115], v[140:143], v[156:159], v[112:115]
	v_mfma_f32_16x16x32_bf16 v[108:111], v[132:135], v[164:167], v[108:111]
	v_mfma_f32_16x16x32_bf16 v[104:107], v[140:143], v[164:167], v[104:107]
	v_mfma_f32_16x16x32_bf16 v[100:103], v[132:135], v[172:175], v[100:103]
	v_mfma_f32_16x16x32_bf16 v[96:99], v[140:143], v[172:175], v[96:99]
	s_barrier
	s_add_i32 s43, 0, 0x1c000
	v_add_u32_e32 v236, s43, v231
	v_mov_b32_e32 v188, v224
	v_mov_b32_e32 v194, v225
	ds_read_b128 v[176:179], v236
	ds_read_b128 v[180:183], v236 offset:1024
	ds_read_b128 v[184:187], v236 offset:2048
	ds_read_b128 v[190:193], v236 offset:3072
	s_add_i32 s40, s40, s21
	v_lshl_add_u64 v[196:197], s[16:17], 0, v[188:189]
	v_mov_b32_e32 v195, v189
	v_lshl_add_u64 v[196:197], v[196:197], 0, s[2:3]
	s_mov_b32 m0, s40
	v_lshl_add_u64 v[194:195], s[16:17], 0, v[194:195]
	s_add_i32 s37, s40, 0x2000
	global_load_lds_dwordx4 v[196:197], off
	v_lshl_add_u64 v[194:195], v[194:195], 0, s[2:3]
	s_mov_b32 m0, s37
	s_nop 0
	global_load_lds_dwordx4 v[194:195], off
	s_barrier
	s_waitcnt lgkmcnt(0)
	s_waitcnt lgkmcnt(0)
	v_mfma_f32_16x16x32_bf16 v[92:95], v[176:179], v[144:147], v[92:95]
	v_mfma_f32_16x16x32_bf16 v[88:91], v[184:187], v[144:147], v[88:91]
	v_mfma_f32_16x16x32_bf16 v[84:87], v[176:179], v[152:155], v[84:87]
	v_mfma_f32_16x16x32_bf16 v[80:83], v[184:187], v[152:155], v[80:83]
	v_mfma_f32_16x16x32_bf16 v[76:79], v[176:179], v[160:163], v[76:79]
	v_mfma_f32_16x16x32_bf16 v[72:75], v[184:187], v[160:163], v[72:75]
	v_mfma_f32_16x16x32_bf16 v[68:71], v[176:179], v[168:171], v[68:71]
	v_mfma_f32_16x16x32_bf16 v[64:67], v[184:187], v[168:171], v[64:67]
	v_mfma_f32_16x16x32_bf16 v[92:95], v[180:183], v[148:151], v[92:95]
	v_mfma_f32_16x16x32_bf16 v[88:91], v[190:193], v[148:151], v[88:91]
	v_mfma_f32_16x16x32_bf16 v[84:87], v[180:183], v[156:159], v[84:87]
	v_mfma_f32_16x16x32_bf16 v[80:83], v[190:193], v[156:159], v[80:83]
	v_mfma_f32_16x16x32_bf16 v[76:79], v[180:183], v[164:167], v[76:79]
	v_mfma_f32_16x16x32_bf16 v[72:75], v[190:193], v[164:167], v[72:75]
	v_mfma_f32_16x16x32_bf16 v[68:71], v[180:183], v[172:175], v[68:71]
	v_mfma_f32_16x16x32_bf16 v[64:67], v[190:193], v[172:175], v[64:67]
	v_mov_b32_e32 v188, v226
	v_mov_b32_e32 v194, v227
	s_barrier
	ds_read_b128 v[144:147], v233 offset:49152
	ds_read_b128 v[148:151], v233 offset:50176
	ds_read_b128 v[152:155], v233 offset:51200
	ds_read_b128 v[156:159], v233 offset:52224
	ds_read_b128 v[160:163], v233 offset:53248
	ds_read_b128 v[164:167], v233 offset:54272
	ds_read_b128 v[168:171], v233 offset:55296
	ds_read_b128 v[172:175], v233 offset:56320
	v_mov_b32_e32 v195, v189
	v_lshl_add_u64 v[196:197], s[14:15], 0, v[188:189]
	s_mov_b32 m0, s28
	v_lshl_add_u64 v[196:197], v[196:197], 0, s[50:51]
	v_lshl_add_u64 v[194:195], s[14:15], 0, v[194:195]
	global_load_lds_dwordx4 v[196:197], off
	v_lshl_add_u64 v[194:195], v[194:195], 0, s[50:51]
	s_mov_b32 m0, s29
	s_nop 0
	global_load_lds_dwordx4 v[194:195], off
	s_barrier
	s_waitcnt lgkmcnt(0)
	s_waitcnt lgkmcnt(0)
	v_mfma_f32_16x16x32_bf16 v[60:63], v[128:131], v[144:147], v[60:63]
	v_mfma_f32_16x16x32_bf16 v[56:59], v[136:139], v[144:147], v[56:59]
	v_mfma_f32_16x16x32_bf16 v[52:55], v[128:131], v[152:155], v[52:55]
	v_mfma_f32_16x16x32_bf16 v[48:51], v[136:139], v[152:155], v[48:51]
	v_mfma_f32_16x16x32_bf16 v[44:47], v[128:131], v[160:163], v[44:47]
	v_mfma_f32_16x16x32_bf16 v[40:43], v[136:139], v[160:163], v[40:43]
	v_mfma_f32_16x16x32_bf16 v[36:39], v[128:131], v[168:171], v[36:39]
	v_mfma_f32_16x16x32_bf16 v[32:35], v[136:139], v[168:171], v[32:35]
	v_mfma_f32_16x16x32_bf16 v[60:63], v[132:135], v[148:151], v[60:63]
	v_mfma_f32_16x16x32_bf16 v[56:59], v[140:143], v[148:151], v[56:59]
	v_mfma_f32_16x16x32_bf16 v[52:55], v[132:135], v[156:159], v[52:55]
	v_mfma_f32_16x16x32_bf16 v[48:51], v[140:143], v[156:159], v[48:51]
	v_mfma_f32_16x16x32_bf16 v[44:47], v[132:135], v[164:167], v[44:47]
	v_mfma_f32_16x16x32_bf16 v[40:43], v[140:143], v[164:167], v[40:43]
	v_mfma_f32_16x16x32_bf16 v[36:39], v[132:135], v[172:175], v[36:39]
	v_mfma_f32_16x16x32_bf16 v[32:35], v[140:143], v[172:175], v[32:35]
	s_barrier
	v_mov_b32_e32 v188, v224
	v_mov_b32_e32 v128, v225
	s_add_i32 s14, s43, s21
	v_lshl_add_u64 v[130:131], s[16:17], 0, v[188:189]
	v_mov_b32_e32 v129, v189
	v_lshl_add_u64 v[130:131], v[130:131], 0, s[52:53]
	s_mov_b32 m0, s14
	v_lshl_add_u64 v[128:129], s[16:17], 0, v[128:129]
	s_add_i32 s15, s14, 0x2000
	global_load_lds_dwordx4 v[130:131], off
	v_lshl_add_u64 v[128:129], v[128:129], 0, s[52:53]
	s_mov_b32 m0, s15
	s_nop 0
	global_load_lds_dwordx4 v[128:129], off
	s_waitcnt vmcnt(6)
	s_barrier
	v_mfma_f32_16x16x32_bf16 v[28:31], v[176:179], v[144:147], v[28:31]
	v_mfma_f32_16x16x32_bf16 v[24:27], v[184:187], v[144:147], v[24:27]
	v_mfma_f32_16x16x32_bf16 v[20:23], v[176:179], v[152:155], v[20:23]
	v_mfma_f32_16x16x32_bf16 v[16:19], v[184:187], v[152:155], v[16:19]
	v_mfma_f32_16x16x32_bf16 v[12:15], v[176:179], v[160:163], v[12:15]
	v_mfma_f32_16x16x32_bf16 v[8:11], v[184:187], v[160:163], v[8:11]
	v_mfma_f32_16x16x32_bf16 v[4:7], v[176:179], v[168:171], v[4:7]
	v_mfma_f32_16x16x32_bf16 v[0:3], v[184:187], v[168:171], v[0:3]
	v_mfma_f32_16x16x32_bf16 v[28:31], v[180:183], v[148:151], v[28:31]
	v_mfma_f32_16x16x32_bf16 v[24:27], v[190:193], v[148:151], v[24:27]
	v_mfma_f32_16x16x32_bf16 v[20:23], v[180:183], v[156:159], v[20:23]
	v_mfma_f32_16x16x32_bf16 v[16:19], v[190:193], v[156:159], v[16:19]
	v_mfma_f32_16x16x32_bf16 v[12:15], v[180:183], v[164:167], v[12:15]
	v_mfma_f32_16x16x32_bf16 v[8:11], v[190:193], v[164:167], v[8:11]
	v_mfma_f32_16x16x32_bf16 v[4:7], v[180:183], v[172:175], v[4:7]
	v_mfma_f32_16x16x32_bf16 v[0:3], v[190:193], v[172:175], v[0:3]
	s_add_i32 s9, s9, 2
	s_add_u32 s10, s10, 0x100
	s_addc_u32 s11, s11, 0
	s_cmp_lt_u32 s9, 12
	s_barrier
	s_cbranch_scc1 .LBB0_125
	v_add_u32_e32 v128, 0, v231
	v_add_u32_e32 v128, 0x10000, v128
	ds_read_b128 v[140:143], v128
	ds_read_b128 v[144:147], v128 offset:1024
	ds_read_b128 v[148:151], v128 offset:2048
	ds_read_b128 v[152:155], v128 offset:3072
	v_readlane_b32 s10, v252, 14
	v_mov_b32_e32 v128, v228
	v_mov_b32_e32 v129, v229
	s_mov_b32 m0, s41
	v_readlane_b32 s11, v252, 15
	ds_read_b128 v[180:183], v233
	ds_read_b128 v[184:187], v233 offset:1024
	ds_read_b128 v[172:175], v233 offset:2048
	ds_read_b128 v[176:179], v233 offset:3072
	ds_read_b128 v[164:167], v233 offset:4096
	ds_read_b128 v[168:171], v233 offset:5120
	ds_read_b128 v[156:159], v233 offset:6144
	ds_read_b128 v[160:163], v233 offset:7168
	s_nop 0
	global_load_lds_dwordx4 v128, s[10:11]
	s_mov_b32 m0, s42
	s_nop 0
	global_load_lds_dwordx4 v129, s[10:11]
	s_waitcnt lgkmcnt(8)
	s_barrier
	s_waitcnt lgkmcnt(0)
	s_waitcnt lgkmcnt(0)
	v_mfma_f32_16x16x32_bf16 v[124:127], v[140:143], v[180:183], v[124:127]
	v_mfma_f32_16x16x32_bf16 v[120:123], v[148:151], v[180:183], v[120:123]
	v_mfma_f32_16x16x32_bf16 v[116:119], v[140:143], v[172:175], v[116:119]
	v_mfma_f32_16x16x32_bf16 v[112:115], v[148:151], v[172:175], v[112:115]
	v_mfma_f32_16x16x32_bf16 v[108:111], v[140:143], v[164:167], v[108:111]
	v_mfma_f32_16x16x32_bf16 v[104:107], v[148:151], v[164:167], v[104:107]
	v_mfma_f32_16x16x32_bf16 v[100:103], v[140:143], v[156:159], v[100:103]
	v_mfma_f32_16x16x32_bf16 v[96:99], v[148:151], v[156:159], v[96:99]
	v_mfma_f32_16x16x32_bf16 v[124:127], v[144:147], v[184:187], v[124:127]
	v_mfma_f32_16x16x32_bf16 v[120:123], v[152:155], v[184:187], v[120:123]
	v_mfma_f32_16x16x32_bf16 v[116:119], v[144:147], v[176:179], v[116:119]
	v_mfma_f32_16x16x32_bf16 v[128:131], v[152:155], v[176:179], v[112:115]
	v_mfma_f32_16x16x32_bf16 v[108:111], v[144:147], v[168:171], v[108:111]
	v_mfma_f32_16x16x32_bf16 v[132:135], v[152:155], v[168:171], v[104:107]
	v_mfma_f32_16x16x32_bf16 v[100:103], v[144:147], v[160:163], v[100:103]
	v_mfma_f32_16x16x32_bf16 v[136:139], v[152:155], v[160:163], v[96:99]
	s_barrier
	s_andn2_b64 vcc, exec, s[6:7]
	s_cbranch_vccnz .LBB0_117
	v_lshl_add_u32 v226, v198, 11, v223
	v_lshl_add_u32 v227, v199, 11, v223
	v_lshl_add_u32 v228, v200, 11, v223
	v_lshl_add_u32 v229, v201, 11, v223
	s_branch .LBB0_117

.LBB0_332:
	s_add_i32 s36, 0, 0x10000
	v_add_u32_e32 v128, s36, v165
	ds_read_b128 v[130:133], v128
	ds_read_b128 v[134:137], v128 offset:1024
	ds_read_b128 v[138:141], v128 offset:2048
	ds_read_b128 v[142:145], v128 offset:3072
	s_add_u32 s14, s16, s12
	v_mov_b32_e32 v188, v160
	v_mov_b32_e32 v158, v162
	s_addc_u32 s15, s17, s13
	ds_read_b128 v[146:149], v167
	ds_read_b128 v[150:153], v167 offset:1024
	ds_read_b128 v[154:157], v167 offset:2048
	ds_read_b128 v[168:171], v167 offset:3072
	ds_read_b128 v[172:175], v167 offset:4096
	ds_read_b128 v[176:179], v167 offset:5120
	ds_read_b128 v[180:183], v167 offset:6144
	ds_read_b128 v[184:187], v167 offset:7168
	s_add_i32 s34, s24, 0xc000
	v_lshl_add_u64 v[190:191], s[14:15], 0, v[188:189]
	v_mov_b32_e32 v159, v189
	v_lshl_add_u64 v[190:191], v[190:191], 0, s[46:47]
	s_mov_b32 m0, s34
	v_lshl_add_u64 v[158:159], s[14:15], 0, v[158:159]
	s_add_i32 s35, s24, 0xe000
	global_load_lds_dwordx4 v[190:191], off
	v_lshl_add_u64 v[158:159], v[158:159], 0, s[46:47]
	s_mov_b32 m0, s35
	s_nop 0
	global_load_lds_dwordx4 v[158:159], off
	s_waitcnt lgkmcnt(8)
	s_barrier
	s_waitcnt lgkmcnt(0)
	s_waitcnt lgkmcnt(0)
	v_mfma_f32_16x16x32_bf16 v[124:127], v[130:133], v[146:149], v[124:127]
	v_mfma_f32_16x16x32_bf16 v[120:123], v[138:141], v[146:149], v[120:123]
	v_mfma_f32_16x16x32_bf16 v[116:119], v[130:133], v[154:157], v[116:119]
	v_mfma_f32_16x16x32_bf16 v[112:115], v[138:141], v[154:157], v[112:115]
	v_mfma_f32_16x16x32_bf16 v[108:111], v[130:133], v[172:175], v[108:111]
	v_mfma_f32_16x16x32_bf16 v[104:107], v[138:141], v[172:175], v[104:107]
	v_mfma_f32_16x16x32_bf16 v[100:103], v[130:133], v[180:183], v[100:103]
	v_mfma_f32_16x16x32_bf16 v[96:99], v[138:141], v[180:183], v[96:99]
	v_mfma_f32_16x16x32_bf16 v[124:127], v[134:137], v[150:153], v[124:127]
	v_mfma_f32_16x16x32_bf16 v[120:123], v[142:145], v[150:153], v[120:123]
	v_mfma_f32_16x16x32_bf16 v[116:119], v[134:137], v[168:171], v[116:119]
	v_mfma_f32_16x16x32_bf16 v[112:115], v[142:145], v[168:171], v[112:115]
	v_mfma_f32_16x16x32_bf16 v[108:111], v[134:137], v[176:179], v[108:111]
	v_mfma_f32_16x16x32_bf16 v[104:107], v[142:145], v[176:179], v[104:107]
	v_mfma_f32_16x16x32_bf16 v[100:103], v[134:137], v[184:187], v[100:103]
	v_mfma_f32_16x16x32_bf16 v[96:99], v[142:145], v[184:187], v[96:99]
	s_barrier
	s_add_i32 s40, 0, 0x14000
	s_add_u32 s18, s10, s12
	v_add_u32_e32 v129, s40, v165
	v_mov_b32_e32 v188, v161
	v_mov_b32_e32 v158, v163
	s_addc_u32 s19, s11, s13
	ds_read_b128 v[190:193], v129
	ds_read_b128 v[202:205], v129 offset:1024
	ds_read_b128 v[222:225], v129 offset:2048
	ds_read_b128 v[226:229], v129 offset:3072
	s_add_i32 s36, s36, s23
	v_lshl_add_u64 v[194:195], s[18:19], 0, v[188:189]
	v_mov_b32_e32 v159, v189
	v_lshl_add_u64 v[194:195], v[194:195], 0, s[88:89]
	s_mov_b32 m0, s36
	v_lshl_add_u64 v[158:159], s[18:19], 0, v[158:159]
	s_add_i32 s37, s36, 0x2000
	global_load_lds_dwordx4 v[194:195], off
	v_lshl_add_u64 v[158:159], v[158:159], 0, s[88:89]
	s_mov_b32 m0, s37
	s_nop 0
	global_load_lds_dwordx4 v[158:159], off
	s_barrier
	s_waitcnt lgkmcnt(0)
	s_waitcnt lgkmcnt(0)
	v_mfma_f32_16x16x32_bf16 v[92:95], v[190:193], v[146:149], v[92:95]
	v_mfma_f32_16x16x32_bf16 v[88:91], v[222:225], v[146:149], v[88:91]
	v_mfma_f32_16x16x32_bf16 v[84:87], v[190:193], v[154:157], v[84:87]
	v_mfma_f32_16x16x32_bf16 v[80:83], v[222:225], v[154:157], v[80:83]
	v_mfma_f32_16x16x32_bf16 v[76:79], v[190:193], v[172:175], v[76:79]
	v_mfma_f32_16x16x32_bf16 v[72:75], v[222:225], v[172:175], v[72:75]
	v_mfma_f32_16x16x32_bf16 v[68:71], v[190:193], v[180:183], v[68:71]
	v_mfma_f32_16x16x32_bf16 v[64:67], v[222:225], v[180:183], v[64:67]
	v_mfma_f32_16x16x32_bf16 v[92:95], v[202:205], v[150:153], v[92:95]
	v_mfma_f32_16x16x32_bf16 v[88:91], v[226:229], v[150:153], v[88:91]
	v_mfma_f32_16x16x32_bf16 v[84:87], v[202:205], v[168:171], v[84:87]
	v_mfma_f32_16x16x32_bf16 v[80:83], v[226:229], v[168:171], v[80:83]
	v_mfma_f32_16x16x32_bf16 v[76:79], v[202:205], v[176:179], v[76:79]
	v_mfma_f32_16x16x32_bf16 v[72:75], v[226:229], v[176:179], v[72:75]
	v_mfma_f32_16x16x32_bf16 v[68:71], v[202:205], v[184:187], v[68:71]
	v_mfma_f32_16x16x32_bf16 v[64:67], v[226:229], v[184:187], v[64:67]
	v_mov_b32_e32 v188, v160
	v_mov_b32_e32 v158, v162
	s_barrier
	ds_read_b128 v[146:149], v167 offset:16384
	ds_read_b128 v[150:153], v167 offset:17408
	ds_read_b128 v[154:157], v167 offset:18432
	ds_read_b128 v[168:171], v167 offset:19456
	ds_read_b128 v[172:175], v167 offset:20480
	ds_read_b128 v[176:179], v167 offset:21504
	ds_read_b128 v[180:183], v167 offset:22528
	ds_read_b128 v[184:187], v167 offset:23552
	v_mov_b32_e32 v159, v189
	v_lshl_add_u64 v[194:195], s[14:15], 0, v[188:189]
	s_mov_b32 m0, s24
	v_lshl_add_u64 v[194:195], v[194:195], 0, s[88:89]
	v_lshl_add_u64 v[158:159], s[14:15], 0, v[158:159]
	global_load_lds_dwordx4 v[194:195], off
	v_lshl_add_u64 v[158:159], v[158:159], 0, s[88:89]
	s_mov_b32 m0, s25
	s_nop 0
	global_load_lds_dwordx4 v[158:159], off
	s_barrier
	s_waitcnt lgkmcnt(0)
	s_waitcnt lgkmcnt(0)
	v_mfma_f32_16x16x32_bf16 v[60:63], v[130:133], v[146:149], v[60:63]
	v_mfma_f32_16x16x32_bf16 v[56:59], v[138:141], v[146:149], v[56:59]
	v_mfma_f32_16x16x32_bf16 v[52:55], v[130:133], v[154:157], v[52:55]
	v_mfma_f32_16x16x32_bf16 v[48:51], v[138:141], v[154:157], v[48:51]
	v_mfma_f32_16x16x32_bf16 v[44:47], v[130:133], v[172:175], v[44:47]
	v_mfma_f32_16x16x32_bf16 v[40:43], v[138:141], v[172:175], v[40:43]
	v_mfma_f32_16x16x32_bf16 v[36:39], v[130:133], v[180:183], v[36:39]
	v_mfma_f32_16x16x32_bf16 v[32:35], v[138:141], v[180:183], v[32:35]
	v_mfma_f32_16x16x32_bf16 v[60:63], v[134:137], v[150:153], v[60:63]
	v_mfma_f32_16x16x32_bf16 v[56:59], v[142:145], v[150:153], v[56:59]
	v_mfma_f32_16x16x32_bf16 v[52:55], v[134:137], v[168:171], v[52:55]
	v_mfma_f32_16x16x32_bf16 v[48:51], v[142:145], v[168:171], v[48:51]
	v_mfma_f32_16x16x32_bf16 v[44:47], v[134:137], v[176:179], v[44:47]
	v_mfma_f32_16x16x32_bf16 v[40:43], v[142:145], v[176:179], v[40:43]
	v_mfma_f32_16x16x32_bf16 v[36:39], v[134:137], v[184:187], v[36:39]
	v_mfma_f32_16x16x32_bf16 v[32:35], v[142:145], v[184:187], v[32:35]
	s_barrier
	v_mov_b32_e32 v188, v161
	v_mov_b32_e32 v130, v163
	s_add_i32 s40, s40, s23
	v_lshl_add_u64 v[132:133], s[18:19], 0, v[188:189]
	v_mov_b32_e32 v131, v189
	v_lshl_add_u64 v[132:133], v[132:133], 0, s[38:39]
	s_mov_b32 m0, s40
	v_lshl_add_u64 v[130:131], s[18:19], 0, v[130:131]
	s_add_i32 s41, s40, 0x2000
	global_load_lds_dwordx4 v[132:133], off
	v_lshl_add_u64 v[130:131], v[130:131], 0, s[38:39]
	s_mov_b32 m0, s41
	s_nop 0
	global_load_lds_dwordx4 v[130:131], off
	s_waitcnt vmcnt(6)
	s_barrier
	v_mfma_f32_16x16x32_bf16 v[28:31], v[190:193], v[146:149], v[28:31]
	v_mfma_f32_16x16x32_bf16 v[24:27], v[222:225], v[146:149], v[24:27]
	v_mfma_f32_16x16x32_bf16 v[20:23], v[190:193], v[154:157], v[20:23]
	v_mfma_f32_16x16x32_bf16 v[16:19], v[222:225], v[154:157], v[16:19]
	v_mfma_f32_16x16x32_bf16 v[12:15], v[190:193], v[172:175], v[12:15]
	v_mfma_f32_16x16x32_bf16 v[8:11], v[222:225], v[172:175], v[8:11]
	v_mfma_f32_16x16x32_bf16 v[4:7], v[190:193], v[180:183], v[4:7]
	v_mfma_f32_16x16x32_bf16 v[0:3], v[222:225], v[180:183], v[0:3]
	v_mfma_f32_16x16x32_bf16 v[28:31], v[202:205], v[150:153], v[28:31]
	v_mfma_f32_16x16x32_bf16 v[24:27], v[226:229], v[150:153], v[24:27]
	v_mfma_f32_16x16x32_bf16 v[20:23], v[202:205], v[168:171], v[20:23]
	v_mfma_f32_16x16x32_bf16 v[16:19], v[226:229], v[168:171], v[16:19]
	v_mfma_f32_16x16x32_bf16 v[12:15], v[202:205], v[176:179], v[12:15]
	v_mfma_f32_16x16x32_bf16 v[8:11], v[226:229], v[176:179], v[8:11]
	v_mfma_f32_16x16x32_bf16 v[4:7], v[202:205], v[184:187], v[4:7]
	v_mfma_f32_16x16x32_bf16 v[0:3], v[226:229], v[184:187], v[0:3]
	s_add_i32 s45, 0, 0x18000
	v_add_u32_e32 v130, s45, v165
	s_barrier
	ds_read_b128 v[132:135], v130
	ds_read_b128 v[136:139], v130 offset:1024
	ds_read_b128 v[140:143], v130 offset:2048
	ds_read_b128 v[144:147], v130 offset:3072
	v_mov_b32_e32 v188, v160
	v_mov_b32_e32 v190, v162
	ds_read_b128 v[148:151], v167 offset:32768
	ds_read_b128 v[152:155], v167 offset:33792
	ds_read_b128 v[156:159], v167 offset:34816
	ds_read_b128 v[168:171], v167 offset:35840
	ds_read_b128 v[172:175], v167 offset:36864
	ds_read_b128 v[176:179], v167 offset:37888
	ds_read_b128 v[180:183], v167 offset:38912
	ds_read_b128 v[184:187], v167 offset:39936
	v_mov_b32_e32 v191, v189
	v_lshl_add_u64 v[192:193], s[14:15], 0, v[188:189]
	s_mov_b32 m0, s26
	v_lshl_add_u64 v[192:193], v[192:193], 0, s[38:39]
	v_lshl_add_u64 v[190:191], s[14:15], 0, v[190:191]
	global_load_lds_dwordx4 v[192:193], off
	v_lshl_add_u64 v[190:191], v[190:191], 0, s[38:39]
	s_mov_b32 m0, s27
	s_nop 0
	global_load_lds_dwordx4 v[190:191], off
	s_waitcnt lgkmcnt(8)
	s_barrier
	s_waitcnt lgkmcnt(0)
	s_waitcnt lgkmcnt(0)
	v_mfma_f32_16x16x32_bf16 v[124:127], v[132:135], v[148:151], v[124:127]
	v_mfma_f32_16x16x32_bf16 v[120:123], v[140:143], v[148:151], v[120:123]
	v_mfma_f32_16x16x32_bf16 v[116:119], v[132:135], v[156:159], v[116:119]
	v_mfma_f32_16x16x32_bf16 v[112:115], v[140:143], v[156:159], v[112:115]
	v_mfma_f32_16x16x32_bf16 v[108:111], v[132:135], v[172:175], v[108:111]
	v_mfma_f32_16x16x32_bf16 v[104:107], v[140:143], v[172:175], v[104:107]
	v_mfma_f32_16x16x32_bf16 v[100:103], v[132:135], v[180:183], v[100:103]
	v_mfma_f32_16x16x32_bf16 v[96:99], v[140:143], v[180:183], v[96:99]
	v_mfma_f32_16x16x32_bf16 v[124:127], v[136:139], v[152:155], v[124:127]
	v_mfma_f32_16x16x32_bf16 v[120:123], v[144:147], v[152:155], v[120:123]
	v_mfma_f32_16x16x32_bf16 v[116:119], v[136:139], v[168:171], v[116:119]
	v_mfma_f32_16x16x32_bf16 v[112:115], v[144:147], v[168:171], v[112:115]
	v_mfma_f32_16x16x32_bf16 v[108:111], v[136:139], v[176:179], v[108:111]
	v_mfma_f32_16x16x32_bf16 v[104:107], v[144:147], v[176:179], v[104:107]
	v_mfma_f32_16x16x32_bf16 v[100:103], v[136:139], v[184:187], v[100:103]
	v_mfma_f32_16x16x32_bf16 v[96:99], v[144:147], v[184:187], v[96:99]
	s_barrier
	s_add_i32 s43, 0, 0x1c000
	v_add_u32_e32 v131, s43, v165
	v_mov_b32_e32 v188, v161
	v_mov_b32_e32 v194, v163
	ds_read_b128 v[190:193], v131
	ds_read_b128 v[202:205], v131 offset:1024
	ds_read_b128 v[222:225], v131 offset:2048
	ds_read_b128 v[226:229], v131 offset:3072
	s_add_i32 s45, s45, s23
	v_lshl_add_u64 v[196:197], s[18:19], 0, v[188:189]
	v_mov_b32_e32 v195, v189
	v_lshl_add_u64 v[196:197], v[196:197], 0, s[2:3]
	s_mov_b32 m0, s45
	v_lshl_add_u64 v[194:195], s[18:19], 0, v[194:195]
	s_add_i32 s42, s45, 0x2000
	global_load_lds_dwordx4 v[196:197], off
	v_lshl_add_u64 v[194:195], v[194:195], 0, s[2:3]
	s_mov_b32 m0, s42
	s_nop 0
	global_load_lds_dwordx4 v[194:195], off
	s_barrier
	s_waitcnt lgkmcnt(0)
	s_waitcnt lgkmcnt(0)
	v_mfma_f32_16x16x32_bf16 v[92:95], v[190:193], v[148:151], v[92:95]
	v_mfma_f32_16x16x32_bf16 v[88:91], v[222:225], v[148:151], v[88:91]
	v_mfma_f32_16x16x32_bf16 v[84:87], v[190:193], v[156:159], v[84:87]
	v_mfma_f32_16x16x32_bf16 v[80:83], v[222:225], v[156:159], v[80:83]
	v_mfma_f32_16x16x32_bf16 v[76:79], v[190:193], v[172:175], v[76:79]
	v_mfma_f32_16x16x32_bf16 v[72:75], v[222:225], v[172:175], v[72:75]
	v_mfma_f32_16x16x32_bf16 v[68:71], v[190:193], v[180:183], v[68:71]
	v_mfma_f32_16x16x32_bf16 v[64:67], v[222:225], v[180:183], v[64:67]
	v_mfma_f32_16x16x32_bf16 v[92:95], v[202:205], v[152:155], v[92:95]
	v_mfma_f32_16x16x32_bf16 v[88:91], v[226:229], v[152:155], v[88:91]
	v_mfma_f32_16x16x32_bf16 v[84:87], v[202:205], v[168:171], v[84:87]
	v_mfma_f32_16x16x32_bf16 v[80:83], v[226:229], v[168:171], v[80:83]
	v_mfma_f32_16x16x32_bf16 v[76:79], v[202:205], v[176:179], v[76:79]
	v_mfma_f32_16x16x32_bf16 v[72:75], v[226:229], v[176:179], v[72:75]
	v_mfma_f32_16x16x32_bf16 v[68:71], v[202:205], v[184:187], v[68:71]
	v_mfma_f32_16x16x32_bf16 v[64:67], v[226:229], v[184:187], v[64:67]
	v_mov_b32_e32 v188, v160
	v_mov_b32_e32 v194, v162
	s_barrier
; template <bool GATHER, class Epi>
; __device__ __forceinline__ void gemm_phase(LAS unsigned char* lds, const Sched& S, const Epi& E) {
;     ...
;         const bool has_next = S.next(ui + 1, nxt);
;         const char* nA = cA; const char* nB = cB;
;         if (has_next) { nA = GATHER ? S.A : S.A + (size_t)nxt.pm * tstep + (size_t)nxt.br * S.abr; nB = S.bptr(nxt); }
	ds_read_b128 v[148:151], v167 offset:49152
	ds_read_b128 v[152:155], v167 offset:50176
	ds_read_b128 v[156:159], v167 offset:51200
	ds_read_b128 v[168:171], v167 offset:52224
	ds_read_b128 v[172:175], v167 offset:53248
	ds_read_b128 v[176:179], v167 offset:54272
	ds_read_b128 v[180:183], v167 offset:55296
	ds_read_b128 v[184:187], v167 offset:56320
	v_mov_b32_e32 v195, v189
	v_lshl_add_u64 v[196:197], s[14:15], 0, v[188:189]
	s_mov_b32 m0, s28
	v_lshl_add_u64 v[196:197], v[196:197], 0, s[2:3]
	v_lshl_add_u64 v[194:195], s[14:15], 0, v[194:195]
	global_load_lds_dwordx4 v[196:197], off
	v_lshl_add_u64 v[194:195], v[194:195], 0, s[2:3]
	s_mov_b32 m0, s29
	s_nop 0
	global_load_lds_dwordx4 v[194:195], off
	s_barrier
	s_waitcnt lgkmcnt(0)
	s_waitcnt lgkmcnt(0)
	v_mfma_f32_16x16x32_bf16 v[60:63], v[132:135], v[148:151], v[60:63]
	v_mfma_f32_16x16x32_bf16 v[56:59], v[140:143], v[148:151], v[56:59]
	v_mfma_f32_16x16x32_bf16 v[52:55], v[132:135], v[156:159], v[52:55]
	v_mfma_f32_16x16x32_bf16 v[48:51], v[140:143], v[156:159], v[48:51]
	v_mfma_f32_16x16x32_bf16 v[44:47], v[132:135], v[172:175], v[44:47]
	v_mfma_f32_16x16x32_bf16 v[40:43], v[140:143], v[172:175], v[40:43]
	v_mfma_f32_16x16x32_bf16 v[36:39], v[132:135], v[180:183], v[36:39]
	v_mfma_f32_16x16x32_bf16 v[32:35], v[140:143], v[180:183], v[32:35]
	v_mfma_f32_16x16x32_bf16 v[60:63], v[136:139], v[152:155], v[60:63]
	v_mfma_f32_16x16x32_bf16 v[56:59], v[144:147], v[152:155], v[56:59]
	v_mfma_f32_16x16x32_bf16 v[52:55], v[136:139], v[168:171], v[52:55]
	v_mfma_f32_16x16x32_bf16 v[48:51], v[144:147], v[168:171], v[48:51]
	v_mfma_f32_16x16x32_bf16 v[44:47], v[136:139], v[176:179], v[44:47]
	v_mfma_f32_16x16x32_bf16 v[40:43], v[144:147], v[176:179], v[40:43]
	v_mfma_f32_16x16x32_bf16 v[36:39], v[136:139], v[184:187], v[36:39]
	v_mfma_f32_16x16x32_bf16 v[32:35], v[144:147], v[184:187], v[32:35]
	s_barrier
	v_mov_b32_e32 v188, v161
	v_mov_b32_e32 v132, v163
	s_add_i32 s43, s43, s23
	v_lshl_add_u64 v[134:135], s[18:19], 0, v[188:189]
	v_mov_b32_e32 v133, v189
	v_lshl_add_u64 v[134:135], v[134:135], 0, s[48:49]
	s_mov_b32 m0, s43
	v_lshl_add_u64 v[132:133], s[18:19], 0, v[132:133]
	s_add_i32 s44, s43, 0x2000
	global_load_lds_dwordx4 v[134:135], off
	v_lshl_add_u64 v[132:133], v[132:133], 0, s[48:49]
	s_mov_b32 m0, s44
	s_nop 0
	global_load_lds_dwordx4 v[132:133], off
	s_waitcnt vmcnt(6)
	s_barrier
	v_mfma_f32_16x16x32_bf16 v[28:31], v[190:193], v[148:151], v[28:31]
	v_mfma_f32_16x16x32_bf16 v[24:27], v[222:225], v[148:151], v[24:27]
	v_mfma_f32_16x16x32_bf16 v[20:23], v[190:193], v[156:159], v[20:23]
	v_mfma_f32_16x16x32_bf16 v[16:19], v[222:225], v[156:159], v[16:19]
	v_mfma_f32_16x16x32_bf16 v[12:15], v[190:193], v[172:175], v[12:15]
	v_mfma_f32_16x16x32_bf16 v[8:11], v[222:225], v[172:175], v[8:11]
	v_mfma_f32_16x16x32_bf16 v[4:7], v[190:193], v[180:183], v[4:7]
	v_mfma_f32_16x16x32_bf16 v[0:3], v[222:225], v[180:183], v[0:3]
	v_mfma_f32_16x16x32_bf16 v[28:31], v[202:205], v[152:155], v[28:31]
	v_mfma_f32_16x16x32_bf16 v[24:27], v[226:229], v[152:155], v[24:27]
	v_mfma_f32_16x16x32_bf16 v[20:23], v[202:205], v[168:171], v[20:23]
	v_mfma_f32_16x16x32_bf16 v[16:19], v[226:229], v[168:171], v[16:19]
	v_mfma_f32_16x16x32_bf16 v[12:15], v[202:205], v[176:179], v[12:15]
	v_mfma_f32_16x16x32_bf16 v[8:11], v[226:229], v[176:179], v[8:11]
	v_mfma_f32_16x16x32_bf16 v[4:7], v[202:205], v[184:187], v[4:7]
	v_mfma_f32_16x16x32_bf16 v[0:3], v[226:229], v[184:187], v[0:3]
	s_add_i32 s7, s7, 2
	s_add_u32 s12, s12, 0x100
	s_addc_u32 s13, s13, 0
	s_cmp_lt_u32 s7, 12
	s_barrier
	s_cbranch_scc1 .LBB0_332
	s_ashr_i32 s9, s8, 31
	s_ashr_i32 s7, s6, 31
	s_lshl_b64 s[14:15], s[8:9], 19
	s_lshl_b64 s[12:13], s[6:7], 19
	s_add_u32 s12, s21, s12
	ds_read_b128 v[132:135], v128
	ds_read_b128 v[136:139], v128 offset:1024
	ds_read_b128 v[140:143], v128 offset:2048
	ds_read_b128 v[144:147], v128 offset:3072
	s_addc_u32 s13, s22, s13
	s_and_b64 s[18:19], vcc, exec
	v_readlane_b32 s18, v253, 61
	s_cselect_b32 s11, s13, s11
	s_cselect_b32 s10, s12, s10
	v_readlane_b32 s19, v253, 62
	s_add_u32 s14, s18, s14
	s_addc_u32 s15, s19, s15
	s_and_b64 s[18:19], vcc, exec
	s_cselect_b32 s19, s15, s17
	s_cselect_b32 s18, s14, s16
	s_add_u32 s16, s16, 0x40780
	v_mov_b32_e32 v128, v160
	v_mov_b32_e32 v188, v162
	s_addc_u32 s17, s17, 0
	s_mov_b32 m0, s34
	ds_read_b128 v[148:151], v167
	ds_read_b128 v[152:155], v167 offset:1024
	ds_read_b128 v[156:159], v167 offset:2048
	ds_read_b128 v[168:171], v167 offset:3072
	ds_read_b128 v[172:175], v167 offset:4096
	ds_read_b128 v[176:179], v167 offset:5120
	ds_read_b128 v[180:183], v167 offset:6144
	ds_read_b128 v[184:187], v167 offset:7168
	s_nop 0
	global_load_lds_dwordx4 v128, s[16:17]
	s_mov_b32 m0, s35
	s_nop 0
	global_load_lds_dwordx4 v188, s[16:17]
	s_waitcnt lgkmcnt(8)
	s_barrier
	s_waitcnt lgkmcnt(0)
	s_waitcnt lgkmcnt(0)
	v_mfma_f32_16x16x32_bf16 v[124:127], v[132:135], v[148:151], v[124:127]
	v_mfma_f32_16x16x32_bf16 v[120:123], v[140:143], v[148:151], v[120:123]
	v_mfma_f32_16x16x32_bf16 v[116:119], v[132:135], v[156:159], v[116:119]
	v_mfma_f32_16x16x32_bf16 v[112:115], v[140:143], v[156:159], v[112:115]
	v_mfma_f32_16x16x32_bf16 v[108:111], v[132:135], v[172:175], v[108:111]
	v_mfma_f32_16x16x32_bf16 v[104:107], v[140:143], v[172:175], v[104:107]
	v_mfma_f32_16x16x32_bf16 v[100:103], v[132:135], v[180:183], v[100:103]
	v_mfma_f32_16x16x32_bf16 v[96:99], v[140:143], v[180:183], v[96:99]
	v_mfma_f32_16x16x32_bf16 v[124:127], v[136:139], v[152:155], v[124:127]
	v_mfma_f32_16x16x32_bf16 v[120:123], v[144:147], v[152:155], v[120:123]
	v_mfma_f32_16x16x32_bf16 v[116:119], v[136:139], v[168:171], v[116:119]
	v_mfma_f32_16x16x32_bf16 v[112:115], v[144:147], v[168:171], v[112:115]
	v_mfma_f32_16x16x32_bf16 v[108:111], v[136:139], v[176:179], v[108:111]
	v_mfma_f32_16x16x32_bf16 v[104:107], v[144:147], v[176:179], v[104:107]
	v_mfma_f32_16x16x32_bf16 v[100:103], v[136:139], v[184:187], v[100:103]
	v_mfma_f32_16x16x32_bf16 v[190:193], v[144:147], v[184:187], v[96:99]
	s_barrier
	s_nop 0
	ds_read_b128 v[96:99], v129
	ds_read_b128 v[202:205], v129 offset:1024
	ds_read_b128 v[222:225], v129 offset:2048
	ds_read_b128 v[226:229], v129 offset:3072
	v_mov_b32_e32 v128, v161
	v_mov_b32_e32 v129, v163
	s_mov_b32 m0, s36
	s_nop 0
	global_load_lds_dwordx4 v128, s[10:11]
	s_mov_b32 m0, s37
	s_nop 0
	global_load_lds_dwordx4 v129, s[10:11]
	s_barrier
	s_waitcnt lgkmcnt(0)
	s_waitcnt lgkmcnt(0)
	v_mfma_f32_16x16x32_bf16 v[92:95], v[96:99], v[148:151], v[92:95]
	v_mfma_f32_16x16x32_bf16 v[88:91], v[222:225], v[148:151], v[88:91]
	v_mfma_f32_16x16x32_bf16 v[84:87], v[96:99], v[156:159], v[84:87]
	v_mfma_f32_16x16x32_bf16 v[80:83], v[222:225], v[156:159], v[80:83]
	v_mfma_f32_16x16x32_bf16 v[76:79], v[96:99], v[172:175], v[76:79]
	v_mfma_f32_16x16x32_bf16 v[72:75], v[222:225], v[172:175], v[72:75]
	v_mfma_f32_16x16x32_bf16 v[68:71], v[96:99], v[180:183], v[68:71]
	v_mfma_f32_16x16x32_bf16 v[64:67], v[222:225], v[180:183], v[64:67]
	v_mfma_f32_16x16x32_bf16 v[92:95], v[202:205], v[152:155], v[92:95]
	v_mfma_f32_16x16x32_bf16 v[88:91], v[226:229], v[152:155], v[88:91]
	v_mfma_f32_16x16x32_bf16 v[148:151], v[202:205], v[168:171], v[84:87]
	v_mfma_f32_16x16x32_bf16 v[152:155], v[226:229], v[168:171], v[80:83]
	v_mfma_f32_16x16x32_bf16 v[76:79], v[202:205], v[176:179], v[76:79]
	v_mfma_f32_16x16x32_bf16 v[72:75], v[226:229], v[176:179], v[72:75]
	v_mfma_f32_16x16x32_bf16 v[68:71], v[202:205], v[184:187], v[68:71]
	v_mfma_f32_16x16x32_bf16 v[64:67], v[226:229], v[184:187], v[64:67]
	v_mov_b32_e32 v128, v160
	v_mov_b32_e32 v129, v162
	s_mov_b32 m0, s24
	s_barrier
	ds_read_b128 v[80:83], v167 offset:16384
	ds_read_b128 v[84:87], v167 offset:17408
	ds_read_b128 v[156:159], v167 offset:18432
	ds_read_b128 v[168:171], v167 offset:19456
	ds_read_b128 v[172:175], v167 offset:20480
	ds_read_b128 v[176:179], v167 offset:21504
	ds_read_b128 v[180:183], v167 offset:22528
	ds_read_b128 v[184:187], v167 offset:23552
	s_nop 0
	global_load_lds_dwordx4 v128, s[18:19]
	s_mov_b32 m0, s25
	s_nop 0
	global_load_lds_dwordx4 v129, s[18:19]
	s_barrier
	s_waitcnt lgkmcnt(0)
	s_waitcnt lgkmcnt(0)
	v_mfma_f32_16x16x32_bf16 v[60:63], v[132:135], v[80:83], v[60:63]
	v_mfma_f32_16x16x32_bf16 v[56:59], v[140:143], v[80:83], v[56:59]
	v_mfma_f32_16x16x32_bf16 v[52:55], v[132:135], v[156:159], v[52:55]
	v_mfma_f32_16x16x32_bf16 v[48:51], v[140:143], v[156:159], v[48:51]
	v_mfma_f32_16x16x32_bf16 v[44:47], v[132:135], v[172:175], v[44:47]
	v_mfma_f32_16x16x32_bf16 v[40:43], v[140:143], v[172:175], v[40:43]
	v_mfma_f32_16x16x32_bf16 v[36:39], v[132:135], v[180:183], v[36:39]
	v_mfma_f32_16x16x32_bf16 v[32:35], v[140:143], v[180:183], v[32:35]
	v_mfma_f32_16x16x32_bf16 v[60:63], v[136:139], v[84:87], v[60:63]
	v_mfma_f32_16x16x32_bf16 v[230:233], v[144:147], v[84:87], v[56:59]
	v_mfma_f32_16x16x32_bf16 v[234:237], v[136:139], v[168:171], v[52:55]
	v_mfma_f32_16x16x32_bf16 v[238:241], v[144:147], v[168:171], v[48:51]
	v_mfma_f32_16x16x32_bf16 v[44:47], v[136:139], v[176:179], v[44:47]
	v_mfma_f32_16x16x32_bf16 v[242:245], v[144:147], v[176:179], v[40:43]
	v_mfma_f32_16x16x32_bf16 v[36:39], v[136:139], v[184:187], v[36:39]
	v_mfma_f32_16x16x32_bf16 v[144:147], v[144:147], v[184:187], v[32:35]
	s_barrier
	s_add_u32 s16, s10, 0x40000
	v_mov_b32_e32 v32, v161
	v_mov_b32_e32 v33, v163
	s_addc_u32 s17, s11, 0
	s_mov_b32 m0, s40
	s_nop 0
	global_load_lds_dwordx4 v32, s[16:17]
	s_mov_b32 m0, s41
	s_nop 0
	global_load_lds_dwordx4 v33, s[16:17]
	s_waitcnt vmcnt(6)
	s_barrier
	v_mfma_f32_16x16x32_bf16 v[28:31], v[96:99], v[80:83], v[28:31]
	v_mfma_f32_16x16x32_bf16 v[24:27], v[222:225], v[80:83], v[24:27]
	v_mfma_f32_16x16x32_bf16 v[20:23], v[96:99], v[156:159], v[20:23]
	v_mfma_f32_16x16x32_bf16 v[16:19], v[222:225], v[156:159], v[16:19]
	v_mfma_f32_16x16x32_bf16 v[12:15], v[96:99], v[172:175], v[12:15]
	v_mfma_f32_16x16x32_bf16 v[8:11], v[222:225], v[172:175], v[8:11]
	v_mfma_f32_16x16x32_bf16 v[4:7], v[96:99], v[180:183], v[4:7]
	v_mfma_f32_16x16x32_bf16 v[0:3], v[222:225], v[180:183], v[0:3]
	v_mfma_f32_16x16x32_bf16 v[28:31], v[202:205], v[84:87], v[28:31]
	v_mfma_f32_16x16x32_bf16 v[246:249], v[226:229], v[84:87], v[24:27]
	v_mfma_f32_16x16x32_bf16 v[20:23], v[202:205], v[168:171], v[20:23]
	v_mfma_f32_16x16x32_bf16 v[156:159], v[226:229], v[168:171], v[16:19]
	v_mfma_f32_16x16x32_bf16 v[12:15], v[202:205], v[176:179], v[12:15]
	v_mfma_f32_16x16x32_bf16 v[168:171], v[226:229], v[176:179], v[8:11]
	v_mfma_f32_16x16x32_bf16 v[4:7], v[202:205], v[184:187], v[4:7]
	v_mfma_f32_16x16x32_bf16 v[172:175], v[226:229], v[184:187], v[0:3]
	s_barrier
	s_nop 0
	ds_read_b128 v[0:3], v130
	ds_read_b128 v[8:11], v130 offset:1024
	ds_read_b128 v[176:179], v130 offset:2048
	ds_read_b128 v[180:183], v130 offset:3072
	s_add_u32 s16, s18, 0x40000
	v_mov_b32_e32 v48, v160
	v_mov_b32_e32 v49, v162
	s_addc_u32 s17, s19, 0
	s_mov_b32 m0, s26
	ds_read_b128 v[16:19], v167 offset:32768
	ds_read_b128 v[24:27], v167 offset:33792
	ds_read_b128 v[32:35], v167 offset:34816
	ds_read_b128 v[40:43], v167 offset:35840
	ds_read_b128 v[52:55], v167 offset:36864
	ds_read_b128 v[184:187], v167 offset:37888
	ds_read_b128 v[202:205], v167 offset:38912
	ds_read_b128 v[222:225], v167 offset:39936
	s_nop 0
	global_load_lds_dwordx4 v48, s[16:17]
	s_mov_b32 m0, s27
	s_nop 0
	global_load_lds_dwordx4 v49, s[16:17]
	s_waitcnt lgkmcnt(8)
	s_barrier
	s_waitcnt lgkmcnt(0)
	s_waitcnt lgkmcnt(0)
	v_mfma_f32_16x16x32_bf16 v[48:51], v[0:3], v[16:19], v[124:127]
	v_mfma_f32_16x16x32_bf16 v[226:229], v[8:11], v[24:27], v[48:51]
	v_mfma_f32_16x16x32_bf16 v[48:51], v[176:179], v[16:19], v[120:123]
	v_mfma_f32_16x16x32_bf16 v[194:197], v[180:183], v[24:27], v[48:51]
	v_mfma_f32_16x16x32_bf16 v[48:51], v[0:3], v[32:35], v[116:119]
	v_mfma_f32_16x16x32_bf16 v[132:135], v[8:11], v[40:43], v[48:51]
	v_mfma_f32_16x16x32_bf16 v[48:51], v[176:179], v[32:35], v[112:115]
	v_mfma_f32_16x16x32_bf16 v[96:99], v[180:183], v[40:43], v[48:51]
	v_mfma_f32_16x16x32_bf16 v[48:51], v[0:3], v[52:55], v[108:111]
	v_mfma_f32_16x16x32_bf16 v[84:87], v[8:11], v[184:187], v[48:51]
	v_mfma_f32_16x16x32_bf16 v[48:51], v[176:179], v[52:55], v[104:107]
	v_mfma_f32_16x16x32_bf16 v[80:83], v[180:183], v[184:187], v[48:51]
	v_mfma_f32_16x16x32_bf16 v[48:51], v[0:3], v[202:205], v[100:103]
	v_mfma_f32_16x16x32_bf16 v[56:59], v[8:11], v[222:225], v[48:51]
	v_mfma_f32_16x16x32_bf16 v[48:51], v[176:179], v[202:205], v[190:193]
	v_mfma_f32_16x16x32_bf16 v[48:51], v[180:183], v[222:225], v[48:51]
	s_barrier
	v_mov_b32_e32 v188, v161
	v_mov_b32_e32 v100, v163
	ds_read_b128 v[108:111], v131
	ds_read_b128 v[112:115], v131 offset:1024
	ds_read_b128 v[116:119], v131 offset:2048
	ds_read_b128 v[120:123], v131 offset:3072
	s_mov_b64 s[16:17], 0x80
	v_lshl_add_u64 v[102:103], s[10:11], 0, v[188:189]
	v_mov_b32_e32 v101, v189
	s_mov_b32 m0, s45
	v_lshl_add_u64 v[102:103], v[102:103], 0, s[16:17]
	v_lshl_add_u64 v[100:101], s[10:11], 0, v[100:101]
	global_load_lds_dwordx4 v[102:103], off
	v_lshl_add_u64 v[100:101], v[100:101], 0, s[16:17]
	s_mov_b32 m0, s42
	s_nop 0
	global_load_lds_dwordx4 v[100:101], off
	s_barrier
	s_waitcnt lgkmcnt(0)
	s_waitcnt lgkmcnt(0)
	v_mfma_f32_16x16x32_bf16 v[92:95], v[108:111], v[16:19], v[92:95]
	v_mfma_f32_16x16x32_bf16 v[16:19], v[116:119], v[16:19], v[88:91]
	v_mfma_f32_16x16x32_bf16 v[136:139], v[120:123], v[24:27], v[16:19]
	v_mfma_f32_16x16x32_bf16 v[16:19], v[108:111], v[32:35], v[148:151]
	v_mfma_f32_16x16x32_bf16 v[104:107], v[112:115], v[40:43], v[16:19]
	v_mfma_f32_16x16x32_bf16 v[16:19], v[116:119], v[32:35], v[152:155]
	v_mfma_f32_16x16x32_bf16 v[100:103], v[120:123], v[40:43], v[16:19]
	v_mfma_f32_16x16x32_bf16 v[16:19], v[108:111], v[52:55], v[76:79]
	v_mfma_f32_16x16x32_bf16 v[140:143], v[112:115], v[24:27], v[92:95]
	v_mfma_f32_16x16x32_bf16 v[92:95], v[112:115], v[184:187], v[16:19]
	v_mfma_f32_16x16x32_bf16 v[16:19], v[116:119], v[52:55], v[72:75]
	v_mfma_f32_16x16x32_bf16 v[88:91], v[120:123], v[184:187], v[16:19]
	v_mfma_f32_16x16x32_bf16 v[16:19], v[108:111], v[202:205], v[68:71]
	v_mfma_f32_16x16x32_bf16 v[76:79], v[112:115], v[222:225], v[16:19]
	v_mfma_f32_16x16x32_bf16 v[16:19], v[116:119], v[202:205], v[64:67]
	v_mfma_f32_16x16x32_bf16 v[68:71], v[120:123], v[222:225], v[16:19]
	v_mov_b32_e32 v188, v160
	s_nop 4
	v_mov_b32_e32 v16, v162
	s_barrier
	ds_read_b128 v[124:127], v167 offset:49152
	ds_read_b128 v[128:131], v167 offset:50176
	ds_read_b128 v[148:151], v167 offset:51200
	ds_read_b128 v[152:155], v167 offset:52224
	ds_read_b128 v[184:187], v167 offset:53248
	ds_read_b128 v[190:193], v167 offset:54272
	ds_read_b128 v[202:205], v167 offset:55296
	ds_read_b128 v[222:225], v167 offset:56320
	v_mov_b32_e32 v17, v189
	v_lshl_add_u64 v[18:19], s[18:19], 0, v[188:189]
	s_mov_b32 m0, s28
	v_lshl_add_u64 v[18:19], v[18:19], 0, s[16:17]
	v_lshl_add_u64 v[16:17], s[18:19], 0, v[16:17]
	global_load_lds_dwordx4 v[18:19], off
	v_lshl_add_u64 v[16:17], v[16:17], 0, s[16:17]
	s_mov_b32 m0, s29
	s_nop 0
	global_load_lds_dwordx4 v[16:17], off
	s_barrier
	s_waitcnt lgkmcnt(0)
	s_waitcnt lgkmcnt(0)
	v_mfma_f32_16x16x32_bf16 v[16:19], v[0:3], v[124:127], v[60:63]
	v_mfma_f32_16x16x32_bf16 v[64:67], v[8:11], v[128:131], v[16:19]
	v_mfma_f32_16x16x32_bf16 v[16:19], v[176:179], v[124:127], v[230:233]
	v_mfma_f32_16x16x32_bf16 v[52:55], v[180:183], v[128:131], v[16:19]
	v_mfma_f32_16x16x32_bf16 v[16:19], v[0:3], v[148:151], v[234:237]
	v_mfma_f32_16x16x32_bf16 v[40:43], v[8:11], v[152:155], v[16:19]
	v_mfma_f32_16x16x32_bf16 v[16:19], v[176:179], v[148:151], v[238:241]
	v_mfma_f32_16x16x32_bf16 v[32:35], v[180:183], v[152:155], v[16:19]
	v_mfma_f32_16x16x32_bf16 v[16:19], v[0:3], v[184:187], v[44:47]
	v_mfma_f32_16x16x32_bf16 v[0:3], v[0:3], v[202:205], v[36:39]
	v_mfma_f32_16x16x32_bf16 v[24:27], v[8:11], v[190:193], v[16:19]
	v_mfma_f32_16x16x32_bf16 v[16:19], v[176:179], v[184:187], v[242:245]
	v_mfma_f32_16x16x32_bf16 v[8:11], v[8:11], v[222:225], v[0:3]
	v_mfma_f32_16x16x32_bf16 v[0:3], v[176:179], v[202:205], v[144:147]
	v_mfma_f32_16x16x32_bf16 v[16:19], v[180:183], v[190:193], v[16:19]
	v_mfma_f32_16x16x32_bf16 v[0:3], v[180:183], v[222:225], v[0:3]
	s_barrier
	s_add_u32 s10, s10, 0x40080
	v_mov_b32_e32 v36, v161
	v_mov_b32_e32 v37, v163
	s_addc_u32 s11, s11, 0
	s_mov_b32 m0, s43
	s_nop 0
	global_load_lds_dwordx4 v36, s[10:11]
	s_mov_b32 m0, s44
	s_nop 0
	global_load_lds_dwordx4 v37, s[10:11]
	s_waitcnt vmcnt(6)
	s_barrier
; __device__ __forceinline__ unsigned cvt_pk_bf16(float lo, float hi) { unsigned r; asm("v_cvt_pk_bf16_f32 %0, %1, %2" : "=v"(r) : "v"(lo), "v"(hi)); return r; }
; __device__ __forceinline__ float bf_lo(unsigned w) { return __uint_as_float(w << 16); }
; __device__ __forceinline__ float bf_hi(unsigned w) { return __uint_as_float(w & 0xffff0000u); }
;     __device__ __forceinline__ void operator()(const f32x4 (&acc)[2][2][4][2], const Unit& u, int wr, int wc, int fr, int fq) const {
;         const int row0 = u.pm * BM + wr * 64 + fr, col0 = u.pn * BM + wc * 32 + 8 * fq;
; #pragma unroll
;         for (int ai = 0; ai < 2; ++ai) {
;             u32x4 xrr[4][2];
; #pragma unroll
;             for (int m = 0; m < 4; ++m)
; #pragma unroll
;                 for (int bj = 0; bj < 2; ++bj) xrr[m][bj] = *(const u32x4*)(xres + (size_t)(row0 + ai * HALF + m * 16) * DM + col0 + bj * HALF);
; #pragma unroll
;             for (int m = 0; m < 4; ++m) { const size_t off = (size_t)(row0 + ai * HALF + m * 16) * DM + col0;
; #pragma unroll
;                 for (int bj = 0; bj < 2; ++bj) { const u32x4 xr = xrr[m][bj];
;                     const f32x4 v0 = acc[ai][bj][m][0], v1 = acc[ai][bj][m][1];
;                     u32x4 w; w.x = cvt_pk_bf16(fmaf(bf_lo(xr.x), ALPHA, v0[0]), fmaf(bf_hi(xr.x), ALPHA, v0[1])); w.y = cvt_pk_bf16(fmaf(bf_lo(xr.y), ALPHA, v0[2]), fmaf(bf_hi(xr.y), ALPHA, v0[3]));
;                     w.z = cvt_pk_bf16(fmaf(bf_lo(xr.z), ALPHA, v1[0]), fmaf(bf_hi(xr.z), ALPHA, v1[1])); w.w = cvt_pk_bf16(fmaf(bf_lo(xr.w), ALPHA, v1[2]), fmaf(bf_hi(xr.w), ALPHA, v1[3]));
;                     *(u32x4*)(O + off + bj * HALF) = w; } }
;             asm volatile("" ::: "memory"); }
	v_mfma_f32_16x16x32_bf16 v[28:31], v[108:111], v[124:127], v[28:31]
	v_mfma_f32_16x16x32_bf16 v[72:75], v[112:115], v[128:131], v[28:31]
	v_mfma_f32_16x16x32_bf16 v[28:31], v[116:119], v[124:127], v[246:249]
	v_mfma_f32_16x16x32_bf16 v[20:23], v[108:111], v[148:151], v[20:23]
	v_mfma_f32_16x16x32_bf16 v[12:15], v[108:111], v[184:187], v[12:15]
	v_mfma_f32_16x16x32_bf16 v[60:63], v[120:123], v[128:131], v[28:31]
	v_mfma_f32_16x16x32_bf16 v[44:47], v[112:115], v[152:155], v[20:23]
	v_mfma_f32_16x16x32_bf16 v[20:23], v[116:119], v[148:151], v[156:159]
	v_mfma_f32_16x16x32_bf16 v[28:31], v[112:115], v[190:193], v[12:15]
	v_mfma_f32_16x16x32_bf16 v[12:15], v[116:119], v[184:187], v[168:171]
	v_mfma_f32_16x16x32_bf16 v[4:7], v[108:111], v[202:205], v[4:7]
	v_mfma_f32_16x16x32_bf16 v[36:39], v[120:123], v[152:155], v[20:23]
	v_mfma_f32_16x16x32_bf16 v[20:23], v[120:123], v[190:193], v[12:15]
	v_mfma_f32_16x16x32_bf16 v[12:15], v[112:115], v[222:225], v[4:7]
	v_mfma_f32_16x16x32_bf16 v[4:7], v[116:119], v[202:205], v[172:175]
	v_mfma_f32_16x16x32_bf16 v[4:7], v[120:123], v[222:225], v[4:7]
	v_lshl_or_b32 v110, s31, 8, v166
	v_lshl_add_u32 v108, s33, 8, v164
	v_ashrrev_i32_e32 v111, 31, v110
	v_lshlrev_b64 v[148:149], 1, v[110:111]
	v_ashrrev_i32_e32 v109, 31, v108
	v_lshl_add_u64 v[150:151], s[66:67], 0, v[148:149]
	v_lshlrev_b64 v[152:153], 11, v[108:109]
	v_lshl_add_u64 v[110:111], v[150:151], 0, v[152:153]
	s_barrier
	global_load_dwordx4 v[168:171], v[110:111], off
	global_load_dwordx4 v[144:147], v[110:111], off offset:256
	v_or_b32_e32 v110, 16, v108
	v_ashrrev_i32_e32 v111, 31, v110
	v_lshlrev_b64 v[158:159], 11, v[110:111]
	v_lshl_add_u64 v[110:111], v[150:151], 0, v[158:159]
	global_load_dwordx4 v[128:131], v[110:111], off
	global_load_dwordx4 v[124:127], v[110:111], off offset:256
	v_or_b32_e32 v110, 32, v108
	v_ashrrev_i32_e32 v111, 31, v110
	v_lshlrev_b64 v[156:157], 11, v[110:111]
	v_lshl_add_u64 v[110:111], v[150:151], 0, v[156:157]
	global_load_dwordx4 v[120:123], v[110:111], off
	global_load_dwordx4 v[112:115], v[110:111], off offset:256
	v_or_b32_e32 v108, 48, v108
	v_ashrrev_i32_e32 v109, 31, v108
	v_lshlrev_b64 v[154:155], 11, v[108:109]
	v_lshl_add_u64 v[108:109], v[150:151], 0, v[154:155]
	global_load_dwordx4 v[116:119], v[108:109], off
	s_nop 0
	global_load_dwordx4 v[108:111], v[108:109], off offset:256
	v_readlane_b32 s10, v252, 59
	v_readlane_b32 s11, v252, 60
	s_mov_b64 s[16:17], 0x40000
	s_andn2_b64 vcc, exec, s[4:5]
	s_mov_b32 s31, s6
	s_mov_b32 s33, s8
	v_readlane_b32 s34, v255, 31
	v_readlane_b32 s35, v255, 32
	v_readlane_b32 s36, v255, 33
	v_readlane_b32 s37, v255, 34
	s_waitcnt vmcnt(0)
	v_lshlrev_b32_e32 v172, 16, v168
	v_and_b32_e32 v168, 0xffff0000, v168
	v_fmamk_f32 v172, v172, 0x3fb504f3, v226
	v_fmamk_f32 v168, v168, 0x3fb504f3, v227
	v_cvt_pk_bf16_f32 v168, v172, v168
	v_lshlrev_b32_e32 v172, 16, v169
	v_fmamk_f32 v172, v172, 0x3fb504f3, v228
	v_and_b32_e32 v169, 0xffff0000, v169
	v_fmac_f32_e32 v229, 0x3fb504f3, v169
	v_cvt_pk_bf16_f32 v169, v172, v229
	v_lshlrev_b32_e32 v172, 16, v170
	v_and_b32_e32 v170, 0xffff0000, v170
	v_fmamk_f32 v172, v172, 0x3fb504f3, v194
	v_fmamk_f32 v170, v170, 0x3fb504f3, v195
	v_cvt_pk_bf16_f32 v170, v172, v170
	v_lshlrev_b32_e32 v172, 16, v171
	v_fmamk_f32 v172, v172, 0x3fb504f3, v196
	v_and_b32_e32 v171, 0xffff0000, v171
	v_fmac_f32_e32 v197, 0x3fb504f3, v171
	v_cvt_pk_bf16_f32 v171, v172, v197
	v_lshl_add_u64 v[172:173], s[10:11], 0, v[152:153]
	v_lshl_add_u64 v[172:173], v[172:173], 0, v[148:149]
	global_store_dwordx4 v[172:173], v[168:171], off
	s_nop 1
	v_lshlrev_b32_e32 v168, 16, v144
	v_and_b32_e32 v144, 0xffff0000, v144
	v_fmamk_f32 v140, v168, 0x3fb504f3, v140
	v_fmamk_f32 v141, v144, 0x3fb504f3, v141
	v_cvt_pk_bf16_f32 v140, v140, v141
	v_lshlrev_b32_e32 v141, 16, v145
	v_fmamk_f32 v141, v141, 0x3fb504f3, v142
	v_and_b32_e32 v142, 0xffff0000, v145
	v_fmac_f32_e32 v143, 0x3fb504f3, v142
	v_lshlrev_b32_e32 v142, 16, v146
	v_fmamk_f32 v136, v142, 0x3fb504f3, v136
	v_and_b32_e32 v142, 0xffff0000, v146
	v_fmamk_f32 v137, v142, 0x3fb504f3, v137
	v_cvt_pk_bf16_f32 v142, v136, v137
	v_lshlrev_b32_e32 v136, 16, v147
	v_fmamk_f32 v136, v136, 0x3fb504f3, v138
	v_and_b32_e32 v137, 0xffff0000, v147
	v_cvt_pk_bf16_f32 v141, v141, v143
	v_fmac_f32_e32 v139, 0x3fb504f3, v137
	v_cvt_pk_bf16_f32 v143, v136, v139
	v_lshlrev_b32_e32 v136, 16, v128
	v_and_b32_e32 v128, 0xffff0000, v128
	v_fmamk_f32 v132, v136, 0x3fb504f3, v132
	v_fmamk_f32 v128, v128, 0x3fb504f3, v133
	v_cvt_pk_bf16_f32 v128, v132, v128
	v_lshlrev_b32_e32 v132, 16, v129
	v_fmamk_f32 v132, v132, 0x3fb504f3, v134
	v_and_b32_e32 v129, 0xffff0000, v129
	v_fmac_f32_e32 v135, 0x3fb504f3, v129
	v_cvt_pk_bf16_f32 v129, v132, v135
	v_lshlrev_b32_e32 v132, 16, v130
	v_fmamk_f32 v96, v132, 0x3fb504f3, v96
	v_and_b32_e32 v130, 0xffff0000, v130
	v_fmamk_f32 v97, v130, 0x3fb504f3, v97
	v_cvt_pk_bf16_f32 v130, v96, v97
	v_lshlrev_b32_e32 v96, 16, v131
	v_fmamk_f32 v96, v96, 0x3fb504f3, v98
	v_and_b32_e32 v97, 0xffff0000, v131
	v_fmac_f32_e32 v99, 0x3fb504f3, v97
	v_cvt_pk_bf16_f32 v131, v96, v99
	v_lshl_add_u64 v[96:97], s[10:11], 0, v[158:159]
	v_and_b32_e32 v98, 0xffff0000, v125
	v_lshl_add_u64 v[132:133], v[96:97], 0, v[148:149]
	v_lshlrev_b32_e32 v96, 16, v124
	v_and_b32_e32 v97, 0xffff0000, v124
	v_fmac_f32_e32 v107, 0x3fb504f3, v98
	v_lshlrev_b32_e32 v98, 16, v126
	v_and_b32_e32 v99, 0xffff0000, v126
	v_fmamk_f32 v96, v96, 0x3fb504f3, v104
	v_fmamk_f32 v97, v97, 0x3fb504f3, v105
	v_fmamk_f32 v98, v98, 0x3fb504f3, v100
	v_fmamk_f32 v99, v99, 0x3fb504f3, v101
	v_cvt_pk_bf16_f32 v96, v96, v97
	v_lshlrev_b32_e32 v97, 16, v125
; __device__ __forceinline__ unsigned cvt_pk_bf16(float lo, float hi) { unsigned r; asm("v_cvt_pk_bf16_f32 %0, %1, %2" : "=v"(r) : "v"(lo), "v"(hi)); return r; }
; __device__ __forceinline__ float bf_lo(unsigned w) { return __uint_as_float(w << 16); }
; __device__ __forceinline__ float bf_hi(unsigned w) { return __uint_as_float(w & 0xffff0000u); }
;     __device__ __forceinline__ void operator()(const f32x4 (&acc)[2][2][4][2], const Unit& u, int wr, int wc, int fr, int fq) const {
;         const int row0 = u.pm * BM + wr * 64 + fr, col0 = u.pn * BM + wc * 32 + 8 * fq;
; #pragma unroll
;         for (int ai = 0; ai < 2; ++ai) {
;             u32x4 xrr[4][2];
; #pragma unroll
;             for (int m = 0; m < 4; ++m)
; #pragma unroll
;                 for (int bj = 0; bj < 2; ++bj) xrr[m][bj] = *(const u32x4*)(xres + (size_t)(row0 + ai * HALF + m * 16) * DM + col0 + bj * HALF);
; #pragma unroll
;             for (int m = 0; m < 4; ++m) { const size_t off = (size_t)(row0 + ai * HALF + m * 16) * DM + col0;
; #pragma unroll
;                 for (int bj = 0; bj < 2; ++bj) { const u32x4 xr = xrr[m][bj];
;                     const f32x4 v0 = acc[ai][bj][m][0], v1 = acc[ai][bj][m][1];
;                     u32x4 w; w.x = cvt_pk_bf16(fmaf(bf_lo(xr.x), ALPHA, v0[0]), fmaf(bf_hi(xr.x), ALPHA, v0[1])); w.y = cvt_pk_bf16(fmaf(bf_lo(xr.y), ALPHA, v0[2]), fmaf(bf_hi(xr.y), ALPHA, v0[3]));
;                     w.z = cvt_pk_bf16(fmaf(bf_lo(xr.z), ALPHA, v1[0]), fmaf(bf_hi(xr.z), ALPHA, v1[1])); w.w = cvt_pk_bf16(fmaf(bf_lo(xr.w), ALPHA, v1[2]), fmaf(bf_hi(xr.w), ALPHA, v1[3]));
;                     *(u32x4*)(O + off + bj * HALF) = w; } }
;             asm volatile("" ::: "memory"); }
	v_cvt_pk_bf16_f32 v98, v98, v99
	v_lshlrev_b32_e32 v99, 16, v127
	v_fmamk_f32 v97, v97, 0x3fb504f3, v106
	v_fmamk_f32 v99, v99, 0x3fb504f3, v102
	v_and_b32_e32 v100, 0xffff0000, v127
	v_cvt_pk_bf16_f32 v97, v97, v107
	v_fmac_f32_e32 v103, 0x3fb504f3, v100
	v_cvt_pk_bf16_f32 v99, v99, v103
	global_store_dwordx4 v[132:133], v[96:99], off offset:256
	global_store_dwordx4 v[172:173], v[140:143], off offset:256
	global_store_dwordx4 v[132:133], v[128:131], off
	v_lshlrev_b32_e32 v96, 16, v120
	v_fmamk_f32 v84, v96, 0x3fb504f3, v84
	v_and_b32_e32 v96, 0xffff0000, v120
	v_fmamk_f32 v85, v96, 0x3fb504f3, v85
	v_cvt_pk_bf16_f32 v84, v84, v85
	v_lshlrev_b32_e32 v85, 16, v121
	v_fmamk_f32 v85, v85, 0x3fb504f3, v86
	v_and_b32_e32 v86, 0xffff0000, v121
	v_fmac_f32_e32 v87, 0x3fb504f3, v86
	v_lshlrev_b32_e32 v86, 16, v122
	v_fmamk_f32 v80, v86, 0x3fb504f3, v80
	v_and_b32_e32 v86, 0xffff0000, v122
	v_fmamk_f32 v81, v86, 0x3fb504f3, v81
	v_cvt_pk_bf16_f32 v86, v80, v81
	v_lshlrev_b32_e32 v80, 16, v123
	v_fmamk_f32 v80, v80, 0x3fb504f3, v82
	v_and_b32_e32 v81, 0xffff0000, v123
	v_cvt_pk_bf16_f32 v85, v85, v87
	v_fmac_f32_e32 v83, 0x3fb504f3, v81
	v_cvt_pk_bf16_f32 v87, v80, v83
	v_lshl_add_u64 v[80:81], s[10:11], 0, v[156:157]
	v_and_b32_e32 v82, 0xffff0000, v113
	v_lshl_add_u64 v[96:97], v[80:81], 0, v[148:149]
	v_lshlrev_b32_e32 v80, 16, v112
	v_and_b32_e32 v81, 0xffff0000, v112
	v_fmac_f32_e32 v95, 0x3fb504f3, v82
	v_lshlrev_b32_e32 v82, 16, v114
	v_and_b32_e32 v83, 0xffff0000, v114
	v_fmamk_f32 v80, v80, 0x3fb504f3, v92
	v_fmamk_f32 v81, v81, 0x3fb504f3, v93
	v_fmamk_f32 v82, v82, 0x3fb504f3, v88
	v_fmamk_f32 v83, v83, 0x3fb504f3, v89
	v_cvt_pk_bf16_f32 v80, v80, v81
	v_lshlrev_b32_e32 v81, 16, v113
	v_cvt_pk_bf16_f32 v82, v82, v83
	v_lshlrev_b32_e32 v83, 16, v115
	global_store_dwordx4 v[96:97], v[84:87], off
	v_fmamk_f32 v81, v81, 0x3fb504f3, v94
	v_fmamk_f32 v83, v83, 0x3fb504f3, v90
	v_and_b32_e32 v84, 0xffff0000, v115
	v_cvt_pk_bf16_f32 v81, v81, v95
	v_fmac_f32_e32 v91, 0x3fb504f3, v84
	v_cvt_pk_bf16_f32 v83, v83, v91
	global_store_dwordx4 v[96:97], v[80:83], off offset:256
	v_lshl_add_u64 v[96:97], v[152:153], 0, s[16:17]
	s_mov_b64 s[16:17], 0x48000
	v_lshlrev_b32_e32 v80, 16, v116
	v_fmamk_f32 v56, v80, 0x3fb504f3, v56
	v_and_b32_e32 v80, 0xffff0000, v116
	v_fmamk_f32 v57, v80, 0x3fb504f3, v57
	v_cvt_pk_bf16_f32 v56, v56, v57
	v_lshlrev_b32_e32 v57, 16, v117
	v_fmamk_f32 v57, v57, 0x3fb504f3, v58
	v_and_b32_e32 v58, 0xffff0000, v117
	v_fmac_f32_e32 v59, 0x3fb504f3, v58
	v_lshlrev_b32_e32 v58, 16, v118
	v_fmamk_f32 v48, v58, 0x3fb504f3, v48
	v_and_b32_e32 v58, 0xffff0000, v118
	v_fmamk_f32 v49, v58, 0x3fb504f3, v49
	v_cvt_pk_bf16_f32 v58, v48, v49
	v_lshlrev_b32_e32 v48, 16, v119
	v_fmamk_f32 v48, v48, 0x3fb504f3, v50
	v_and_b32_e32 v49, 0xffff0000, v119
	v_cvt_pk_bf16_f32 v57, v57, v59
	v_fmac_f32_e32 v51, 0x3fb504f3, v49
	v_cvt_pk_bf16_f32 v59, v48, v51
	v_lshl_add_u64 v[48:49], s[10:11], 0, v[154:155]
	v_and_b32_e32 v50, 0xffff0000, v109
	v_lshl_add_u64 v[80:81], v[48:49], 0, v[148:149]
	v_lshlrev_b32_e32 v48, 16, v108
	v_and_b32_e32 v49, 0xffff0000, v108
	v_fmac_f32_e32 v79, 0x3fb504f3, v50
	v_lshlrev_b32_e32 v50, 16, v110
	v_and_b32_e32 v51, 0xffff0000, v110
	v_fmamk_f32 v48, v48, 0x3fb504f3, v76
	v_fmamk_f32 v49, v49, 0x3fb504f3, v77
	v_fmamk_f32 v50, v50, 0x3fb504f3, v68
	v_fmamk_f32 v51, v51, 0x3fb504f3, v69
	v_cvt_pk_bf16_f32 v48, v48, v49
	v_lshlrev_b32_e32 v49, 16, v109
	v_cvt_pk_bf16_f32 v50, v50, v51
	v_lshlrev_b32_e32 v51, 16, v111
	global_store_dwordx4 v[80:81], v[56:59], off
	v_fmamk_f32 v49, v49, 0x3fb504f3, v78
	v_fmamk_f32 v51, v51, 0x3fb504f3, v70
	v_and_b32_e32 v56, 0xffff0000, v111
	v_cvt_pk_bf16_f32 v49, v49, v79
	v_fmac_f32_e32 v71, 0x3fb504f3, v56
	v_cvt_pk_bf16_f32 v51, v51, v71
	global_store_dwordx4 v[80:81], v[48:51], off offset:256
	v_lshl_add_u64 v[56:57], v[150:151], 0, v[96:97]
	global_load_dwordx4 v[48:51], v[56:57], off
	s_nop 0
	global_load_dwordx4 v[56:59], v[56:57], off offset:256
	v_lshl_add_u64 v[98:99], v[152:153], 0, s[16:17]
	v_lshl_add_u64 v[76:77], v[150:151], 0, v[98:99]
	global_load_dwordx4 v[68:71], v[76:77], off
	s_nop 0
	global_load_dwordx4 v[76:79], v[76:77], off offset:256
	s_mov_b64 s[16:17], 0x50000
	v_lshl_add_u64 v[100:101], v[152:153], 0, s[16:17]
	v_lshl_add_u64 v[84:85], v[150:151], 0, v[100:101]
	global_load_dwordx4 v[80:83], v[84:85], off
	s_nop 0
	global_load_dwordx4 v[84:87], v[84:85], off offset:256
	s_mov_b64 s[16:17], 0x58000
	v_lshl_add_u64 v[102:103], v[152:153], 0, s[16:17]
	v_lshl_add_u64 v[92:93], v[150:151], 0, v[102:103]
	global_load_dwordx4 v[88:91], v[92:93], off
	s_nop 0
	global_load_dwordx4 v[92:95], v[92:93], off offset:256
	s_mov_b64 s[16:17], s[14:15]
	s_waitcnt vmcnt(0)
; __device__ __forceinline__ unsigned cvt_pk_bf16(float lo, float hi) { unsigned r; asm("v_cvt_pk_bf16_f32 %0, %1, %2" : "=v"(r) : "v"(lo), "v"(hi)); return r; }
; __device__ __forceinline__ float bf_lo(unsigned w) { return __uint_as_float(w << 16); }
; __device__ __forceinline__ float bf_hi(unsigned w) { return __uint_as_float(w & 0xffff0000u); }
;     __device__ __forceinline__ void operator()(const f32x4 (&acc)[2][2][4][2], const Unit& u, int wr, int wc, int fr, int fq) const {
;         const int row0 = u.pm * BM + wr * 64 + fr, col0 = u.pn * BM + wc * 32 + 8 * fq;
; #pragma unroll
;         for (int ai = 0; ai < 2; ++ai) {
;             u32x4 xrr[4][2];
; #pragma unroll
;             for (int m = 0; m < 4; ++m)
; #pragma unroll
;                 for (int bj = 0; bj < 2; ++bj) xrr[m][bj] = *(const u32x4*)(xres + (size_t)(row0 + ai * HALF + m * 16) * DM + col0 + bj * HALF);
; #pragma unroll
;             for (int m = 0; m < 4; ++m) { const size_t off = (size_t)(row0 + ai * HALF + m * 16) * DM + col0;
; #pragma unroll
;                 for (int bj = 0; bj < 2; ++bj) { const u32x4 xr = xrr[m][bj];
;                     const f32x4 v0 = acc[ai][bj][m][0], v1 = acc[ai][bj][m][1];
;                     u32x4 w; w.x = cvt_pk_bf16(fmaf(bf_lo(xr.x), ALPHA, v0[0]), fmaf(bf_hi(xr.x), ALPHA, v0[1])); w.y = cvt_pk_bf16(fmaf(bf_lo(xr.y), ALPHA, v0[2]), fmaf(bf_hi(xr.y), ALPHA, v0[3]));
;                     w.z = cvt_pk_bf16(fmaf(bf_lo(xr.z), ALPHA, v1[0]), fmaf(bf_hi(xr.z), ALPHA, v1[1])); w.w = cvt_pk_bf16(fmaf(bf_lo(xr.w), ALPHA, v1[2]), fmaf(bf_hi(xr.w), ALPHA, v1[3]));
;                     *(u32x4*)(O + off + bj * HALF) = w; } }
;             asm volatile("" ::: "memory"); }
; template <bool GATHER, class Epi>
; __device__ __forceinline__ void gemm_phase(LAS unsigned char* lds, const Sched& S, const Epi& E) {
;     ...
;         E(acc, cur, wr, wc, fr, fq);
;         PG8_WAIT_V(0);
;         if (!has_next) break;
;         if (!Epi::KEEP || nxt.br == 0)
; #pragma unroll
;         for (int a = 0; a < 2; ++a)
; #pragma unroll
;             for (int b = 0; b < 2; ++b)
; #pragma unroll
;                 for (int m = 0; m < 4; ++m)
; #pragma unroll
;                     for (int n = 0; n < 2; ++n) acc[a][b][m][n] = (f32x4){0.f, 0.f, 0.f, 0.f};
;         cur = nxt; cA = nA; cB = nB; ++ui;
;     }
;     PG8_WAIT_V(0);
	v_lshlrev_b32_e32 v104, 16, v48
	v_and_b32_e32 v48, 0xffff0000, v48
	v_fmamk_f32 v64, v104, 0x3fb504f3, v64
	v_fmamk_f32 v48, v48, 0x3fb504f3, v65
	v_cvt_pk_bf16_f32 v48, v64, v48
	v_lshlrev_b32_e32 v64, 16, v49
	v_fmamk_f32 v64, v64, 0x3fb504f3, v66
	v_and_b32_e32 v49, 0xffff0000, v49
	v_fmac_f32_e32 v67, 0x3fb504f3, v49
	v_cvt_pk_bf16_f32 v49, v64, v67
	v_lshlrev_b32_e32 v64, 16, v50
	v_and_b32_e32 v50, 0xffff0000, v50
	v_fmamk_f32 v52, v64, 0x3fb504f3, v52
	v_fmamk_f32 v50, v50, 0x3fb504f3, v53
	v_cvt_pk_bf16_f32 v50, v52, v50
	v_lshlrev_b32_e32 v52, 16, v51
	v_fmamk_f32 v52, v52, 0x3fb504f3, v54
	v_and_b32_e32 v51, 0xffff0000, v51
	v_fmac_f32_e32 v55, 0x3fb504f3, v51
	v_cvt_pk_bf16_f32 v51, v52, v55
	v_lshl_add_u64 v[52:53], s[10:11], 0, v[96:97]
	v_lshl_add_u64 v[52:53], v[52:53], 0, v[148:149]
	global_store_dwordx4 v[52:53], v[48:51], off
	v_and_b32_e32 v54, 0xffff0000, v59
	v_fmac_f32_e32 v63, 0x3fb504f3, v54
	v_and_b32_e32 v50, 0xffff0000, v57
	v_lshlrev_b32_e32 v48, 16, v56
	v_and_b32_e32 v49, 0xffff0000, v56
	v_fmac_f32_e32 v75, 0x3fb504f3, v50
	v_lshlrev_b32_e32 v50, 16, v58
	v_and_b32_e32 v51, 0xffff0000, v58
	v_fmamk_f32 v48, v48, 0x3fb504f3, v72
	v_fmamk_f32 v49, v49, 0x3fb504f3, v73
	v_fmamk_f32 v50, v50, 0x3fb504f3, v60
	v_fmamk_f32 v51, v51, 0x3fb504f3, v61
	v_cvt_pk_bf16_f32 v48, v48, v49
	v_lshlrev_b32_e32 v49, 16, v57
	v_cvt_pk_bf16_f32 v50, v50, v51
	v_lshlrev_b32_e32 v51, 16, v59
	v_fmamk_f32 v49, v49, 0x3fb504f3, v74
	v_fmamk_f32 v51, v51, 0x3fb504f3, v62
	v_cvt_pk_bf16_f32 v49, v49, v75
	v_cvt_pk_bf16_f32 v51, v51, v63
	global_store_dwordx4 v[52:53], v[48:51], off offset:256
	s_nop 1
	v_lshlrev_b32_e32 v48, 16, v68
	v_fmamk_f32 v40, v48, 0x3fb504f3, v40
	v_and_b32_e32 v48, 0xffff0000, v68
	v_fmamk_f32 v41, v48, 0x3fb504f3, v41
	v_cvt_pk_bf16_f32 v40, v40, v41
	v_lshlrev_b32_e32 v41, 16, v69
	v_fmamk_f32 v41, v41, 0x3fb504f3, v42
	v_and_b32_e32 v42, 0xffff0000, v69
	v_fmac_f32_e32 v43, 0x3fb504f3, v42
	v_lshlrev_b32_e32 v42, 16, v70
	v_fmamk_f32 v32, v42, 0x3fb504f3, v32
	v_and_b32_e32 v42, 0xffff0000, v70
	v_fmamk_f32 v33, v42, 0x3fb504f3, v33
	v_cvt_pk_bf16_f32 v42, v32, v33
	v_lshlrev_b32_e32 v32, 16, v71
	v_fmamk_f32 v32, v32, 0x3fb504f3, v34
	v_and_b32_e32 v33, 0xffff0000, v71
	v_cvt_pk_bf16_f32 v41, v41, v43
	v_fmac_f32_e32 v35, 0x3fb504f3, v33
	v_cvt_pk_bf16_f32 v43, v32, v35
	v_lshl_add_u64 v[32:33], s[10:11], 0, v[98:99]
	v_and_b32_e32 v34, 0xffff0000, v77
	v_lshl_add_u64 v[48:49], v[32:33], 0, v[148:149]
	v_lshlrev_b32_e32 v32, 16, v76
	v_and_b32_e32 v33, 0xffff0000, v76
	v_fmac_f32_e32 v47, 0x3fb504f3, v34
	v_lshlrev_b32_e32 v34, 16, v78
	v_and_b32_e32 v35, 0xffff0000, v78
	v_fmamk_f32 v32, v32, 0x3fb504f3, v44
	v_fmamk_f32 v33, v33, 0x3fb504f3, v45
	v_fmamk_f32 v34, v34, 0x3fb504f3, v36
	v_fmamk_f32 v35, v35, 0x3fb504f3, v37
	v_cvt_pk_bf16_f32 v32, v32, v33
	v_lshlrev_b32_e32 v33, 16, v77
	v_cvt_pk_bf16_f32 v34, v34, v35
	v_lshlrev_b32_e32 v35, 16, v79
	v_fmamk_f32 v33, v33, 0x3fb504f3, v46
	v_fmamk_f32 v35, v35, 0x3fb504f3, v38
	v_and_b32_e32 v36, 0xffff0000, v79
	v_cvt_pk_bf16_f32 v33, v33, v47
	v_fmac_f32_e32 v39, 0x3fb504f3, v36
	v_cvt_pk_bf16_f32 v35, v35, v39
	global_store_dwordx4 v[48:49], v[32:35], off offset:256
	global_store_dwordx4 v[48:49], v[40:43], off
	s_nop 0
	v_lshlrev_b32_e32 v32, 16, v80
	v_fmamk_f32 v24, v32, 0x3fb504f3, v24
	v_and_b32_e32 v32, 0xffff0000, v80
	v_fmamk_f32 v25, v32, 0x3fb504f3, v25
	v_cvt_pk_bf16_f32 v24, v24, v25
	v_lshlrev_b32_e32 v25, 16, v81
	v_fmamk_f32 v25, v25, 0x3fb504f3, v26
	v_and_b32_e32 v26, 0xffff0000, v81
	v_fmac_f32_e32 v27, 0x3fb504f3, v26
	v_lshlrev_b32_e32 v26, 16, v82
	v_fmamk_f32 v16, v26, 0x3fb504f3, v16
	v_and_b32_e32 v26, 0xffff0000, v82
	v_fmamk_f32 v17, v26, 0x3fb504f3, v17
	v_cvt_pk_bf16_f32 v26, v16, v17
	v_lshlrev_b32_e32 v16, 16, v83
	v_fmamk_f32 v16, v16, 0x3fb504f3, v18
	v_and_b32_e32 v17, 0xffff0000, v83
	v_cvt_pk_bf16_f32 v25, v25, v27
	v_fmac_f32_e32 v19, 0x3fb504f3, v17
	v_cvt_pk_bf16_f32 v27, v16, v19
	v_lshl_add_u64 v[16:17], s[10:11], 0, v[100:101]
	v_and_b32_e32 v18, 0xffff0000, v85
	v_lshl_add_u64 v[32:33], v[16:17], 0, v[148:149]
	v_lshlrev_b32_e32 v16, 16, v84
	v_and_b32_e32 v17, 0xffff0000, v84
	v_fmac_f32_e32 v31, 0x3fb504f3, v18
	v_lshlrev_b32_e32 v18, 16, v86
	v_and_b32_e32 v19, 0xffff0000, v86
	v_fmamk_f32 v16, v16, 0x3fb504f3, v28
	v_fmamk_f32 v17, v17, 0x3fb504f3, v29
	v_fmamk_f32 v18, v18, 0x3fb504f3, v20
	v_fmamk_f32 v19, v19, 0x3fb504f3, v21
	v_cvt_pk_bf16_f32 v16, v16, v17
	v_lshlrev_b32_e32 v17, 16, v85
	v_cvt_pk_bf16_f32 v18, v18, v19
	v_lshlrev_b32_e32 v19, 16, v87
	v_fmamk_f32 v17, v17, 0x3fb504f3, v30
	v_fmamk_f32 v19, v19, 0x3fb504f3, v22
	v_and_b32_e32 v20, 0xffff0000, v87
	v_cvt_pk_bf16_f32 v17, v17, v31
	v_fmac_f32_e32 v23, 0x3fb504f3, v20
	v_cvt_pk_bf16_f32 v19, v19, v23
	global_store_dwordx4 v[32:33], v[16:19], off offset:256
	global_store_dwordx4 v[32:33], v[24:27], off
	s_nop 0
	v_lshlrev_b32_e32 v16, 16, v88
	v_fmamk_f32 v8, v16, 0x3fb504f3, v8
	v_and_b32_e32 v16, 0xffff0000, v88
	v_fmamk_f32 v9, v16, 0x3fb504f3, v9
	v_cvt_pk_bf16_f32 v8, v8, v9
	v_lshlrev_b32_e32 v9, 16, v89
	v_fmamk_f32 v9, v9, 0x3fb504f3, v10
	v_and_b32_e32 v10, 0xffff0000, v89
	v_fmac_f32_e32 v11, 0x3fb504f3, v10
	v_lshlrev_b32_e32 v10, 16, v90
	v_fmamk_f32 v0, v10, 0x3fb504f3, v0
	v_and_b32_e32 v10, 0xffff0000, v90
	v_fmamk_f32 v1, v10, 0x3fb504f3, v1
	v_cvt_pk_bf16_f32 v10, v0, v1
	v_lshlrev_b32_e32 v0, 16, v91
	v_fmamk_f32 v0, v0, 0x3fb504f3, v2
	v_and_b32_e32 v1, 0xffff0000, v91
	v_cvt_pk_bf16_f32 v9, v9, v11
	v_fmac_f32_e32 v3, 0x3fb504f3, v1
	v_cvt_pk_bf16_f32 v11, v0, v3
	v_lshl_add_u64 v[0:1], s[10:11], 0, v[102:103]
	v_and_b32_e32 v2, 0xffff0000, v93
	v_lshl_add_u64 v[16:17], v[0:1], 0, v[148:149]
	v_lshlrev_b32_e32 v0, 16, v92
	v_and_b32_e32 v1, 0xffff0000, v92
	v_fmac_f32_e32 v15, 0x3fb504f3, v2
	v_lshlrev_b32_e32 v2, 16, v94
	v_and_b32_e32 v3, 0xffff0000, v94
	v_fmamk_f32 v0, v0, 0x3fb504f3, v12
	v_fmamk_f32 v1, v1, 0x3fb504f3, v13
	v_fmamk_f32 v2, v2, 0x3fb504f3, v4
	v_fmamk_f32 v3, v3, 0x3fb504f3, v5
	v_cvt_pk_bf16_f32 v0, v0, v1
	v_lshlrev_b32_e32 v1, 16, v93
	v_cvt_pk_bf16_f32 v2, v2, v3
	v_lshlrev_b32_e32 v3, 16, v95
	v_fmamk_f32 v1, v1, 0x3fb504f3, v14
	v_fmamk_f32 v3, v3, 0x3fb504f3, v6
	v_and_b32_e32 v4, 0xffff0000, v95
	global_store_dwordx4 v[16:17], v[8:11], off
	v_cvt_pk_bf16_f32 v1, v1, v15
	v_fmac_f32_e32 v7, 0x3fb504f3, v4
	v_cvt_pk_bf16_f32 v3, v3, v7
	global_store_dwordx4 v[16:17], v[0:3], off offset:256
	s_waitcnt vmcnt(0)
	s_mov_b64 s[10:11], s[12:13]
	s_cbranch_vccnz .LBB0_325
	s_waitcnt vmcnt(0)
	v_readlane_b32 s28, v255, 23
	s_cmpk_gt_u32 s20, 0xff
	v_readlane_b32 s29, v255, 24
	v_readlane_b32 s30, v255, 25
	v_readlane_b32 s33, v255, 27
	v_readlane_b32 s31, v255, 26
	s_cbranch_scc1 .LBB0_336
	s_barrier

.LBB0_357:
	s_add_i32 s43, 0, 0x10000
	v_add_u32_e32 v128, s43, v151
	ds_read_b128 v[130:133], v128
	ds_read_b128 v[138:141], v128 offset:1024
	ds_read_b128 v[142:145], v128 offset:2048
	ds_read_b128 v[154:157], v128 offset:3072
	s_add_u32 s22, s10, s6
	v_mov_b32_e32 v188, v146
	v_mov_b32_e32 v134, v148
	s_addc_u32 s23, s11, s7
	ds_read_b128 v[158:161], v153
	ds_read_b128 v[162:165], v153 offset:1024
	ds_read_b128 v[166:169], v153 offset:2048
	ds_read_b128 v[170:173], v153 offset:3072
	ds_read_b128 v[174:177], v153 offset:4096
	ds_read_b128 v[178:181], v153 offset:5120
	ds_read_b128 v[182:185], v153 offset:6144
	ds_read_b128 v[190:193], v153 offset:7168
	s_add_i32 s15, s30, 0xc000
	v_lshl_add_u64 v[186:187], s[22:23], 0, v[188:189]
	v_mov_b32_e32 v135, v189
	v_lshl_add_u64 v[186:187], v[186:187], 0, s[50:51]
	s_mov_b32 m0, s15
	v_lshl_add_u64 v[134:135], s[22:23], 0, v[134:135]
	s_add_i32 s17, s30, 0xe000
	global_load_lds_dwordx4 v[186:187], off
	v_lshl_add_u64 v[134:135], v[134:135], 0, s[50:51]
	s_mov_b32 m0, s17
	s_nop 0
	global_load_lds_dwordx4 v[134:135], off
	s_waitcnt lgkmcnt(8)
	s_barrier
	s_waitcnt lgkmcnt(0)
	s_waitcnt lgkmcnt(0)
	v_mfma_f32_16x16x32_bf16 v[4:7], v[130:133], v[158:161], v[4:7]
	v_mfma_f32_16x16x32_bf16 v[0:3], v[142:145], v[158:161], v[0:3]
	v_mfma_f32_16x16x32_bf16 v[20:23], v[130:133], v[166:169], v[20:23]
	v_mfma_f32_16x16x32_bf16 v[16:19], v[142:145], v[166:169], v[16:19]
	v_mfma_f32_16x16x32_bf16 v[36:39], v[130:133], v[174:177], v[36:39]
	v_mfma_f32_16x16x32_bf16 v[32:35], v[142:145], v[174:177], v[32:35]
	v_mfma_f32_16x16x32_bf16 v[52:55], v[130:133], v[182:185], v[52:55]
	v_mfma_f32_16x16x32_bf16 v[48:51], v[142:145], v[182:185], v[48:51]
	v_mfma_f32_16x16x32_bf16 v[4:7], v[138:141], v[162:165], v[4:7]
	v_mfma_f32_16x16x32_bf16 v[0:3], v[154:157], v[162:165], v[0:3]
	v_mfma_f32_16x16x32_bf16 v[20:23], v[138:141], v[170:173], v[20:23]
	v_mfma_f32_16x16x32_bf16 v[16:19], v[154:157], v[170:173], v[16:19]
	v_mfma_f32_16x16x32_bf16 v[36:39], v[138:141], v[178:181], v[36:39]
	v_mfma_f32_16x16x32_bf16 v[32:35], v[154:157], v[178:181], v[32:35]
	v_mfma_f32_16x16x32_bf16 v[52:55], v[138:141], v[190:193], v[52:55]
	v_mfma_f32_16x16x32_bf16 v[48:51], v[154:157], v[190:193], v[48:51]
	s_barrier
	s_add_i32 s45, 0, 0x14000
	s_add_u32 s24, s8, s6
	v_add_u32_e32 v129, s45, v151
	v_mov_b32_e32 v188, v147
	v_mov_b32_e32 v134, v149
	s_addc_u32 s25, s9, s7
	ds_read_b128 v[202:205], v129
	ds_read_b128 v[222:225], v129 offset:1024
	ds_read_b128 v[226:229], v129 offset:2048
	ds_read_b128 v[230:233], v129 offset:3072
	s_add_i32 s43, s43, s29
	v_lshl_add_u64 v[186:187], s[24:25], 0, v[188:189]
	v_mov_b32_e32 v135, v189
	v_lshl_add_u64 v[186:187], v[186:187], 0, s[88:89]
	s_mov_b32 m0, s43
	v_lshl_add_u64 v[134:135], s[24:25], 0, v[134:135]
	s_add_i32 s44, s43, 0x2000
	global_load_lds_dwordx4 v[186:187], off
	v_lshl_add_u64 v[134:135], v[134:135], 0, s[88:89]
	s_mov_b32 m0, s44
	s_nop 0
	global_load_lds_dwordx4 v[134:135], off
	s_barrier
	s_waitcnt lgkmcnt(0)
	s_waitcnt lgkmcnt(0)
	v_mfma_f32_16x16x32_bf16 v[12:15], v[202:205], v[158:161], v[12:15]
	v_mfma_f32_16x16x32_bf16 v[8:11], v[226:229], v[158:161], v[8:11]
	v_mfma_f32_16x16x32_bf16 v[28:31], v[202:205], v[166:169], v[28:31]
	v_mfma_f32_16x16x32_bf16 v[24:27], v[226:229], v[166:169], v[24:27]
	v_mfma_f32_16x16x32_bf16 v[44:47], v[202:205], v[174:177], v[44:47]
	v_mfma_f32_16x16x32_bf16 v[40:43], v[226:229], v[174:177], v[40:43]
	v_mfma_f32_16x16x32_bf16 v[60:63], v[202:205], v[182:185], v[60:63]
	v_mfma_f32_16x16x32_bf16 v[56:59], v[226:229], v[182:185], v[56:59]
	v_mfma_f32_16x16x32_bf16 v[12:15], v[222:225], v[162:165], v[12:15]
	v_mfma_f32_16x16x32_bf16 v[8:11], v[230:233], v[162:165], v[8:11]
	v_mfma_f32_16x16x32_bf16 v[28:31], v[222:225], v[170:173], v[28:31]
	v_mfma_f32_16x16x32_bf16 v[24:27], v[230:233], v[170:173], v[24:27]
	v_mfma_f32_16x16x32_bf16 v[44:47], v[222:225], v[178:181], v[44:47]
	v_mfma_f32_16x16x32_bf16 v[40:43], v[230:233], v[178:181], v[40:43]
	v_mfma_f32_16x16x32_bf16 v[60:63], v[222:225], v[190:193], v[60:63]
	v_mfma_f32_16x16x32_bf16 v[56:59], v[230:233], v[190:193], v[56:59]
	v_mov_b32_e32 v188, v146
	v_mov_b32_e32 v134, v148
	s_barrier
	ds_read_b128 v[158:161], v153 offset:16384
	ds_read_b128 v[162:165], v153 offset:17408
	ds_read_b128 v[166:169], v153 offset:18432
	ds_read_b128 v[170:173], v153 offset:19456
	ds_read_b128 v[174:177], v153 offset:20480
	ds_read_b128 v[178:181], v153 offset:21504
	ds_read_b128 v[182:185], v153 offset:22528
	ds_read_b128 v[190:193], v153 offset:23552
	v_mov_b32_e32 v135, v189
	v_lshl_add_u64 v[186:187], s[22:23], 0, v[188:189]
	s_mov_b32 m0, s30
	v_lshl_add_u64 v[186:187], v[186:187], 0, s[88:89]
	v_lshl_add_u64 v[134:135], s[22:23], 0, v[134:135]
	global_load_lds_dwordx4 v[186:187], off
	v_lshl_add_u64 v[134:135], v[134:135], 0, s[88:89]
	s_mov_b32 m0, s31
	s_nop 0
	global_load_lds_dwordx4 v[134:135], off
	s_barrier
	s_waitcnt lgkmcnt(0)
	s_waitcnt lgkmcnt(0)
	v_mfma_f32_16x16x32_bf16 v[68:71], v[130:133], v[158:161], v[68:71]
	v_mfma_f32_16x16x32_bf16 v[64:67], v[142:145], v[158:161], v[64:67]
	v_mfma_f32_16x16x32_bf16 v[84:87], v[130:133], v[166:169], v[84:87]
	v_mfma_f32_16x16x32_bf16 v[80:83], v[142:145], v[166:169], v[80:83]
	v_mfma_f32_16x16x32_bf16 v[100:103], v[130:133], v[174:177], v[100:103]
	v_mfma_f32_16x16x32_bf16 v[96:99], v[142:145], v[174:177], v[96:99]
	v_mfma_f32_16x16x32_bf16 v[120:123], v[130:133], v[182:185], v[120:123]
	v_mfma_f32_16x16x32_bf16 v[116:119], v[142:145], v[182:185], v[116:119]
	v_mfma_f32_16x16x32_bf16 v[68:71], v[138:141], v[162:165], v[68:71]
	v_mfma_f32_16x16x32_bf16 v[64:67], v[154:157], v[162:165], v[64:67]
	v_mfma_f32_16x16x32_bf16 v[84:87], v[138:141], v[170:173], v[84:87]
	v_mfma_f32_16x16x32_bf16 v[80:83], v[154:157], v[170:173], v[80:83]
	v_mfma_f32_16x16x32_bf16 v[100:103], v[138:141], v[178:181], v[100:103]
	v_mfma_f32_16x16x32_bf16 v[96:99], v[154:157], v[178:181], v[96:99]
	v_mfma_f32_16x16x32_bf16 v[120:123], v[138:141], v[190:193], v[120:123]
	v_mfma_f32_16x16x32_bf16 v[116:119], v[154:157], v[190:193], v[116:119]
	s_barrier
	v_mov_b32_e32 v188, v147
	v_mov_b32_e32 v130, v149
	s_add_i32 s45, s45, s29
	v_lshl_add_u64 v[132:133], s[24:25], 0, v[188:189]
	v_mov_b32_e32 v131, v189
	v_lshl_add_u64 v[132:133], v[132:133], 0, s[52:53]
	s_mov_b32 m0, s45
	v_lshl_add_u64 v[130:131], s[24:25], 0, v[130:131]
	s_add_i32 s46, s45, 0x2000
	global_load_lds_dwordx4 v[132:133], off
	v_lshl_add_u64 v[130:131], v[130:131], 0, s[52:53]
	s_mov_b32 m0, s46
	s_nop 0
	global_load_lds_dwordx4 v[130:131], off
	s_waitcnt vmcnt(6)
	s_barrier
	v_mfma_f32_16x16x32_bf16 v[76:79], v[202:205], v[158:161], v[76:79]
	v_mfma_f32_16x16x32_bf16 v[72:75], v[226:229], v[158:161], v[72:75]
	v_mfma_f32_16x16x32_bf16 v[92:95], v[202:205], v[166:169], v[92:95]
	v_mfma_f32_16x16x32_bf16 v[88:91], v[226:229], v[166:169], v[88:91]
	v_mfma_f32_16x16x32_bf16 v[108:111], v[202:205], v[174:177], v[108:111]
	v_mfma_f32_16x16x32_bf16 v[104:107], v[226:229], v[174:177], v[104:107]
	v_mfma_f32_16x16x32_bf16 v[124:127], v[202:205], v[182:185], v[124:127]
	v_mfma_f32_16x16x32_bf16 v[112:115], v[226:229], v[182:185], v[112:115]
	v_mfma_f32_16x16x32_bf16 v[76:79], v[222:225], v[162:165], v[76:79]
	v_mfma_f32_16x16x32_bf16 v[72:75], v[230:233], v[162:165], v[72:75]
	v_mfma_f32_16x16x32_bf16 v[92:95], v[222:225], v[170:173], v[92:95]
	v_mfma_f32_16x16x32_bf16 v[88:91], v[230:233], v[170:173], v[88:91]
	v_mfma_f32_16x16x32_bf16 v[108:111], v[222:225], v[178:181], v[108:111]
	v_mfma_f32_16x16x32_bf16 v[104:107], v[230:233], v[178:181], v[104:107]
	v_mfma_f32_16x16x32_bf16 v[124:127], v[222:225], v[190:193], v[124:127]
	v_mfma_f32_16x16x32_bf16 v[112:115], v[230:233], v[190:193], v[112:115]
	s_add_i32 s48, 0, 0x18000
	v_add_u32_e32 v130, s48, v151
	s_barrier
	ds_read_b128 v[132:135], v130
	ds_read_b128 v[138:141], v130 offset:1024
	ds_read_b128 v[142:145], v130 offset:2048
	ds_read_b128 v[154:157], v130 offset:3072
	v_mov_b32_e32 v188, v146
	v_mov_b32_e32 v186, v148
	ds_read_b128 v[158:161], v153 offset:32768
	ds_read_b128 v[162:165], v153 offset:33792
	ds_read_b128 v[166:169], v153 offset:34816
	ds_read_b128 v[170:173], v153 offset:35840
	ds_read_b128 v[174:177], v153 offset:36864
	ds_read_b128 v[178:181], v153 offset:37888
	ds_read_b128 v[182:185], v153 offset:38912
	ds_read_b128 v[190:193], v153 offset:39936
	v_mov_b32_e32 v187, v189
	v_lshl_add_u64 v[194:195], s[22:23], 0, v[188:189]
	s_mov_b32 m0, s34
	v_lshl_add_u64 v[194:195], v[194:195], 0, s[52:53]
	v_lshl_add_u64 v[186:187], s[22:23], 0, v[186:187]
	global_load_lds_dwordx4 v[194:195], off
	v_lshl_add_u64 v[186:187], v[186:187], 0, s[52:53]
	s_mov_b32 m0, s35
	s_nop 0
	global_load_lds_dwordx4 v[186:187], off
	s_waitcnt lgkmcnt(8)
	s_barrier
	s_waitcnt lgkmcnt(0)
	s_waitcnt lgkmcnt(0)
	v_mfma_f32_16x16x32_bf16 v[4:7], v[132:135], v[158:161], v[4:7]
	v_mfma_f32_16x16x32_bf16 v[0:3], v[142:145], v[158:161], v[0:3]
	v_mfma_f32_16x16x32_bf16 v[20:23], v[132:135], v[166:169], v[20:23]
	v_mfma_f32_16x16x32_bf16 v[16:19], v[142:145], v[166:169], v[16:19]
	v_mfma_f32_16x16x32_bf16 v[36:39], v[132:135], v[174:177], v[36:39]
	v_mfma_f32_16x16x32_bf16 v[32:35], v[142:145], v[174:177], v[32:35]
	v_mfma_f32_16x16x32_bf16 v[52:55], v[132:135], v[182:185], v[52:55]
	v_mfma_f32_16x16x32_bf16 v[48:51], v[142:145], v[182:185], v[48:51]
	v_mfma_f32_16x16x32_bf16 v[4:7], v[138:141], v[162:165], v[4:7]
	v_mfma_f32_16x16x32_bf16 v[0:3], v[154:157], v[162:165], v[0:3]
	v_mfma_f32_16x16x32_bf16 v[20:23], v[138:141], v[170:173], v[20:23]
	v_mfma_f32_16x16x32_bf16 v[16:19], v[154:157], v[170:173], v[16:19]
	v_mfma_f32_16x16x32_bf16 v[36:39], v[138:141], v[178:181], v[36:39]
	v_mfma_f32_16x16x32_bf16 v[32:35], v[154:157], v[178:181], v[32:35]
	v_mfma_f32_16x16x32_bf16 v[52:55], v[138:141], v[190:193], v[52:55]
	v_mfma_f32_16x16x32_bf16 v[48:51], v[154:157], v[190:193], v[48:51]
	s_barrier
	s_add_i32 s49, 0, 0x1c000
	v_add_u32_e32 v131, s49, v151
	v_mov_b32_e32 v188, v147
	v_mov_b32_e32 v186, v149
	ds_read_b128 v[202:205], v131
	ds_read_b128 v[222:225], v131 offset:1024
	ds_read_b128 v[226:229], v131 offset:2048
	ds_read_b128 v[230:233], v131 offset:3072
	s_add_i32 s48, s48, s29
	v_lshl_add_u64 v[194:195], s[24:25], 0, v[188:189]
	v_mov_b32_e32 v187, v189
	v_lshl_add_u64 v[194:195], v[194:195], 0, s[2:3]
	s_mov_b32 m0, s48
	v_lshl_add_u64 v[186:187], s[24:25], 0, v[186:187]
	s_add_i32 s47, s48, 0x2000
	global_load_lds_dwordx4 v[194:195], off
	v_lshl_add_u64 v[186:187], v[186:187], 0, s[2:3]
	s_mov_b32 m0, s47
	s_nop 0
	global_load_lds_dwordx4 v[186:187], off
	s_barrier
	s_waitcnt lgkmcnt(0)
	s_waitcnt lgkmcnt(0)
	v_mfma_f32_16x16x32_bf16 v[12:15], v[202:205], v[158:161], v[12:15]
	v_mfma_f32_16x16x32_bf16 v[8:11], v[226:229], v[158:161], v[8:11]
	v_mfma_f32_16x16x32_bf16 v[28:31], v[202:205], v[166:169], v[28:31]
	v_mfma_f32_16x16x32_bf16 v[24:27], v[226:229], v[166:169], v[24:27]
	v_mfma_f32_16x16x32_bf16 v[44:47], v[202:205], v[174:177], v[44:47]
	v_mfma_f32_16x16x32_bf16 v[40:43], v[226:229], v[174:177], v[40:43]
	v_mfma_f32_16x16x32_bf16 v[60:63], v[202:205], v[182:185], v[60:63]
	v_mfma_f32_16x16x32_bf16 v[56:59], v[226:229], v[182:185], v[56:59]
	v_mfma_f32_16x16x32_bf16 v[12:15], v[222:225], v[162:165], v[12:15]
	v_mfma_f32_16x16x32_bf16 v[8:11], v[230:233], v[162:165], v[8:11]
	v_mfma_f32_16x16x32_bf16 v[28:31], v[222:225], v[170:173], v[28:31]
	v_mfma_f32_16x16x32_bf16 v[24:27], v[230:233], v[170:173], v[24:27]
	v_mfma_f32_16x16x32_bf16 v[44:47], v[222:225], v[178:181], v[44:47]
	v_mfma_f32_16x16x32_bf16 v[40:43], v[230:233], v[178:181], v[40:43]
	v_mfma_f32_16x16x32_bf16 v[60:63], v[222:225], v[190:193], v[60:63]
	v_mfma_f32_16x16x32_bf16 v[56:59], v[230:233], v[190:193], v[56:59]
	v_mov_b32_e32 v188, v146
	v_mov_b32_e32 v186, v148
	s_barrier
	ds_read_b128 v[158:161], v153 offset:49152
	ds_read_b128 v[162:165], v153 offset:50176
	ds_read_b128 v[166:169], v153 offset:51200
	ds_read_b128 v[170:173], v153 offset:52224
	ds_read_b128 v[174:177], v153 offset:53248
	ds_read_b128 v[178:181], v153 offset:54272
	ds_read_b128 v[182:185], v153 offset:55296
	ds_read_b128 v[190:193], v153 offset:56320
	v_mov_b32_e32 v187, v189
	v_lshl_add_u64 v[194:195], s[22:23], 0, v[188:189]
	s_mov_b32 m0, s36
	v_lshl_add_u64 v[194:195], v[194:195], 0, s[2:3]
	v_lshl_add_u64 v[186:187], s[22:23], 0, v[186:187]
	global_load_lds_dwordx4 v[194:195], off
	v_lshl_add_u64 v[186:187], v[186:187], 0, s[2:3]
	s_mov_b32 m0, s37
	s_nop 0
	global_load_lds_dwordx4 v[186:187], off
	s_barrier
	s_waitcnt lgkmcnt(0)
	s_waitcnt lgkmcnt(0)
	v_mfma_f32_16x16x32_bf16 v[68:71], v[132:135], v[158:161], v[68:71]
	v_mfma_f32_16x16x32_bf16 v[64:67], v[142:145], v[158:161], v[64:67]
	v_mfma_f32_16x16x32_bf16 v[84:87], v[132:135], v[166:169], v[84:87]
	v_mfma_f32_16x16x32_bf16 v[80:83], v[142:145], v[166:169], v[80:83]
	v_mfma_f32_16x16x32_bf16 v[100:103], v[132:135], v[174:177], v[100:103]
	v_mfma_f32_16x16x32_bf16 v[96:99], v[142:145], v[174:177], v[96:99]
	v_mfma_f32_16x16x32_bf16 v[120:123], v[132:135], v[182:185], v[120:123]
	v_mfma_f32_16x16x32_bf16 v[116:119], v[142:145], v[182:185], v[116:119]
	v_mfma_f32_16x16x32_bf16 v[68:71], v[138:141], v[162:165], v[68:71]
	v_mfma_f32_16x16x32_bf16 v[64:67], v[154:157], v[162:165], v[64:67]
	v_mfma_f32_16x16x32_bf16 v[84:87], v[138:141], v[170:173], v[84:87]
	v_mfma_f32_16x16x32_bf16 v[80:83], v[154:157], v[170:173], v[80:83]
	v_mfma_f32_16x16x32_bf16 v[100:103], v[138:141], v[178:181], v[100:103]
	v_mfma_f32_16x16x32_bf16 v[96:99], v[154:157], v[178:181], v[96:99]
	v_mfma_f32_16x16x32_bf16 v[120:123], v[138:141], v[190:193], v[120:123]
	v_mfma_f32_16x16x32_bf16 v[116:119], v[154:157], v[190:193], v[116:119]
	s_barrier
	v_mov_b32_e32 v188, v147
	v_mov_b32_e32 v132, v149
	s_add_i32 s22, s49, s29
	v_lshl_add_u64 v[134:135], s[24:25], 0, v[188:189]
	v_mov_b32_e32 v133, v189
	v_lshl_add_u64 v[134:135], v[134:135], 0, s[54:55]
	s_mov_b32 m0, s22
	v_lshl_add_u64 v[132:133], s[24:25], 0, v[132:133]
	s_add_i32 s23, s22, 0x2000
	global_load_lds_dwordx4 v[134:135], off
	v_lshl_add_u64 v[132:133], v[132:133], 0, s[54:55]
	s_mov_b32 m0, s23
	s_nop 0
	global_load_lds_dwordx4 v[132:133], off
	s_waitcnt vmcnt(6)
	s_barrier
	v_mfma_f32_16x16x32_bf16 v[76:79], v[202:205], v[158:161], v[76:79]
	v_mfma_f32_16x16x32_bf16 v[72:75], v[226:229], v[158:161], v[72:75]
	v_mfma_f32_16x16x32_bf16 v[92:95], v[202:205], v[166:169], v[92:95]
	v_mfma_f32_16x16x32_bf16 v[88:91], v[226:229], v[166:169], v[88:91]
	v_mfma_f32_16x16x32_bf16 v[108:111], v[202:205], v[174:177], v[108:111]
	v_mfma_f32_16x16x32_bf16 v[104:107], v[226:229], v[174:177], v[104:107]
	v_mfma_f32_16x16x32_bf16 v[124:127], v[202:205], v[182:185], v[124:127]
	v_mfma_f32_16x16x32_bf16 v[112:115], v[226:229], v[182:185], v[112:115]
	v_mfma_f32_16x16x32_bf16 v[76:79], v[222:225], v[162:165], v[76:79]
	v_mfma_f32_16x16x32_bf16 v[72:75], v[230:233], v[162:165], v[72:75]
	v_mfma_f32_16x16x32_bf16 v[92:95], v[222:225], v[170:173], v[92:95]
	v_mfma_f32_16x16x32_bf16 v[88:91], v[230:233], v[170:173], v[88:91]
	v_mfma_f32_16x16x32_bf16 v[108:111], v[222:225], v[178:181], v[108:111]
	v_mfma_f32_16x16x32_bf16 v[104:107], v[230:233], v[178:181], v[104:107]
	v_mfma_f32_16x16x32_bf16 v[124:127], v[222:225], v[190:193], v[124:127]
	v_mfma_f32_16x16x32_bf16 v[112:115], v[230:233], v[190:193], v[112:115]
	s_add_i32 s13, s13, 2
	s_add_u32 s6, s6, 0x100
	s_addc_u32 s7, s7, 0
	s_cmp_lt_u32 s13, 4
	s_barrier
	s_cbranch_scc1 .LBB0_357
	ds_read_b128 v[132:135], v128
	ds_read_b128 v[138:141], v128 offset:1024
	ds_read_b128 v[142:145], v128 offset:2048
	ds_read_b128 v[154:157], v128 offset:3072
	s_add_u32 s6, s10, 0x20380
	v_mov_b32_e32 v128, v148
	v_mov_b32_e32 v186, v146
	s_addc_u32 s7, s11, 0
	s_mov_b32 m0, s15
	ds_read_b128 v[158:161], v153
	ds_read_b128 v[162:165], v153 offset:1024
	ds_read_b128 v[166:169], v153 offset:2048
	ds_read_b128 v[170:173], v153 offset:3072
	ds_read_b128 v[174:177], v153 offset:4096
	ds_read_b128 v[178:181], v153 offset:5120
	ds_read_b128 v[182:185], v153 offset:6144
	ds_read_b128 v[190:193], v153 offset:7168
	s_nop 0
	global_load_lds_dwordx4 v186, s[6:7]
	s_mov_b32 m0, s17
	s_nop 0
	global_load_lds_dwordx4 v128, s[6:7]
	s_waitcnt lgkmcnt(8)
	s_barrier
	s_waitcnt lgkmcnt(0)
	s_waitcnt lgkmcnt(0)
	v_mfma_f32_16x16x32_bf16 v[4:7], v[132:135], v[158:161], v[4:7]
	v_mfma_f32_16x16x32_bf16 v[0:3], v[142:145], v[158:161], v[0:3]
	v_mfma_f32_16x16x32_bf16 v[20:23], v[132:135], v[166:169], v[20:23]
	v_mfma_f32_16x16x32_bf16 v[16:19], v[142:145], v[166:169], v[16:19]
	v_mfma_f32_16x16x32_bf16 v[36:39], v[132:135], v[174:177], v[36:39]
	v_mfma_f32_16x16x32_bf16 v[32:35], v[142:145], v[174:177], v[32:35]
	v_mfma_f32_16x16x32_bf16 v[52:55], v[132:135], v[182:185], v[52:55]
	v_mfma_f32_16x16x32_bf16 v[48:51], v[142:145], v[182:185], v[48:51]
	v_mfma_f32_16x16x32_bf16 v[4:7], v[138:141], v[162:165], v[4:7]
	v_mfma_f32_16x16x32_bf16 v[0:3], v[154:157], v[162:165], v[0:3]
	v_mfma_f32_16x16x32_bf16 v[20:23], v[138:141], v[170:173], v[20:23]
	v_mfma_f32_16x16x32_bf16 v[16:19], v[154:157], v[170:173], v[16:19]
	v_mfma_f32_16x16x32_bf16 v[36:39], v[138:141], v[178:181], v[36:39]
	v_mfma_f32_16x16x32_bf16 v[32:35], v[154:157], v[178:181], v[32:35]
	v_mfma_f32_16x16x32_bf16 v[52:55], v[138:141], v[190:193], v[52:55]
	v_mfma_f32_16x16x32_bf16 v[48:51], v[154:157], v[190:193], v[48:51]
	s_barrier
	ds_read_b128 v[202:205], v129
	ds_read_b128 v[222:225], v129 offset:1024
	ds_read_b128 v[226:229], v129 offset:2048
	ds_read_b128 v[230:233], v129 offset:3072
	v_mov_b32_e32 v128, v149
	v_mov_b32_e32 v129, v147
	s_mov_b32 m0, s43
	s_nop 0
	global_load_lds_dwordx4 v129, s[20:21]
	s_mov_b32 m0, s44
	s_nop 0
	global_load_lds_dwordx4 v128, s[20:21]
	s_barrier
	s_waitcnt lgkmcnt(0)
	s_waitcnt lgkmcnt(0)
	v_mfma_f32_16x16x32_bf16 v[12:15], v[202:205], v[158:161], v[12:15]
	v_mfma_f32_16x16x32_bf16 v[8:11], v[226:229], v[158:161], v[8:11]
	v_mfma_f32_16x16x32_bf16 v[28:31], v[202:205], v[166:169], v[28:31]
	v_mfma_f32_16x16x32_bf16 v[24:27], v[226:229], v[166:169], v[24:27]
	v_mfma_f32_16x16x32_bf16 v[44:47], v[202:205], v[174:177], v[44:47]
	v_mfma_f32_16x16x32_bf16 v[40:43], v[226:229], v[174:177], v[40:43]
	v_mfma_f32_16x16x32_bf16 v[60:63], v[202:205], v[182:185], v[60:63]
	v_mfma_f32_16x16x32_bf16 v[56:59], v[226:229], v[182:185], v[56:59]
	v_mfma_f32_16x16x32_bf16 v[12:15], v[222:225], v[162:165], v[12:15]
	v_mfma_f32_16x16x32_bf16 v[8:11], v[230:233], v[162:165], v[8:11]
	v_mfma_f32_16x16x32_bf16 v[28:31], v[222:225], v[170:173], v[28:31]
	v_mfma_f32_16x16x32_bf16 v[24:27], v[230:233], v[170:173], v[24:27]
	v_mfma_f32_16x16x32_bf16 v[44:47], v[222:225], v[178:181], v[44:47]
	v_mfma_f32_16x16x32_bf16 v[40:43], v[230:233], v[178:181], v[40:43]
	v_mfma_f32_16x16x32_bf16 v[60:63], v[222:225], v[190:193], v[60:63]
	v_mfma_f32_16x16x32_bf16 v[56:59], v[230:233], v[190:193], v[56:59]
	v_mov_b32_e32 v128, v148
	v_mov_b32_e32 v129, v146
	s_mov_b32 m0, s30
	s_barrier
	ds_read_b128 v[158:161], v153 offset:16384
	ds_read_b128 v[162:165], v153 offset:17408
	ds_read_b128 v[166:169], v153 offset:18432
	ds_read_b128 v[170:173], v153 offset:19456
	ds_read_b128 v[174:177], v153 offset:20480
	ds_read_b128 v[178:181], v153 offset:21504
	ds_read_b128 v[182:185], v153 offset:22528
	ds_read_b128 v[190:193], v153 offset:23552
	s_nop 0
	global_load_lds_dwordx4 v129, s[18:19]
	s_mov_b32 m0, s31
	s_nop 0
	global_load_lds_dwordx4 v128, s[18:19]
	s_barrier
	s_waitcnt lgkmcnt(0)
	s_waitcnt lgkmcnt(0)
	v_mfma_f32_16x16x32_bf16 v[68:71], v[132:135], v[158:161], v[68:71]
	v_mfma_f32_16x16x32_bf16 v[64:67], v[142:145], v[158:161], v[64:67]
	v_mfma_f32_16x16x32_bf16 v[84:87], v[132:135], v[166:169], v[84:87]
	v_mfma_f32_16x16x32_bf16 v[80:83], v[142:145], v[166:169], v[80:83]
	v_mfma_f32_16x16x32_bf16 v[100:103], v[132:135], v[174:177], v[100:103]
	v_mfma_f32_16x16x32_bf16 v[96:99], v[142:145], v[174:177], v[96:99]
	v_mfma_f32_16x16x32_bf16 v[120:123], v[132:135], v[182:185], v[120:123]
	v_mfma_f32_16x16x32_bf16 v[116:119], v[142:145], v[182:185], v[116:119]
	v_mfma_f32_16x16x32_bf16 v[68:71], v[138:141], v[162:165], v[68:71]
	v_mfma_f32_16x16x32_bf16 v[64:67], v[154:157], v[162:165], v[64:67]
	v_mfma_f32_16x16x32_bf16 v[84:87], v[138:141], v[170:173], v[84:87]
	v_mfma_f32_16x16x32_bf16 v[80:83], v[154:157], v[170:173], v[80:83]
	v_mfma_f32_16x16x32_bf16 v[100:103], v[138:141], v[178:181], v[100:103]
	v_mfma_f32_16x16x32_bf16 v[96:99], v[154:157], v[178:181], v[96:99]
	v_mfma_f32_16x16x32_bf16 v[120:123], v[138:141], v[190:193], v[120:123]
	v_mfma_f32_16x16x32_bf16 v[116:119], v[154:157], v[190:193], v[116:119]
	s_barrier
	s_add_u32 s6, s20, 0x20000
	v_mov_b32_e32 v128, v149
	v_mov_b32_e32 v129, v147
	s_addc_u32 s7, s21, 0
	s_mov_b32 m0, s45
	s_nop 0
	global_load_lds_dwordx4 v129, s[6:7]
	s_mov_b32 m0, s46
	s_nop 0
	global_load_lds_dwordx4 v128, s[6:7]
	s_waitcnt vmcnt(6)
	s_barrier
	v_mfma_f32_16x16x32_bf16 v[76:79], v[202:205], v[158:161], v[76:79]
	v_mfma_f32_16x16x32_bf16 v[72:75], v[226:229], v[158:161], v[72:75]
	v_mfma_f32_16x16x32_bf16 v[92:95], v[202:205], v[166:169], v[92:95]
	v_mfma_f32_16x16x32_bf16 v[88:91], v[226:229], v[166:169], v[88:91]
	v_mfma_f32_16x16x32_bf16 v[108:111], v[202:205], v[174:177], v[108:111]
	v_mfma_f32_16x16x32_bf16 v[104:107], v[226:229], v[174:177], v[104:107]
	v_mfma_f32_16x16x32_bf16 v[124:127], v[202:205], v[182:185], v[124:127]
	v_mfma_f32_16x16x32_bf16 v[112:115], v[226:229], v[182:185], v[112:115]
	v_mfma_f32_16x16x32_bf16 v[76:79], v[222:225], v[162:165], v[76:79]
	v_mfma_f32_16x16x32_bf16 v[72:75], v[230:233], v[162:165], v[72:75]
	v_mfma_f32_16x16x32_bf16 v[92:95], v[222:225], v[170:173], v[92:95]
	v_mfma_f32_16x16x32_bf16 v[88:91], v[230:233], v[170:173], v[88:91]
	v_mfma_f32_16x16x32_bf16 v[108:111], v[222:225], v[178:181], v[108:111]
	v_mfma_f32_16x16x32_bf16 v[104:107], v[230:233], v[178:181], v[104:107]
	v_mfma_f32_16x16x32_bf16 v[124:127], v[222:225], v[190:193], v[124:127]
	v_mfma_f32_16x16x32_bf16 v[112:115], v[230:233], v[190:193], v[112:115]
	s_barrier
	ds_read_b128 v[132:135], v130
	ds_read_b128 v[138:141], v130 offset:1024
	ds_read_b128 v[142:145], v130 offset:2048
	ds_read_b128 v[154:157], v130 offset:3072
	s_add_u32 s6, s18, 0x20000
	v_mov_b32_e32 v128, v148
	v_mov_b32_e32 v129, v146
	s_addc_u32 s7, s19, 0
	s_mov_b32 m0, s34
	ds_read_b128 v[158:161], v153 offset:32768
	ds_read_b128 v[162:165], v153 offset:33792
	ds_read_b128 v[166:169], v153 offset:34816
	ds_read_b128 v[170:173], v153 offset:35840
	ds_read_b128 v[174:177], v153 offset:36864
	ds_read_b128 v[178:181], v153 offset:37888
	ds_read_b128 v[182:185], v153 offset:38912
	ds_read_b128 v[190:193], v153 offset:39936
	s_nop 0
	global_load_lds_dwordx4 v129, s[6:7]
	s_mov_b32 m0, s35
	s_nop 0
	global_load_lds_dwordx4 v128, s[6:7]
	s_waitcnt lgkmcnt(8)
	s_barrier
	s_waitcnt lgkmcnt(0)
	s_waitcnt lgkmcnt(0)
	v_mfma_f32_16x16x32_bf16 v[4:7], v[132:135], v[158:161], v[4:7]
	v_mfma_f32_16x16x32_bf16 v[0:3], v[142:145], v[158:161], v[0:3]
	v_mfma_f32_16x16x32_bf16 v[20:23], v[132:135], v[166:169], v[20:23]
	v_mfma_f32_16x16x32_bf16 v[16:19], v[142:145], v[166:169], v[16:19]
	v_mfma_f32_16x16x32_bf16 v[36:39], v[132:135], v[174:177], v[36:39]
	v_mfma_f32_16x16x32_bf16 v[32:35], v[142:145], v[174:177], v[32:35]
	v_mfma_f32_16x16x32_bf16 v[52:55], v[132:135], v[182:185], v[52:55]
	v_mfma_f32_16x16x32_bf16 v[48:51], v[142:145], v[182:185], v[48:51]
	v_mfma_f32_16x16x32_bf16 v[4:7], v[138:141], v[162:165], v[4:7]
	v_mfma_f32_16x16x32_bf16 v[0:3], v[154:157], v[162:165], v[0:3]
	v_mfma_f32_16x16x32_bf16 v[20:23], v[138:141], v[170:173], v[20:23]
	v_mfma_f32_16x16x32_bf16 v[16:19], v[154:157], v[170:173], v[16:19]
	v_mfma_f32_16x16x32_bf16 v[36:39], v[138:141], v[178:181], v[36:39]
	v_mfma_f32_16x16x32_bf16 v[32:35], v[154:157], v[178:181], v[32:35]
	v_mfma_f32_16x16x32_bf16 v[52:55], v[138:141], v[190:193], v[52:55]
	v_mfma_f32_16x16x32_bf16 v[48:51], v[154:157], v[190:193], v[48:51]
	s_barrier
	v_mov_b32_e32 v186, v149
	v_mov_b32_e32 v188, v147
	ds_read_b128 v[202:205], v131
	ds_read_b128 v[222:225], v131 offset:1024
	ds_read_b128 v[226:229], v131 offset:2048
	ds_read_b128 v[128:131], v131 offset:3072
	s_mov_b64 s[6:7], 0x80
	v_lshl_add_u64 v[194:195], s[20:21], 0, v[188:189]
	v_mov_b32_e32 v187, v189
	s_mov_b32 m0, s48
	v_lshl_add_u64 v[194:195], v[194:195], 0, s[6:7]
	v_lshl_add_u64 v[186:187], s[20:21], 0, v[186:187]
	global_load_lds_dwordx4 v[194:195], off
	v_lshl_add_u64 v[186:187], v[186:187], 0, s[6:7]
	s_mov_b32 m0, s47
	s_nop 0
	global_load_lds_dwordx4 v[186:187], off
	s_barrier
	s_waitcnt lgkmcnt(0)
	s_waitcnt lgkmcnt(0)
	v_mfma_f32_16x16x32_bf16 v[12:15], v[202:205], v[158:161], v[12:15]
	v_mfma_f32_16x16x32_bf16 v[8:11], v[226:229], v[158:161], v[8:11]
	v_mfma_f32_16x16x32_bf16 v[28:31], v[202:205], v[166:169], v[28:31]
	v_mfma_f32_16x16x32_bf16 v[24:27], v[226:229], v[166:169], v[24:27]
	v_mfma_f32_16x16x32_bf16 v[44:47], v[202:205], v[174:177], v[44:47]
	v_mfma_f32_16x16x32_bf16 v[40:43], v[226:229], v[174:177], v[40:43]
	v_mfma_f32_16x16x32_bf16 v[60:63], v[202:205], v[182:185], v[60:63]
	v_mfma_f32_16x16x32_bf16 v[56:59], v[226:229], v[182:185], v[56:59]
	v_mfma_f32_16x16x32_bf16 v[12:15], v[222:225], v[162:165], v[12:15]
	v_mfma_f32_16x16x32_bf16 v[8:11], v[128:131], v[162:165], v[8:11]
	v_mfma_f32_16x16x32_bf16 v[28:31], v[222:225], v[170:173], v[28:31]
	v_mfma_f32_16x16x32_bf16 v[24:27], v[128:131], v[170:173], v[24:27]
	v_mfma_f32_16x16x32_bf16 v[44:47], v[222:225], v[178:181], v[44:47]
	v_mfma_f32_16x16x32_bf16 v[40:43], v[128:131], v[178:181], v[40:43]
	v_mfma_f32_16x16x32_bf16 v[60:63], v[222:225], v[190:193], v[60:63]
	v_mfma_f32_16x16x32_bf16 v[56:59], v[128:131], v[190:193], v[56:59]
	v_mov_b32_e32 v186, v148
	v_mov_b32_e32 v188, v146
	s_barrier
	ds_read_b128 v[158:161], v153 offset:49152
	ds_read_b128 v[162:165], v153 offset:50176
	ds_read_b128 v[166:169], v153 offset:51200
	ds_read_b128 v[170:173], v153 offset:52224
	ds_read_b128 v[174:177], v153 offset:53248
	ds_read_b128 v[178:181], v153 offset:54272
	ds_read_b128 v[182:185], v153 offset:55296
	ds_read_b128 v[190:193], v153 offset:56320
	v_mov_b32_e32 v187, v189
	v_lshl_add_u64 v[194:195], s[18:19], 0, v[188:189]
	s_mov_b32 m0, s36
	v_lshl_add_u64 v[194:195], v[194:195], 0, s[6:7]
	v_lshl_add_u64 v[186:187], s[18:19], 0, v[186:187]
	global_load_lds_dwordx4 v[194:195], off
	v_lshl_add_u64 v[186:187], v[186:187], 0, s[6:7]
	s_mov_b32 m0, s37
	s_nop 0
	global_load_lds_dwordx4 v[186:187], off
	s_barrier
	s_waitcnt lgkmcnt(0)
	s_waitcnt lgkmcnt(0)
	v_mfma_f32_16x16x32_bf16 v[68:71], v[132:135], v[158:161], v[68:71]
	v_mfma_f32_16x16x32_bf16 v[64:67], v[142:145], v[158:161], v[64:67]
	v_mfma_f32_16x16x32_bf16 v[84:87], v[132:135], v[166:169], v[84:87]
	v_mfma_f32_16x16x32_bf16 v[80:83], v[142:145], v[166:169], v[80:83]
	v_mfma_f32_16x16x32_bf16 v[100:103], v[132:135], v[174:177], v[100:103]
	v_mfma_f32_16x16x32_bf16 v[96:99], v[142:145], v[174:177], v[96:99]
	v_mfma_f32_16x16x32_bf16 v[120:123], v[132:135], v[182:185], v[120:123]
	v_mfma_f32_16x16x32_bf16 v[116:119], v[142:145], v[182:185], v[116:119]
	v_mfma_f32_16x16x32_bf16 v[68:71], v[138:141], v[162:165], v[68:71]
	v_mfma_f32_16x16x32_bf16 v[64:67], v[154:157], v[162:165], v[64:67]
	v_mfma_f32_16x16x32_bf16 v[84:87], v[138:141], v[170:173], v[84:87]
	v_mfma_f32_16x16x32_bf16 v[80:83], v[154:157], v[170:173], v[80:83]
	v_mfma_f32_16x16x32_bf16 v[100:103], v[138:141], v[178:181], v[100:103]
	v_mfma_f32_16x16x32_bf16 v[96:99], v[154:157], v[178:181], v[96:99]
	v_mfma_f32_16x16x32_bf16 v[120:123], v[138:141], v[190:193], v[120:123]
	v_mfma_f32_16x16x32_bf16 v[116:119], v[154:157], v[190:193], v[116:119]
	s_barrier
;     __device__ __forceinline__ void operator()(f32x4 (&acc)[2][2][4][2], const Unit& u, int wr, int wc, int fr, int fq) const {
;         const int row0 = u.pm * BM + wr * 64 + fr, col0 = u.pn * BM + wc * 32 + 8 * fq;
;         const bool fin = (u.br == 2);
;         const int tidl = (wr * 4 + wc) * 64 + fq * 16 + fr;
;         const u32x4* gn = GT + ((size_t)((u.br * 64 + u.pm) * 4 + u.pn) * 16) * 512 + tidl;
;         const u32x4* gd = gn + (size_t)64 * 4 * 16 * 512;
; #pragma unroll
;         for (int ai = 0; ai < 2; ++ai)
; #pragma unroll
;             for (int m = 0; m < 4; ++m) { const size_t row = (size_t)(row0 + ai * HALF + m * 16);
; #pragma unroll
;                 for (int bj = 0; bj < 2; ++bj) { const size_t so = (size_t)((ai * 4 + m) * 2 + bj) * 512;
;                     const u32x4 zn = gn[so]; u32x4 zd = zn; if (!fin) zd = gd[so];
	s_add_u32 s6, s20, 0x20080
	v_mov_b32_e32 v132, v149
	v_mov_b32_e32 v133, v147
	s_addc_u32 s7, s21, 0
	s_mov_b32 m0, s22
	s_nop 0
	global_load_lds_dwordx4 v133, s[6:7]
	s_mov_b32 m0, s23
	s_nop 0
	global_load_lds_dwordx4 v132, s[6:7]
	s_waitcnt vmcnt(6)
	s_barrier
	v_mfma_f32_16x16x32_bf16 v[76:79], v[202:205], v[158:161], v[76:79]
	v_mfma_f32_16x16x32_bf16 v[72:75], v[226:229], v[158:161], v[72:75]
	v_mfma_f32_16x16x32_bf16 v[92:95], v[202:205], v[166:169], v[92:95]
	v_mfma_f32_16x16x32_bf16 v[88:91], v[226:229], v[166:169], v[88:91]
	v_mfma_f32_16x16x32_bf16 v[108:111], v[202:205], v[174:177], v[108:111]
	v_mfma_f32_16x16x32_bf16 v[104:107], v[226:229], v[174:177], v[104:107]
	v_mfma_f32_16x16x32_bf16 v[124:127], v[202:205], v[182:185], v[124:127]
	v_mfma_f32_16x16x32_bf16 v[112:115], v[226:229], v[182:185], v[112:115]
	v_mfma_f32_16x16x32_bf16 v[76:79], v[222:225], v[162:165], v[76:79]
	v_mfma_f32_16x16x32_bf16 v[72:75], v[128:131], v[162:165], v[72:75]
	v_mfma_f32_16x16x32_bf16 v[92:95], v[222:225], v[170:173], v[92:95]
	v_mfma_f32_16x16x32_bf16 v[88:91], v[128:131], v[170:173], v[88:91]
	v_mfma_f32_16x16x32_bf16 v[108:111], v[222:225], v[178:181], v[108:111]
	v_mfma_f32_16x16x32_bf16 v[104:107], v[128:131], v[178:181], v[104:107]
	v_mfma_f32_16x16x32_bf16 v[124:127], v[222:225], v[190:193], v[124:127]
	v_mfma_f32_16x16x32_bf16 v[112:115], v[128:131], v[190:193], v[112:115]
	s_cmp_eq_u32 s42, 2
	s_cselect_b64 s[6:7], -1, 0
	s_cmp_lg_u32 s42, 2
	s_cselect_b64 s[22:23], -1, 0
	s_lshl_b32 s9, s41, 2
	s_lshl_b32 s8, s42, 8
	s_add_i32 s9, s9, s33
	s_add_i32 s8, s9, s8
	s_ashr_i32 s9, s8, 31
	s_lshl_b64 s[8:9], s[8:9], 17
	v_lshl_add_u64 v[138:139], v[136:137], 0, s[8:9]
	s_barrier
	v_mov_b32_e32 v200, 0x2000000
	v_mov_b32_e32 v201, 0
	v_cndmask_b32_e64 v200, v200, 0, s[6:7]
	global_load_dwordx4 v[156:159], v[138:139], off
	v_lshl_add_u64 v[198:199], v[138:139], 0, v[200:201]
	global_load_dwordx4 v[160:163], v[198:199], off
	v_add_co_u32_e32 v198, vcc, 0x2000, v138
	s_nop 1
	v_addc_co_u32_e32 v199, vcc, 0, v139, vcc
	global_load_dwordx4 v[164:167], v[198:199], off
	v_lshl_add_u64 v[198:199], v[198:199], 0, v[200:201]
	global_load_dwordx4 v[168:171], v[198:199], off
	v_add_co_u32_e32 v198, vcc, 0x4000, v138
	s_nop 1
	v_addc_co_u32_e32 v199, vcc, 0, v139, vcc
	global_load_dwordx4 v[172:175], v[198:199], off
	v_lshl_add_u64 v[198:199], v[198:199], 0, v[200:201]
	global_load_dwordx4 v[176:179], v[198:199], off
	v_add_co_u32_e32 v198, vcc, 0x6000, v138
	s_nop 1
	v_addc_co_u32_e32 v199, vcc, 0, v139, vcc
	global_load_dwordx4 v[180:183], v[198:199], off
	v_lshl_add_u64 v[198:199], v[198:199], 0, v[200:201]
	global_load_dwordx4 v[184:187], v[198:199], off
	v_add_co_u32_e32 v198, vcc, 0x8000, v138
	s_nop 1
	v_addc_co_u32_e32 v199, vcc, 0, v139, vcc
	global_load_dwordx4 v[226:229], v[198:199], off
	v_lshl_add_u64 v[198:199], v[198:199], 0, v[200:201]
	global_load_dwordx4 v[230:233], v[198:199], off
	v_add_co_u32_e32 v198, vcc, 0xa000, v138
	s_nop 1
	v_addc_co_u32_e32 v199, vcc, 0, v139, vcc
	global_load_dwordx4 v[234:237], v[198:199], off
	v_lshl_add_u64 v[198:199], v[198:199], 0, v[200:201]
	global_load_dwordx4 v[238:241], v[198:199], off
	v_add_co_u32_e32 v198, vcc, 0xc000, v138
	s_nop 1
	v_addc_co_u32_e32 v199, vcc, 0, v139, vcc
	global_load_dwordx4 v[242:245], v[198:199], off
	v_lshl_add_u64 v[198:199], v[198:199], 0, v[200:201]
	global_load_dwordx4 v[246:249], v[198:199], off
	v_add_co_u32_e32 v198, vcc, 0xe000, v138
	s_nop 1
	v_addc_co_u32_e32 v199, vcc, 0, v139, vcc
	global_load_dwordx4 v[202:205], v[198:199], off
	v_lshl_add_u64 v[198:199], v[198:199], 0, v[200:201]
	global_load_dwordx4 v[194:197], v[198:199], off
	s_waitcnt vmcnt(14)
	v_mov_b64_e32 v[128:129], v[156:157]
	v_mov_b64_e32 v[130:131], v[158:159]
	s_and_b64 vcc, exec, s[6:7]
	v_mov_b64_e32 v[132:133], v[160:161]
	v_mov_b64_e32 v[134:135], v[162:163]
	v_add_co_u32_e32 v198, vcc, 0x10000, v138
	s_nop 1
	v_addc_co_u32_e32 v199, vcc, 0, v139, vcc
	global_load_dwordx4 v[156:159], v[198:199], off
	v_lshl_add_u64 v[198:199], v[198:199], 0, v[200:201]
	global_load_dwordx4 v[160:163], v[198:199], off

; #define LAS __attribute__((address_space(3)))
; __device__ void attn_mfma(const Params& p, int l, const bf16_t* proj, bf16_t* y0, LAS unsigned char* lds) {
;     ...
;         for (int tile = 0; tile < 4; ++tile) {
;             const int tl = (wv & 1) * 64 + tile * 16 + fr, t = n * 128 + tl;
;             bf16x8 qf[2];
; #pragma unroll
;             for (int ks = 0; ks < 2; ++ks) { qf[ks] = qn[ks]; qn[ks] = *(const bf16x8*)(proj + (size_t)(t + (tile < 3 ? 16 : 0)) * NP + AQ + hq * 64 + ks * 32 + g * 8); }
;             f32x4 sacc[24];
; #pragma unroll
;             for (int kt = 0; kt < 24; ++kt) { f32x4 a = {0.f, 0.f, 0.f, 0.f};
; #pragma unroll
;                 for (int ks = 0; ks < 2; ++ks) { const bf16x8 kf = *(const LAS bf16x8*)(Ks + (kt * 16 + fr) * KP + ks * 32 + g * 8); a = __builtin_amdgcn_mfma_f32_16x16x32_bf16(kf, qf[ks], a, 0, 0, 0); }
;                 sacc[kt] = a; if ((kt % 6) == 5) __builtin_amdgcn_sched_barrier(0); }
.LBB0_478:
	ds_read_b128 v[0:3], v141
	ds_read_b128 v[4:7], v141 offset:64
	ds_read_b128 v[12:15], v141 offset:2304
	ds_read_b128 v[16:19], v141 offset:2368
	s_cmp_eq_u32 s12, 48
	v_add_u32_e32 v118, s12, v148
	s_waitcnt vmcnt(2) lgkmcnt(3)
	v_mfma_f32_16x16x32_bf16 v[0:3], v[0:3], v[100:103], 0
	s_cselect_b32 s13, 0, 16
	v_add_u32_e32 v22, s13, v118
	v_mov_b64_e32 v[20:21], s[94:95]
	s_waitcnt lgkmcnt(1)
	v_mfma_f32_16x16x32_bf16 v[12:15], v[12:15], v[100:103], 0
	s_waitcnt vmcnt(1)
	v_mfma_f32_16x16x32_bf16 v[104:107], v[4:7], v[8:11], v[0:3]
	ds_read_b128 v[4:7], v141 offset:4672
	s_nop 1
	ds_read_b128 v[0:3], v141 offset:4608
	s_waitcnt lgkmcnt(2)
	v_mfma_f32_16x16x32_bf16 v[96:99], v[16:19], v[8:11], v[12:15]
	ds_read_b128 v[16:19], v141 offset:6976
	s_nop 1
	ds_read_b128 v[12:15], v141 offset:6912
	s_waitcnt lgkmcnt(2)
	v_mfma_f32_16x16x32_bf16 v[0:3], v[0:3], v[100:103], 0
	v_mfma_f32_16x16x32_bf16 v[92:95], v[4:7], v[8:11], v[0:3]
	s_waitcnt lgkmcnt(0)
	v_mfma_f32_16x16x32_bf16 v[4:7], v[12:15], v[100:103], 0
	s_nop 4
	ds_read_b128 v[0:3], v141 offset:9216
	ds_read_b128 v[12:15], v141 offset:9280
	v_mfma_f32_16x16x32_bf16 v[88:91], v[16:19], v[8:11], v[4:7]
	s_waitcnt lgkmcnt(1)
	v_mfma_f32_16x16x32_bf16 v[0:3], v[0:3], v[100:103], 0
	s_nop 0
	v_mad_i64_i32 v[4:5], s[14:15], v22, s63, v[20:21]
	v_lshl_add_u64 v[4:5], v[114:115], 1, v[4:5]
	v_lshl_add_u64 v[16:17], v[4:5], 0, v[188:189]
	ds_read_b128 v[4:7], v141 offset:11520
	v_add_co_u32_e32 v22, vcc, 0x1000, v16
	v_lshl_add_u64 v[20:21], v[16:17], 0, s[24:25]
	s_nop 0
	v_addc_co_u32_e32 v23, vcc, 0, v17, vcc
	s_waitcnt lgkmcnt(1)
	v_mfma_f32_16x16x32_bf16 v[84:87], v[12:15], v[8:11], v[0:3]
	ds_read_b128 v[12:15], v141 offset:11584
	s_waitcnt lgkmcnt(1)
	v_mfma_f32_16x16x32_bf16 v[16:19], v[4:7], v[100:103], 0
	global_load_dwordx4 v[0:3], v[22:23], off offset:2048
	global_load_dwordx4 v[4:7], v[20:21], off offset:64
	s_waitcnt lgkmcnt(0)
	v_mfma_f32_16x16x32_bf16 v[80:83], v[12:15], v[8:11], v[16:19]
	ds_read_b128 v[12:15], v141 offset:13824
	s_nop 2
	ds_read_b128 v[16:19], v141 offset:13888
	ds_read_b128 v[20:23], v141 offset:16128
	ds_read_b128 v[24:27], v141 offset:16192
	s_waitcnt lgkmcnt(3)
	v_mfma_f32_16x16x32_bf16 v[12:15], v[12:15], v[100:103], 0
	s_waitcnt lgkmcnt(2)
	v_mfma_f32_16x16x32_bf16 v[76:79], v[16:19], v[8:11], v[12:15]
	ds_read_b128 v[16:19], v141 offset:18496
	s_nop 4
	ds_read_b128 v[12:15], v141 offset:18432
	s_waitcnt lgkmcnt(3)
	v_mfma_f32_16x16x32_bf16 v[20:23], v[20:23], v[100:103], 0
	s_waitcnt lgkmcnt(2)
	v_mfma_f32_16x16x32_bf16 v[72:75], v[24:27], v[8:11], v[20:23]
	s_waitcnt lgkmcnt(0)
	v_mfma_f32_16x16x32_bf16 v[12:15], v[12:15], v[100:103], 0
	s_nop 3
	ds_read_b128 v[20:23], v141 offset:20736
	v_mfma_f32_16x16x32_bf16 v[68:71], v[16:19], v[8:11], v[12:15]
	s_nop 2
	ds_read_b128 v[12:15], v141 offset:20800
	s_waitcnt lgkmcnt(1)
	v_mfma_f32_16x16x32_bf16 v[16:19], v[20:23], v[100:103], 0
	ds_read_b128 v[20:23], v141 offset:23040
	s_waitcnt lgkmcnt(1)
	v_mfma_f32_16x16x32_bf16 v[64:67], v[12:15], v[8:11], v[16:19]
	ds_read_b128 v[12:15], v141 offset:23104
	s_waitcnt lgkmcnt(1)
	v_mfma_f32_16x16x32_bf16 v[16:19], v[20:23], v[100:103], 0
	ds_read_b128 v[20:23], v141 offset:25344
	s_waitcnt lgkmcnt(1)
	v_mfma_f32_16x16x32_bf16 v[60:63], v[12:15], v[8:11], v[16:19]
	ds_read_b128 v[12:15], v141 offset:25408
	s_waitcnt lgkmcnt(1)
	v_mfma_f32_16x16x32_bf16 v[16:19], v[20:23], v[100:103], 0
	s_waitcnt lgkmcnt(0)
	v_mfma_f32_16x16x32_bf16 v[56:59], v[12:15], v[8:11], v[16:19]
	ds_read_b128 v[12:15], v141 offset:27648
	s_nop 4
	ds_read_b128 v[16:19], v141 offset:27712
	ds_read_b128 v[20:23], v141 offset:29952
	ds_read_b128 v[24:27], v141 offset:30016
	s_waitcnt lgkmcnt(3)
	v_mfma_f32_16x16x32_bf16 v[12:15], v[12:15], v[100:103], 0
	s_waitcnt lgkmcnt(2)
	v_mfma_f32_16x16x32_bf16 v[52:55], v[16:19], v[8:11], v[12:15]
	ds_read_b128 v[16:19], v141 offset:32320
	s_nop 4
	ds_read_b128 v[12:15], v141 offset:32256
	s_waitcnt lgkmcnt(3)
	v_mfma_f32_16x16x32_bf16 v[20:23], v[20:23], v[100:103], 0
	s_waitcnt lgkmcnt(2)
	v_mfma_f32_16x16x32_bf16 v[48:51], v[24:27], v[8:11], v[20:23]
	s_waitcnt lgkmcnt(0)
	v_mfma_f32_16x16x32_bf16 v[12:15], v[12:15], v[100:103], 0
	s_nop 3
	ds_read_b128 v[20:23], v141 offset:34560
	v_mfma_f32_16x16x32_bf16 v[44:47], v[16:19], v[8:11], v[12:15]
	s_nop 2
	ds_read_b128 v[12:15], v141 offset:34624
	s_waitcnt lgkmcnt(1)
	v_mfma_f32_16x16x32_bf16 v[16:19], v[20:23], v[100:103], 0
	ds_read_b128 v[20:23], v141 offset:36864
	s_waitcnt lgkmcnt(1)
	v_mfma_f32_16x16x32_bf16 v[40:43], v[12:15], v[8:11], v[16:19]
	ds_read_b128 v[12:15], v141 offset:36928
	s_waitcnt lgkmcnt(1)
	v_mfma_f32_16x16x32_bf16 v[16:19], v[20:23], v[100:103], 0
	ds_read_b128 v[20:23], v141 offset:39168
	s_waitcnt lgkmcnt(1)
	v_mfma_f32_16x16x32_bf16 v[36:39], v[12:15], v[8:11], v[16:19]
	ds_read_b128 v[12:15], v141 offset:39232
	s_waitcnt lgkmcnt(1)
	v_mfma_f32_16x16x32_bf16 v[16:19], v[20:23], v[100:103], 0
	s_waitcnt lgkmcnt(0)
	v_mfma_f32_16x16x32_bf16 v[32:35], v[12:15], v[8:11], v[16:19]
	ds_read_b128 v[12:15], v141 offset:41472
	s_nop 4
	ds_read_b128 v[16:19], v141 offset:41536
	s_waitcnt lgkmcnt(1)
	v_mfma_f32_16x16x32_bf16 v[12:15], v[12:15], v[100:103], 0
	ds_read_b128 v[150:153], v141 offset:50752
	s_waitcnt lgkmcnt(1)
	v_mfma_f32_16x16x32_bf16 v[28:31], v[16:19], v[8:11], v[12:15]
	ds_read_b128 v[16:19], v141 offset:43840
	s_nop 3
	ds_read_b128 v[12:15], v141 offset:43776
	s_waitcnt lgkmcnt(0)
	v_mfma_f32_16x16x32_bf16 v[12:15], v[12:15], v[100:103], 0
	v_mfma_f32_16x16x32_bf16 v[24:27], v[16:19], v[8:11], v[12:15]
	ds_read_b128 v[16:19], v141 offset:46144
	s_nop 5
	ds_read_b128 v[12:15], v141 offset:46080
	s_waitcnt lgkmcnt(0)
; #define LAS __attribute__((address_space(3)))
; __device__ void attn_mfma(const Params& p, int l, const bf16_t* proj, bf16_t* y0, LAS unsigned char* lds) {
;     ...
;             for (int kt = 0; kt < 24; ++kt) { f32x4 a = {0.f, 0.f, 0.f, 0.f};
; #pragma unroll
;                 for (int ks = 0; ks < 2; ++ks) { const bf16x8 kf = *(const LAS bf16x8*)(Ks + (kt * 16 + fr) * KP + ks * 32 + g * 8); a = __builtin_amdgcn_mfma_f32_16x16x32_bf16(kf, qf[ks], a, 0, 0, 0); }
;                 sacc[kt] = a; if ((kt % 6) == 5) __builtin_amdgcn_sched_barrier(0); }
;             const float tq = (float)(tl + 128 - 4 * g);
;             float mx = sink;
; #pragma unroll
;             for (int kt = 0; kt < 24; ++kt)
; #pragma unroll
;                 for (int r = 0; r < 4; ++r) { const float x = (float)(kt * 16 + r) - tq; float sc = fmaf(sacc[kt][r], 0.125f, -slope * fabsf(x));
;                     bool valid = fabsf(x) <= 128.0f;
;                     if (edge) { const int kl = kt * 16 + 4 * g + r; valid = valid && (n == 0 ? kl >= 128 : kl < 256); }
;                     sc = valid ? sc : -1e30f; sacc[kt][r] = sc; mx = fmaxf(mx, sc); }
	v_mfma_f32_16x16x32_bf16 v[12:15], v[12:15], v[100:103], 0
	v_mfma_f32_16x16x32_bf16 v[20:23], v[16:19], v[8:11], v[12:15]
	ds_read_b128 v[16:19], v141 offset:48448
	s_nop 5
	ds_read_b128 v[12:15], v141 offset:48384
	s_waitcnt lgkmcnt(0)
	v_mfma_f32_16x16x32_bf16 v[12:15], v[12:15], v[100:103], 0
	v_mfma_f32_16x16x32_bf16 v[16:19], v[16:19], v[8:11], v[12:15]
	s_nop 6
	ds_read_b128 v[12:15], v141 offset:50688
	s_waitcnt lgkmcnt(0)
	v_mfma_f32_16x16x32_bf16 v[12:15], v[12:15], v[100:103], 0
	v_mfma_f32_16x16x32_bf16 v[12:15], v[150:153], v[8:11], v[12:15]
	ds_read_b128 v[150:153], v141 offset:52992
	s_waitcnt lgkmcnt(0)
	v_mfma_f32_16x16x32_bf16 v[100:103], v[150:153], v[100:103], 0
	ds_read_b128 v[150:153], v141 offset:53056
	s_waitcnt lgkmcnt(0)
	v_mfma_f32_16x16x32_bf16 v[8:11], v[150:153], v[8:11], v[100:103]
	s_nop 4
	v_add_u32_e32 v100, s12, v134
	v_cvt_f32_u32_e32 v101, v100
	v_cndmask_b32_e64 v119, 0, 1, s[4:5]
	v_sub_f32_e32 v100, 0, v101
	v_cmp_le_f32_e64 s[14:15], |v100|, s71
	v_cmp_nle_f32_e64 s[16:17], |v100|, s71
	s_and_b64 s[14:15], s[8:9], s[14:15]
	v_mul_f32_e64 v102, |v100|, -v147
	v_cndmask_b32_e64 v100, 0, 1, s[14:15]
	s_or_b64 vcc, s[8:9], s[16:17]
	v_cndmask_b32_e32 v100, v119, v100, vcc
	v_and_b32_e32 v100, 1, v100
	v_fmac_f32_e32 v102, 0x3e000000, v104
	v_cmp_eq_u32_e32 vcc, 1, v100
	s_nop 1
	v_cndmask_b32_e32 v100, v220, v102, vcc
	v_sub_f32_e32 v102, 1.0, v101
	v_cmp_le_f32_e64 s[14:15], |v102|, s71
	v_cmp_nle_f32_e64 s[16:17], |v102|, s71
	s_and_b64 s[14:15], s[8:9], s[14:15]
	v_mul_f32_e64 v103, |v102|, -v147
	v_cndmask_b32_e64 v102, 0, 1, s[14:15]
	s_or_b64 vcc, s[8:9], s[16:17]
	v_cndmask_b32_e32 v102, v119, v102, vcc
	v_and_b32_e32 v102, 1, v102
	v_fmac_f32_e32 v103, 0x3e000000, v105
	v_cmp_eq_u32_e32 vcc, 1, v102
	s_nop 1
	v_cndmask_b32_e32 v102, v220, v103, vcc
	v_sub_f32_e32 v103, 2.0, v101
	v_cmp_le_f32_e64 s[14:15], |v103|, s71
	v_cmp_nle_f32_e64 s[16:17], |v103|, s71
	s_and_b64 s[14:15], s[8:9], s[14:15]
	v_mul_f32_e64 v104, |v103|, -v147
	v_cndmask_b32_e64 v103, 0, 1, s[14:15]
	s_or_b64 vcc, s[8:9], s[16:17]
	v_cndmask_b32_e32 v103, v119, v103, vcc
	v_and_b32_e32 v103, 1, v103
	v_fmac_f32_e32 v104, 0x3e000000, v106
	v_cmp_eq_u32_e32 vcc, 1, v103
	s_waitcnt vmcnt(2)
	v_max3_f32 v105, v146, v100, v102
	v_cndmask_b32_e32 v103, v220, v104, vcc
	v_sub_f32_e32 v104, 0x40400000, v101
	v_cmp_le_f32_e64 s[14:15], |v104|, s71
	v_cmp_nle_f32_e64 s[16:17], |v104|, s71
	s_and_b64 s[14:15], s[8:9], s[14:15]
	v_mul_f32_e64 v106, |v104|, -v147
	v_cndmask_b32_e64 v104, 0, 1, s[14:15]
	s_or_b64 vcc, s[8:9], s[16:17]
	v_cndmask_b32_e32 v104, v119, v104, vcc
	v_and_b32_e32 v104, 1, v104
	v_fmac_f32_e32 v106, 0x3e000000, v107
	v_cmp_eq_u32_e32 vcc, 1, v104
	s_nop 1
	v_cndmask_b32_e32 v104, v220, v106, vcc
	v_sub_f32_e32 v106, 0x41800000, v101
	v_cmp_le_f32_e64 s[14:15], |v106|, s71
	v_mul_f32_e64 v107, |v106|, -v147
	v_cmp_nle_f32_e64 s[16:17], |v106|, s71
	s_and_b64 s[14:15], s[8:9], s[14:15]
	v_fmac_f32_e32 v107, 0x3e000000, v96
	v_cndmask_b32_e64 v96, 0, 1, s[14:15]
	s_or_b64 vcc, s[8:9], s[16:17]
	v_cndmask_b32_e32 v96, v119, v96, vcc
	v_and_b32_e32 v96, 1, v96
	v_sub_f32_e32 v106, 0x41880000, v101
	v_cmp_eq_u32_e32 vcc, 1, v96
	v_cmp_le_f32_e64 s[14:15], |v106|, s71
	v_cmp_nle_f32_e64 s[16:17], |v106|, s71
	v_cndmask_b32_e32 v96, v220, v107, vcc
	v_mul_f32_e64 v107, |v106|, -v147
	s_and_b64 s[14:15], s[8:9], s[14:15]
	v_fmac_f32_e32 v107, 0x3e000000, v97
	v_cndmask_b32_e64 v97, 0, 1, s[14:15]
	s_or_b64 vcc, s[8:9], s[16:17]
	v_cndmask_b32_e32 v97, v119, v97, vcc
	v_and_b32_e32 v97, 1, v97
	v_sub_f32_e32 v106, 0x41900000, v101
	v_cmp_eq_u32_e32 vcc, 1, v97
	v_cmp_le_f32_e64 s[14:15], |v106|, s71
	v_cmp_nle_f32_e64 s[16:17], |v106|, s71
	v_cndmask_b32_e32 v97, v220, v107, vcc
	v_mul_f32_e64 v107, |v106|, -v147
	s_and_b64 s[14:15], s[8:9], s[14:15]
	v_fmac_f32_e32 v107, 0x3e000000, v98
	v_cndmask_b32_e64 v98, 0, 1, s[14:15]
	s_or_b64 vcc, s[8:9], s[16:17]
	v_cndmask_b32_e32 v98, v119, v98, vcc
	v_and_b32_e32 v98, 1, v98
	v_sub_f32_e32 v106, 0x41980000, v101
	v_cmp_eq_u32_e32 vcc, 1, v98
	v_cmp_le_f32_e64 s[14:15], |v106|, s71
	v_cmp_nle_f32_e64 s[16:17], |v106|, s71
	v_cndmask_b32_e32 v98, v220, v107, vcc
	v_mul_f32_e64 v107, |v106|, -v147
	s_and_b64 s[14:15], s[8:9], s[14:15]
	v_fmac_f32_e32 v107, 0x3e000000, v99
	v_cndmask_b32_e64 v99, 0, 1, s[14:15]
	s_or_b64 vcc, s[8:9], s[16:17]
	v_cndmask_b32_e32 v99, v119, v99, vcc
	v_and_b32_e32 v99, 1, v99
	v_sub_f32_e32 v106, 0x42000000, v101
	v_cmp_eq_u32_e32 vcc, 1, v99
	v_cmp_le_f32_e64 s[14:15], |v106|, s71
	v_cmp_nle_f32_e64 s[16:17], |v106|, s71
	v_cndmask_b32_e32 v99, v220, v107, vcc
	v_mul_f32_e64 v107, |v106|, -v147
	s_and_b64 s[14:15], s[8:9], s[14:15]
	v_fmac_f32_e32 v107, 0x3e000000, v92
	v_cndmask_b32_e64 v92, 0, 1, s[14:15]
	s_or_b64 vcc, s[8:9], s[16:17]
	v_cndmask_b32_e32 v92, v119, v92, vcc
	v_and_b32_e32 v92, 1, v92
	v_sub_f32_e32 v106, 0x42040000, v101
	v_cmp_eq_u32_e32 vcc, 1, v92
	v_cmp_le_f32_e64 s[14:15], |v106|, s71
	v_cmp_nle_f32_e64 s[16:17], |v106|, s71
	v_cndmask_b32_e32 v92, v220, v107, vcc
	v_mul_f32_e64 v107, |v106|, -v147
	s_and_b64 s[14:15], s[8:9], s[14:15]
	v_fmac_f32_e32 v107, 0x3e000000, v93
	v_cndmask_b32_e64 v93, 0, 1, s[14:15]
	s_or_b64 vcc, s[8:9], s[16:17]
	v_cndmask_b32_e32 v93, v119, v93, vcc
	v_and_b32_e32 v93, 1, v93
	v_sub_f32_e32 v106, 0x42080000, v101
	v_cmp_eq_u32_e32 vcc, 1, v93
	v_cmp_le_f32_e64 s[14:15], |v106|, s71
	v_cmp_nle_f32_e64 s[16:17], |v106|, s71
	v_cndmask_b32_e32 v93, v220, v107, vcc
	v_mul_f32_e64 v107, |v106|, -v147
	s_and_b64 s[14:15], s[8:9], s[14:15]
	v_fmac_f32_e32 v107, 0x3e000000, v94
; __device__ void attn_mfma(const Params& p, int l, const bf16_t* proj, bf16_t* y0, LAS unsigned char* lds) {
;     ...
;             const float tq = (float)(tl + 128 - 4 * g);
;             float mx = sink;
; #pragma unroll
;             for (int kt = 0; kt < 24; ++kt)
; #pragma unroll
;                 for (int r = 0; r < 4; ++r) { const float x = (float)(kt * 16 + r) - tq; float sc = fmaf(sacc[kt][r], 0.125f, -slope * fabsf(x));
;                     bool valid = fabsf(x) <= 128.0f;
;                     if (edge) { const int kl = kt * 16 + 4 * g + r; valid = valid && (n == 0 ? kl >= 128 : kl < 256); }
;                     sc = valid ? sc : -1e30f; sacc[kt][r] = sc; mx = fmaxf(mx, sc); }
	v_cndmask_b32_e64 v94, 0, 1, s[14:15]
	s_or_b64 vcc, s[8:9], s[16:17]
	v_cndmask_b32_e32 v94, v119, v94, vcc
	v_and_b32_e32 v94, 1, v94
	v_sub_f32_e32 v106, 0x420c0000, v101
	v_cmp_eq_u32_e32 vcc, 1, v94
	v_cmp_le_f32_e64 s[14:15], |v106|, s71
	v_cmp_nle_f32_e64 s[16:17], |v106|, s71
	v_cndmask_b32_e32 v94, v220, v107, vcc
	v_mul_f32_e64 v107, |v106|, -v147
	s_and_b64 s[14:15], s[8:9], s[14:15]
	v_fmac_f32_e32 v107, 0x3e000000, v95
	v_cndmask_b32_e64 v95, 0, 1, s[14:15]
	s_or_b64 vcc, s[8:9], s[16:17]
	v_cndmask_b32_e32 v95, v119, v95, vcc
	v_and_b32_e32 v95, 1, v95
	v_sub_f32_e32 v106, 0x42400000, v101
	v_cmp_eq_u32_e32 vcc, 1, v95
	v_cmp_le_f32_e64 s[14:15], |v106|, s71
	v_cmp_nle_f32_e64 s[16:17], |v106|, s71
	v_cndmask_b32_e32 v95, v220, v107, vcc
	v_mul_f32_e64 v107, |v106|, -v147
	s_and_b64 s[14:15], s[8:9], s[14:15]
	v_fmac_f32_e32 v107, 0x3e000000, v88
	v_cndmask_b32_e64 v88, 0, 1, s[14:15]
	s_or_b64 vcc, s[8:9], s[16:17]
	v_cndmask_b32_e32 v88, v119, v88, vcc
	v_and_b32_e32 v88, 1, v88
	v_sub_f32_e32 v106, 0x42440000, v101
	v_cmp_eq_u32_e32 vcc, 1, v88
	v_cmp_le_f32_e64 s[14:15], |v106|, s71
	v_cmp_nle_f32_e64 s[16:17], |v106|, s71
	v_cndmask_b32_e32 v88, v220, v107, vcc
	v_mul_f32_e64 v107, |v106|, -v147
	s_and_b64 s[14:15], s[8:9], s[14:15]
	v_fmac_f32_e32 v107, 0x3e000000, v89
	v_cndmask_b32_e64 v89, 0, 1, s[14:15]
	s_or_b64 vcc, s[8:9], s[16:17]
	v_cndmask_b32_e32 v89, v119, v89, vcc
	v_and_b32_e32 v89, 1, v89
	v_sub_f32_e32 v106, 0x42480000, v101
	v_cmp_eq_u32_e32 vcc, 1, v89
	v_cmp_le_f32_e64 s[14:15], |v106|, s71
	v_cmp_nle_f32_e64 s[16:17], |v106|, s71
	v_cndmask_b32_e32 v89, v220, v107, vcc
	v_mul_f32_e64 v107, |v106|, -v147
	s_and_b64 s[14:15], s[8:9], s[14:15]
	v_fmac_f32_e32 v107, 0x3e000000, v90
	v_cndmask_b32_e64 v90, 0, 1, s[14:15]
	s_or_b64 vcc, s[8:9], s[16:17]
	v_cndmask_b32_e32 v90, v119, v90, vcc
	v_and_b32_e32 v90, 1, v90
	v_sub_f32_e32 v106, 0x424c0000, v101
	v_cmp_eq_u32_e32 vcc, 1, v90
	v_cmp_le_f32_e64 s[14:15], |v106|, s71
	v_cmp_nle_f32_e64 s[16:17], |v106|, s71
	v_cndmask_b32_e32 v90, v220, v107, vcc
	v_mul_f32_e64 v107, |v106|, -v147
	s_and_b64 s[14:15], s[8:9], s[14:15]
	v_fmac_f32_e32 v107, 0x3e000000, v91
	v_cndmask_b32_e64 v91, 0, 1, s[14:15]
	s_or_b64 vcc, s[8:9], s[16:17]
	v_cndmask_b32_e32 v91, v119, v91, vcc
	v_and_b32_e32 v91, 1, v91
	v_sub_f32_e32 v106, 0x42800000, v101
	v_cmp_eq_u32_e32 vcc, 1, v91
	v_cmp_le_f32_e64 s[14:15], |v106|, s71
	v_cmp_nle_f32_e64 s[16:17], |v106|, s71
	v_cndmask_b32_e32 v91, v220, v107, vcc
	v_mul_f32_e64 v107, |v106|, -v147
	s_and_b64 s[14:15], s[8:9], s[14:15]
	v_fmac_f32_e32 v107, 0x3e000000, v84
	v_cndmask_b32_e64 v84, 0, 1, s[14:15]
	s_or_b64 vcc, s[8:9], s[16:17]
	v_cndmask_b32_e32 v84, v119, v84, vcc
	v_and_b32_e32 v84, 1, v84
	v_sub_f32_e32 v106, 0x42820000, v101
	v_cmp_eq_u32_e32 vcc, 1, v84
	v_cmp_le_f32_e64 s[14:15], |v106|, s71
	v_cmp_nle_f32_e64 s[16:17], |v106|, s71
	v_cndmask_b32_e32 v84, v220, v107, vcc
	v_mul_f32_e64 v107, |v106|, -v147
	s_and_b64 s[14:15], s[8:9], s[14:15]
	v_fmac_f32_e32 v107, 0x3e000000, v85
	v_cndmask_b32_e64 v85, 0, 1, s[14:15]
	s_or_b64 vcc, s[8:9], s[16:17]
	v_cndmask_b32_e32 v85, v119, v85, vcc
	v_and_b32_e32 v85, 1, v85
	v_sub_f32_e32 v106, 0x42840000, v101
	v_cmp_eq_u32_e32 vcc, 1, v85
	v_cmp_le_f32_e64 s[14:15], |v106|, s71
	v_cmp_nle_f32_e64 s[16:17], |v106|, s71
	v_cndmask_b32_e32 v85, v220, v107, vcc
	v_mul_f32_e64 v107, |v106|, -v147
	s_and_b64 s[14:15], s[8:9], s[14:15]
	v_fmac_f32_e32 v107, 0x3e000000, v86
	v_cndmask_b32_e64 v86, 0, 1, s[14:15]
	s_or_b64 vcc, s[8:9], s[16:17]
	v_cndmask_b32_e32 v86, v119, v86, vcc
	v_and_b32_e32 v86, 1, v86
	v_sub_f32_e32 v106, 0x42860000, v101
	v_cmp_eq_u32_e32 vcc, 1, v86
	v_cmp_le_f32_e64 s[14:15], |v106|, s71
	v_cmp_nle_f32_e64 s[16:17], |v106|, s71
	v_cndmask_b32_e32 v86, v220, v107, vcc
	v_mul_f32_e64 v107, |v106|, -v147
	s_and_b64 s[14:15], s[8:9], s[14:15]
	v_fmac_f32_e32 v107, 0x3e000000, v87
	v_cndmask_b32_e64 v87, 0, 1, s[14:15]
	s_or_b64 vcc, s[8:9], s[16:17]
	v_cndmask_b32_e32 v87, v119, v87, vcc
	v_and_b32_e32 v87, 1, v87
	v_sub_f32_e32 v106, 0x42a00000, v101
	v_cmp_eq_u32_e32 vcc, 1, v87
	v_cmp_le_f32_e64 s[14:15], |v106|, s71
	v_cmp_nle_f32_e64 s[16:17], |v106|, s71
	v_cndmask_b32_e32 v87, v220, v107, vcc
	v_mul_f32_e64 v107, |v106|, -v147
	s_and_b64 s[14:15], s[8:9], s[14:15]
	v_fmac_f32_e32 v107, 0x3e000000, v80
	v_cndmask_b32_e64 v80, 0, 1, s[14:15]
	s_or_b64 vcc, s[8:9], s[16:17]
	v_cndmask_b32_e32 v80, v119, v80, vcc
	v_and_b32_e32 v80, 1, v80
	v_sub_f32_e32 v106, 0x42a20000, v101
	v_cmp_eq_u32_e32 vcc, 1, v80
	v_cmp_le_f32_e64 s[14:15], |v106|, s71
	v_cmp_nle_f32_e64 s[16:17], |v106|, s71
	v_cndmask_b32_e32 v80, v220, v107, vcc
	v_mul_f32_e64 v107, |v106|, -v147
	s_and_b64 s[14:15], s[8:9], s[14:15]
	v_fmac_f32_e32 v107, 0x3e000000, v81
	v_cndmask_b32_e64 v81, 0, 1, s[14:15]
	s_or_b64 vcc, s[8:9], s[16:17]
	v_cndmask_b32_e32 v81, v119, v81, vcc
	v_and_b32_e32 v81, 1, v81
	v_sub_f32_e32 v106, 0x42a40000, v101
	v_cmp_eq_u32_e32 vcc, 1, v81
	v_cmp_le_f32_e64 s[14:15], |v106|, s71
	v_cmp_nle_f32_e64 s[16:17], |v106|, s71
	v_cndmask_b32_e32 v81, v220, v107, vcc
	v_mul_f32_e64 v107, |v106|, -v147
	s_and_b64 s[14:15], s[8:9], s[14:15]
	v_fmac_f32_e32 v107, 0x3e000000, v82
	v_cndmask_b32_e64 v82, 0, 1, s[14:15]
	s_or_b64 vcc, s[8:9], s[16:17]
	v_cndmask_b32_e32 v82, v119, v82, vcc
	v_and_b32_e32 v82, 1, v82
	v_sub_f32_e32 v106, 0x42a60000, v101
	v_cmp_eq_u32_e32 vcc, 1, v82
	v_cmp_le_f32_e64 s[14:15], |v106|, s71
	v_cmp_nle_f32_e64 s[16:17], |v106|, s71
	v_cndmask_b32_e32 v82, v220, v107, vcc
	v_mul_f32_e64 v107, |v106|, -v147
	s_and_b64 s[14:15], s[8:9], s[14:15]
; __device__ void attn_mfma(const Params& p, int l, const bf16_t* proj, bf16_t* y0, LAS unsigned char* lds) {
;     ...
;             const float tq = (float)(tl + 128 - 4 * g);
;             float mx = sink;
; #pragma unroll
;             for (int kt = 0; kt < 24; ++kt)
; #pragma unroll
;                 for (int r = 0; r < 4; ++r) { const float x = (float)(kt * 16 + r) - tq; float sc = fmaf(sacc[kt][r], 0.125f, -slope * fabsf(x));
;                     bool valid = fabsf(x) <= 128.0f;
;                     if (edge) { const int kl = kt * 16 + 4 * g + r; valid = valid && (n == 0 ? kl >= 128 : kl < 256); }
;                     sc = valid ? sc : -1e30f; sacc[kt][r] = sc; mx = fmaxf(mx, sc); }
	v_fmac_f32_e32 v107, 0x3e000000, v83
	v_cndmask_b32_e64 v83, 0, 1, s[14:15]
	s_or_b64 vcc, s[8:9], s[16:17]
	v_cndmask_b32_e32 v83, v119, v83, vcc
	v_and_b32_e32 v83, 1, v83
	v_sub_f32_e32 v106, 0x42c00000, v101
	v_cmp_eq_u32_e32 vcc, 1, v83
	v_cmp_le_f32_e64 s[14:15], |v106|, s71
	v_cmp_nle_f32_e64 s[16:17], |v106|, s71
	v_cndmask_b32_e32 v83, v220, v107, vcc
	v_mul_f32_e64 v107, |v106|, -v147
	s_and_b64 s[14:15], s[8:9], s[14:15]
	v_fmac_f32_e32 v107, 0x3e000000, v76
	v_cndmask_b32_e64 v76, 0, 1, s[14:15]
	s_or_b64 vcc, s[8:9], s[16:17]
	v_cndmask_b32_e32 v76, v119, v76, vcc
	v_and_b32_e32 v76, 1, v76
	v_sub_f32_e32 v106, 0x42c20000, v101
	v_cmp_eq_u32_e32 vcc, 1, v76
	v_cmp_le_f32_e64 s[14:15], |v106|, s71
	v_cmp_nle_f32_e64 s[16:17], |v106|, s71
	v_cndmask_b32_e32 v76, v220, v107, vcc
	v_mul_f32_e64 v107, |v106|, -v147
	s_and_b64 s[14:15], s[8:9], s[14:15]
	v_fmac_f32_e32 v107, 0x3e000000, v77
	v_cndmask_b32_e64 v77, 0, 1, s[14:15]
	s_or_b64 vcc, s[8:9], s[16:17]
	v_cndmask_b32_e32 v77, v119, v77, vcc
	v_and_b32_e32 v77, 1, v77
	v_sub_f32_e32 v106, 0x42c40000, v101
	v_cmp_eq_u32_e32 vcc, 1, v77
	v_cmp_le_f32_e64 s[14:15], |v106|, s71
	v_cmp_nle_f32_e64 s[16:17], |v106|, s71
	v_cndmask_b32_e32 v77, v220, v107, vcc
	v_mul_f32_e64 v107, |v106|, -v147
	s_and_b64 s[14:15], s[8:9], s[14:15]
	v_fmac_f32_e32 v107, 0x3e000000, v78
	v_cndmask_b32_e64 v78, 0, 1, s[14:15]
	s_or_b64 vcc, s[8:9], s[16:17]
	v_cndmask_b32_e32 v78, v119, v78, vcc
	v_and_b32_e32 v78, 1, v78
	v_sub_f32_e32 v106, 0x42c60000, v101
	v_cmp_eq_u32_e32 vcc, 1, v78
	v_cmp_le_f32_e64 s[14:15], |v106|, s71
	v_cmp_nle_f32_e64 s[16:17], |v106|, s71
	v_cndmask_b32_e32 v78, v220, v107, vcc
	v_mul_f32_e64 v107, |v106|, -v147
	s_and_b64 s[14:15], s[8:9], s[14:15]
	v_fmac_f32_e32 v107, 0x3e000000, v79
	v_cndmask_b32_e64 v79, 0, 1, s[14:15]
	s_or_b64 vcc, s[8:9], s[16:17]
	v_cndmask_b32_e32 v79, v119, v79, vcc
	v_max3_f32 v105, v105, v103, v104
	v_and_b32_e32 v79, 1, v79
	v_sub_f32_e32 v106, 0x42e00000, v101
	v_max3_f32 v105, v105, v96, v97
	v_cmp_eq_u32_e32 vcc, 1, v79
	v_cmp_le_f32_e64 s[14:15], |v106|, s71
	v_max3_f32 v105, v105, v98, v99
	v_cndmask_b32_e32 v79, v220, v107, vcc
	v_mul_f32_e64 v107, |v106|, -v147
	v_cmp_nle_f32_e64 s[16:17], |v106|, s71
	s_and_b64 s[14:15], s[8:9], s[14:15]
	v_max3_f32 v105, v105, v92, v93
	v_fmac_f32_e32 v107, 0x3e000000, v72
	v_cndmask_b32_e64 v72, 0, 1, s[14:15]
	s_or_b64 vcc, s[8:9], s[16:17]
	v_max3_f32 v105, v105, v94, v95
	v_cndmask_b32_e32 v72, v119, v72, vcc
	v_max3_f32 v105, v105, v88, v89
	v_and_b32_e32 v72, 1, v72
	v_sub_f32_e32 v106, 0x42e20000, v101
	v_max3_f32 v105, v105, v90, v91
	v_cmp_eq_u32_e32 vcc, 1, v72
	v_cmp_le_f32_e64 s[14:15], |v106|, s71
	v_max3_f32 v105, v105, v84, v85
	v_cndmask_b32_e32 v72, v220, v107, vcc
	v_mul_f32_e64 v107, |v106|, -v147
	v_cmp_nle_f32_e64 s[16:17], |v106|, s71
	s_and_b64 s[14:15], s[8:9], s[14:15]
	v_max3_f32 v105, v105, v86, v87
	v_fmac_f32_e32 v107, 0x3e000000, v73
	v_cndmask_b32_e64 v73, 0, 1, s[14:15]
	s_or_b64 vcc, s[8:9], s[16:17]
	v_max3_f32 v105, v105, v80, v81
	v_cndmask_b32_e32 v73, v119, v73, vcc
	v_max3_f32 v105, v105, v82, v83
	v_and_b32_e32 v73, 1, v73
	v_max3_f32 v105, v105, v76, v77
	v_cmp_eq_u32_e32 vcc, 1, v73
	v_max3_f32 v105, v105, v78, v79
	s_nop 0
	v_cndmask_b32_e32 v73, v220, v107, vcc
	v_max3_f32 v106, v105, v72, v73
	v_sub_f32_e32 v105, 0x42e40000, v101
	v_cmp_le_f32_e64 s[14:15], |v105|, s71
	v_mul_f32_e64 v107, |v105|, -v147
	v_cmp_nle_f32_e64 s[16:17], |v105|, s71
	s_and_b64 s[14:15], s[8:9], s[14:15]
	v_fmac_f32_e32 v107, 0x3e000000, v74
	v_cndmask_b32_e64 v74, 0, 1, s[14:15]
	s_or_b64 vcc, s[8:9], s[16:17]
	v_cndmask_b32_e32 v74, v119, v74, vcc
	v_and_b32_e32 v74, 1, v74
	v_cmp_eq_u32_e32 vcc, 1, v74
	v_sub_f32_e32 v74, 0x42e60000, v101
	v_cmp_le_f32_e64 s[14:15], |v74|, s71
	v_cmp_nle_f32_e64 s[16:17], |v74|, s71
	s_and_b64 s[14:15], s[8:9], s[14:15]
	v_cndmask_b32_e32 v105, v220, v107, vcc
	v_mul_f32_e64 v107, |v74|, -v147
	v_cndmask_b32_e64 v74, 0, 1, s[14:15]
	s_or_b64 vcc, s[8:9], s[16:17]
	v_cndmask_b32_e32 v74, v119, v74, vcc
	v_and_b32_e32 v74, 1, v74
	v_fmac_f32_e32 v107, 0x3e000000, v75
	v_cmp_eq_u32_e32 vcc, 1, v74
	v_sub_f32_e32 v75, 0x43000000, v101
	v_cndmask_b32_e64 v119, 0, 1, s[6:7]
	v_cndmask_b32_e32 v107, v220, v107, vcc
	v_max3_f32 v74, v106, v105, v107
	v_mul_f32_e64 v106, |v75|, -v147
	v_fmac_f32_e32 v106, 0x3e000000, v68
	v_sub_f32_e32 v68, 0x43010000, v101
	v_cmp_le_f32_e64 vcc, |v75|, s71
	v_mul_f32_e64 v75, |v68|, -v147
	v_fmac_f32_e32 v75, 0x3e000000, v69
	v_cndmask_b32_e32 v106, v220, v106, vcc
	v_cmp_le_f32_e64 vcc, |v68|, s71
	v_sub_f32_e32 v69, 0x43020000, v101
	s_nop 0
	v_cndmask_b32_e32 v75, v220, v75, vcc
	v_max3_f32 v68, v74, v106, v75
	v_mul_f32_e64 v74, |v69|, -v147
	v_cmp_le_f32_e64 vcc, |v69|, s71
	v_sub_f32_e32 v69, 0x43030000, v101
	v_fmac_f32_e32 v74, 0x3e000000, v70
	v_mul_f32_e64 v70, |v69|, -v147
	v_cndmask_b32_e32 v74, v220, v74, vcc
	v_fmac_f32_e32 v70, 0x3e000000, v71
	v_cmp_le_f32_e64 vcc, |v69|, s71
	v_sub_f32_e32 v69, 0x43100000, v101
	s_nop 0
	v_cndmask_b32_e32 v71, v220, v70, vcc
	v_mul_f32_e64 v70, |v69|, -v147
	v_fmac_f32_e32 v70, 0x3e000000, v64
	v_sub_f32_e32 v64, 0x43110000, v101
	v_cmp_le_f32_e64 vcc, |v69|, s71
	v_mul_f32_e64 v69, |v64|, -v147
	v_fmac_f32_e32 v69, 0x3e000000, v65
	v_cndmask_b32_e32 v70, v220, v70, vcc
	v_cmp_le_f32_e64 vcc, |v64|, s71
	v_max3_f32 v68, v68, v74, v71
	v_sub_f32_e32 v65, 0x43120000, v101
	v_cndmask_b32_e32 v69, v220, v69, vcc
	v_max3_f32 v64, v68, v70, v69
	v_mul_f32_e64 v68, |v65|, -v147
	v_cmp_le_f32_e64 vcc, |v65|, s71
	v_sub_f32_e32 v65, 0x43130000, v101
	v_fmac_f32_e32 v68, 0x3e000000, v66
; __device__ void attn_mfma(const Params& p, int l, const bf16_t* proj, bf16_t* y0, LAS unsigned char* lds) {
;     ...
;             const float tq = (float)(tl + 128 - 4 * g);
;             float mx = sink;
; #pragma unroll
;             for (int kt = 0; kt < 24; ++kt)
; #pragma unroll
;                 for (int r = 0; r < 4; ++r) { const float x = (float)(kt * 16 + r) - tq; float sc = fmaf(sacc[kt][r], 0.125f, -slope * fabsf(x));
;                     bool valid = fabsf(x) <= 128.0f;
;                     if (edge) { const int kl = kt * 16 + 4 * g + r; valid = valid && (n == 0 ? kl >= 128 : kl < 256); }
;                     sc = valid ? sc : -1e30f; sacc[kt][r] = sc; mx = fmaxf(mx, sc); }
	v_mul_f32_e64 v66, |v65|, -v147
	v_cndmask_b32_e32 v68, v220, v68, vcc
	v_fmac_f32_e32 v66, 0x3e000000, v67
	v_cmp_le_f32_e64 vcc, |v65|, s71
	v_sub_f32_e32 v65, 0x43200000, v101
	s_nop 0
	v_cndmask_b32_e32 v67, v220, v66, vcc
	v_mul_f32_e64 v66, |v65|, -v147
	v_fmac_f32_e32 v66, 0x3e000000, v60
	v_sub_f32_e32 v60, 0x43210000, v101
	v_cmp_le_f32_e64 vcc, |v65|, s71
	v_mul_f32_e64 v65, |v60|, -v147
	v_fmac_f32_e32 v65, 0x3e000000, v61
	v_cndmask_b32_e32 v66, v220, v66, vcc
	v_cmp_le_f32_e64 vcc, |v60|, s71
	v_max3_f32 v64, v64, v68, v67
	v_sub_f32_e32 v61, 0x43220000, v101
	v_cndmask_b32_e32 v65, v220, v65, vcc
	v_max3_f32 v60, v64, v66, v65
	v_mul_f32_e64 v64, |v61|, -v147
	v_cmp_le_f32_e64 vcc, |v61|, s71
	v_sub_f32_e32 v61, 0x43230000, v101
	v_fmac_f32_e32 v64, 0x3e000000, v62
	v_mul_f32_e64 v62, |v61|, -v147
	v_cndmask_b32_e32 v64, v220, v64, vcc
	v_fmac_f32_e32 v62, 0x3e000000, v63
	v_cmp_le_f32_e64 vcc, |v61|, s71
	v_sub_f32_e32 v61, 0x43300000, v101
	s_nop 0
	v_cndmask_b32_e32 v63, v220, v62, vcc
	v_mul_f32_e64 v62, |v61|, -v147
	v_fmac_f32_e32 v62, 0x3e000000, v56
	v_sub_f32_e32 v56, 0x43310000, v101
	v_cmp_le_f32_e64 vcc, |v61|, s71
	v_mul_f32_e64 v61, |v56|, -v147
	v_fmac_f32_e32 v61, 0x3e000000, v57
	v_cndmask_b32_e32 v62, v220, v62, vcc
	v_cmp_le_f32_e64 vcc, |v56|, s71
	v_max3_f32 v60, v60, v64, v63
	v_sub_f32_e32 v57, 0x43320000, v101
	v_cndmask_b32_e32 v61, v220, v61, vcc
	v_max3_f32 v56, v60, v62, v61
	v_mul_f32_e64 v60, |v57|, -v147
	v_cmp_le_f32_e64 vcc, |v57|, s71
	v_sub_f32_e32 v57, 0x43330000, v101
	v_fmac_f32_e32 v60, 0x3e000000, v58
	v_mul_f32_e64 v58, |v57|, -v147
	v_cndmask_b32_e32 v60, v220, v60, vcc
	v_fmac_f32_e32 v58, 0x3e000000, v59
	v_cmp_le_f32_e64 vcc, |v57|, s71
	v_sub_f32_e32 v57, 0x43400000, v101
	s_nop 0
	v_cndmask_b32_e32 v59, v220, v58, vcc
	v_mul_f32_e64 v58, |v57|, -v147
	v_fmac_f32_e32 v58, 0x3e000000, v52
	v_sub_f32_e32 v52, 0x43410000, v101
	v_cmp_le_f32_e64 vcc, |v57|, s71
	v_mul_f32_e64 v57, |v52|, -v147
	v_fmac_f32_e32 v57, 0x3e000000, v53
	v_cndmask_b32_e32 v58, v220, v58, vcc
	v_cmp_le_f32_e64 vcc, |v52|, s71
	v_max3_f32 v56, v56, v60, v59
	v_sub_f32_e32 v53, 0x43420000, v101
	v_cndmask_b32_e32 v57, v220, v57, vcc
	v_max3_f32 v52, v56, v58, v57
	v_mul_f32_e64 v56, |v53|, -v147
	v_cmp_le_f32_e64 vcc, |v53|, s71
	v_sub_f32_e32 v53, 0x43430000, v101
	v_fmac_f32_e32 v56, 0x3e000000, v54
	v_mul_f32_e64 v54, |v53|, -v147
	v_cndmask_b32_e32 v56, v220, v56, vcc
	v_fmac_f32_e32 v54, 0x3e000000, v55
	v_cmp_le_f32_e64 vcc, |v53|, s71
	v_sub_f32_e32 v53, 0x43500000, v101
	s_nop 0
	v_cndmask_b32_e32 v55, v220, v54, vcc
	v_mul_f32_e64 v54, |v53|, -v147
	v_fmac_f32_e32 v54, 0x3e000000, v48
	v_sub_f32_e32 v48, 0x43510000, v101
	v_cmp_le_f32_e64 vcc, |v53|, s71
	v_mul_f32_e64 v53, |v48|, -v147
	v_fmac_f32_e32 v53, 0x3e000000, v49
	v_cndmask_b32_e32 v54, v220, v54, vcc
	v_cmp_le_f32_e64 vcc, |v48|, s71
	v_max3_f32 v52, v52, v56, v55
	v_sub_f32_e32 v49, 0x43520000, v101
	v_cndmask_b32_e32 v53, v220, v53, vcc
	v_max3_f32 v48, v52, v54, v53
	v_mul_f32_e64 v52, |v49|, -v147
	v_cmp_le_f32_e64 vcc, |v49|, s71
	v_sub_f32_e32 v49, 0x43530000, v101
	v_fmac_f32_e32 v52, 0x3e000000, v50
	v_mul_f32_e64 v50, |v49|, -v147
	v_cndmask_b32_e32 v52, v220, v52, vcc
	v_fmac_f32_e32 v50, 0x3e000000, v51
	v_cmp_le_f32_e64 vcc, |v49|, s71
	v_sub_f32_e32 v49, 0x43600000, v101
	s_nop 0
	v_cndmask_b32_e32 v51, v220, v50, vcc
	v_mul_f32_e64 v50, |v49|, -v147
	v_fmac_f32_e32 v50, 0x3e000000, v44
	v_sub_f32_e32 v44, 0x43610000, v101
	v_cmp_le_f32_e64 vcc, |v49|, s71
	v_mul_f32_e64 v49, |v44|, -v147
	v_fmac_f32_e32 v49, 0x3e000000, v45
	v_cndmask_b32_e32 v50, v220, v50, vcc
	v_cmp_le_f32_e64 vcc, |v44|, s71
	v_max3_f32 v48, v48, v52, v51
	v_sub_f32_e32 v45, 0x43620000, v101
	v_cndmask_b32_e32 v49, v220, v49, vcc
	v_max3_f32 v44, v48, v50, v49
	v_mul_f32_e64 v48, |v45|, -v147
	v_cmp_le_f32_e64 vcc, |v45|, s71
	v_sub_f32_e32 v45, 0x43630000, v101
	v_fmac_f32_e32 v48, 0x3e000000, v46
	v_mul_f32_e64 v46, |v45|, -v147
	v_cndmask_b32_e32 v48, v220, v48, vcc
	v_fmac_f32_e32 v46, 0x3e000000, v47
	v_cmp_le_f32_e64 vcc, |v45|, s71
	s_nop 1
	v_cndmask_b32_e32 v46, v220, v46, vcc
	v_max3_f32 v47, v44, v48, v46
	v_sub_f32_e32 v44, 0x43700000, v101
	v_mul_f32_e64 v45, |v44|, -v147
	v_fmac_f32_e32 v45, 0x3e000000, v40
	v_sub_f32_e32 v40, 0x43710000, v101
	v_cmp_le_f32_e64 vcc, |v44|, s71
	v_mul_f32_e64 v44, |v40|, -v147
	v_fmac_f32_e32 v44, 0x3e000000, v41
	v_cndmask_b32_e32 v45, v220, v45, vcc
	v_cmp_le_f32_e64 vcc, |v40|, s71
	v_sub_f32_e32 v40, 0x43720000, v101
	v_mul_f32_e64 v41, |v40|, -v147
	v_cndmask_b32_e32 v44, v220, v44, vcc
	v_cmp_le_f32_e64 vcc, |v40|, s71
	v_sub_f32_e32 v40, 0x43730000, v101
	v_fmac_f32_e32 v41, 0x3e000000, v42
	v_mul_f32_e64 v42, |v40|, -v147
	v_cndmask_b32_e32 v41, v220, v41, vcc
	v_fmac_f32_e32 v42, 0x3e000000, v43
	v_cmp_le_f32_e64 vcc, |v40|, s71
	v_sub_f32_e32 v43, 0x43800000, v101
	v_max3_f32 v47, v47, v45, v44
	v_cndmask_b32_e32 v40, v220, v42, vcc
	v_cmp_le_f32_e64 s[14:15], |v43|, s71
	v_max3_f32 v42, v47, v41, v40
	v_mul_f32_e64 v47, |v43|, -v147
	v_cmp_nle_f32_e64 s[16:17], |v43|, s71
	s_and_b64 s[14:15], s[8:9], s[14:15]
	v_fmac_f32_e32 v47, 0x3e000000, v36
	v_cndmask_b32_e64 v36, 0, 1, s[14:15]
	s_or_b64 vcc, s[8:9], s[16:17]
	v_cndmask_b32_e32 v36, v119, v36, vcc
	v_and_b32_e32 v36, 1, v36
	v_sub_f32_e32 v43, 0x43808000, v101
	v_cmp_eq_u32_e32 vcc, 1, v36
	v_cmp_le_f32_e64 s[14:15], |v43|, s71
	v_cmp_nle_f32_e64 s[16:17], |v43|, s71
	v_cndmask_b32_e32 v36, v220, v47, vcc
	v_mul_f32_e64 v47, |v43|, -v147
	s_and_b64 s[14:15], s[8:9], s[14:15]
	v_fmac_f32_e32 v47, 0x3e000000, v37
	v_cndmask_b32_e64 v37, 0, 1, s[14:15]
; __device__ void attn_mfma(const Params& p, int l, const bf16_t* proj, bf16_t* y0, LAS unsigned char* lds) {
;     ...
;             const float tq = (float)(tl + 128 - 4 * g);
;             float mx = sink;
; #pragma unroll
;             for (int kt = 0; kt < 24; ++kt)
; #pragma unroll
;                 for (int r = 0; r < 4; ++r) { const float x = (float)(kt * 16 + r) - tq; float sc = fmaf(sacc[kt][r], 0.125f, -slope * fabsf(x));
;                     bool valid = fabsf(x) <= 128.0f;
;                     if (edge) { const int kl = kt * 16 + 4 * g + r; valid = valid && (n == 0 ? kl >= 128 : kl < 256); }
;                     sc = valid ? sc : -1e30f; sacc[kt][r] = sc; mx = fmaxf(mx, sc); }
	s_or_b64 vcc, s[8:9], s[16:17]
	v_cndmask_b32_e32 v37, v119, v37, vcc
	v_and_b32_e32 v37, 1, v37
	v_sub_f32_e32 v43, 0x43810000, v101
	v_cmp_eq_u32_e32 vcc, 1, v37
	v_cmp_le_f32_e64 s[14:15], |v43|, s71
	v_cmp_nle_f32_e64 s[16:17], |v43|, s71
	v_cndmask_b32_e32 v37, v220, v47, vcc
	v_mul_f32_e64 v47, |v43|, -v147
	s_and_b64 s[14:15], s[8:9], s[14:15]
	v_fmac_f32_e32 v47, 0x3e000000, v38
	v_cndmask_b32_e64 v38, 0, 1, s[14:15]
	s_or_b64 vcc, s[8:9], s[16:17]
	v_cndmask_b32_e32 v38, v119, v38, vcc
	v_and_b32_e32 v38, 1, v38
	v_sub_f32_e32 v43, 0x43818000, v101
	v_cmp_eq_u32_e32 vcc, 1, v38
	v_cmp_le_f32_e64 s[14:15], |v43|, s71
	v_cmp_nle_f32_e64 s[16:17], |v43|, s71
	v_cndmask_b32_e32 v38, v220, v47, vcc
	v_mul_f32_e64 v47, |v43|, -v147
	s_and_b64 s[14:15], s[8:9], s[14:15]
	v_fmac_f32_e32 v47, 0x3e000000, v39
	v_cndmask_b32_e64 v39, 0, 1, s[14:15]
	s_or_b64 vcc, s[8:9], s[16:17]
	v_cndmask_b32_e32 v39, v119, v39, vcc
	v_and_b32_e32 v39, 1, v39
	v_sub_f32_e32 v43, 0x43880000, v101
	v_cmp_eq_u32_e32 vcc, 1, v39
	v_cmp_le_f32_e64 s[14:15], |v43|, s71
	v_cmp_nle_f32_e64 s[16:17], |v43|, s71
	v_cndmask_b32_e32 v39, v220, v47, vcc
	v_mul_f32_e64 v47, |v43|, -v147
	s_and_b64 s[14:15], s[8:9], s[14:15]
	v_fmac_f32_e32 v47, 0x3e000000, v32
	v_cndmask_b32_e64 v32, 0, 1, s[14:15]
	s_or_b64 vcc, s[8:9], s[16:17]
	v_cndmask_b32_e32 v32, v119, v32, vcc
	v_and_b32_e32 v32, 1, v32
	v_sub_f32_e32 v43, 0x43888000, v101
	v_cmp_eq_u32_e32 vcc, 1, v32
	v_cmp_le_f32_e64 s[14:15], |v43|, s71
	v_cmp_nle_f32_e64 s[16:17], |v43|, s71
	v_cndmask_b32_e32 v32, v220, v47, vcc
	v_mul_f32_e64 v47, |v43|, -v147
	s_and_b64 s[14:15], s[8:9], s[14:15]
	v_fmac_f32_e32 v47, 0x3e000000, v33
	v_cndmask_b32_e64 v33, 0, 1, s[14:15]
	s_or_b64 vcc, s[8:9], s[16:17]
	v_cndmask_b32_e32 v33, v119, v33, vcc
	v_and_b32_e32 v33, 1, v33
	v_sub_f32_e32 v43, 0x43890000, v101
	v_cmp_eq_u32_e32 vcc, 1, v33
	v_cmp_le_f32_e64 s[14:15], |v43|, s71
	v_cmp_nle_f32_e64 s[16:17], |v43|, s71
	v_cndmask_b32_e32 v33, v220, v47, vcc
	v_mul_f32_e64 v47, |v43|, -v147
	s_and_b64 s[14:15], s[8:9], s[14:15]
	v_fmac_f32_e32 v47, 0x3e000000, v34
	v_cndmask_b32_e64 v34, 0, 1, s[14:15]
	s_or_b64 vcc, s[8:9], s[16:17]
	v_cndmask_b32_e32 v34, v119, v34, vcc
	v_and_b32_e32 v34, 1, v34
	v_sub_f32_e32 v43, 0x43898000, v101
	v_cmp_eq_u32_e32 vcc, 1, v34
	v_cmp_le_f32_e64 s[14:15], |v43|, s71
	v_cmp_nle_f32_e64 s[16:17], |v43|, s71
	v_cndmask_b32_e32 v34, v220, v47, vcc
	v_mul_f32_e64 v47, |v43|, -v147
	s_and_b64 s[14:15], s[8:9], s[14:15]
	v_fmac_f32_e32 v47, 0x3e000000, v35
	v_cndmask_b32_e64 v35, 0, 1, s[14:15]
	s_or_b64 vcc, s[8:9], s[16:17]
	v_cndmask_b32_e32 v35, v119, v35, vcc
	v_and_b32_e32 v35, 1, v35
	v_sub_f32_e32 v43, 0x43900000, v101
	v_cmp_eq_u32_e32 vcc, 1, v35
	v_cmp_le_f32_e64 s[14:15], |v43|, s71
	v_cmp_nle_f32_e64 s[16:17], |v43|, s71
	v_cndmask_b32_e32 v35, v220, v47, vcc
	v_mul_f32_e64 v47, |v43|, -v147
	s_and_b64 s[14:15], s[8:9], s[14:15]
	v_fmac_f32_e32 v47, 0x3e000000, v28
	v_cndmask_b32_e64 v28, 0, 1, s[14:15]
	s_or_b64 vcc, s[8:9], s[16:17]
	v_cndmask_b32_e32 v28, v119, v28, vcc
	v_and_b32_e32 v28, 1, v28
	v_sub_f32_e32 v43, 0x43908000, v101
	v_cmp_eq_u32_e32 vcc, 1, v28
	v_cmp_le_f32_e64 s[14:15], |v43|, s71
	v_cmp_nle_f32_e64 s[16:17], |v43|, s71
	v_cndmask_b32_e32 v28, v220, v47, vcc
	v_mul_f32_e64 v47, |v43|, -v147
	s_and_b64 s[14:15], s[8:9], s[14:15]
	v_fmac_f32_e32 v47, 0x3e000000, v29
	v_cndmask_b32_e64 v29, 0, 1, s[14:15]
	s_or_b64 vcc, s[8:9], s[16:17]
	v_cndmask_b32_e32 v29, v119, v29, vcc
	v_and_b32_e32 v29, 1, v29
	v_sub_f32_e32 v43, 0x43910000, v101
	v_cmp_eq_u32_e32 vcc, 1, v29
	v_cmp_le_f32_e64 s[14:15], |v43|, s71
	v_cmp_nle_f32_e64 s[16:17], |v43|, s71
	v_cndmask_b32_e32 v29, v220, v47, vcc
	v_mul_f32_e64 v47, |v43|, -v147
	s_and_b64 s[14:15], s[8:9], s[14:15]
	v_fmac_f32_e32 v47, 0x3e000000, v30
	v_cndmask_b32_e64 v30, 0, 1, s[14:15]
	s_or_b64 vcc, s[8:9], s[16:17]
	v_cndmask_b32_e32 v30, v119, v30, vcc
	v_and_b32_e32 v30, 1, v30
	v_sub_f32_e32 v43, 0x43918000, v101
	v_cmp_eq_u32_e32 vcc, 1, v30
	v_cmp_le_f32_e64 s[14:15], |v43|, s71
	v_cmp_nle_f32_e64 s[16:17], |v43|, s71
	v_cndmask_b32_e32 v30, v220, v47, vcc
	v_mul_f32_e64 v47, |v43|, -v147
	s_and_b64 s[14:15], s[8:9], s[14:15]
	v_fmac_f32_e32 v47, 0x3e000000, v31
	v_cndmask_b32_e64 v31, 0, 1, s[14:15]
	s_or_b64 vcc, s[8:9], s[16:17]
	v_cndmask_b32_e32 v31, v119, v31, vcc
	v_and_b32_e32 v31, 1, v31
	v_sub_f32_e32 v43, 0x43980000, v101
	v_cmp_eq_u32_e32 vcc, 1, v31
	v_cmp_le_f32_e64 s[14:15], |v43|, s71
	v_cmp_nle_f32_e64 s[16:17], |v43|, s71
	v_cndmask_b32_e32 v31, v220, v47, vcc
	v_mul_f32_e64 v47, |v43|, -v147
	s_and_b64 s[14:15], s[8:9], s[14:15]
	v_fmac_f32_e32 v47, 0x3e000000, v24
	v_cndmask_b32_e64 v24, 0, 1, s[14:15]
	s_or_b64 vcc, s[8:9], s[16:17]
	v_cndmask_b32_e32 v24, v119, v24, vcc
	v_and_b32_e32 v24, 1, v24
	v_sub_f32_e32 v43, 0x43988000, v101
	v_cmp_eq_u32_e32 vcc, 1, v24
	v_cmp_le_f32_e64 s[14:15], |v43|, s71
	v_cmp_nle_f32_e64 s[16:17], |v43|, s71
	v_cndmask_b32_e32 v24, v220, v47, vcc
	v_mul_f32_e64 v47, |v43|, -v147
	s_and_b64 s[14:15], s[8:9], s[14:15]
	v_fmac_f32_e32 v47, 0x3e000000, v25
	v_cndmask_b32_e64 v25, 0, 1, s[14:15]
	s_or_b64 vcc, s[8:9], s[16:17]
	v_cndmask_b32_e32 v25, v119, v25, vcc
	v_and_b32_e32 v25, 1, v25
	v_sub_f32_e32 v43, 0x43990000, v101
	v_cmp_eq_u32_e32 vcc, 1, v25
	v_cmp_le_f32_e64 s[14:15], |v43|, s71
	v_cmp_nle_f32_e64 s[16:17], |v43|, s71
	v_cndmask_b32_e32 v25, v220, v47, vcc
	v_mul_f32_e64 v47, |v43|, -v147
	s_and_b64 s[14:15], s[8:9], s[14:15]
	v_fmac_f32_e32 v47, 0x3e000000, v26
	v_cndmask_b32_e64 v26, 0, 1, s[14:15]
	s_or_b64 vcc, s[8:9], s[16:17]
; __device__ void attn_mfma(const Params& p, int l, const bf16_t* proj, bf16_t* y0, LAS unsigned char* lds) {
;     ...
;             const float tq = (float)(tl + 128 - 4 * g);
;             float mx = sink;
; #pragma unroll
;             for (int kt = 0; kt < 24; ++kt)
; #pragma unroll
;                 for (int r = 0; r < 4; ++r) { const float x = (float)(kt * 16 + r) - tq; float sc = fmaf(sacc[kt][r], 0.125f, -slope * fabsf(x));
;                     bool valid = fabsf(x) <= 128.0f;
;                     if (edge) { const int kl = kt * 16 + 4 * g + r; valid = valid && (n == 0 ? kl >= 128 : kl < 256); }
;                     sc = valid ? sc : -1e30f; sacc[kt][r] = sc; mx = fmaxf(mx, sc); }
	v_cndmask_b32_e32 v26, v119, v26, vcc
	v_and_b32_e32 v26, 1, v26
	v_sub_f32_e32 v43, 0x43998000, v101
	v_cmp_eq_u32_e32 vcc, 1, v26
	v_cmp_le_f32_e64 s[14:15], |v43|, s71
	v_cmp_nle_f32_e64 s[16:17], |v43|, s71
	v_cndmask_b32_e32 v26, v220, v47, vcc
	v_mul_f32_e64 v47, |v43|, -v147
	s_and_b64 s[14:15], s[8:9], s[14:15]
	v_fmac_f32_e32 v47, 0x3e000000, v27
	v_cndmask_b32_e64 v27, 0, 1, s[14:15]
	s_or_b64 vcc, s[8:9], s[16:17]
	v_cndmask_b32_e32 v27, v119, v27, vcc
	v_and_b32_e32 v27, 1, v27
	v_sub_f32_e32 v43, 0x43a00000, v101
	v_cmp_eq_u32_e32 vcc, 1, v27
	v_cmp_le_f32_e64 s[14:15], |v43|, s71
	v_cmp_nle_f32_e64 s[16:17], |v43|, s71
	v_cndmask_b32_e32 v27, v220, v47, vcc
	v_mul_f32_e64 v47, |v43|, -v147
	s_and_b64 s[14:15], s[8:9], s[14:15]
	v_fmac_f32_e32 v47, 0x3e000000, v20
	v_cndmask_b32_e64 v20, 0, 1, s[14:15]
	s_or_b64 vcc, s[8:9], s[16:17]
	v_cndmask_b32_e32 v20, v119, v20, vcc
	v_and_b32_e32 v20, 1, v20
	v_sub_f32_e32 v43, 0x43a08000, v101
	v_cmp_eq_u32_e32 vcc, 1, v20
	v_cmp_le_f32_e64 s[14:15], |v43|, s71
	v_cmp_nle_f32_e64 s[16:17], |v43|, s71
	v_cndmask_b32_e32 v20, v220, v47, vcc
	v_mul_f32_e64 v47, |v43|, -v147
	s_and_b64 s[14:15], s[8:9], s[14:15]
	v_fmac_f32_e32 v47, 0x3e000000, v21
	v_cndmask_b32_e64 v21, 0, 1, s[14:15]
	s_or_b64 vcc, s[8:9], s[16:17]
	v_cndmask_b32_e32 v21, v119, v21, vcc
	v_and_b32_e32 v21, 1, v21
	v_sub_f32_e32 v43, 0x43a10000, v101
	v_cmp_eq_u32_e32 vcc, 1, v21
	v_cmp_le_f32_e64 s[14:15], |v43|, s71
	v_cmp_nle_f32_e64 s[16:17], |v43|, s71
	v_cndmask_b32_e32 v21, v220, v47, vcc
	v_mul_f32_e64 v47, |v43|, -v147
	s_and_b64 s[14:15], s[8:9], s[14:15]
	v_fmac_f32_e32 v47, 0x3e000000, v22
	v_cndmask_b32_e64 v22, 0, 1, s[14:15]
	s_or_b64 vcc, s[8:9], s[16:17]
	v_cndmask_b32_e32 v22, v119, v22, vcc
	v_and_b32_e32 v22, 1, v22
	v_sub_f32_e32 v43, 0x43a18000, v101
	v_cmp_eq_u32_e32 vcc, 1, v22
	v_cmp_le_f32_e64 s[14:15], |v43|, s71
	v_cmp_nle_f32_e64 s[16:17], |v43|, s71
	v_cndmask_b32_e32 v22, v220, v47, vcc
	v_mul_f32_e64 v47, |v43|, -v147
	s_and_b64 s[14:15], s[8:9], s[14:15]
	v_fmac_f32_e32 v47, 0x3e000000, v23
	v_cndmask_b32_e64 v23, 0, 1, s[14:15]
	s_or_b64 vcc, s[8:9], s[16:17]
	v_cndmask_b32_e32 v23, v119, v23, vcc
	v_and_b32_e32 v23, 1, v23
	v_sub_f32_e32 v43, 0x43a80000, v101
	v_cmp_eq_u32_e32 vcc, 1, v23
	v_cmp_le_f32_e64 s[14:15], |v43|, s71
	v_cmp_nle_f32_e64 s[16:17], |v43|, s71
	v_cndmask_b32_e32 v23, v220, v47, vcc
	v_mul_f32_e64 v47, |v43|, -v147
	s_and_b64 s[14:15], s[8:9], s[14:15]
	v_fmac_f32_e32 v47, 0x3e000000, v16
	v_cndmask_b32_e64 v16, 0, 1, s[14:15]
	s_or_b64 vcc, s[8:9], s[16:17]
	v_cndmask_b32_e32 v16, v119, v16, vcc
	v_and_b32_e32 v16, 1, v16
	v_sub_f32_e32 v43, 0x43a88000, v101
	v_cmp_eq_u32_e32 vcc, 1, v16
	v_cmp_le_f32_e64 s[14:15], |v43|, s71
	v_cmp_nle_f32_e64 s[16:17], |v43|, s71
	v_cndmask_b32_e32 v16, v220, v47, vcc
	v_mul_f32_e64 v47, |v43|, -v147
	s_and_b64 s[14:15], s[8:9], s[14:15]
	v_fmac_f32_e32 v47, 0x3e000000, v17
	v_cndmask_b32_e64 v17, 0, 1, s[14:15]
	s_or_b64 vcc, s[8:9], s[16:17]
	v_cndmask_b32_e32 v17, v119, v17, vcc
	v_and_b32_e32 v17, 1, v17
	v_sub_f32_e32 v43, 0x43a90000, v101
	v_cmp_eq_u32_e32 vcc, 1, v17
	v_cmp_le_f32_e64 s[14:15], |v43|, s71
	v_cmp_nle_f32_e64 s[16:17], |v43|, s71
	v_cndmask_b32_e32 v17, v220, v47, vcc
	v_mul_f32_e64 v47, |v43|, -v147
	s_and_b64 s[14:15], s[8:9], s[14:15]
	v_fmac_f32_e32 v47, 0x3e000000, v18
	v_cndmask_b32_e64 v18, 0, 1, s[14:15]
	s_or_b64 vcc, s[8:9], s[16:17]
	v_cndmask_b32_e32 v18, v119, v18, vcc
	v_and_b32_e32 v18, 1, v18
	v_sub_f32_e32 v43, 0x43a98000, v101
	v_cmp_eq_u32_e32 vcc, 1, v18
	v_cmp_le_f32_e64 s[14:15], |v43|, s71
	v_cmp_nle_f32_e64 s[16:17], |v43|, s71
	v_cndmask_b32_e32 v18, v220, v47, vcc
	v_mul_f32_e64 v47, |v43|, -v147
	s_and_b64 s[14:15], s[8:9], s[14:15]
	v_fmac_f32_e32 v47, 0x3e000000, v19
	v_cndmask_b32_e64 v19, 0, 1, s[14:15]
	s_or_b64 vcc, s[8:9], s[16:17]
	v_cndmask_b32_e32 v19, v119, v19, vcc
	v_and_b32_e32 v19, 1, v19
	v_sub_f32_e32 v43, 0x43b00000, v101
	v_cmp_eq_u32_e32 vcc, 1, v19
	v_cmp_le_f32_e64 s[14:15], |v43|, s71
	v_cmp_nle_f32_e64 s[16:17], |v43|, s71
	v_cndmask_b32_e32 v19, v220, v47, vcc
	v_mul_f32_e64 v47, |v43|, -v147
	s_and_b64 s[14:15], s[8:9], s[14:15]
	v_fmac_f32_e32 v47, 0x3e000000, v12
	v_cndmask_b32_e64 v12, 0, 1, s[14:15]
	s_or_b64 vcc, s[8:9], s[16:17]
	v_cndmask_b32_e32 v12, v119, v12, vcc
	v_and_b32_e32 v12, 1, v12
	v_sub_f32_e32 v43, 0x43b08000, v101
	v_cmp_eq_u32_e32 vcc, 1, v12
	v_cmp_le_f32_e64 s[14:15], |v43|, s71
	v_cmp_nle_f32_e64 s[16:17], |v43|, s71
	v_cndmask_b32_e32 v12, v220, v47, vcc
	v_mul_f32_e64 v47, |v43|, -v147
	s_and_b64 s[14:15], s[8:9], s[14:15]
	v_fmac_f32_e32 v47, 0x3e000000, v13
	v_cndmask_b32_e64 v13, 0, 1, s[14:15]
	s_or_b64 vcc, s[8:9], s[16:17]
	v_cndmask_b32_e32 v13, v119, v13, vcc
	v_max3_f32 v42, v42, v36, v37
	v_and_b32_e32 v13, 1, v13
	v_sub_f32_e32 v43, 0x43b10000, v101
	v_max3_f32 v42, v42, v38, v39
	v_cmp_eq_u32_e32 vcc, 1, v13
	v_cmp_le_f32_e64 s[14:15], |v43|, s71
	v_max3_f32 v42, v42, v32, v33
	v_cndmask_b32_e32 v13, v220, v47, vcc
	v_mul_f32_e64 v47, |v43|, -v147
	v_cmp_nle_f32_e64 s[16:17], |v43|, s71
	s_and_b64 s[14:15], s[8:9], s[14:15]
	v_max3_f32 v42, v42, v34, v35
	v_fmac_f32_e32 v47, 0x3e000000, v14
	v_cndmask_b32_e64 v14, 0, 1, s[14:15]
	s_or_b64 vcc, s[8:9], s[16:17]
	v_max3_f32 v42, v42, v28, v29
	v_cndmask_b32_e32 v14, v119, v14, vcc
	v_max3_f32 v42, v42, v30, v31
	v_and_b32_e32 v14, 1, v14
	v_sub_f32_e32 v43, 0x43b18000, v101
	v_max3_f32 v42, v42, v24, v25
	v_cmp_eq_u32_e32 vcc, 1, v14
	v_cmp_le_f32_e64 s[14:15], |v43|, s71
	v_max3_f32 v42, v42, v26, v27
	v_cndmask_b32_e32 v14, v220, v47, vcc
	v_mul_f32_e64 v47, |v43|, -v147
; __device__ void attn_mfma(const Params& p, int l, const bf16_t* proj, bf16_t* y0, LAS unsigned char* lds) {
;     ...
;                 for (int r = 0; r < 4; ++r) { const float x = (float)(kt * 16 + r) - tq; float sc = fmaf(sacc[kt][r], 0.125f, -slope * fabsf(x));
;                     bool valid = fabsf(x) <= 128.0f;
;                     if (edge) { const int kl = kt * 16 + 4 * g + r; valid = valid && (n == 0 ? kl >= 128 : kl < 256); }
;                     sc = valid ? sc : -1e30f; sacc[kt][r] = sc; mx = fmaxf(mx, sc); }
;             mx = fmaxf(mx, __shfl_xor(mx, 16)); mx = fmaxf(mx, __shfl_xor(mx, 32));
;             float sum = 0.f; const float mxl = mx * 1.44269504f;
; #pragma unroll
;             for (int kt = 0; kt < 24; ++kt)
; #pragma unroll
;                 for (int r = 0; r < 4; ++r) { const float pr = exp2f(fmaf(sacc[kt][r], 1.44269504f, -mxl)); sacc[kt][r] = pr; sum += pr; }
	v_cmp_nle_f32_e64 s[16:17], |v43|, s71
	s_and_b64 s[14:15], s[8:9], s[14:15]
	v_max3_f32 v42, v42, v20, v21
	v_fmac_f32_e32 v47, 0x3e000000, v15
	v_cndmask_b32_e64 v15, 0, 1, s[14:15]
	s_or_b64 vcc, s[8:9], s[16:17]
	v_max3_f32 v42, v42, v22, v23
	v_cndmask_b32_e32 v15, v119, v15, vcc
	v_max3_f32 v42, v42, v16, v17
	v_and_b32_e32 v15, 1, v15
	v_max3_f32 v42, v42, v18, v19
	v_cmp_eq_u32_e32 vcc, 1, v15
	v_max3_f32 v42, v42, v12, v13
	s_nop 0
	v_cndmask_b32_e32 v15, v220, v47, vcc
	v_max3_f32 v47, v42, v14, v15
	v_sub_f32_e32 v42, 0x43b80000, v101
	v_cmp_le_f32_e64 s[14:15], |v42|, s71
	v_mul_f32_e64 v43, |v42|, -v147
	v_cmp_nle_f32_e64 s[16:17], |v42|, s71
	s_and_b64 s[14:15], s[8:9], s[14:15]
	v_fmac_f32_e32 v43, 0x3e000000, v8
	v_cndmask_b32_e64 v8, 0, 1, s[14:15]
	s_or_b64 vcc, s[8:9], s[16:17]
	v_cndmask_b32_e32 v8, v119, v8, vcc
	v_and_b32_e32 v8, 1, v8
	v_cmp_eq_u32_e32 vcc, 1, v8
	v_sub_f32_e32 v8, 0x43b88000, v101
	v_cmp_le_f32_e64 s[14:15], |v8|, s71
	v_cmp_nle_f32_e64 s[16:17], |v8|, s71
	s_and_b64 s[14:15], s[8:9], s[14:15]
	v_cndmask_b32_e32 v42, v220, v43, vcc
	v_mul_f32_e64 v43, |v8|, -v147
	v_cndmask_b32_e64 v8, 0, 1, s[14:15]
	s_or_b64 vcc, s[8:9], s[16:17]
	v_cndmask_b32_e32 v8, v119, v8, vcc
	v_fmac_f32_e32 v43, 0x3e000000, v9
	v_and_b32_e32 v8, 1, v8
	v_sub_f32_e32 v9, 0x43b90000, v101
	v_cmp_eq_u32_e32 vcc, 1, v8
	v_cmp_le_f32_e64 s[14:15], |v9|, s71
	v_cmp_nle_f32_e64 s[16:17], |v9|, s71
	v_cndmask_b32_e32 v43, v220, v43, vcc
	s_and_b64 s[14:15], s[8:9], s[14:15]
	v_max3_f32 v8, v47, v42, v43
	v_mul_f32_e64 v47, |v9|, -v147
	v_cndmask_b32_e64 v9, 0, 1, s[14:15]
	s_or_b64 vcc, s[8:9], s[16:17]
	v_cndmask_b32_e32 v9, v119, v9, vcc
	v_and_b32_e32 v9, 1, v9
	v_cmp_eq_u32_e32 vcc, 1, v9
	v_sub_f32_e32 v9, 0x43b98000, v101
	v_cmp_le_f32_e64 s[14:15], |v9|, s71
	v_fmac_f32_e32 v47, 0x3e000000, v10
	v_cmp_nle_f32_e64 s[16:17], |v9|, s71
	s_and_b64 s[14:15], s[8:9], s[14:15]
	v_cndmask_b32_e32 v10, v220, v47, vcc
	v_mul_f32_e64 v47, |v9|, -v147
	v_cndmask_b32_e64 v9, 0, 1, s[14:15]
	s_or_b64 vcc, s[8:9], s[16:17]
	v_cndmask_b32_e32 v9, v119, v9, vcc
	v_and_b32_e32 v9, 1, v9
	v_fmac_f32_e32 v47, 0x3e000000, v11
	v_cmp_eq_u32_e32 vcc, 1, v9
	s_nop 1
	v_cndmask_b32_e32 v47, v220, v47, vcc
	v_max3_f32 v8, v8, v10, v47
	v_mov_b32_e32 v9, v8
	s_waitcnt lgkmcnt(0)
	s_nop 1
	v_permlane16_swap_b32_e32 v9, v8
	v_max_f32_e32 v8, v8, v9
	v_mov_b32_e32 v9, v8
	s_waitcnt lgkmcnt(0)
	s_nop 1
	v_permlane32_swap_b32_e32 v9, v8
	v_max_f32_e32 v8, v8, v9
	v_mul_f32_e32 v119, 0xbfb8aa3b, v8
	v_fmamk_f32 v9, v100, 0x3fb8aa3b, v119
	v_cmp_gt_f32_e32 vcc, s65, v9
	v_fmamk_f32 v101, v103, 0x3fb8aa3b, v119
	v_fmamk_f32 v96, v96, 0x3fb8aa3b, v119
	v_cndmask_b32_e32 v11, 0, v218, vcc
	v_add_f32_e32 v9, v9, v11
	v_exp_f32_e32 v9, v9
	v_cndmask_b32_e32 v11, 0, v219, vcc
	v_fmamk_f32 v97, v97, 0x3fb8aa3b, v119
	v_fmamk_f32 v98, v98, 0x3fb8aa3b, v119
	v_ldexp_f32 v9, v9, v11
	v_fmamk_f32 v11, v102, 0x3fb8aa3b, v119
	v_cmp_gt_f32_e32 vcc, s65, v11
	v_fmamk_f32 v99, v99, 0x3fb8aa3b, v119
	v_fmamk_f32 v92, v92, 0x3fb8aa3b, v119
	v_cndmask_b32_e32 v100, 0, v218, vcc
	v_add_f32_e32 v11, v11, v100
	v_cndmask_b32_e32 v100, 0, v219, vcc
	v_cmp_gt_f32_e32 vcc, s65, v101
	v_exp_f32_e32 v11, v11
	v_fmamk_f32 v94, v94, 0x3fb8aa3b, v119
	v_cndmask_b32_e32 v102, 0, v218, vcc
	v_add_f32_e32 v101, v101, v102
	v_exp_f32_e32 v101, v101
	v_cndmask_b32_e32 v102, 0, v219, vcc
	v_ldexp_f32 v100, v11, v100
	v_add_f32_e32 v11, v9, v100
	v_ldexp_f32 v101, v101, v102
	v_fmamk_f32 v102, v104, 0x3fb8aa3b, v119
	v_cmp_gt_f32_e32 vcc, s65, v102
	v_add_f32_e32 v11, v101, v11
	v_fmamk_f32 v95, v95, 0x3fb8aa3b, v119
	v_cndmask_b32_e32 v103, 0, v218, vcc
	v_add_f32_e32 v102, v102, v103
	v_cndmask_b32_e32 v103, 0, v219, vcc
	v_cmp_gt_f32_e32 vcc, s65, v96
	v_exp_f32_e32 v102, v102
	v_fmamk_f32 v88, v88, 0x3fb8aa3b, v119
	v_cndmask_b32_e32 v104, 0, v218, vcc
	v_add_f32_e32 v96, v96, v104
	v_exp_f32_e32 v96, v96
	v_ldexp_f32 v102, v102, v103
	v_cndmask_b32_e32 v103, 0, v219, vcc
	v_cmp_gt_f32_e32 vcc, s65, v97
	v_ldexp_f32 v96, v96, v103
	v_add_f32_e32 v11, v102, v11
	v_cndmask_b32_e32 v103, 0, v218, vcc
	v_add_f32_e32 v97, v97, v103
	v_cndmask_b32_e32 v103, 0, v219, vcc
	v_cmp_gt_f32_e32 vcc, s65, v98
	v_exp_f32_e32 v97, v97
	v_add_f32_e32 v11, v96, v11
	v_cndmask_b32_e32 v104, 0, v218, vcc
	v_add_f32_e32 v98, v98, v104
	v_exp_f32_e32 v98, v98
	v_ldexp_f32 v97, v97, v103
	v_cndmask_b32_e32 v103, 0, v219, vcc
	v_cmp_gt_f32_e32 vcc, s65, v99
	v_ldexp_f32 v98, v98, v103
	v_add_f32_e32 v11, v97, v11
	v_cndmask_b32_e32 v103, 0, v218, vcc
	v_add_f32_e32 v99, v99, v103
	v_cndmask_b32_e32 v103, 0, v219, vcc
	v_cmp_gt_f32_e32 vcc, s65, v92
	v_exp_f32_e32 v99, v99
	v_add_f32_e32 v11, v98, v11
	v_cndmask_b32_e32 v104, 0, v218, vcc
	v_add_f32_e32 v92, v92, v104
	v_exp_f32_e32 v92, v92
	v_ldexp_f32 v99, v99, v103
	v_add_f32_e32 v103, v99, v11
	v_cndmask_b32_e32 v11, 0, v219, vcc
	v_ldexp_f32 v11, v92, v11
	v_fmamk_f32 v92, v93, 0x3fb8aa3b, v119
	v_cmp_gt_f32_e32 vcc, s65, v92
	v_add_f32_e32 v103, v11, v103
	v_fmamk_f32 v89, v89, 0x3fb8aa3b, v119
	v_cndmask_b32_e32 v93, 0, v218, vcc
	v_add_f32_e32 v92, v92, v93
	v_cndmask_b32_e32 v93, 0, v219, vcc
	v_cmp_gt_f32_e32 vcc, s65, v94
	v_exp_f32_e32 v92, v92
	v_fmamk_f32 v90, v90, 0x3fb8aa3b, v119
	v_cndmask_b32_e32 v104, 0, v218, vcc
	v_add_f32_e32 v94, v94, v104
	v_exp_f32_e32 v94, v94
	v_ldexp_f32 v92, v92, v93
	v_cndmask_b32_e32 v93, 0, v219, vcc
	v_add_f32_e32 v103, v92, v103
	v_ldexp_f32 v93, v94, v93
	v_cmp_gt_f32_e32 vcc, s65, v95
	v_add_f32_e32 v94, v93, v103
	v_fmamk_f32 v91, v91, 0x3fb8aa3b, v119
	v_cndmask_b32_e32 v103, 0, v218, vcc
; __device__ void attn_mfma(const Params& p, int l, const bf16_t* proj, bf16_t* y0, LAS unsigned char* lds) {
;     ...
;             float sum = 0.f; const float mxl = mx * 1.44269504f;
; #pragma unroll
;             for (int kt = 0; kt < 24; ++kt)
; #pragma unroll
;                 for (int r = 0; r < 4; ++r) { const float pr = exp2f(fmaf(sacc[kt][r], 1.44269504f, -mxl)); sacc[kt][r] = pr; sum += pr; }
	v_add_f32_e32 v95, v95, v103
	v_exp_f32_e32 v95, v95
	v_cndmask_b32_e32 v103, 0, v219, vcc
	v_cmp_gt_f32_e32 vcc, s65, v88
	v_fmamk_f32 v84, v84, 0x3fb8aa3b, v119
	v_fmamk_f32 v85, v85, 0x3fb8aa3b, v119
	v_cndmask_b32_e32 v104, 0, v218, vcc
	v_add_f32_e32 v88, v88, v104
	v_exp_f32_e32 v104, v88
	v_ldexp_f32 v88, v95, v103
	v_add_f32_e32 v95, v88, v94
	v_cndmask_b32_e32 v94, 0, v219, vcc
	v_cmp_gt_f32_e32 vcc, s65, v89
	v_ldexp_f32 v94, v104, v94
	v_fmamk_f32 v86, v86, 0x3fb8aa3b, v119
	v_cndmask_b32_e32 v103, 0, v218, vcc
	v_add_f32_e32 v89, v89, v103
	v_cndmask_b32_e32 v103, 0, v219, vcc
	v_cmp_gt_f32_e32 vcc, s65, v90
	v_exp_f32_e32 v89, v89
	v_fmamk_f32 v87, v87, 0x3fb8aa3b, v119
	v_cndmask_b32_e32 v104, 0, v218, vcc
	v_add_f32_e32 v90, v90, v104
	v_exp_f32_e32 v90, v90
	v_ldexp_f32 v89, v89, v103
	v_cndmask_b32_e32 v103, 0, v219, vcc
	v_cmp_gt_f32_e32 vcc, s65, v91
	v_ldexp_f32 v90, v90, v103
	v_fmamk_f32 v80, v80, 0x3fb8aa3b, v119
	v_cndmask_b32_e32 v103, 0, v218, vcc
	v_add_f32_e32 v91, v91, v103
	v_cndmask_b32_e32 v103, 0, v219, vcc
	v_cmp_gt_f32_e32 vcc, s65, v84
	v_exp_f32_e32 v91, v91
	v_fmamk_f32 v81, v81, 0x3fb8aa3b, v119
	v_cndmask_b32_e32 v104, 0, v218, vcc
	v_add_f32_e32 v84, v84, v104
	v_exp_f32_e32 v84, v84
	v_ldexp_f32 v91, v91, v103
	v_cndmask_b32_e32 v103, 0, v219, vcc
	v_cmp_gt_f32_e32 vcc, s65, v85
	v_ldexp_f32 v84, v84, v103
	v_add_f32_e32 v95, v94, v95
	v_cndmask_b32_e32 v103, 0, v218, vcc
	v_add_f32_e32 v85, v85, v103
	v_exp_f32_e32 v85, v85
	v_cndmask_b32_e32 v103, 0, v219, vcc
	v_cmp_gt_f32_e32 vcc, s65, v86
	v_add_f32_e32 v95, v89, v95
	v_fmamk_f32 v82, v82, 0x3fb8aa3b, v119
	v_cndmask_b32_e32 v104, 0, v218, vcc
	v_add_f32_e32 v86, v86, v104
	v_exp_f32_e32 v104, v86
	v_ldexp_f32 v86, v85, v103
	v_cndmask_b32_e32 v85, 0, v219, vcc
	v_cmp_gt_f32_e32 vcc, s65, v87
	v_ldexp_f32 v85, v104, v85
	v_add_f32_e32 v95, v90, v95
	v_cndmask_b32_e32 v103, 0, v218, vcc
	v_add_f32_e32 v87, v87, v103
	v_exp_f32_e32 v87, v87
	v_cndmask_b32_e32 v103, 0, v219, vcc
	v_cmp_gt_f32_e32 vcc, s65, v80
	v_add_f32_e32 v95, v91, v95
	v_add_f32_e32 v95, v84, v95
	v_cndmask_b32_e32 v104, 0, v218, vcc
	v_add_f32_e32 v80, v80, v104
	v_exp_f32_e32 v104, v80
	v_ldexp_f32 v80, v87, v103
	v_cndmask_b32_e32 v87, 0, v219, vcc
	v_cmp_gt_f32_e32 vcc, s65, v81
	v_ldexp_f32 v87, v104, v87
	v_add_f32_e32 v95, v86, v95
	v_cndmask_b32_e32 v103, 0, v218, vcc
	v_add_f32_e32 v81, v81, v103
	v_cndmask_b32_e32 v103, 0, v219, vcc
	v_cmp_gt_f32_e32 vcc, s65, v82
	v_exp_f32_e32 v81, v81
	v_add_f32_e32 v95, v85, v95
	v_cndmask_b32_e32 v104, 0, v218, vcc
	v_add_f32_e32 v82, v82, v104
	v_exp_f32_e32 v82, v82
	v_add_f32_e32 v95, v80, v95
	v_add_f32_e32 v95, v87, v95
	v_ldexp_f32 v81, v81, v103
	v_cndmask_b32_e32 v103, 0, v219, vcc
	v_fmamk_f32 v83, v83, 0x3fb8aa3b, v119
	v_add_f32_e32 v95, v81, v95
	v_ldexp_f32 v82, v82, v103
	v_cmp_gt_f32_e32 vcc, s65, v83
	v_add_f32_e32 v103, v82, v95
	v_fmamk_f32 v76, v76, 0x3fb8aa3b, v119
	v_cndmask_b32_e32 v95, 0, v218, vcc
	v_add_f32_e32 v83, v83, v95
	v_cndmask_b32_e32 v95, 0, v219, vcc
	v_cmp_gt_f32_e32 vcc, s65, v76
	v_exp_f32_e32 v83, v83
	v_fmamk_f32 v77, v77, 0x3fb8aa3b, v119
	v_cndmask_b32_e32 v104, 0, v218, vcc
	v_add_f32_e32 v76, v76, v104
	v_exp_f32_e32 v76, v76
	v_ldexp_f32 v95, v83, v95
	v_add_f32_e32 v83, v95, v103
	v_cndmask_b32_e32 v103, 0, v219, vcc
	v_cmp_gt_f32_e32 vcc, s65, v77
	v_ldexp_f32 v76, v76, v103
	v_fmamk_f32 v78, v78, 0x3fb8aa3b, v119
	v_cndmask_b32_e32 v103, 0, v218, vcc
	v_add_f32_e32 v77, v77, v103
	v_cndmask_b32_e32 v103, 0, v219, vcc
	v_cmp_gt_f32_e32 vcc, s65, v78
	v_exp_f32_e32 v77, v77
	v_fmamk_f32 v79, v79, 0x3fb8aa3b, v119
	v_cndmask_b32_e32 v104, 0, v218, vcc
	v_add_f32_e32 v78, v78, v104
	v_exp_f32_e32 v78, v78
	v_ldexp_f32 v77, v77, v103
	v_cndmask_b32_e32 v103, 0, v219, vcc
	v_cmp_gt_f32_e32 vcc, s65, v79
	v_ldexp_f32 v78, v78, v103
	v_fmamk_f32 v72, v72, 0x3fb8aa3b, v119
	v_cndmask_b32_e32 v103, 0, v218, vcc
	v_add_f32_e32 v79, v79, v103
	v_cndmask_b32_e32 v103, 0, v219, vcc
	v_cmp_gt_f32_e32 vcc, s65, v72
	v_exp_f32_e32 v79, v79
	v_add_f32_e32 v83, v76, v83
	v_cndmask_b32_e32 v104, 0, v218, vcc
	v_add_f32_e32 v72, v72, v104
	v_exp_f32_e32 v72, v72
	v_add_f32_e32 v83, v77, v83
	v_add_f32_e32 v83, v78, v83
	v_ldexp_f32 v79, v79, v103
	v_add_f32_e32 v103, v79, v83
	v_cndmask_b32_e32 v83, 0, v219, vcc
	v_fmamk_f32 v73, v73, 0x3fb8aa3b, v119
	v_ldexp_f32 v83, v72, v83
	v_cmp_gt_f32_e32 vcc, s65, v73
	v_add_f32_e32 v72, v83, v103
	v_fmamk_f32 v104, v105, 0x3fb8aa3b, v119
	v_cndmask_b32_e32 v103, 0, v218, vcc
	v_add_f32_e32 v73, v73, v103
	v_cndmask_b32_e32 v103, 0, v219, vcc
	v_cmp_gt_f32_e32 vcc, s65, v104
	v_exp_f32_e32 v73, v73
	v_fmamk_f32 v106, v106, 0x3fb8aa3b, v119
	v_cndmask_b32_e32 v105, 0, v218, vcc
	v_add_f32_e32 v104, v104, v105
	v_exp_f32_e32 v104, v104
	v_ldexp_f32 v103, v73, v103
	v_cndmask_b32_e32 v73, 0, v219, vcc
	v_add_f32_e32 v72, v103, v72
	v_ldexp_f32 v104, v104, v73
	v_fmamk_f32 v73, v107, 0x3fb8aa3b, v119
	v_cmp_gt_f32_e32 vcc, s65, v73
	v_add_f32_e32 v72, v104, v72
	v_fmamk_f32 v75, v75, 0x3fb8aa3b, v119
	v_cndmask_b32_e32 v105, 0, v218, vcc
	v_add_f32_e32 v73, v73, v105
	v_cndmask_b32_e32 v105, 0, v219, vcc
	v_cmp_gt_f32_e32 vcc, s65, v106
	v_exp_f32_e32 v73, v73
	v_fmamk_f32 v74, v74, 0x3fb8aa3b, v119
	v_cndmask_b32_e32 v107, 0, v218, vcc
	v_add_f32_e32 v106, v106, v107
	v_exp_f32_e32 v106, v106
	v_ldexp_f32 v105, v73, v105
	v_add_f32_e32 v73, v105, v72
	v_cndmask_b32_e32 v72, 0, v219, vcc
	v_cmp_gt_f32_e32 vcc, s65, v75
	v_ldexp_f32 v72, v106, v72
	v_add_f32_e32 v73, v72, v73
	v_cndmask_b32_e32 v106, 0, v218, vcc
	v_add_f32_e32 v75, v75, v106
	v_exp_f32_e32 v75, v75
; __device__ void attn_mfma(const Params& p, int l, const bf16_t* proj, bf16_t* y0, LAS unsigned char* lds) {
;     ...
;             float sum = 0.f; const float mxl = mx * 1.44269504f;
; #pragma unroll
;             for (int kt = 0; kt < 24; ++kt)
; #pragma unroll
;                 for (int r = 0; r < 4; ++r) { const float pr = exp2f(fmaf(sacc[kt][r], 1.44269504f, -mxl)); sacc[kt][r] = pr; sum += pr; }
	v_cndmask_b32_e32 v106, 0, v219, vcc
	v_cmp_gt_f32_e32 vcc, s65, v74
	v_fmamk_f32 v71, v71, 0x3fb8aa3b, v119
	v_fmamk_f32 v70, v70, 0x3fb8aa3b, v119
	v_cndmask_b32_e32 v107, 0, v218, vcc
	v_add_f32_e32 v74, v74, v107
	v_exp_f32_e32 v107, v74
	v_ldexp_f32 v74, v75, v106
	v_add_f32_e32 v75, v74, v73
	v_cndmask_b32_e32 v73, 0, v219, vcc
	v_cmp_gt_f32_e32 vcc, s65, v71
	v_ldexp_f32 v73, v107, v73
	v_fmamk_f32 v69, v69, 0x3fb8aa3b, v119
	v_cndmask_b32_e32 v106, 0, v218, vcc
	v_add_f32_e32 v71, v71, v106
	v_exp_f32_e32 v71, v71
	v_cndmask_b32_e32 v106, 0, v219, vcc
	v_cmp_gt_f32_e32 vcc, s65, v70
	v_fmamk_f32 v68, v68, 0x3fb8aa3b, v119
	v_fmamk_f32 v67, v67, 0x3fb8aa3b, v119
	v_cndmask_b32_e32 v107, 0, v218, vcc
	v_add_f32_e32 v70, v70, v107
	v_exp_f32_e32 v107, v70
	v_ldexp_f32 v70, v71, v106
	v_cndmask_b32_e32 v71, 0, v219, vcc
	v_cmp_gt_f32_e32 vcc, s65, v69
	v_ldexp_f32 v71, v107, v71
	v_fmamk_f32 v66, v66, 0x3fb8aa3b, v119
	v_cndmask_b32_e32 v106, 0, v218, vcc
	v_add_f32_e32 v69, v69, v106
	v_exp_f32_e32 v69, v69
	v_cndmask_b32_e32 v106, 0, v219, vcc
	v_cmp_gt_f32_e32 vcc, s65, v68
	v_fmamk_f32 v65, v65, 0x3fb8aa3b, v119
	v_fmamk_f32 v64, v64, 0x3fb8aa3b, v119
	v_cndmask_b32_e32 v107, 0, v218, vcc
	v_add_f32_e32 v68, v68, v107
	v_exp_f32_e32 v107, v68
	v_ldexp_f32 v68, v69, v106
	v_cndmask_b32_e32 v69, 0, v219, vcc
	v_cmp_gt_f32_e32 vcc, s65, v67
	v_ldexp_f32 v69, v107, v69
	v_fmamk_f32 v63, v63, 0x3fb8aa3b, v119
	v_cndmask_b32_e32 v106, 0, v218, vcc
	v_add_f32_e32 v67, v67, v106
	v_cndmask_b32_e32 v106, 0, v219, vcc
	v_cmp_gt_f32_e32 vcc, s65, v66
	v_exp_f32_e32 v67, v67
	v_fmamk_f32 v62, v62, 0x3fb8aa3b, v119
	v_cndmask_b32_e32 v107, 0, v218, vcc
	v_add_f32_e32 v66, v66, v107
	v_exp_f32_e32 v66, v66
	v_ldexp_f32 v67, v67, v106
	v_cndmask_b32_e32 v106, 0, v219, vcc
	v_cmp_gt_f32_e32 vcc, s65, v65
	v_ldexp_f32 v66, v66, v106
	v_fmamk_f32 v61, v61, 0x3fb8aa3b, v119
	v_cndmask_b32_e32 v106, 0, v218, vcc
	v_add_f32_e32 v65, v65, v106
	v_exp_f32_e32 v65, v65
	v_cndmask_b32_e32 v106, 0, v219, vcc
	v_cmp_gt_f32_e32 vcc, s65, v64
	v_fmamk_f32 v60, v60, 0x3fb8aa3b, v119
	v_fmamk_f32 v59, v59, 0x3fb8aa3b, v119
	v_cndmask_b32_e32 v107, 0, v218, vcc
	v_add_f32_e32 v64, v64, v107
	v_exp_f32_e32 v107, v64
	v_ldexp_f32 v64, v65, v106
	v_cndmask_b32_e32 v65, 0, v219, vcc
	v_cmp_gt_f32_e32 vcc, s65, v63
	v_ldexp_f32 v65, v107, v65
	v_fmamk_f32 v58, v58, 0x3fb8aa3b, v119
	v_cndmask_b32_e32 v106, 0, v218, vcc
	v_add_f32_e32 v63, v63, v106
	v_exp_f32_e32 v63, v63
	v_cndmask_b32_e32 v106, 0, v219, vcc
	v_cmp_gt_f32_e32 vcc, s65, v62
	v_fmamk_f32 v57, v57, 0x3fb8aa3b, v119
	v_fmamk_f32 v56, v56, 0x3fb8aa3b, v119
	v_cndmask_b32_e32 v107, 0, v218, vcc
	v_add_f32_e32 v62, v62, v107
	v_exp_f32_e32 v107, v62
	v_ldexp_f32 v62, v63, v106
	v_cndmask_b32_e32 v63, 0, v219, vcc
	v_cmp_gt_f32_e32 vcc, s65, v61
	v_ldexp_f32 v63, v107, v63
	v_fmamk_f32 v55, v55, 0x3fb8aa3b, v119
	v_cndmask_b32_e32 v106, 0, v218, vcc
	v_add_f32_e32 v61, v61, v106
	v_exp_f32_e32 v61, v61
	v_cndmask_b32_e32 v106, 0, v219, vcc
	v_cmp_gt_f32_e32 vcc, s65, v60
	v_fmamk_f32 v54, v54, 0x3fb8aa3b, v119
	v_fmamk_f32 v53, v53, 0x3fb8aa3b, v119
	v_cndmask_b32_e32 v107, 0, v218, vcc
	v_add_f32_e32 v60, v60, v107
	v_exp_f32_e32 v107, v60
	v_ldexp_f32 v60, v61, v106
	v_cndmask_b32_e32 v61, 0, v219, vcc
	v_cmp_gt_f32_e32 vcc, s65, v59
	v_ldexp_f32 v61, v107, v61
	v_fmamk_f32 v52, v52, 0x3fb8aa3b, v119
	v_cndmask_b32_e32 v106, 0, v218, vcc
	v_add_f32_e32 v59, v59, v106
	v_cndmask_b32_e32 v106, 0, v219, vcc
	v_cmp_gt_f32_e32 vcc, s65, v58
	v_exp_f32_e32 v59, v59
	v_fmamk_f32 v51, v51, 0x3fb8aa3b, v119
	v_cndmask_b32_e32 v107, 0, v218, vcc
	v_add_f32_e32 v58, v58, v107
	v_exp_f32_e32 v58, v58
	v_ldexp_f32 v59, v59, v106
	v_cndmask_b32_e32 v106, 0, v219, vcc
	v_cmp_gt_f32_e32 vcc, s65, v57
	v_ldexp_f32 v58, v58, v106
	v_fmamk_f32 v50, v50, 0x3fb8aa3b, v119
	v_cndmask_b32_e32 v106, 0, v218, vcc
	v_add_f32_e32 v57, v57, v106
	v_cndmask_b32_e32 v106, 0, v219, vcc
	v_cmp_gt_f32_e32 vcc, s65, v56
	v_exp_f32_e32 v57, v57
	v_fmamk_f32 v49, v49, 0x3fb8aa3b, v119
	v_cndmask_b32_e32 v107, 0, v218, vcc
	v_add_f32_e32 v56, v56, v107
	v_exp_f32_e32 v56, v56
	v_ldexp_f32 v57, v57, v106
	v_cndmask_b32_e32 v106, 0, v219, vcc
	v_cmp_gt_f32_e32 vcc, s65, v55
	v_ldexp_f32 v56, v56, v106
	v_fmamk_f32 v48, v48, 0x3fb8aa3b, v119
	v_cndmask_b32_e32 v106, 0, v218, vcc
	v_add_f32_e32 v55, v55, v106
	v_exp_f32_e32 v55, v55
	v_cndmask_b32_e32 v106, 0, v219, vcc
	v_cmp_gt_f32_e32 vcc, s65, v54
	v_fmamk_f32 v46, v46, 0x3fb8aa3b, v119
	v_fmamk_f32 v45, v45, 0x3fb8aa3b, v119
	v_cndmask_b32_e32 v107, 0, v218, vcc
	v_add_f32_e32 v54, v54, v107
	v_exp_f32_e32 v107, v54
	v_ldexp_f32 v54, v55, v106
	v_cndmask_b32_e32 v55, 0, v219, vcc
	v_cmp_gt_f32_e32 vcc, s65, v53
	v_ldexp_f32 v55, v107, v55
	v_fmamk_f32 v44, v44, 0x3fb8aa3b, v119
	v_cndmask_b32_e32 v106, 0, v218, vcc
	v_add_f32_e32 v53, v53, v106
	v_exp_f32_e32 v53, v53
	v_cndmask_b32_e32 v106, 0, v219, vcc
	v_cmp_gt_f32_e32 vcc, s65, v52
	v_fmamk_f32 v41, v41, 0x3fb8aa3b, v119
	v_fmamk_f32 v40, v40, 0x3fb8aa3b, v119
	v_cndmask_b32_e32 v107, 0, v218, vcc
	v_add_f32_e32 v52, v52, v107
	v_exp_f32_e32 v107, v52
	v_ldexp_f32 v52, v53, v106
	v_cndmask_b32_e32 v53, 0, v219, vcc
	v_cmp_gt_f32_e32 vcc, s65, v51
	v_ldexp_f32 v53, v107, v53
	v_fmamk_f32 v36, v36, 0x3fb8aa3b, v119
	v_cndmask_b32_e32 v106, 0, v218, vcc
	v_add_f32_e32 v51, v51, v106
	v_cndmask_b32_e32 v106, 0, v219, vcc
	v_cmp_gt_f32_e32 vcc, s65, v50
	v_exp_f32_e32 v51, v51
	v_fmamk_f32 v37, v37, 0x3fb8aa3b, v119
	v_cndmask_b32_e32 v107, 0, v218, vcc
	v_add_f32_e32 v50, v50, v107
	v_exp_f32_e32 v50, v50
	v_ldexp_f32 v51, v51, v106
; __device__ void attn_mfma(const Params& p, int l, const bf16_t* proj, bf16_t* y0, LAS unsigned char* lds) {
;     ...
;             float sum = 0.f; const float mxl = mx * 1.44269504f;
; #pragma unroll
;             for (int kt = 0; kt < 24; ++kt)
; #pragma unroll
;                 for (int r = 0; r < 4; ++r) { const float pr = exp2f(fmaf(sacc[kt][r], 1.44269504f, -mxl)); sacc[kt][r] = pr; sum += pr; }
	v_cndmask_b32_e32 v106, 0, v219, vcc
	v_cmp_gt_f32_e32 vcc, s65, v49
	v_ldexp_f32 v50, v50, v106
	v_fmamk_f32 v38, v38, 0x3fb8aa3b, v119
	v_cndmask_b32_e32 v106, 0, v218, vcc
	v_add_f32_e32 v49, v49, v106
	v_exp_f32_e32 v49, v49
	v_cndmask_b32_e32 v106, 0, v219, vcc
	v_cmp_gt_f32_e32 vcc, s65, v48
	v_fmamk_f32 v39, v39, 0x3fb8aa3b, v119
	v_fmamk_f32 v32, v32, 0x3fb8aa3b, v119
	v_cndmask_b32_e32 v107, 0, v218, vcc
	v_add_f32_e32 v48, v48, v107
	v_exp_f32_e32 v107, v48
	v_ldexp_f32 v48, v49, v106
	v_cndmask_b32_e32 v49, 0, v219, vcc
	v_cmp_gt_f32_e32 vcc, s65, v46
	v_ldexp_f32 v49, v107, v49
	v_fmamk_f32 v33, v33, 0x3fb8aa3b, v119
	v_cndmask_b32_e32 v106, 0, v218, vcc
	v_add_f32_e32 v46, v46, v106
	v_exp_f32_e32 v46, v46
	v_cndmask_b32_e32 v106, 0, v219, vcc
	v_cmp_gt_f32_e32 vcc, s65, v45
	v_fmamk_f32 v34, v34, 0x3fb8aa3b, v119
	v_fmamk_f32 v35, v35, 0x3fb8aa3b, v119
	v_cndmask_b32_e32 v107, 0, v218, vcc
	v_add_f32_e32 v45, v45, v107
	v_exp_f32_e32 v107, v45
	v_ldexp_f32 v45, v46, v106
	v_cndmask_b32_e32 v46, 0, v219, vcc
	v_cmp_gt_f32_e32 vcc, s65, v44
	v_ldexp_f32 v46, v107, v46
	v_fmamk_f32 v28, v28, 0x3fb8aa3b, v119
	v_cndmask_b32_e32 v106, 0, v218, vcc
	v_add_f32_e32 v44, v44, v106
	v_exp_f32_e32 v44, v44
	v_cndmask_b32_e32 v106, 0, v219, vcc
	v_cmp_gt_f32_e32 vcc, s65, v41
	v_fmamk_f32 v29, v29, 0x3fb8aa3b, v119
	v_fmamk_f32 v30, v30, 0x3fb8aa3b, v119
	v_cndmask_b32_e32 v107, 0, v218, vcc
	v_add_f32_e32 v41, v41, v107
	v_exp_f32_e32 v107, v41
	v_ldexp_f32 v41, v44, v106
	v_cndmask_b32_e32 v44, 0, v219, vcc
	v_cmp_gt_f32_e32 vcc, s65, v40
	v_ldexp_f32 v44, v107, v44
	v_add_f32_e32 v75, v73, v75
	v_cndmask_b32_e32 v106, 0, v218, vcc
	v_add_f32_e32 v40, v40, v106
	v_cndmask_b32_e32 v106, 0, v219, vcc
	v_cmp_gt_f32_e32 vcc, s65, v36
	v_exp_f32_e32 v40, v40
	v_add_f32_e32 v75, v70, v75
	v_cndmask_b32_e32 v107, 0, v218, vcc
	v_add_f32_e32 v36, v36, v107
	v_exp_f32_e32 v36, v36
	v_ldexp_f32 v40, v40, v106
	v_cndmask_b32_e32 v106, 0, v219, vcc
	v_cmp_gt_f32_e32 vcc, s65, v37
	v_ldexp_f32 v36, v36, v106
	v_add_f32_e32 v75, v71, v75
	v_cndmask_b32_e32 v106, 0, v218, vcc
	v_add_f32_e32 v37, v37, v106
	v_exp_f32_e32 v37, v37
	v_cndmask_b32_e32 v106, 0, v219, vcc
	v_cmp_gt_f32_e32 vcc, s65, v38
	v_add_f32_e32 v75, v68, v75
	v_add_f32_e32 v75, v69, v75
	v_cndmask_b32_e32 v107, 0, v218, vcc
	v_add_f32_e32 v38, v38, v107
	v_exp_f32_e32 v107, v38
	v_ldexp_f32 v38, v37, v106
	v_cndmask_b32_e32 v37, 0, v219, vcc
	v_cmp_gt_f32_e32 vcc, s65, v39
	v_ldexp_f32 v37, v107, v37
	v_fmamk_f32 v31, v31, 0x3fb8aa3b, v119
	v_cndmask_b32_e32 v106, 0, v218, vcc
	v_add_f32_e32 v39, v39, v106
	v_exp_f32_e32 v39, v39
	v_cndmask_b32_e32 v106, 0, v219, vcc
	v_cmp_gt_f32_e32 vcc, s65, v32
	v_add_f32_e32 v75, v67, v75
	v_add_f32_e32 v75, v66, v75
	v_cndmask_b32_e32 v107, 0, v218, vcc
	v_add_f32_e32 v32, v32, v107
	v_exp_f32_e32 v107, v32
	v_ldexp_f32 v32, v39, v106
	v_cndmask_b32_e32 v39, 0, v219, vcc
	v_cmp_gt_f32_e32 vcc, s65, v33
	v_ldexp_f32 v39, v107, v39
	v_add_f32_e32 v75, v64, v75
	v_cndmask_b32_e32 v106, 0, v218, vcc
	v_add_f32_e32 v33, v33, v106
	v_cndmask_b32_e32 v106, 0, v219, vcc
	v_cmp_gt_f32_e32 vcc, s65, v34
	v_exp_f32_e32 v33, v33
	v_fmamk_f32 v24, v24, 0x3fb8aa3b, v119
	v_cndmask_b32_e32 v107, 0, v218, vcc
	v_add_f32_e32 v34, v34, v107
	v_exp_f32_e32 v34, v34
	v_ldexp_f32 v33, v33, v106
	v_cndmask_b32_e32 v106, 0, v219, vcc
	v_cmp_gt_f32_e32 vcc, s65, v35
	v_ldexp_f32 v34, v34, v106
	v_add_f32_e32 v75, v65, v75
	v_cndmask_b32_e32 v106, 0, v218, vcc
	v_add_f32_e32 v35, v35, v106
	v_cndmask_b32_e32 v106, 0, v219, vcc
	v_cmp_gt_f32_e32 vcc, s65, v28
	v_exp_f32_e32 v35, v35
	v_add_f32_e32 v75, v62, v75
	v_cndmask_b32_e32 v107, 0, v218, vcc
	v_add_f32_e32 v28, v28, v107
	v_exp_f32_e32 v28, v28
	v_ldexp_f32 v35, v35, v106
	v_cndmask_b32_e32 v106, 0, v219, vcc
	v_cmp_gt_f32_e32 vcc, s65, v29
	v_ldexp_f32 v28, v28, v106
	v_add_f32_e32 v75, v63, v75
	v_cndmask_b32_e32 v106, 0, v218, vcc
	v_add_f32_e32 v29, v29, v106
	v_cndmask_b32_e32 v106, 0, v219, vcc
	v_cmp_gt_f32_e32 vcc, s65, v30
	v_exp_f32_e32 v29, v29
	v_add_f32_e32 v75, v60, v75
	v_cndmask_b32_e32 v107, 0, v218, vcc
	v_add_f32_e32 v30, v30, v107
	v_exp_f32_e32 v30, v30
	v_ldexp_f32 v29, v29, v106
	v_cndmask_b32_e32 v106, 0, v219, vcc
	v_cmp_gt_f32_e32 vcc, s65, v31
	v_ldexp_f32 v30, v30, v106
	v_fmamk_f32 v25, v25, 0x3fb8aa3b, v119
	v_cndmask_b32_e32 v106, 0, v218, vcc
	v_add_f32_e32 v31, v31, v106
	v_exp_f32_e32 v31, v31
	v_cndmask_b32_e32 v106, 0, v219, vcc
	v_cmp_gt_f32_e32 vcc, s65, v24
	v_add_f32_e32 v75, v61, v75
	v_add_f32_e32 v75, v59, v75
	v_cndmask_b32_e32 v107, 0, v218, vcc
	v_add_f32_e32 v24, v24, v107
	v_exp_f32_e32 v107, v24
	v_ldexp_f32 v24, v31, v106
	v_cndmask_b32_e32 v31, 0, v219, vcc
	v_cmp_gt_f32_e32 vcc, s65, v25
	v_fmamk_f32 v26, v26, 0x3fb8aa3b, v119
	v_add_f32_e32 v75, v58, v75
	v_cndmask_b32_e32 v106, 0, v218, vcc
	v_add_f32_e32 v25, v25, v106
	v_cndmask_b32_e32 v106, 0, v219, vcc
	v_cmp_gt_f32_e32 vcc, s65, v26
	v_add_f32_e32 v75, v57, v75
	v_ldexp_f32 v31, v107, v31
	v_cndmask_b32_e32 v107, 0, v218, vcc
	v_add_f32_e32 v75, v56, v75
	v_exp_f32_e32 v25, v25
	v_add_f32_e32 v26, v26, v107
	v_add_f32_e32 v75, v54, v75
	v_exp_f32_e32 v26, v26
	v_add_f32_e32 v75, v55, v75
	v_add_f32_e32 v75, v52, v75
	v_fmamk_f32 v27, v27, 0x3fb8aa3b, v119
	v_add_f32_e32 v75, v53, v75
	v_ldexp_f32 v25, v25, v106
	v_cndmask_b32_e32 v106, 0, v219, vcc
	v_cmp_gt_f32_e32 vcc, s65, v27
	v_add_f32_e32 v75, v51, v75
	v_ldexp_f32 v26, v26, v106
	v_cndmask_b32_e32 v106, 0, v218, vcc
	v_fmamk_f32 v20, v20, 0x3fb8aa3b, v119
	v_add_f32_e32 v75, v50, v75
	v_add_f32_e32 v27, v27, v106
	v_cndmask_b32_e32 v106, 0, v219, vcc
; #define LAS __attribute__((address_space(3)))
; __device__ __forceinline__ unsigned cvt_pk_bf16_mfma(float lo, float hi) { const f32x2 v = {lo, hi}; return __builtin_bit_cast(unsigned, __builtin_convertvector(v, bf16v2_t)); }
; __device__ void attn_mfma(const Params& p, int l, const bf16_t* proj, bf16_t* y0, LAS unsigned char* lds) {
;     ...
;             for (int kt = 0; kt < 24; ++kt)
; #pragma unroll
;                 for (int r = 0; r < 4; ++r) { const float pr = exp2f(fmaf(sacc[kt][r], 1.44269504f, -mxl)); sacc[kt][r] = pr; sum += pr; }
;     ...
; #pragma unroll
;             for (int i = 0; i < 12; ++i) {
;                 u32x4 pw; pw.x = cvt_pk_bf16_mfma(sacc[2 * i][0], sacc[2 * i][1]); pw.y = cvt_pk_bf16_mfma(sacc[2 * i][2], sacc[2 * i][3]); pw.z = cvt_pk_bf16_mfma(sacc[2 * i + 1][0], sacc[2 * i + 1][1]); pw.w = cvt_pk_bf16_mfma(sacc[2 * i + 1][2], sacc[2 * i + 1][3]);
;                 const bf16x8 pf = __builtin_bit_cast(bf16x8, pw);
; #pragma unroll
;                 for (int dt = 0; dt < 4; ++dt) { const LAS bf16_t* vp = Vt + (dt * 16 + fr) * VP + 32 * i + 4 * g;
;                     const u32x2 lo = *(const LAS u32x2*)vp, hi = *(const LAS u32x2*)(vp + 16);
;                     u32x4 vw; vw.x = lo.x; vw.y = lo.y; vw.z = hi.x; vw.w = hi.y;
;                     oacc[dt] = __builtin_amdgcn_mfma_f32_16x16x32_bf16(__builtin_bit_cast(bf16x8, vw), pf, oacc[dt], 0, 0, 0); }
	v_cmp_gt_f32_e32 vcc, s65, v20
	v_add_f32_e32 v75, v48, v75
	v_add_f32_e32 v75, v49, v75
	v_cndmask_b32_e32 v107, 0, v218, vcc
	v_exp_f32_e32 v27, v27
	v_add_f32_e32 v20, v20, v107
	v_add_f32_e32 v75, v45, v75
	v_exp_f32_e32 v20, v20
	v_add_f32_e32 v75, v46, v75
	v_add_f32_e32 v75, v41, v75
	v_fmamk_f32 v21, v21, 0x3fb8aa3b, v119
	v_add_f32_e32 v75, v44, v75
	v_ldexp_f32 v27, v27, v106
	v_cndmask_b32_e32 v106, 0, v219, vcc
	v_cmp_gt_f32_e32 vcc, s65, v21
	v_add_f32_e32 v75, v40, v75
	v_ldexp_f32 v20, v20, v106
	v_cndmask_b32_e32 v106, 0, v218, vcc
	v_add_f32_e32 v75, v36, v75
	v_add_f32_e32 v21, v21, v106
	v_add_f32_e32 v75, v38, v75
	v_exp_f32_e32 v21, v21
	v_fmamk_f32 v22, v22, 0x3fb8aa3b, v119
	v_add_f32_e32 v75, v37, v75
	v_cndmask_b32_e32 v106, 0, v219, vcc
	v_cmp_gt_f32_e32 vcc, s65, v22
	v_add_f32_e32 v75, v32, v75
	v_add_f32_e32 v75, v39, v75
	v_cndmask_b32_e32 v107, 0, v218, vcc
	v_add_f32_e32 v22, v22, v107
	v_fmamk_f32 v23, v23, 0x3fb8aa3b, v119
	v_add_f32_e32 v75, v33, v75
	v_exp_f32_e32 v107, v22
	v_ldexp_f32 v22, v21, v106
	v_cndmask_b32_e32 v21, 0, v219, vcc
	v_cmp_gt_f32_e32 vcc, s65, v23
	v_add_f32_e32 v75, v34, v75
	v_add_f32_e32 v75, v35, v75
	v_cndmask_b32_e32 v106, 0, v218, vcc
	v_add_f32_e32 v23, v23, v106
	v_fmamk_f32 v16, v16, 0x3fb8aa3b, v119
	v_add_f32_e32 v75, v28, v75
	v_exp_f32_e32 v23, v23
	v_cndmask_b32_e32 v106, 0, v219, vcc
	v_cmp_gt_f32_e32 vcc, s65, v16
	v_add_f32_e32 v75, v29, v75
	v_ldexp_f32 v21, v107, v21
	v_cndmask_b32_e32 v107, 0, v218, vcc
	v_add_f32_e32 v75, v30, v75
	v_add_f32_e32 v16, v16, v107
	v_add_f32_e32 v75, v24, v75
	v_exp_f32_e32 v107, v16
	v_fmamk_f32 v17, v17, 0x3fb8aa3b, v119
	v_add_f32_e32 v75, v31, v75
	v_ldexp_f32 v16, v23, v106
	v_cndmask_b32_e32 v23, 0, v219, vcc
	v_cmp_gt_f32_e32 vcc, s65, v17
	v_add_f32_e32 v75, v25, v75
	v_fmamk_f32 v18, v18, 0x3fb8aa3b, v119
	v_cndmask_b32_e32 v106, 0, v218, vcc
	v_add_f32_e32 v75, v26, v75
	v_add_f32_e32 v17, v17, v106
	v_cndmask_b32_e32 v106, 0, v219, vcc
	v_cmp_gt_f32_e32 vcc, s65, v18
	v_add_f32_e32 v75, v27, v75
	v_ldexp_f32 v23, v107, v23
	v_cndmask_b32_e32 v107, 0, v218, vcc
	v_add_f32_e32 v75, v20, v75
	v_exp_f32_e32 v17, v17
	v_add_f32_e32 v18, v18, v107
	v_add_f32_e32 v75, v22, v75
	v_exp_f32_e32 v18, v18
	v_add_f32_e32 v75, v21, v75
	v_add_f32_e32 v75, v16, v75
	v_add_f32_e32 v75, v23, v75
	v_ldexp_f32 v17, v17, v106
	v_cndmask_b32_e32 v106, 0, v219, vcc
	v_fmamk_f32 v19, v19, 0x3fb8aa3b, v119
	v_add_f32_e32 v75, v17, v75
	v_ldexp_f32 v18, v18, v106
	v_cmp_gt_f32_e32 vcc, s65, v19
	v_add_f32_e32 v106, v18, v75
	v_fmamk_f32 v12, v12, 0x3fb8aa3b, v119
	v_cndmask_b32_e32 v75, 0, v218, vcc
	v_add_f32_e32 v19, v19, v75
	v_cndmask_b32_e32 v75, 0, v219, vcc
	v_cmp_gt_f32_e32 vcc, s65, v12
	v_exp_f32_e32 v19, v19
	v_fmamk_f32 v13, v13, 0x3fb8aa3b, v119
	v_cndmask_b32_e32 v107, 0, v218, vcc
	v_add_f32_e32 v12, v12, v107
	v_exp_f32_e32 v12, v12
	v_ldexp_f32 v75, v19, v75
	v_add_f32_e32 v19, v75, v106
	v_cndmask_b32_e32 v106, 0, v219, vcc
	v_cmp_gt_f32_e32 vcc, s65, v13
	v_ldexp_f32 v12, v12, v106
	v_fmamk_f32 v14, v14, 0x3fb8aa3b, v119
	v_cndmask_b32_e32 v106, 0, v218, vcc
	v_add_f32_e32 v13, v13, v106
	v_cndmask_b32_e32 v106, 0, v219, vcc
	v_cmp_gt_f32_e32 vcc, s65, v14
	v_exp_f32_e32 v13, v13
	v_fmamk_f32 v15, v15, 0x3fb8aa3b, v119
	v_cndmask_b32_e32 v107, 0, v218, vcc
	v_add_f32_e32 v14, v14, v107
	v_exp_f32_e32 v14, v14
	v_ldexp_f32 v13, v13, v106
	v_cndmask_b32_e32 v106, 0, v219, vcc
	v_cmp_gt_f32_e32 vcc, s65, v15
	v_ldexp_f32 v14, v14, v106
	v_fmamk_f32 v42, v42, 0x3fb8aa3b, v119
	v_cndmask_b32_e32 v106, 0, v218, vcc
	v_add_f32_e32 v15, v15, v106
	v_cndmask_b32_e32 v106, 0, v219, vcc
	v_cmp_gt_f32_e32 vcc, s65, v42
	v_exp_f32_e32 v15, v15
	v_add_f32_e32 v19, v12, v19
	v_cndmask_b32_e32 v107, 0, v218, vcc
	v_add_f32_e32 v42, v42, v107
	v_exp_f32_e32 v42, v42
	v_add_f32_e32 v19, v13, v19
	v_add_f32_e32 v19, v14, v19
	v_ldexp_f32 v15, v15, v106
	v_add_f32_e32 v106, v15, v19
	v_cndmask_b32_e32 v19, 0, v219, vcc
	v_fmamk_f32 v43, v43, 0x3fb8aa3b, v119
	v_ldexp_f32 v19, v42, v19
	v_cmp_gt_f32_e32 vcc, s65, v43
	v_add_f32_e32 v42, v19, v106
	v_fmamk_f32 v10, v10, 0x3fb8aa3b, v119
	v_cndmask_b32_e32 v106, 0, v218, vcc
	v_add_f32_e32 v43, v43, v106
	v_exp_f32_e32 v43, v43
	v_cndmask_b32_e32 v106, 0, v219, vcc
	v_cmp_gt_f32_e32 vcc, s65, v10
	v_fmac_f32_e32 v119, 0x3fb8aa3b, v47
	v_add_u32_e32 v47, 0xd800, v142
	v_cndmask_b32_e32 v107, 0, v218, vcc
	v_add_f32_e32 v10, v10, v107
	v_exp_f32_e32 v107, v10
	v_ldexp_f32 v10, v43, v106
	v_add_f32_e32 v106, v10, v42
	v_cndmask_b32_e32 v42, 0, v219, vcc
	v_cmp_gt_f32_e32 vcc, s65, v119
	v_ldexp_f32 v42, v107, v42
	v_cvt_pk_bf16_f32 v154, v9, v100
	v_cndmask_b32_e32 v43, 0, v218, vcc
	v_add_f32_e32 v107, v119, v43
	v_add_u32_e32 v9, 0xd800, v143
	v_cvt_pk_bf16_f32 v156, v96, v97
	v_add_u32_e32 v43, 0xd800, v144
	v_add_u32_e32 v96, 0xd800, v145
	ds_read2_b64 v[150:153], v47 offset1:4
	v_cvt_pk_bf16_f32 v155, v101, v102
	ds_read2_b64 v[158:161], v9 offset1:4
	v_cvt_pk_bf16_f32 v157, v98, v99
	ds_read2_b64 v[98:101], v43 offset1:4
	ds_read2_b64 v[162:165], v96 offset1:4
	ds_read2_b64 v[166:169], v47 offset0:8 offset1:12
	s_waitcnt lgkmcnt(4)
	v_mfma_f32_16x16x32_bf16 v[150:153], v[150:153], v[154:157], 0
	v_exp_f32_e32 v97, v107
	v_add_f32_e32 v102, v42, v106
	v_cndmask_b32_e32 v106, 0, v219, vcc
	s_waitcnt lgkmcnt(3)
	v_mfma_f32_16x16x32_bf16 v[158:161], v[158:161], v[154:157], 0
	v_ldexp_f32 v97, v97, v106
	v_cvt_pk_bf16_f32 v170, v11, v92
	v_cvt_pk_bf16_f32 v171, v93, v88
	s_waitcnt lgkmcnt(2)
	v_mfma_f32_16x16x32_bf16 v[98:101], v[98:101], v[154:157], 0
	v_cvt_pk_bf16_f32 v172, v94, v89
	v_cvt_pk_bf16_f32 v173, v90, v91
	v_add_f32_e32 v102, v97, v102
	s_waitcnt lgkmcnt(1)
; #define LAS __attribute__((address_space(3)))
; __device__ __forceinline__ unsigned cvt_pk_bf16_mfma(float lo, float hi) { const f32x2 v = {lo, hi}; return __builtin_bit_cast(unsigned, __builtin_convertvector(v, bf16v2_t)); }
; __device__ void attn_mfma(const Params& p, int l, const bf16_t* proj, bf16_t* y0, LAS unsigned char* lds) {
;     ...
;             sum += __shfl_xor(sum, 16); sum += __shfl_xor(sum, 32);
;             const float inv = 1.0f / (sum + __expf(sink - mx));
;             f32x4 oacc[4];
; #pragma unroll
;             for (int dt = 0; dt < 4; ++dt) oacc[dt] = (f32x4){0.f, 0.f, 0.f, 0.f};
; #pragma unroll
;             for (int i = 0; i < 12; ++i) {
;                 u32x4 pw; pw.x = cvt_pk_bf16_mfma(sacc[2 * i][0], sacc[2 * i][1]); pw.y = cvt_pk_bf16_mfma(sacc[2 * i][2], sacc[2 * i][3]); pw.z = cvt_pk_bf16_mfma(sacc[2 * i + 1][0], sacc[2 * i + 1][1]); pw.w = cvt_pk_bf16_mfma(sacc[2 * i + 1][2], sacc[2 * i + 1][3]);
;                 const bf16x8 pf = __builtin_bit_cast(bf16x8, pw);
; #pragma unroll
;                 for (int dt = 0; dt < 4; ++dt) { const LAS bf16_t* vp = Vt + (dt * 16 + fr) * VP + 32 * i + 4 * g;
;                     const u32x2 lo = *(const LAS u32x2*)vp, hi = *(const LAS u32x2*)(vp + 16);
;                     u32x4 vw; vw.x = lo.x; vw.y = lo.y; vw.z = hi.x; vw.w = hi.y;
;                     oacc[dt] = __builtin_amdgcn_mfma_f32_16x16x32_bf16(__builtin_bit_cast(bf16x8, vw), pf, oacc[dt], 0, 0, 0); }
	v_mfma_f32_16x16x32_bf16 v[154:157], v[162:165], v[154:157], 0
	ds_read2_b64 v[162:165], v9 offset0:8 offset1:12
	ds_bpermute_b32 v106, v121, v102
	v_sub_f32_e32 v8, v146, v8
	s_waitcnt lgkmcnt(2)
	v_mfma_f32_16x16x32_bf16 v[88:91], v[166:169], v[170:173], v[150:153]
	v_mul_f32_e32 v8, 0x3fb8aa3b, v8
	v_exp_f32_e32 v8, v8
	s_waitcnt lgkmcnt(0)
	v_add_f32_e32 v11, v102, v106
	ds_read2_b64 v[150:153], v43 offset0:8 offset1:12
	v_mfma_f32_16x16x32_bf16 v[158:161], v[162:165], v[170:173], v[158:161]
	ds_read2_b64 v[162:165], v96 offset0:8 offset1:12
	v_mov_b32_e32 v92, v11
	s_waitcnt lgkmcnt(0)
	s_nop 1
	v_permlane32_swap_b32_e32 v92, v11
	v_add_f32_e32 v11, v11, v92
	v_mfma_f32_16x16x32_bf16 v[98:101], v[150:153], v[170:173], v[98:101]
	v_add_f32_e32 v106, v8, v11
	v_mfma_f32_16x16x32_bf16 v[150:153], v[162:165], v[170:173], v[154:157]
	v_cvt_pk_bf16_f32 v84, v84, v86
	v_cvt_pk_bf16_f32 v86, v87, v81
	v_cvt_pk_bf16_f32 v87, v82, v95
	ds_read2_b64 v[92:95], v43 offset0:16 offset1:20
	ds_read2_b64 v[154:157], v47 offset0:16 offset1:20
	v_cvt_pk_bf16_f32 v85, v85, v80
	ds_read2_b64 v[162:165], v9 offset0:16 offset1:20
	v_cvt_pk_bf16_f32 v76, v76, v77
	v_cvt_pk_bf16_f32 v77, v78, v79
	s_waitcnt lgkmcnt(2)
	v_mfma_f32_16x16x32_bf16 v[92:95], v[92:95], v[84:87], v[98:101]
	s_nop 2
	ds_read2_b64 v[98:101], v47 offset0:24 offset1:28
	v_cvt_pk_bf16_f32 v78, v83, v103
	v_cvt_pk_bf16_f32 v79, v104, v105
	s_waitcnt lgkmcnt(2)
	v_mfma_f32_16x16x32_bf16 v[88:91], v[154:157], v[84:87], v[88:91]
	s_waitcnt lgkmcnt(0)
	v_mfma_f32_16x16x32_bf16 v[80:83], v[98:101], v[76:79], v[88:91]
	ds_read2_b64 v[98:101], v43 offset0:24 offset1:28
	s_nop 4
	ds_read2_b64 v[88:91], v9 offset0:24 offset1:28
	v_mfma_f32_16x16x32_bf16 v[154:157], v[162:165], v[84:87], v[158:161]
	s_nop 2
	ds_read2_b64 v[158:161], v96 offset0:16 offset1:20
	s_waitcnt lgkmcnt(2)
	v_mfma_f32_16x16x32_bf16 v[92:95], v[98:101], v[76:79], v[92:95]
	ds_read2_b64 v[98:101], v96 offset0:24 offset1:28
	s_waitcnt lgkmcnt(1)
	v_mfma_f32_16x16x32_bf16 v[84:87], v[158:161], v[84:87], v[150:153]
	v_mfma_f32_16x16x32_bf16 v[88:91], v[88:91], v[76:79], v[154:157]
	s_waitcnt lgkmcnt(0)
	v_mfma_f32_16x16x32_bf16 v[76:79], v[98:101], v[76:79], v[84:87]
	s_nop 4
	ds_read2_b64 v[84:87], v47 offset0:32 offset1:36
	v_cvt_pk_bf16_f32 v98, v72, v74
	v_cvt_pk_bf16_f32 v99, v73, v70
	v_cvt_pk_bf16_f32 v100, v71, v68
	v_cvt_pk_bf16_f32 v101, v69, v67
	ds_read2_b64 v[102:105], v9 offset0:32 offset1:36
	v_cvt_pk_bf16_f32 v64, v66, v64
	v_cvt_pk_bf16_f32 v65, v65, v62
	v_cvt_pk_bf16_f32 v66, v63, v60
	s_waitcnt lgkmcnt(1)
	v_mfma_f32_16x16x32_bf16 v[68:71], v[84:87], v[98:101], v[80:83]
	v_cvt_pk_bf16_f32 v67, v61, v59
	s_nop 1
	ds_read2_b64 v[80:83], v43 offset0:32 offset1:36
	s_waitcnt lgkmcnt(1)
	v_mfma_f32_16x16x32_bf16 v[84:87], v[102:105], v[98:101], v[88:91]
	s_waitcnt lgkmcnt(0)
	v_mfma_f32_16x16x32_bf16 v[80:83], v[80:83], v[98:101], v[92:95]
	s_nop 2
	ds_read2_b64 v[92:95], v47 offset0:40 offset1:44
	ds_read2_b64 v[88:91], v96 offset0:32 offset1:36
	s_waitcnt lgkmcnt(0)
	v_mfma_f32_16x16x32_bf16 v[76:79], v[88:91], v[98:101], v[76:79]
	v_mfma_f32_16x16x32_bf16 v[60:63], v[92:95], v[64:67], v[68:71]
	s_nop 2
	ds_read2_b64 v[68:71], v9 offset0:40 offset1:44
	s_waitcnt lgkmcnt(0)
	v_mfma_f32_16x16x32_bf16 v[68:71], v[68:71], v[64:67], v[84:87]
	s_nop 2
	ds_read2_b64 v[84:87], v43 offset0:40 offset1:44
	s_waitcnt lgkmcnt(0)
	v_mfma_f32_16x16x32_bf16 v[80:83], v[84:87], v[64:67], v[80:83]
	ds_read2_b64 v[84:87], v96 offset0:40 offset1:44
	s_waitcnt lgkmcnt(0)
	v_mfma_f32_16x16x32_bf16 v[64:67], v[84:87], v[64:67], v[76:79]
	s_nop 2
	ds_read2_b64 v[76:79], v47 offset0:48 offset1:52
	ds_read2_b64 v[88:91], v9 offset0:48 offset1:52
	v_cvt_pk_bf16_f32 v84, v58, v57
	v_cvt_pk_bf16_f32 v85, v56, v54
	v_cvt_pk_bf16_f32 v86, v55, v52
	v_cvt_pk_bf16_f32 v87, v53, v51
	ds_read2_b64 v[56:59], v43 offset0:48 offset1:52
	v_cvt_pk_bf16_f32 v48, v50, v48
	v_cvt_pk_bf16_f32 v49, v49, v45
	s_waitcnt lgkmcnt(2)
	v_mfma_f32_16x16x32_bf16 v[52:55], v[76:79], v[84:87], v[60:63]
	v_cvt_pk_bf16_f32 v50, v46, v41
	v_cvt_pk_bf16_f32 v51, v44, v40
	ds_read2_b64 v[76:79], v47 offset0:56 offset1:60
	s_waitcnt lgkmcnt(2)
	v_mfma_f32_16x16x32_bf16 v[60:63], v[88:91], v[84:87], v[68:71]
	s_nop 2
	ds_read2_b64 v[68:71], v96 offset0:48 offset1:52
	s_waitcnt lgkmcnt(0)
	v_mfma_f32_16x16x32_bf16 v[64:67], v[68:71], v[84:87], v[64:67]
	ds_read2_b64 v[68:71], v9 offset0:56 offset1:60
	s_waitcnt lgkmcnt(0)
	v_mfma_f32_16x16x32_bf16 v[60:63], v[68:71], v[48:51], v[60:63]
	ds_read2_b64 v[68:71], v43 offset0:56 offset1:60
	v_mfma_f32_16x16x32_bf16 v[56:59], v[56:59], v[84:87], v[80:83]
	s_waitcnt lgkmcnt(0)
; #define LAS __attribute__((address_space(3)))
; __device__ __forceinline__ unsigned cvt_pk_bf16(float lo, float hi) { unsigned r; asm("v_cvt_pk_bf16_f32 %0, %1, %2" : "=v"(r) : "v"(lo), "v"(hi)); return r; }
; __device__ __forceinline__ unsigned cvt_pk_bf16_mfma(float lo, float hi) { const f32x2 v = {lo, hi}; return __builtin_bit_cast(unsigned, __builtin_convertvector(v, bf16v2_t)); }
; __device__ void attn_mfma(const Params& p, int l, const bf16_t* proj, bf16_t* y0, LAS unsigned char* lds) {
;     ...
;             const float inv = 1.0f / (sum + __expf(sink - mx));
;             f32x4 oacc[4];
; #pragma unroll
;             for (int dt = 0; dt < 4; ++dt) oacc[dt] = (f32x4){0.f, 0.f, 0.f, 0.f};
; #pragma unroll
;             for (int i = 0; i < 12; ++i) {
;                 u32x4 pw; pw.x = cvt_pk_bf16_mfma(sacc[2 * i][0], sacc[2 * i][1]); pw.y = cvt_pk_bf16_mfma(sacc[2 * i][2], sacc[2 * i][3]); pw.z = cvt_pk_bf16_mfma(sacc[2 * i + 1][0], sacc[2 * i + 1][1]); pw.w = cvt_pk_bf16_mfma(sacc[2 * i + 1][2], sacc[2 * i + 1][3]);
;                 const bf16x8 pf = __builtin_bit_cast(bf16x8, pw);
; #pragma unroll
;                 for (int dt = 0; dt < 4; ++dt) { const LAS bf16_t* vp = Vt + (dt * 16 + fr) * VP + 32 * i + 4 * g;
;                     const u32x2 lo = *(const LAS u32x2*)vp, hi = *(const LAS u32x2*)(vp + 16);
;                     u32x4 vw; vw.x = lo.x; vw.y = lo.y; vw.z = hi.x; vw.w = hi.y;
;                     oacc[dt] = __builtin_amdgcn_mfma_f32_16x16x32_bf16(__builtin_bit_cast(bf16x8, vw), pf, oacc[dt], 0, 0, 0); }
;                 if (i & 1) __builtin_amdgcn_sched_barrier(0); }
; #pragma unroll
;             for (int dt = 0; dt < 4; ++dt) { u32x2 w; w.x = cvt_pk_bf16(oacc[dt][0] * inv, oacc[dt][1] * inv); w.y = cvt_pk_bf16(oacc[dt][2] * inv, oacc[dt][3] * inv);
;                 *(u32x2*)(y0 + (size_t)t * 512 + hq * 64 + dt * 16 + 4 * g) = w; }
	v_mfma_f32_16x16x32_bf16 v[56:59], v[68:71], v[48:51], v[56:59]
	ds_read2_b64 v[68:71], v96 offset0:56 offset1:60
	v_mfma_f32_16x16x32_bf16 v[52:55], v[76:79], v[48:51], v[52:55]
	s_waitcnt lgkmcnt(0)
	v_mfma_f32_16x16x32_bf16 v[48:51], v[68:71], v[48:51], v[64:67]
	s_nop 2
	ds_read2_b64 v[64:67], v47 offset0:64 offset1:68
	v_cvt_pk_bf16_f32 v36, v36, v38
	v_cvt_pk_bf16_f32 v37, v37, v32
	v_cvt_pk_bf16_f32 v38, v39, v33
	v_cvt_pk_bf16_f32 v39, v34, v35
	ds_read2_b64 v[68:71], v9 offset0:64 offset1:68
	v_cvt_pk_bf16_f32 v28, v28, v29
	v_cvt_pk_bf16_f32 v29, v30, v24
	v_cvt_pk_bf16_f32 v30, v31, v25
	s_waitcnt lgkmcnt(1)
	v_mfma_f32_16x16x32_bf16 v[32:35], v[64:67], v[36:39], v[52:55]
	ds_read2_b64 v[64:67], v96 offset0:64 offset1:68
	v_cvt_pk_bf16_f32 v31, v26, v27
	s_nop 0
	ds_read2_b64 v[52:55], v43 offset0:64 offset1:68
	s_waitcnt lgkmcnt(2)
	v_mfma_f32_16x16x32_bf16 v[60:63], v[68:71], v[36:39], v[60:63]
	s_waitcnt lgkmcnt(0)
	v_mfma_f32_16x16x32_bf16 v[52:55], v[52:55], v[36:39], v[56:59]
	s_nop 2
	ds_read2_b64 v[56:59], v47 offset0:72 offset1:76
	v_mfma_f32_16x16x32_bf16 v[36:39], v[64:67], v[36:39], v[48:51]
	s_nop 2
	ds_read2_b64 v[48:51], v43 offset0:72 offset1:76
	s_waitcnt lgkmcnt(1)
	v_mfma_f32_16x16x32_bf16 v[24:27], v[56:59], v[28:31], v[32:35]
	s_nop 2
	ds_read2_b64 v[32:35], v9 offset0:72 offset1:76
	s_waitcnt lgkmcnt(1)
	v_mfma_f32_16x16x32_bf16 v[48:51], v[48:51], v[28:31], v[52:55]
	s_nop 2
	ds_read2_b64 v[52:55], v96 offset0:72 offset1:76
	s_waitcnt lgkmcnt(1)
	v_mfma_f32_16x16x32_bf16 v[32:35], v[32:35], v[28:31], v[60:63]
	s_waitcnt lgkmcnt(0)
	v_mfma_f32_16x16x32_bf16 v[28:31], v[52:55], v[28:31], v[36:39]
	s_nop 2
	ds_read2_b64 v[36:39], v47 offset0:80 offset1:84
	ds_read2_b64 v[52:55], v9 offset0:80 offset1:84
	v_cvt_pk_bf16_f32 v20, v20, v22
	v_cvt_pk_bf16_f32 v21, v21, v16
	v_cvt_pk_bf16_f32 v22, v23, v17
	v_cvt_pk_bf16_f32 v23, v18, v75
	ds_read2_b64 v[44:47], v47 offset0:88 offset1:92
	v_cvt_pk_bf16_f32 v12, v12, v13
	v_cvt_pk_bf16_f32 v13, v14, v15
	s_waitcnt lgkmcnt(2)
	v_mfma_f32_16x16x32_bf16 v[24:27], v[36:39], v[20:23], v[24:27]
	ds_read2_b64 v[36:39], v43 offset0:80 offset1:84
	v_cvt_pk_bf16_f32 v14, v19, v10
	ds_read2_b64 v[8:11], v9 offset0:88 offset1:92
	s_waitcnt lgkmcnt(3)
	v_mfma_f32_16x16x32_bf16 v[32:35], v[52:55], v[20:23], v[32:35]
	ds_read2_b64 v[52:55], v96 offset0:80 offset1:84
	v_cvt_pk_bf16_f32 v15, v42, v97
	s_waitcnt lgkmcnt(2)
	v_mfma_f32_16x16x32_bf16 v[36:39], v[36:39], v[20:23], v[48:51]
	s_waitcnt lgkmcnt(0)
	v_mfma_f32_16x16x32_bf16 v[20:23], v[52:55], v[20:23], v[28:31]
	v_mfma_f32_16x16x32_bf16 v[16:19], v[44:47], v[12:15], v[24:27]
	s_nop 1
	ds_read2_b64 v[28:31], v96 offset0:88 offset1:92
	ds_read2_b64 v[24:27], v43 offset0:88 offset1:92
	v_mfma_f32_16x16x32_bf16 v[8:11], v[8:11], v[12:15], v[32:35]
	s_waitcnt lgkmcnt(0)
	v_mfma_f32_16x16x32_bf16 v[24:27], v[24:27], v[12:15], v[36:39]
	v_mfma_f32_16x16x32_bf16 v[12:15], v[28:31], v[12:15], v[20:23]
	s_nop 2
	v_div_scale_f32 v20, s[14:15], v106, v106, 1.0
	v_rcp_f32_e32 v21, v20
	v_div_scale_f32 v22, vcc, 1.0, v106, 1.0
	v_ashrrev_i32_e32 v119, 31, v118
	v_fma_f32 v23, -v20, v21, 1.0
	v_fmac_f32_e32 v21, v23, v21
	v_mul_f32_e32 v23, v22, v21
	v_fma_f32 v28, -v20, v23, v22
	v_fmac_f32_e32 v23, v28, v21
	v_fma_f32 v20, -v20, v23, v22
	v_div_fmas_f32 v20, v20, v21, v23
	v_div_fixup_f32 v22, v20, v106, 1.0
	v_mul_f32_e32 v8, v22, v8
	v_mul_f32_e32 v9, v22, v9
	v_lshlrev_b64 v[20:21], 10, v[118:119]
	v_cvt_pk_bf16_f32 v8, v8, v9
	v_mul_f32_e32 v9, v22, v10
	v_lshl_add_u64 v[20:21], v[116:117], 0, v[20:21]
	v_mul_f32_e32 v10, v22, v11
	v_cvt_pk_bf16_f32 v9, v9, v10
	global_store_dwordx2 v[20:21], v[8:9], off offset:32
	v_mul_f32_e32 v8, v22, v24
	v_mul_f32_e32 v9, v22, v25
	v_cvt_pk_bf16_f32 v8, v8, v9
	v_mul_f32_e32 v9, v22, v26
	v_mul_f32_e32 v10, v22, v27
	v_cvt_pk_bf16_f32 v9, v9, v10
	global_store_dwordx2 v[20:21], v[8:9], off offset:64
	v_mul_f32_e32 v8, v22, v12
	v_mul_f32_e32 v9, v22, v13
	v_cvt_pk_bf16_f32 v8, v8, v9
	v_mul_f32_e32 v9, v22, v14
	v_mul_f32_e32 v10, v22, v15
	v_cvt_pk_bf16_f32 v9, v9, v10
	v_mul_f32_e32 v16, v22, v16
	v_mul_f32_e32 v17, v22, v17
	global_store_dwordx2 v[20:21], v[8:9], off offset:96
	s_add_i32 s12, s12, 16
	s_waitcnt vmcnt(3)
	v_mov_b64_e32 v[10:11], v[6:7]
	v_mov_b64_e32 v[102:103], v[2:3]
	v_cvt_pk_bf16_f32 v16, v16, v17
	v_mul_f32_e32 v17, v22, v18
	s_cmp_eq_u32 s12, 64
	v_mov_b64_e32 v[8:9], v[4:5]
	v_mov_b64_e32 v[100:101], v[0:1]
	v_mul_f32_e32 v18, v22, v19
	v_cvt_pk_bf16_f32 v17, v17, v18
	global_store_dwordx2 v[20:21], v[16:17], off
	s_cbranch_scc0 .LBB0_478
	s_add_i32 s11, s11, s59
	s_cmpk_gt_i32 s11, 0xff
	s_cbranch_scc0 .LBB0_459

; #define LAS __attribute__((address_space(3)))
; __device__ __forceinline__ unsigned cvt_pk_bf16(float lo, float hi) { unsigned r; asm("v_cvt_pk_bf16_f32 %0, %1, %2" : "=v"(r) : "v"(lo), "v"(hi)); return r; }
; template <bool OUT>
; __device__ __forceinline__ void gla_chunks(const Params& p, int l, const bf16_t* proj, LAS unsigned char* lds, int seg, int h, int dir, f32x4 (&Sacc)[4], float* outbuf, float& alog) {
;     ...
;         { float off = 0.f, tot = 0.f;
; #pragma unroll
;           for (int q = 0; q < 8; ++q) { const float v = PART[q * 64 + d]; tot += v; if (q < tb) off += v; }
;           if (tb == 0) { EBL[d] = __expf(tot); alog += tot; }
;           unsigned kh[4];
; #pragma unroll
;           for (int j = 0; j < 8; j += 2) { const float b0 = bq[j] + off, b1 = bq[j + 1] + off;
;               const int i = tb * 8 + j;
;               if (OUT) { QT[i * GP + d] = (bf16_t)(cvt_pk_bf16(qv[j] * __expf(b0), 0.f) & 0xffffu); QT[(i + 1) * GP + d] = (bf16_t)(cvt_pk_bf16(qv[j + 1] * __expf(b1), 0.f) & 0xffffu);
;                          KT[i * GP + d] = (bf16_t)(cvt_pk_bf16(kv[j] * __expf(-b0), 0.f) & 0xffffu); KT[(i + 1) * GP + d] = (bf16_t)(cvt_pk_bf16(kv[j + 1] * __expf(-b1), 0.f) & 0xffffu); }
;               kh[j >> 1] = cvt_pk_bf16(kv[j] * __expf(tot - b0), kv[j + 1] * __expf(tot - b1)); }
;           u32x4 kw; kw.x = kh[0]; kw.y = kh[1]; kw.z = kh[2]; kw.w = kh[3];
;           *(LAS u32x4*)(KH + d * GP + tb * 8) = kw; }
;     ...
;         for (int dt = 0; dt < 4; ++dt) { const f32x4 eb = *(const LAS f32x4*)(EBL + dt * 16 + 4 * g); f32x4 a = Sacc[dt] * eb;
; #pragma unroll
;             for (int ks = 0; ks < 2; ++ks) { const bf16x8 kf = *(const LAS bf16x8*)(KH + (dt * 16 + fr) * GP + 32 * ks + 8 * g); a = __builtin_amdgcn_mfma_f32_16x16x32_bf16(kf, bv[ks], a, 0, 0, 0); }
;             Sacc[dt] = a; }
;         __syncthreads();
.LBB0_487:
	v_cndmask_b32_e64 v27, 0, v27, s[6:7]
	v_add_f32_e32 v23, v23, v27
	v_cndmask_b32_e64 v23, v27, v23, s[8:9]
	v_add_f32_e32 v20, v20, v23
	v_cndmask_b32_e64 v20, v23, v20, s[10:11]
	v_add_f32_e32 v21, v21, v20
	v_cndmask_b32_e64 v20, v20, v21, s[12:13]
	v_add_f32_e32 v18, v18, v20
	v_cndmask_b32_e64 v18, v20, v18, s[14:15]
	v_add_f32_e32 v19, v19, v18
	v_cndmask_b32_e64 v18, v18, v19, s[16:17]
	v_add_f32_e32 v16, v16, v18
	v_cndmask_b32_e64 v16, v18, v16, s[18:19]
	v_add_f32_e32 v17, v17, v16
	v_cndmask_b32_e64 v19, v16, v17, s[20:21]
	v_add_f32_e32 v16, v64, v19
	v_add_f32_e32 v17, v56, v19
	v_sub_f32_e32 v16, v22, v16
	v_sub_f32_e32 v17, v22, v17
	v_mul_f32_e32 v16, 0x3fb8aa3b, v16
	v_mul_f32_e32 v17, 0x3fb8aa3b, v17
	v_exp_f32_e32 v16, v16
	v_exp_f32_e32 v17, v17
	v_lshlrev_b32_e32 v28, 16, v109
	v_lshlrev_b32_e32 v29, 16, v110
	v_mul_f32_e32 v16, v16, v28
	v_mul_f32_e32 v17, v17, v29
	v_cvt_pk_bf16_f32 v16, v16, v17
	v_add_f32_e32 v17, v48, v19
	v_add_f32_e32 v18, v40, v19
	v_sub_f32_e32 v17, v22, v17
	v_sub_f32_e32 v18, v22, v18
	v_mul_f32_e32 v17, 0x3fb8aa3b, v17
	v_mul_f32_e32 v18, 0x3fb8aa3b, v18
	v_exp_f32_e32 v17, v17
	v_exp_f32_e32 v18, v18
	v_lshlrev_b32_e32 v30, 16, v111
	v_lshlrev_b32_e32 v31, 16, v112
	v_mul_f32_e32 v17, v17, v30
	v_mul_f32_e32 v18, v18, v31
	v_cvt_pk_bf16_f32 v17, v17, v18
	v_add_f32_e32 v18, v32, v19
	v_add_f32_e32 v20, v24, v19
	v_sub_f32_e32 v18, v22, v18
	v_sub_f32_e32 v20, v22, v20
	v_mul_f32_e32 v18, 0x3fb8aa3b, v18
	v_mul_f32_e32 v20, 0x3fb8aa3b, v20
	v_exp_f32_e32 v18, v18
	v_exp_f32_e32 v20, v20
	v_lshlrev_b32_e32 v33, 16, v113
	v_lshlrev_b32_e32 v34, 16, v114
	v_mul_f32_e32 v18, v18, v33
	v_mul_f32_e32 v20, v20, v34
	v_cvt_pk_bf16_f32 v18, v18, v20
	v_add_f32_e32 v20, v25, v19
	v_add_f32_e32 v19, v26, v19
	v_sub_f32_e32 v19, v22, v19
	v_sub_f32_e32 v20, v22, v20
	v_mul_f32_e32 v19, 0x3fb8aa3b, v19
	v_mul_f32_e32 v20, 0x3fb8aa3b, v20
	v_exp_f32_e32 v19, v19
	v_exp_f32_e32 v20, v20
	v_lshlrev_b32_e32 v36, 16, v116
	v_lshlrev_b32_e32 v35, 16, v115
	v_mul_f32_e32 v19, v19, v36
	v_mul_f32_e32 v20, v20, v35
	v_cvt_pk_bf16_f32 v19, v20, v19
	ds_write_b128 v107, v[16:19] offset:18432
	s_waitcnt lgkmcnt(0)
	s_barrier
	ds_read_b128 v[16:19], v82 offset:27648
	ds_read_b128 v[20:23], v82 offset:27712
	ds_read_b128 v[118:121], v80 offset:55296
	ds_read_b128 v[122:125], v80 offset:55360
	ds_read_b128 v[126:129], v80 offset:55424
	ds_read_b128 v[130:133], v80 offset:55488
	ds_read_b128 v[134:137], v108 offset:18432
	ds_read_b128 v[138:141], v108 offset:18496
	ds_read_b128 v[142:145], v108 offset:20736
	ds_read_b128 v[146:149], v108 offset:20800
	ds_read_b128 v[150:153], v108 offset:23040
	ds_read_b128 v[154:157], v108 offset:23104
	ds_read_b128 v[158:161], v108 offset:25344
	ds_read_b128 v[162:165], v108 offset:25408
	s_add_i32 s34, s34, 1
	s_add_i32 s33, s33, -1
	s_waitcnt lgkmcnt(8)
	v_pk_mul_f32 v[14:15], v[14:15], v[120:121]
	v_pk_mul_f32 v[12:13], v[12:13], v[118:119]
	v_pk_mul_f32 v[10:11], v[10:11], v[124:125]
	v_pk_mul_f32 v[8:9], v[8:9], v[122:123]
	v_pk_mul_f32 v[6:7], v[6:7], v[128:129]
	v_pk_mul_f32 v[4:5], v[4:5], v[126:127]
	v_pk_mul_f32 v[2:3], v[2:3], v[132:133]
	v_pk_mul_f32 v[0:1], v[0:1], v[130:131]
	s_waitcnt lgkmcnt(7)
	v_mfma_f32_16x16x32_bf16 v[12:15], v[134:137], v[16:19], v[12:15]
	s_waitcnt lgkmcnt(6)
	v_mfma_f32_16x16x32_bf16 v[12:15], v[138:141], v[20:23], v[12:15]
	s_waitcnt lgkmcnt(5)
	v_mfma_f32_16x16x32_bf16 v[8:11], v[142:145], v[16:19], v[8:11]
	s_waitcnt lgkmcnt(4)
	v_mfma_f32_16x16x32_bf16 v[8:11], v[146:149], v[20:23], v[8:11]
	s_waitcnt lgkmcnt(3)
	v_mfma_f32_16x16x32_bf16 v[4:7], v[150:153], v[16:19], v[4:7]
	s_waitcnt lgkmcnt(2)
	v_mfma_f32_16x16x32_bf16 v[4:7], v[154:157], v[20:23], v[4:7]
	s_waitcnt lgkmcnt(1)
	v_mfma_f32_16x16x32_bf16 v[0:3], v[158:161], v[16:19], v[0:3]
	s_waitcnt lgkmcnt(0)
	v_mfma_f32_16x16x32_bf16 v[0:3], v[162:165], v[20:23], v[0:3]
	s_cmp_lg_u32 s34, 4
	s_waitcnt lgkmcnt(0)
	s_barrier
	s_cbranch_scc0 .LBB0_490

.LBB0_503:
	s_add_i32 s36, 0, 0x10000
	v_add_u32_e32 v130, s36, v137
	ds_read_b128 v[140:143], v130
	ds_read_b128 v[144:147], v130 offset:1024
	ds_read_b128 v[148:151], v130 offset:2048
	ds_read_b128 v[152:155], v130 offset:3072
	s_add_u32 s12, s16, s10
	v_mov_b32_e32 v188, v132
	v_mov_b32_e32 v190, v134
	s_addc_u32 s13, s17, s11
	ds_read_b128 v[156:159], v139
	ds_read_b128 v[160:163], v139 offset:1024
	ds_read_b128 v[164:167], v139 offset:2048
	ds_read_b128 v[168:171], v139 offset:3072
	ds_read_b128 v[172:175], v139 offset:4096
	ds_read_b128 v[176:179], v139 offset:5120
	ds_read_b128 v[180:183], v139 offset:6144
	ds_read_b128 v[184:187], v139 offset:7168
	s_add_i32 s34, s24, 0xc000
	v_lshl_add_u64 v[192:193], s[12:13], 0, v[188:189]
	v_mov_b32_e32 v191, v189
	v_lshl_add_u64 v[192:193], v[192:193], 0, s[46:47]
	s_mov_b32 m0, s34
	v_lshl_add_u64 v[190:191], s[12:13], 0, v[190:191]
	s_add_i32 s35, s24, 0xe000
	global_load_lds_dwordx4 v[192:193], off
	v_lshl_add_u64 v[190:191], v[190:191], 0, s[46:47]
	s_mov_b32 m0, s35
	s_nop 0
	global_load_lds_dwordx4 v[190:191], off
	s_waitcnt lgkmcnt(8)
	s_barrier
	s_waitcnt lgkmcnt(0)
	s_waitcnt lgkmcnt(0)
	v_mfma_f32_16x16x32_bf16 v[124:127], v[140:143], v[156:159], v[124:127]
	v_mfma_f32_16x16x32_bf16 v[120:123], v[148:151], v[156:159], v[120:123]
	v_mfma_f32_16x16x32_bf16 v[116:119], v[140:143], v[164:167], v[116:119]
	v_mfma_f32_16x16x32_bf16 v[112:115], v[148:151], v[164:167], v[112:115]
	v_mfma_f32_16x16x32_bf16 v[108:111], v[140:143], v[172:175], v[108:111]
	v_mfma_f32_16x16x32_bf16 v[104:107], v[148:151], v[172:175], v[104:107]
	v_mfma_f32_16x16x32_bf16 v[100:103], v[140:143], v[180:183], v[100:103]
	v_mfma_f32_16x16x32_bf16 v[96:99], v[148:151], v[180:183], v[96:99]
	v_mfma_f32_16x16x32_bf16 v[124:127], v[144:147], v[160:163], v[124:127]
	v_mfma_f32_16x16x32_bf16 v[120:123], v[152:155], v[160:163], v[120:123]
	v_mfma_f32_16x16x32_bf16 v[116:119], v[144:147], v[168:171], v[116:119]
	v_mfma_f32_16x16x32_bf16 v[112:115], v[152:155], v[168:171], v[112:115]
	v_mfma_f32_16x16x32_bf16 v[108:111], v[144:147], v[176:179], v[108:111]
	v_mfma_f32_16x16x32_bf16 v[104:107], v[152:155], v[176:179], v[104:107]
	v_mfma_f32_16x16x32_bf16 v[100:103], v[144:147], v[184:187], v[100:103]
	v_mfma_f32_16x16x32_bf16 v[96:99], v[152:155], v[184:187], v[96:99]
	s_barrier
	s_add_i32 s40, 0, 0x14000
	s_add_u32 s18, s14, s10
	v_add_u32_e32 v131, s40, v137
	v_mov_b32_e32 v188, v133
	v_mov_b32_e32 v190, v135
	s_addc_u32 s19, s15, s11
	ds_read_b128 v[222:225], v131
	ds_read_b128 v[226:229], v131 offset:1024
	ds_read_b128 v[230:233], v131 offset:2048
	ds_read_b128 v[234:237], v131 offset:3072
	s_add_i32 s36, s36, s23
	v_lshl_add_u64 v[192:193], s[18:19], 0, v[188:189]
	v_mov_b32_e32 v191, v189
	v_lshl_add_u64 v[192:193], v[192:193], 0, s[88:89]
	s_mov_b32 m0, s36
	v_lshl_add_u64 v[190:191], s[18:19], 0, v[190:191]
	s_add_i32 s37, s36, 0x2000
	global_load_lds_dwordx4 v[192:193], off
	v_lshl_add_u64 v[190:191], v[190:191], 0, s[88:89]
	s_mov_b32 m0, s37
	s_nop 0
	global_load_lds_dwordx4 v[190:191], off
	s_barrier
	s_waitcnt lgkmcnt(0)
	s_waitcnt lgkmcnt(0)
	v_mfma_f32_16x16x32_bf16 v[92:95], v[222:225], v[156:159], v[92:95]
	v_mfma_f32_16x16x32_bf16 v[88:91], v[230:233], v[156:159], v[88:91]
	v_mfma_f32_16x16x32_bf16 v[84:87], v[222:225], v[164:167], v[84:87]
	v_mfma_f32_16x16x32_bf16 v[80:83], v[230:233], v[164:167], v[80:83]
	v_mfma_f32_16x16x32_bf16 v[76:79], v[222:225], v[172:175], v[76:79]
	v_mfma_f32_16x16x32_bf16 v[72:75], v[230:233], v[172:175], v[72:75]
	v_mfma_f32_16x16x32_bf16 v[68:71], v[222:225], v[180:183], v[68:71]
	v_mfma_f32_16x16x32_bf16 v[64:67], v[230:233], v[180:183], v[64:67]
	v_mfma_f32_16x16x32_bf16 v[92:95], v[226:229], v[160:163], v[92:95]
	v_mfma_f32_16x16x32_bf16 v[88:91], v[234:237], v[160:163], v[88:91]
	v_mfma_f32_16x16x32_bf16 v[84:87], v[226:229], v[168:171], v[84:87]
	v_mfma_f32_16x16x32_bf16 v[80:83], v[234:237], v[168:171], v[80:83]
	v_mfma_f32_16x16x32_bf16 v[76:79], v[226:229], v[176:179], v[76:79]
	v_mfma_f32_16x16x32_bf16 v[72:75], v[234:237], v[176:179], v[72:75]
	v_mfma_f32_16x16x32_bf16 v[68:71], v[226:229], v[184:187], v[68:71]
	v_mfma_f32_16x16x32_bf16 v[64:67], v[234:237], v[184:187], v[64:67]
	v_mov_b32_e32 v188, v132
	v_mov_b32_e32 v190, v134
	s_barrier
	ds_read_b128 v[156:159], v139 offset:16384
	ds_read_b128 v[160:163], v139 offset:17408
	ds_read_b128 v[164:167], v139 offset:18432
	ds_read_b128 v[168:171], v139 offset:19456
	ds_read_b128 v[172:175], v139 offset:20480
	ds_read_b128 v[176:179], v139 offset:21504
	ds_read_b128 v[180:183], v139 offset:22528
	ds_read_b128 v[184:187], v139 offset:23552
	v_mov_b32_e32 v191, v189
	v_lshl_add_u64 v[192:193], s[12:13], 0, v[188:189]
	s_mov_b32 m0, s24
	v_lshl_add_u64 v[192:193], v[192:193], 0, s[88:89]
	v_lshl_add_u64 v[190:191], s[12:13], 0, v[190:191]
	global_load_lds_dwordx4 v[192:193], off
	v_lshl_add_u64 v[190:191], v[190:191], 0, s[88:89]
	s_mov_b32 m0, s25
	s_nop 0
	global_load_lds_dwordx4 v[190:191], off
	s_barrier
	s_waitcnt lgkmcnt(0)
	s_waitcnt lgkmcnt(0)
	v_mfma_f32_16x16x32_bf16 v[60:63], v[140:143], v[156:159], v[60:63]
	v_mfma_f32_16x16x32_bf16 v[56:59], v[148:151], v[156:159], v[56:59]
	v_mfma_f32_16x16x32_bf16 v[52:55], v[140:143], v[164:167], v[52:55]
	v_mfma_f32_16x16x32_bf16 v[48:51], v[148:151], v[164:167], v[48:51]
	v_mfma_f32_16x16x32_bf16 v[44:47], v[140:143], v[172:175], v[44:47]
	v_mfma_f32_16x16x32_bf16 v[40:43], v[148:151], v[172:175], v[40:43]
	v_mfma_f32_16x16x32_bf16 v[36:39], v[140:143], v[180:183], v[36:39]
	v_mfma_f32_16x16x32_bf16 v[32:35], v[148:151], v[180:183], v[32:35]
	v_mfma_f32_16x16x32_bf16 v[60:63], v[144:147], v[160:163], v[60:63]
	v_mfma_f32_16x16x32_bf16 v[56:59], v[152:155], v[160:163], v[56:59]
	v_mfma_f32_16x16x32_bf16 v[52:55], v[144:147], v[168:171], v[52:55]
	v_mfma_f32_16x16x32_bf16 v[48:51], v[152:155], v[168:171], v[48:51]
	v_mfma_f32_16x16x32_bf16 v[44:47], v[144:147], v[176:179], v[44:47]
	v_mfma_f32_16x16x32_bf16 v[40:43], v[152:155], v[176:179], v[40:43]
	v_mfma_f32_16x16x32_bf16 v[36:39], v[144:147], v[184:187], v[36:39]
	v_mfma_f32_16x16x32_bf16 v[32:35], v[152:155], v[184:187], v[32:35]
	s_barrier
	v_mov_b32_e32 v188, v133
	v_mov_b32_e32 v140, v135
	s_add_i32 s40, s40, s23
	v_lshl_add_u64 v[142:143], s[18:19], 0, v[188:189]
	v_mov_b32_e32 v141, v189
	v_lshl_add_u64 v[142:143], v[142:143], 0, s[38:39]
	s_mov_b32 m0, s40
	v_lshl_add_u64 v[140:141], s[18:19], 0, v[140:141]
	s_add_i32 s41, s40, 0x2000
	global_load_lds_dwordx4 v[142:143], off
	v_lshl_add_u64 v[140:141], v[140:141], 0, s[38:39]
	s_mov_b32 m0, s41
	s_nop 0
	global_load_lds_dwordx4 v[140:141], off
	s_waitcnt vmcnt(6)
	s_barrier
	v_mfma_f32_16x16x32_bf16 v[28:31], v[222:225], v[156:159], v[28:31]
	v_mfma_f32_16x16x32_bf16 v[24:27], v[230:233], v[156:159], v[24:27]
	v_mfma_f32_16x16x32_bf16 v[20:23], v[222:225], v[164:167], v[20:23]
	v_mfma_f32_16x16x32_bf16 v[16:19], v[230:233], v[164:167], v[16:19]
	v_mfma_f32_16x16x32_bf16 v[12:15], v[222:225], v[172:175], v[12:15]
	v_mfma_f32_16x16x32_bf16 v[8:11], v[230:233], v[172:175], v[8:11]
	v_mfma_f32_16x16x32_bf16 v[4:7], v[222:225], v[180:183], v[4:7]
	v_mfma_f32_16x16x32_bf16 v[0:3], v[230:233], v[180:183], v[0:3]
	v_mfma_f32_16x16x32_bf16 v[28:31], v[226:229], v[160:163], v[28:31]
	v_mfma_f32_16x16x32_bf16 v[24:27], v[234:237], v[160:163], v[24:27]
	v_mfma_f32_16x16x32_bf16 v[20:23], v[226:229], v[168:171], v[20:23]
	v_mfma_f32_16x16x32_bf16 v[16:19], v[234:237], v[168:171], v[16:19]
	v_mfma_f32_16x16x32_bf16 v[12:15], v[226:229], v[176:179], v[12:15]
	v_mfma_f32_16x16x32_bf16 v[8:11], v[234:237], v[176:179], v[8:11]
	v_mfma_f32_16x16x32_bf16 v[4:7], v[226:229], v[184:187], v[4:7]
	v_mfma_f32_16x16x32_bf16 v[0:3], v[234:237], v[184:187], v[0:3]
	s_add_i32 s45, 0, 0x18000
	v_add_u32_e32 v140, s45, v137
	s_barrier
	ds_read_b128 v[142:145], v140
	ds_read_b128 v[146:149], v140 offset:1024
	ds_read_b128 v[150:153], v140 offset:2048
	ds_read_b128 v[154:157], v140 offset:3072
	v_mov_b32_e32 v188, v132
	v_mov_b32_e32 v186, v134
	ds_read_b128 v[158:161], v139 offset:32768
	ds_read_b128 v[162:165], v139 offset:33792
	ds_read_b128 v[166:169], v139 offset:34816
	ds_read_b128 v[170:173], v139 offset:35840
	ds_read_b128 v[174:177], v139 offset:36864
	ds_read_b128 v[178:181], v139 offset:37888
	ds_read_b128 v[182:185], v139 offset:38912
	ds_read_b128 v[222:225], v139 offset:39936
	v_mov_b32_e32 v187, v189
	v_lshl_add_u64 v[190:191], s[12:13], 0, v[188:189]
	s_mov_b32 m0, s26
	v_lshl_add_u64 v[190:191], v[190:191], 0, s[38:39]
	v_lshl_add_u64 v[186:187], s[12:13], 0, v[186:187]
	global_load_lds_dwordx4 v[190:191], off
	v_lshl_add_u64 v[186:187], v[186:187], 0, s[38:39]
	s_mov_b32 m0, s27
	s_nop 0
	global_load_lds_dwordx4 v[186:187], off
	s_waitcnt lgkmcnt(8)
	s_barrier
	s_waitcnt lgkmcnt(0)
	s_waitcnt lgkmcnt(0)
	v_mfma_f32_16x16x32_bf16 v[124:127], v[142:145], v[158:161], v[124:127]
	v_mfma_f32_16x16x32_bf16 v[120:123], v[150:153], v[158:161], v[120:123]
	v_mfma_f32_16x16x32_bf16 v[116:119], v[142:145], v[166:169], v[116:119]
	v_mfma_f32_16x16x32_bf16 v[112:115], v[150:153], v[166:169], v[112:115]
	v_mfma_f32_16x16x32_bf16 v[108:111], v[142:145], v[174:177], v[108:111]
	v_mfma_f32_16x16x32_bf16 v[104:107], v[150:153], v[174:177], v[104:107]
	v_mfma_f32_16x16x32_bf16 v[100:103], v[142:145], v[182:185], v[100:103]
	v_mfma_f32_16x16x32_bf16 v[96:99], v[150:153], v[182:185], v[96:99]
	v_mfma_f32_16x16x32_bf16 v[124:127], v[146:149], v[162:165], v[124:127]
	v_mfma_f32_16x16x32_bf16 v[120:123], v[154:157], v[162:165], v[120:123]
	v_mfma_f32_16x16x32_bf16 v[116:119], v[146:149], v[170:173], v[116:119]
	v_mfma_f32_16x16x32_bf16 v[112:115], v[154:157], v[170:173], v[112:115]
	v_mfma_f32_16x16x32_bf16 v[108:111], v[146:149], v[178:181], v[108:111]
	v_mfma_f32_16x16x32_bf16 v[104:107], v[154:157], v[178:181], v[104:107]
	v_mfma_f32_16x16x32_bf16 v[100:103], v[146:149], v[222:225], v[100:103]
	v_mfma_f32_16x16x32_bf16 v[96:99], v[154:157], v[222:225], v[96:99]
	s_barrier
	s_add_i32 s43, 0, 0x1c000
	v_add_u32_e32 v141, s43, v137
	v_mov_b32_e32 v188, v133
	v_mov_b32_e32 v186, v135
	ds_read_b128 v[226:229], v141
	ds_read_b128 v[230:233], v141 offset:1024
	ds_read_b128 v[234:237], v141 offset:2048
	ds_read_b128 v[238:241], v141 offset:3072
	s_add_i32 s45, s45, s23
	v_lshl_add_u64 v[190:191], s[18:19], 0, v[188:189]
	v_mov_b32_e32 v187, v189
	v_lshl_add_u64 v[190:191], v[190:191], 0, s[2:3]
	s_mov_b32 m0, s45
	v_lshl_add_u64 v[186:187], s[18:19], 0, v[186:187]
	s_add_i32 s42, s45, 0x2000
	global_load_lds_dwordx4 v[190:191], off
	v_lshl_add_u64 v[186:187], v[186:187], 0, s[2:3]
	s_mov_b32 m0, s42
	s_nop 0
	global_load_lds_dwordx4 v[186:187], off
	s_barrier
	s_waitcnt lgkmcnt(0)
	s_waitcnt lgkmcnt(0)
	v_mfma_f32_16x16x32_bf16 v[92:95], v[226:229], v[158:161], v[92:95]
	v_mfma_f32_16x16x32_bf16 v[88:91], v[234:237], v[158:161], v[88:91]
	v_mfma_f32_16x16x32_bf16 v[84:87], v[226:229], v[166:169], v[84:87]
	v_mfma_f32_16x16x32_bf16 v[80:83], v[234:237], v[166:169], v[80:83]
	v_mfma_f32_16x16x32_bf16 v[76:79], v[226:229], v[174:177], v[76:79]
	v_mfma_f32_16x16x32_bf16 v[72:75], v[234:237], v[174:177], v[72:75]
	v_mfma_f32_16x16x32_bf16 v[68:71], v[226:229], v[182:185], v[68:71]
	v_mfma_f32_16x16x32_bf16 v[64:67], v[234:237], v[182:185], v[64:67]
	v_mfma_f32_16x16x32_bf16 v[92:95], v[230:233], v[162:165], v[92:95]
	v_mfma_f32_16x16x32_bf16 v[88:91], v[238:241], v[162:165], v[88:91]
	v_mfma_f32_16x16x32_bf16 v[84:87], v[230:233], v[170:173], v[84:87]
	v_mfma_f32_16x16x32_bf16 v[80:83], v[238:241], v[170:173], v[80:83]
	v_mfma_f32_16x16x32_bf16 v[76:79], v[230:233], v[178:181], v[76:79]
	v_mfma_f32_16x16x32_bf16 v[72:75], v[238:241], v[178:181], v[72:75]
	v_mfma_f32_16x16x32_bf16 v[68:71], v[230:233], v[222:225], v[68:71]
	v_mfma_f32_16x16x32_bf16 v[64:67], v[238:241], v[222:225], v[64:67]
	v_mov_b32_e32 v188, v132
	v_mov_b32_e32 v186, v134
	s_barrier
	ds_read_b128 v[158:161], v139 offset:49152
	ds_read_b128 v[162:165], v139 offset:50176
	ds_read_b128 v[166:169], v139 offset:51200
	ds_read_b128 v[170:173], v139 offset:52224
	ds_read_b128 v[174:177], v139 offset:53248
	ds_read_b128 v[178:181], v139 offset:54272
	ds_read_b128 v[182:185], v139 offset:55296
	ds_read_b128 v[222:225], v139 offset:56320
	v_mov_b32_e32 v187, v189
	v_lshl_add_u64 v[190:191], s[12:13], 0, v[188:189]
	s_mov_b32 m0, s28
	v_lshl_add_u64 v[190:191], v[190:191], 0, s[2:3]
	v_lshl_add_u64 v[186:187], s[12:13], 0, v[186:187]
	global_load_lds_dwordx4 v[190:191], off
	v_lshl_add_u64 v[186:187], v[186:187], 0, s[2:3]
	s_mov_b32 m0, s29
	s_nop 0
	global_load_lds_dwordx4 v[186:187], off
	s_barrier
	s_waitcnt lgkmcnt(0)
	s_waitcnt lgkmcnt(0)
	v_mfma_f32_16x16x32_bf16 v[60:63], v[142:145], v[158:161], v[60:63]
	v_mfma_f32_16x16x32_bf16 v[56:59], v[150:153], v[158:161], v[56:59]
	v_mfma_f32_16x16x32_bf16 v[52:55], v[142:145], v[166:169], v[52:55]
	v_mfma_f32_16x16x32_bf16 v[48:51], v[150:153], v[166:169], v[48:51]
	v_mfma_f32_16x16x32_bf16 v[44:47], v[142:145], v[174:177], v[44:47]
	v_mfma_f32_16x16x32_bf16 v[40:43], v[150:153], v[174:177], v[40:43]
	v_mfma_f32_16x16x32_bf16 v[36:39], v[142:145], v[182:185], v[36:39]
	v_mfma_f32_16x16x32_bf16 v[32:35], v[150:153], v[182:185], v[32:35]
	v_mfma_f32_16x16x32_bf16 v[60:63], v[146:149], v[162:165], v[60:63]
	v_mfma_f32_16x16x32_bf16 v[56:59], v[154:157], v[162:165], v[56:59]
	v_mfma_f32_16x16x32_bf16 v[52:55], v[146:149], v[170:173], v[52:55]
	v_mfma_f32_16x16x32_bf16 v[48:51], v[154:157], v[170:173], v[48:51]
	v_mfma_f32_16x16x32_bf16 v[44:47], v[146:149], v[178:181], v[44:47]
	v_mfma_f32_16x16x32_bf16 v[40:43], v[154:157], v[178:181], v[40:43]
	v_mfma_f32_16x16x32_bf16 v[36:39], v[146:149], v[222:225], v[36:39]
	v_mfma_f32_16x16x32_bf16 v[32:35], v[154:157], v[222:225], v[32:35]
	s_barrier
	v_mov_b32_e32 v188, v133
	v_mov_b32_e32 v142, v135
	s_add_i32 s43, s43, s23
	v_lshl_add_u64 v[144:145], s[18:19], 0, v[188:189]
	v_mov_b32_e32 v143, v189
	v_lshl_add_u64 v[144:145], v[144:145], 0, s[48:49]
	s_mov_b32 m0, s43
	v_lshl_add_u64 v[142:143], s[18:19], 0, v[142:143]
	s_add_i32 s44, s43, 0x2000
	global_load_lds_dwordx4 v[144:145], off
	v_lshl_add_u64 v[142:143], v[142:143], 0, s[48:49]
	s_mov_b32 m0, s44
	s_nop 0
	global_load_lds_dwordx4 v[142:143], off
	s_waitcnt vmcnt(6)
	s_barrier
	v_mfma_f32_16x16x32_bf16 v[28:31], v[226:229], v[158:161], v[28:31]
	v_mfma_f32_16x16x32_bf16 v[24:27], v[234:237], v[158:161], v[24:27]
	v_mfma_f32_16x16x32_bf16 v[20:23], v[226:229], v[166:169], v[20:23]
	v_mfma_f32_16x16x32_bf16 v[16:19], v[234:237], v[166:169], v[16:19]
	v_mfma_f32_16x16x32_bf16 v[12:15], v[226:229], v[174:177], v[12:15]
	v_mfma_f32_16x16x32_bf16 v[8:11], v[234:237], v[174:177], v[8:11]
	v_mfma_f32_16x16x32_bf16 v[4:7], v[226:229], v[182:185], v[4:7]
	v_mfma_f32_16x16x32_bf16 v[0:3], v[234:237], v[182:185], v[0:3]
	v_mfma_f32_16x16x32_bf16 v[28:31], v[230:233], v[162:165], v[28:31]
	v_mfma_f32_16x16x32_bf16 v[24:27], v[238:241], v[162:165], v[24:27]
	v_mfma_f32_16x16x32_bf16 v[20:23], v[230:233], v[170:173], v[20:23]
	v_mfma_f32_16x16x32_bf16 v[16:19], v[238:241], v[170:173], v[16:19]
	v_mfma_f32_16x16x32_bf16 v[12:15], v[230:233], v[178:181], v[12:15]
	v_mfma_f32_16x16x32_bf16 v[8:11], v[238:241], v[178:181], v[8:11]
	v_mfma_f32_16x16x32_bf16 v[4:7], v[230:233], v[222:225], v[4:7]
	v_mfma_f32_16x16x32_bf16 v[0:3], v[238:241], v[222:225], v[0:3]
	s_add_i32 s7, s7, 2
	s_add_u32 s10, s10, 0x100
	s_addc_u32 s11, s11, 0
	s_cmp_lt_u32 s7, 12
	s_barrier
	s_cbranch_scc1 .LBB0_503
	s_ashr_i32 s9, s8, 31
	s_ashr_i32 s7, s6, 31
	s_lshl_b64 s[12:13], s[8:9], 19
	s_lshl_b64 s[10:11], s[6:7], 19
	ds_read_b128 v[142:145], v130
	ds_read_b128 v[146:149], v130 offset:1024
	ds_read_b128 v[150:153], v130 offset:2048
	ds_read_b128 v[154:157], v130 offset:3072
	s_add_u32 s10, s21, s10
	s_addc_u32 s11, s22, s11
	s_and_b64 s[18:19], vcc, exec
	s_cselect_b32 s15, s11, s15
	s_cselect_b32 s14, s10, s14
	s_add_u32 s12, s66, s12
	s_addc_u32 s13, s67, s13
	s_and_b64 s[18:19], vcc, exec
	s_cselect_b32 s19, s13, s17
	s_cselect_b32 s18, s12, s16
	s_add_u32 s16, s16, 0x40780
	v_mov_b32_e32 v130, v132
	v_mov_b32_e32 v186, v134
	s_addc_u32 s17, s17, 0
	s_mov_b32 m0, s34
	ds_read_b128 v[158:161], v139
	ds_read_b128 v[162:165], v139 offset:1024
	ds_read_b128 v[166:169], v139 offset:2048
	ds_read_b128 v[170:173], v139 offset:3072
	ds_read_b128 v[174:177], v139 offset:4096
	ds_read_b128 v[178:181], v139 offset:5120
	ds_read_b128 v[182:185], v139 offset:6144
	ds_read_b128 v[222:225], v139 offset:7168
	s_nop 0
	global_load_lds_dwordx4 v130, s[16:17]
	s_mov_b32 m0, s35
	s_nop 0
	global_load_lds_dwordx4 v186, s[16:17]
	s_waitcnt lgkmcnt(8)
	s_barrier
	s_waitcnt lgkmcnt(0)
	s_waitcnt lgkmcnt(0)
	v_mfma_f32_16x16x32_bf16 v[124:127], v[142:145], v[158:161], v[124:127]
	v_mfma_f32_16x16x32_bf16 v[120:123], v[150:153], v[158:161], v[120:123]
	v_mfma_f32_16x16x32_bf16 v[116:119], v[142:145], v[166:169], v[116:119]
	v_mfma_f32_16x16x32_bf16 v[112:115], v[150:153], v[166:169], v[112:115]
	v_mfma_f32_16x16x32_bf16 v[100:103], v[142:145], v[182:185], v[100:103]
	v_mfma_f32_16x16x32_bf16 v[96:99], v[150:153], v[182:185], v[96:99]
	v_mfma_f32_16x16x32_bf16 v[124:127], v[146:149], v[162:165], v[124:127]
	v_mfma_f32_16x16x32_bf16 v[120:123], v[154:157], v[162:165], v[120:123]
	v_mfma_f32_16x16x32_bf16 v[116:119], v[146:149], v[170:173], v[116:119]
	v_mfma_f32_16x16x32_bf16 v[112:115], v[154:157], v[170:173], v[112:115]
	v_mfma_f32_16x16x32_bf16 v[108:111], v[142:145], v[174:177], v[108:111]
	v_mfma_f32_16x16x32_bf16 v[104:107], v[150:153], v[174:177], v[104:107]
	v_mfma_f32_16x16x32_bf16 v[100:103], v[146:149], v[222:225], v[100:103]
	v_mfma_f32_16x16x32_bf16 v[96:99], v[154:157], v[222:225], v[96:99]
	v_mfma_f32_16x16x32_bf16 v[226:229], v[146:149], v[178:181], v[108:111]
	v_mfma_f32_16x16x32_bf16 v[230:233], v[154:157], v[178:181], v[104:107]
	s_barrier
	s_nop 1
	ds_read_b128 v[104:107], v131
	ds_read_b128 v[108:111], v131 offset:1024
	ds_read_b128 v[234:237], v131 offset:2048
	ds_read_b128 v[238:241], v131 offset:3072
	v_mov_b32_e32 v130, v133
	v_mov_b32_e32 v131, v135
	s_mov_b32 m0, s36
	s_nop 0
	global_load_lds_dwordx4 v130, s[14:15]
	s_mov_b32 m0, s37
	s_nop 0
	global_load_lds_dwordx4 v131, s[14:15]
	s_barrier
	s_waitcnt lgkmcnt(0)
	s_waitcnt lgkmcnt(0)
	v_mfma_f32_16x16x32_bf16 v[84:87], v[104:107], v[166:169], v[84:87]
	v_mfma_f32_16x16x32_bf16 v[80:83], v[234:237], v[166:169], v[80:83]
	v_mfma_f32_16x16x32_bf16 v[68:71], v[104:107], v[182:185], v[68:71]
	v_mfma_f32_16x16x32_bf16 v[64:67], v[234:237], v[182:185], v[64:67]
	v_mfma_f32_16x16x32_bf16 v[92:95], v[104:107], v[158:161], v[92:95]
	v_mfma_f32_16x16x32_bf16 v[88:91], v[234:237], v[158:161], v[88:91]
	v_mfma_f32_16x16x32_bf16 v[84:87], v[108:111], v[170:173], v[84:87]
	v_mfma_f32_16x16x32_bf16 v[80:83], v[238:241], v[170:173], v[80:83]
	v_mfma_f32_16x16x32_bf16 v[76:79], v[104:107], v[174:177], v[76:79]
	v_mfma_f32_16x16x32_bf16 v[72:75], v[234:237], v[174:177], v[72:75]
	v_mfma_f32_16x16x32_bf16 v[68:71], v[108:111], v[222:225], v[68:71]
	v_mfma_f32_16x16x32_bf16 v[64:67], v[238:241], v[222:225], v[64:67]
	v_mfma_f32_16x16x32_bf16 v[242:245], v[108:111], v[162:165], v[92:95]
	v_mfma_f32_16x16x32_bf16 v[158:161], v[238:241], v[162:165], v[88:91]
	v_mfma_f32_16x16x32_bf16 v[162:165], v[108:111], v[178:181], v[76:79]
	v_mfma_f32_16x16x32_bf16 v[166:169], v[238:241], v[178:181], v[72:75]
	v_mov_b32_e32 v130, v132
	v_mov_b32_e32 v131, v134
	s_mov_b32 m0, s24
	s_barrier
	ds_read_b128 v[72:75], v139 offset:16384
	ds_read_b128 v[76:79], v139 offset:17408
	ds_read_b128 v[88:91], v139 offset:18432
	ds_read_b128 v[92:95], v139 offset:19456
	ds_read_b128 v[170:173], v139 offset:20480
	ds_read_b128 v[174:177], v139 offset:21504
	ds_read_b128 v[178:181], v139 offset:22528
	ds_read_b128 v[182:185], v139 offset:23552
	s_nop 0
	global_load_lds_dwordx4 v130, s[18:19]
	s_mov_b32 m0, s25
	s_nop 0
	global_load_lds_dwordx4 v131, s[18:19]
	s_barrier
	s_waitcnt lgkmcnt(0)
	s_waitcnt lgkmcnt(0)
	v_mfma_f32_16x16x32_bf16 v[60:63], v[142:145], v[72:75], v[60:63]
	v_mfma_f32_16x16x32_bf16 v[56:59], v[150:153], v[72:75], v[56:59]
	v_mfma_f32_16x16x32_bf16 v[52:55], v[142:145], v[88:91], v[52:55]
	v_mfma_f32_16x16x32_bf16 v[48:51], v[150:153], v[88:91], v[48:51]
	v_mfma_f32_16x16x32_bf16 v[36:39], v[142:145], v[178:181], v[36:39]
	v_mfma_f32_16x16x32_bf16 v[32:35], v[150:153], v[178:181], v[32:35]
	v_mfma_f32_16x16x32_bf16 v[60:63], v[146:149], v[76:79], v[60:63]
	v_mfma_f32_16x16x32_bf16 v[56:59], v[154:157], v[76:79], v[56:59]
	v_mfma_f32_16x16x32_bf16 v[52:55], v[146:149], v[92:95], v[52:55]
	v_mfma_f32_16x16x32_bf16 v[48:51], v[154:157], v[92:95], v[48:51]
	v_mfma_f32_16x16x32_bf16 v[44:47], v[142:145], v[170:173], v[44:47]
	v_mfma_f32_16x16x32_bf16 v[40:43], v[150:153], v[170:173], v[40:43]
	v_mfma_f32_16x16x32_bf16 v[36:39], v[146:149], v[182:185], v[36:39]
	v_mfma_f32_16x16x32_bf16 v[32:35], v[154:157], v[182:185], v[32:35]
	v_mfma_f32_16x16x32_bf16 v[222:225], v[146:149], v[174:177], v[44:47]
	v_mfma_f32_16x16x32_bf16 v[246:249], v[154:157], v[174:177], v[40:43]
	s_barrier
	s_add_u32 s16, s14, 0x40000
	s_nop 0
	v_mov_b32_e32 v40, v133
	v_mov_b32_e32 v41, v135
	s_addc_u32 s17, s15, 0
	s_mov_b32 m0, s40
	s_nop 0
	global_load_lds_dwordx4 v40, s[16:17]
	s_mov_b32 m0, s41
	s_nop 0
	global_load_lds_dwordx4 v41, s[16:17]
	s_waitcnt vmcnt(6)
	s_barrier
	v_mfma_f32_16x16x32_bf16 v[20:23], v[104:107], v[88:91], v[20:23]
	v_mfma_f32_16x16x32_bf16 v[16:19], v[234:237], v[88:91], v[16:19]
	v_mfma_f32_16x16x32_bf16 v[4:7], v[104:107], v[178:181], v[4:7]
	v_mfma_f32_16x16x32_bf16 v[0:3], v[234:237], v[178:181], v[0:3]
	v_mfma_f32_16x16x32_bf16 v[28:31], v[104:107], v[72:75], v[28:31]
	v_mfma_f32_16x16x32_bf16 v[24:27], v[234:237], v[72:75], v[24:27]
	v_mfma_f32_16x16x32_bf16 v[20:23], v[108:111], v[92:95], v[20:23]
	v_mfma_f32_16x16x32_bf16 v[16:19], v[238:241], v[92:95], v[16:19]
	v_mfma_f32_16x16x32_bf16 v[12:15], v[104:107], v[170:173], v[12:15]
	v_mfma_f32_16x16x32_bf16 v[8:11], v[234:237], v[170:173], v[8:11]
	v_mfma_f32_16x16x32_bf16 v[4:7], v[108:111], v[182:185], v[4:7]
	v_mfma_f32_16x16x32_bf16 v[0:3], v[238:241], v[182:185], v[0:3]
	v_mfma_f32_16x16x32_bf16 v[142:145], v[108:111], v[76:79], v[28:31]
	v_mfma_f32_16x16x32_bf16 v[146:149], v[238:241], v[76:79], v[24:27]
	v_mfma_f32_16x16x32_bf16 v[150:153], v[108:111], v[174:177], v[12:15]
	v_mfma_f32_16x16x32_bf16 v[154:157], v[238:241], v[174:177], v[8:11]
	s_barrier
	s_nop 0
	ds_read_b128 v[8:11], v140
	ds_read_b128 v[12:15], v140 offset:1024
	ds_read_b128 v[170:173], v140 offset:2048
	ds_read_b128 v[174:177], v140 offset:3072
	s_add_u32 s16, s18, 0x40000
	v_mov_b32_e32 v72, v132
	v_mov_b32_e32 v73, v134
	s_addc_u32 s17, s19, 0
	s_mov_b32 m0, s26
	ds_read_b128 v[24:27], v139 offset:32768
	ds_read_b128 v[28:31], v139 offset:33792
	ds_read_b128 v[40:43], v139 offset:34816
	ds_read_b128 v[44:47], v139 offset:35840
	ds_read_b128 v[178:181], v139 offset:36864
	ds_read_b128 v[182:185], v139 offset:37888
	ds_read_b128 v[234:237], v139 offset:38912
	ds_read_b128 v[238:241], v139 offset:39936
	s_nop 0
	global_load_lds_dwordx4 v72, s[16:17]
	s_mov_b32 m0, s27
	s_nop 0
	global_load_lds_dwordx4 v73, s[16:17]
	s_waitcnt lgkmcnt(8)
	s_barrier
	s_waitcnt lgkmcnt(0)
	s_waitcnt lgkmcnt(0)
	v_mfma_f32_16x16x32_bf16 v[72:75], v[8:11], v[24:27], v[124:127]
	v_mfma_f32_16x16x32_bf16 v[124:127], v[12:15], v[28:31], v[72:75]
	v_mfma_f32_16x16x32_bf16 v[72:75], v[170:173], v[24:27], v[120:123]
	v_mfma_f32_16x16x32_bf16 v[120:123], v[174:177], v[28:31], v[72:75]
	v_mfma_f32_16x16x32_bf16 v[72:75], v[8:11], v[40:43], v[116:119]
	v_mfma_f32_16x16x32_bf16 v[108:111], v[12:15], v[44:47], v[72:75]
	v_mfma_f32_16x16x32_bf16 v[72:75], v[170:173], v[40:43], v[112:115]
	v_mfma_f32_16x16x32_bf16 v[104:107], v[174:177], v[44:47], v[72:75]
	v_mfma_f32_16x16x32_bf16 v[72:75], v[8:11], v[178:181], v[226:229]
	v_mfma_f32_16x16x32_bf16 v[92:95], v[12:15], v[182:185], v[72:75]
	v_mfma_f32_16x16x32_bf16 v[72:75], v[170:173], v[178:181], v[230:233]
	v_mfma_f32_16x16x32_bf16 v[88:91], v[174:177], v[182:185], v[72:75]
	v_mfma_f32_16x16x32_bf16 v[72:75], v[8:11], v[234:237], v[100:103]
	v_mfma_f32_16x16x32_bf16 v[76:79], v[12:15], v[238:241], v[72:75]
	v_mfma_f32_16x16x32_bf16 v[72:75], v[170:173], v[234:237], v[96:99]
	v_mfma_f32_16x16x32_bf16 v[72:75], v[174:177], v[238:241], v[72:75]
	s_barrier
	v_mov_b32_e32 v188, v133
	v_mov_b32_e32 v96, v135
	ds_read_b128 v[226:229], v141
	ds_read_b128 v[230:233], v141 offset:1024
	ds_read_b128 v[202:205], v141 offset:2048
	ds_read_b128 v[190:193], v141 offset:3072
	s_mov_b64 s[16:17], 0x80
	v_lshl_add_u64 v[98:99], s[14:15], 0, v[188:189]
	v_mov_b32_e32 v97, v189
	s_mov_b32 m0, s45
	v_lshl_add_u64 v[98:99], v[98:99], 0, s[16:17]
	v_lshl_add_u64 v[96:97], s[14:15], 0, v[96:97]
	global_load_lds_dwordx4 v[98:99], off
	v_lshl_add_u64 v[96:97], v[96:97], 0, s[16:17]
	s_mov_b32 m0, s42
	s_nop 0
	global_load_lds_dwordx4 v[96:97], off
	s_barrier
	s_waitcnt lgkmcnt(0)
	s_waitcnt lgkmcnt(0)
	v_mfma_f32_16x16x32_bf16 v[96:99], v[226:229], v[24:27], v[242:245]
	v_mfma_f32_16x16x32_bf16 v[24:27], v[202:205], v[24:27], v[158:161]
	v_mfma_f32_16x16x32_bf16 v[112:115], v[190:193], v[28:31], v[24:27]
	v_mfma_f32_16x16x32_bf16 v[24:27], v[226:229], v[40:43], v[84:87]
	v_mfma_f32_16x16x32_bf16 v[100:103], v[230:233], v[44:47], v[24:27]
	v_mfma_f32_16x16x32_bf16 v[24:27], v[202:205], v[40:43], v[80:83]
	v_mfma_f32_16x16x32_bf16 v[116:119], v[230:233], v[28:31], v[96:99]
	v_mfma_f32_16x16x32_bf16 v[96:99], v[190:193], v[44:47], v[24:27]
	v_mfma_f32_16x16x32_bf16 v[24:27], v[226:229], v[178:181], v[162:165]
	v_mfma_f32_16x16x32_bf16 v[84:87], v[230:233], v[182:185], v[24:27]
	v_mfma_f32_16x16x32_bf16 v[24:27], v[202:205], v[178:181], v[166:169]
	v_mfma_f32_16x16x32_bf16 v[80:83], v[190:193], v[182:185], v[24:27]
	v_mfma_f32_16x16x32_bf16 v[24:27], v[226:229], v[234:237], v[68:71]
	v_mfma_f32_16x16x32_bf16 v[68:71], v[230:233], v[238:241], v[24:27]
	v_mfma_f32_16x16x32_bf16 v[24:27], v[202:205], v[234:237], v[64:67]
	v_mfma_f32_16x16x32_bf16 v[64:67], v[190:193], v[238:241], v[24:27]
	v_mov_b32_e32 v188, v132
	s_nop 4
	v_mov_b32_e32 v24, v134
	s_barrier
	ds_read_b128 v[158:161], v139 offset:49152
	ds_read_b128 v[162:165], v139 offset:50176
	ds_read_b128 v[166:169], v139 offset:51200
	ds_read_b128 v[178:181], v139 offset:52224
	ds_read_b128 v[182:185], v139 offset:53248
	ds_read_b128 v[234:237], v139 offset:54272
	ds_read_b128 v[238:241], v139 offset:55296
	ds_read_b128 v[242:245], v139 offset:56320
	v_mov_b32_e32 v25, v189
	v_lshl_add_u64 v[26:27], s[18:19], 0, v[188:189]
	s_mov_b32 m0, s28
	v_lshl_add_u64 v[26:27], v[26:27], 0, s[16:17]
	v_lshl_add_u64 v[24:25], s[18:19], 0, v[24:25]
	global_load_lds_dwordx4 v[26:27], off
	v_lshl_add_u64 v[24:25], v[24:25], 0, s[16:17]
	s_mov_b32 m0, s29
	s_nop 0
	global_load_lds_dwordx4 v[24:25], off
	s_barrier
	s_waitcnt lgkmcnt(0)
	s_waitcnt lgkmcnt(0)
	v_mfma_f32_16x16x32_bf16 v[24:27], v[8:11], v[158:161], v[60:63]
	v_mfma_f32_16x16x32_bf16 v[60:63], v[12:15], v[162:165], v[24:27]
	v_mfma_f32_16x16x32_bf16 v[24:27], v[170:173], v[158:161], v[56:59]
	v_mfma_f32_16x16x32_bf16 v[56:59], v[174:177], v[162:165], v[24:27]
	v_mfma_f32_16x16x32_bf16 v[24:27], v[8:11], v[166:169], v[52:55]
	v_mfma_f32_16x16x32_bf16 v[44:47], v[12:15], v[178:181], v[24:27]
	v_mfma_f32_16x16x32_bf16 v[24:27], v[170:173], v[166:169], v[48:51]
	v_mfma_f32_16x16x32_bf16 v[40:43], v[174:177], v[178:181], v[24:27]
	v_mfma_f32_16x16x32_bf16 v[24:27], v[8:11], v[182:185], v[222:225]
	v_mfma_f32_16x16x32_bf16 v[8:11], v[8:11], v[238:241], v[36:39]
	v_mfma_f32_16x16x32_bf16 v[28:31], v[12:15], v[234:237], v[24:27]
	v_mfma_f32_16x16x32_bf16 v[24:27], v[170:173], v[182:185], v[246:249]
	v_mfma_f32_16x16x32_bf16 v[12:15], v[12:15], v[242:245], v[8:11]
	v_mfma_f32_16x16x32_bf16 v[8:11], v[170:173], v[238:241], v[32:35]
	v_mfma_f32_16x16x32_bf16 v[24:27], v[174:177], v[234:237], v[24:27]
	v_mfma_f32_16x16x32_bf16 v[8:11], v[174:177], v[242:245], v[8:11]
	s_barrier
	s_add_u32 s14, s14, 0x40080
	v_mov_b32_e32 v32, v133
	v_mov_b32_e32 v33, v135
	s_addc_u32 s15, s15, 0
	s_mov_b32 m0, s43
	s_nop 0
	global_load_lds_dwordx4 v32, s[14:15]
	s_mov_b32 m0, s44
	s_nop 0
	global_load_lds_dwordx4 v33, s[14:15]
	s_waitcnt vmcnt(6)
	s_barrier
; __device__ __forceinline__ unsigned cvt_pk_bf16(float lo, float hi) { unsigned r; asm("v_cvt_pk_bf16_f32 %0, %1, %2" : "=v"(r) : "v"(lo), "v"(hi)); return r; }
;     __device__ __forceinline__ void operator()(const f32x4 (&acc)[2][2][4][2], const Unit& u, int wr, int wc, int fr, int fq) const {
;         const int row0 = u.pm * BM + wr * 64 + fr, col0 = u.pn * BM + wc * 32 + 8 * fq;
; #pragma unroll
;         for (int ai = 0; ai < 2; ++ai)
; #pragma unroll
;             for (int m = 0; m < 4; ++m) { bf16_t* rowp = O + (size_t)(row0 + ai * HALF + m * 16) * ldc + col0;
; #pragma unroll
;                 for (int bj = 0; bj < 2; ++bj) { const f32x4 v0 = acc[ai][bj][m][0], v1 = acc[ai][bj][m][1];
;                     u32x4 w; w.x = cvt_pk_bf16(v0[0], v0[1]); w.y = cvt_pk_bf16(v0[2], v0[3]); w.z = cvt_pk_bf16(v1[0], v1[1]); w.w = cvt_pk_bf16(v1[2], v1[3]);
;                     *(u32x4*)(rowp + bj * HALF) = w; } }
	v_mfma_f32_16x16x32_bf16 v[32:35], v[226:229], v[158:161], v[142:145]
	v_mfma_f32_16x16x32_bf16 v[52:55], v[230:233], v[162:165], v[32:35]
	v_mfma_f32_16x16x32_bf16 v[32:35], v[202:205], v[158:161], v[146:149]
	v_mfma_f32_16x16x32_bf16 v[16:19], v[202:205], v[166:169], v[16:19]
	v_mfma_f32_16x16x32_bf16 v[48:51], v[190:193], v[162:165], v[32:35]
	v_mfma_f32_16x16x32_bf16 v[20:23], v[226:229], v[166:169], v[20:23]
	v_mfma_f32_16x16x32_bf16 v[32:35], v[190:193], v[178:181], v[16:19]
	v_mfma_f32_16x16x32_bf16 v[16:19], v[226:229], v[182:185], v[150:153]
	v_mfma_f32_16x16x32_bf16 v[36:39], v[230:233], v[178:181], v[20:23]
	v_mfma_f32_16x16x32_bf16 v[20:23], v[230:233], v[234:237], v[16:19]
	v_mfma_f32_16x16x32_bf16 v[16:19], v[202:205], v[182:185], v[154:157]
	v_mfma_f32_16x16x32_bf16 v[4:7], v[226:229], v[238:241], v[4:7]
	v_mfma_f32_16x16x32_bf16 v[0:3], v[202:205], v[238:241], v[0:3]
	v_mfma_f32_16x16x32_bf16 v[16:19], v[190:193], v[234:237], v[16:19]
	v_mfma_f32_16x16x32_bf16 v[4:7], v[230:233], v[242:245], v[4:7]
	v_mfma_f32_16x16x32_bf16 v[0:3], v[190:193], v[242:245], v[0:3]
	s_cmp_gt_i32 s31, 11
	s_mov_b64 s[14:15], -1
	s_barrier
	s_cbranch_scc0 .LBB0_506
	v_lshl_or_b32 v188, s31, 9, v138
	v_lshl_add_u32 v146, s33, 8, v136
	v_lshl_add_u64 v[130:131], s[94:95], 0, v[188:189]
	v_mad_i64_i32 v[144:145], s[14:15], v146, s63, v[130:131]
	v_cvt_pk_bf16_f32 v140, v124, v125
	v_cvt_pk_bf16_f32 v141, v126, v127
	v_cvt_pk_bf16_f32 v142, v120, v121
	v_cvt_pk_bf16_f32 v143, v122, v123
	global_store_dwordx4 v[144:145], v[140:143], off
	s_nop 1
	v_cvt_pk_bf16_f32 v140, v116, v117
	v_cvt_pk_bf16_f32 v141, v118, v119
	v_cvt_pk_bf16_f32 v142, v112, v113
	v_cvt_pk_bf16_f32 v143, v114, v115
	global_store_dwordx4 v[144:145], v[140:143], off offset:256
	s_nop 1
	v_or_b32_e32 v140, 16, v146
	v_mad_i64_i32 v[144:145], s[14:15], v140, s63, v[130:131]
	v_cvt_pk_bf16_f32 v140, v108, v109
	v_cvt_pk_bf16_f32 v141, v110, v111
	v_cvt_pk_bf16_f32 v142, v104, v105
	v_cvt_pk_bf16_f32 v143, v106, v107
	global_store_dwordx4 v[144:145], v[140:143], off
	s_nop 1
	v_cvt_pk_bf16_f32 v140, v100, v101
	v_cvt_pk_bf16_f32 v141, v102, v103
	v_cvt_pk_bf16_f32 v142, v96, v97
	v_cvt_pk_bf16_f32 v143, v98, v99
	global_store_dwordx4 v[144:145], v[140:143], off offset:256
	s_nop 1
	v_or_b32_e32 v140, 32, v146
	v_mad_i64_i32 v[144:145], s[14:15], v140, s63, v[130:131]
	v_cvt_pk_bf16_f32 v140, v92, v93
	v_cvt_pk_bf16_f32 v141, v94, v95
	v_cvt_pk_bf16_f32 v142, v88, v89
	v_cvt_pk_bf16_f32 v143, v90, v91
	global_store_dwordx4 v[144:145], v[140:143], off
	s_nop 1
	v_cvt_pk_bf16_f32 v140, v84, v85
	v_cvt_pk_bf16_f32 v141, v86, v87
	v_cvt_pk_bf16_f32 v142, v80, v81
	v_cvt_pk_bf16_f32 v143, v82, v83
	global_store_dwordx4 v[144:145], v[140:143], off offset:256
	s_nop 1
	v_or_b32_e32 v140, 48, v146
	v_mad_i64_i32 v[144:145], s[14:15], v140, s63, v[130:131]
	v_cvt_pk_bf16_f32 v140, v76, v77
	v_cvt_pk_bf16_f32 v141, v78, v79
	v_cvt_pk_bf16_f32 v142, v72, v73
	v_cvt_pk_bf16_f32 v143, v74, v75
	global_store_dwordx4 v[144:145], v[140:143], off
	s_nop 1
	v_cvt_pk_bf16_f32 v140, v68, v69
	v_cvt_pk_bf16_f32 v141, v70, v71
	v_cvt_pk_bf16_f32 v142, v64, v65
	v_cvt_pk_bf16_f32 v143, v66, v67
	global_store_dwordx4 v[144:145], v[140:143], off offset:256
	s_nop 1
	v_add_u32_e32 v140, 0x80, v146
	v_mad_i64_i32 v[144:145], s[14:15], v140, s63, v[130:131]
	v_cvt_pk_bf16_f32 v140, v60, v61
	v_cvt_pk_bf16_f32 v141, v62, v63
	v_cvt_pk_bf16_f32 v142, v56, v57
	v_cvt_pk_bf16_f32 v143, v58, v59
	global_store_dwordx4 v[144:145], v[140:143], off
	s_nop 1
	v_cvt_pk_bf16_f32 v140, v52, v53
	v_cvt_pk_bf16_f32 v141, v54, v55
	v_cvt_pk_bf16_f32 v142, v48, v49
	v_cvt_pk_bf16_f32 v143, v50, v51
	global_store_dwordx4 v[144:145], v[140:143], off offset:256
	s_nop 1
	v_add_u32_e32 v140, 0x90, v146
	v_mad_i64_i32 v[144:145], s[14:15], v140, s63, v[130:131]
	v_cvt_pk_bf16_f32 v140, v44, v45
	v_cvt_pk_bf16_f32 v141, v46, v47
	v_cvt_pk_bf16_f32 v142, v40, v41
	v_cvt_pk_bf16_f32 v143, v42, v43
	global_store_dwordx4 v[144:145], v[140:143], off
	s_nop 1
	v_cvt_pk_bf16_f32 v140, v36, v37
	v_cvt_pk_bf16_f32 v141, v38, v39
	v_cvt_pk_bf16_f32 v142, v32, v33
	v_cvt_pk_bf16_f32 v143, v34, v35
	global_store_dwordx4 v[144:145], v[140:143], off offset:256
	s_nop 1
	v_add_u32_e32 v140, 0xa0, v146
	v_mad_i64_i32 v[144:145], s[14:15], v140, s63, v[130:131]
	v_cvt_pk_bf16_f32 v140, v28, v29
	v_cvt_pk_bf16_f32 v141, v30, v31
	v_cvt_pk_bf16_f32 v142, v24, v25
	v_cvt_pk_bf16_f32 v143, v26, v27
	global_store_dwordx4 v[144:145], v[140:143], off
	s_nop 1
	v_cvt_pk_bf16_f32 v140, v20, v21
	v_cvt_pk_bf16_f32 v141, v22, v23
	v_cvt_pk_bf16_f32 v142, v16, v17
	v_cvt_pk_bf16_f32 v143, v18, v19
	global_store_dwordx4 v[144:145], v[140:143], off offset:256
	s_nop 1
	v_add_u32_e32 v140, 0xb0, v146
	v_mad_i64_i32 v[130:131], s[14:15], v140, s63, v[130:131]
	v_cvt_pk_bf16_f32 v140, v12, v13
	v_cvt_pk_bf16_f32 v141, v14, v15
	v_cvt_pk_bf16_f32 v142, v8, v9
	v_cvt_pk_bf16_f32 v143, v10, v11
	global_store_dwordx4 v[130:131], v[140:143], off
	s_mov_b64 s[14:15], 0
	s_nop 0
	v_cvt_pk_bf16_f32 v140, v4, v5
	v_cvt_pk_bf16_f32 v141, v6, v7
	v_cvt_pk_bf16_f32 v142, v0, v1
	v_cvt_pk_bf16_f32 v143, v2, v3
	global_store_dwordx4 v[130:131], v[140:143], off offset:256
